# v58 + trailing half re-creates its one-barrier offset at each unit's K-loop entry (after the unit scheduler code) instead of before it: scheduler math of waves 4-7 now runs while they would wait
# baseline (speedup 1.0000x reference)
; template <class Epi, class Sched, bool ALIGN_EPI = false, bool SP2 = false>
; __device__ __forceinline__ void gemm_phase(PG8_LAS unsigned char* lds, const Gemm g, const Sched& S, const Epi& E, const int tid_in) {
;     ...
;     const int tid = tid_l, wid = __builtin_amdgcn_readfirstlane(tid >> 6), lane = tid & 63, wr = wid >> 2, wc = wid & 3, fr = lane & 15, fq = lane >> 4;
;     const int K = g.K, nt = K / BK;
;     unsigned voffA[2], voffB[2];
; #pragma unroll
;     for (int i = 0; i < 2; ++i) { int R, C; stage_rc(tid * 16 + i * 8192, R, C); const int Rb = perm_row<Epi::PMODE>(R);
;         voffA[i] = (unsigned)(R * K + C) * 2u; voffB[i] = (unsigned)(Rb * K + C) * 2u; }
;     const size_t kstep = (size_t)(BK * 2);
;     const size_t hstep = (size_t)HALF * K * 2;
;     const size_t tstep = 2 * hstep;
;     const unsigned ldsw = (unsigned)wid * 1024u;
;     const int aoff = lds_byte(wr * 64 + fr, fq * 8), boff = lds_byte(wc * 32 + fr, fq * 8);
;     ...
;     Unit cur, nxt; int ui = 0;
;     if (!S.next(0, cur)) return;
;     f32x4 acc[2][2][4][2];
; #pragma unroll
;     for (int a = 0; a < 2; ++a)
; #pragma unroll
;         for (int b = 0; b < 2; ++b)
; #pragma unroll
;             for (int m = 0; m < 4; ++m)
; #pragma unroll
;                 for (int n = 0; n < 2; ++n) acc[a][b][m][n] = (f32x4){0.f, 0.f, 0.f, 0.f};
;     bf16x8 At[4][2], B0[2][2], B1[2][2];
;     const char* cA = (const char*)g.A + (size_t)cur.pm * tstep; const char* cB = (const char*)g.Bt + (size_t)cur.pn * tstep;
;     S.a_ready(cur);
;     if constexpr (Epi::PREF) E.prefetch(cur, 0, lds, wid, lane);
;     if constexpr (SP2) {
;         PG8_STAGE(PG8_SB(0, 0), cB, voffB); PG8_STAGE(PG8_SB(0, 1), cB + hstep, voffB); PG8_STAGE(PG8_SA(0, 0), cA, voffA); PG8_STAGE(PG8_SA(0, 1), cA + hstep, voffA);
;         if (wr == 1) PG8_BAR;
;         PG8_WAIT_V(2); PG8_BAR;
;         PG8_STAGE(PG8_SB(1, 0), cB + kstep, voffB); PG8_STAGE(PG8_SA(1, 0), cA + kstep, voffA); PG8_STAGE(PG8_SB(1, 1), cB + hstep + kstep, voffB);
;         PG8_WAIT_V(6); PG8_BAR;
; __global__ void __launch_bounds__(512, 2) mega_fwd(Args args) {
;     ...
;                 { PH_CTX const bf16_t* Win = WSP(const bf16_t, WS_WIN) + (size_t)pl * 11776 * 2048;
;                   pg8::Gemm g{Win, HB_CUR, 3584, MROWS, 2048}; pg8::StaticOrder S; S.init(3584, MROWS, G, bx); pg8::EpiG1a<0> E{WSP(bf16_t, WS_UT), WSP(bf16_t, WS_VT)};
.LBB0_342:
	v_readlane_b32 s1, v255, 15
	s_waitcnt lgkmcnt(0)
	s_cmp_ge_i32 s1, s50
	s_cselect_b64 s[40:41], -1, 0
	s_cmp_lt_i32 s1, s51
	s_cselect_b64 s[2:3], -1, 0
	s_and_b64 s[2:3], s[40:41], s[2:3]
	s_andn2_b64 vcc, exec, s[2:3]
	s_cbranch_vccnz .LBB0_463
	v_readlane_b32 s20, v252, 10
	v_readlane_b32 s1, v252, 7
	v_readlane_b32 s21, v252, 11
	v_readlane_b32 s22, v253, 24
	v_mbcnt_lo_u32_b32 v0, -1, 0
	v_mbcnt_hi_u32_b32 v0, -1, v0
	s_mov_b64 s[2:3], s[20:21]
	v_or_b32_e32 v14, s1, v0
	v_readlane_b32 s6, v254, 59
	v_readlane_b32 s7, v255, 12
	v_readlane_b32 s23, v253, 25
	s_andn2_b64 vcc, exec, s[22:23]
	v_readfirstlane_b32 s22, v14
	s_cbranch_vccnz .LBB0_359
	v_lshlrev_b32_e32 v0, 4, v14
	v_add_u32_e32 v1, 0x2000, v0
	v_ashrrev_i32_e32 v2, 31, v1
	v_lshrrev_b32_e32 v2, 22, v2
	v_add_u32_e32 v2, v1, v2
	v_ashrrev_i32_e32 v8, 10, v2
	v_mul_i32_i24_e32 v2, 0x400, v8
	v_sub_u32_e32 v1, v1, v2
	v_lshrrev_b32_e32 v2, 4, v1
	v_bitop3_b32 v1, v2, v1, 32 bitop3:0x6c
	v_ashrrev_i32_e32 v2, 31, v1
	v_lshrrev_b32_e32 v2, 26, v2
	v_add_u32_e32 v2, v1, v2
	v_lshlrev_b32_e32 v3, 3, v8
	v_ashrrev_i32_e32 v9, 6, v2
	v_and_b32_e32 v3, -16, v3
	v_add_u32_e32 v3, v9, v3
	v_lshrrev_b32_e32 v5, 2, v3
	v_lshlrev_b32_e32 v6, 1, v3
	v_and_b32_e32 v4, 0xfffe3, v3
	v_and_b32_e32 v5, 4, v5
	v_and_b32_e32 v6, 24, v6
	v_and_b32_e32 v2, 0xc0, v2
	v_or3_b32 v4, v4, v5, v6
	v_sub_u32_e32 v1, v1, v2
	v_mov_b32_e32 v6, 1
	v_lshlrev_b32_e32 v5, 5, v8
	v_ashrrev_i16_sdwa v1, v6, sext(v1) dst_sel:DWORD dst_unused:UNUSED_PAD src0_sel:DWORD src1_sel:BYTE_0
	v_and_b32_e32 v5, 32, v5
	v_bfe_i32 v10, v1, 0, 16
	v_add_lshl_u32 v1, v5, v10, 1
	v_lshl_add_u32 v130, v4, 12, v1
	v_lshl_add_u32 v132, v3, 12, v1
	v_bfe_i32 v1, v14, 27, 1
	s_load_dwordx2 s[20:21], s[2:3], 0xf0
	v_lshrrev_b32_e32 v1, 22, v1
	v_add_u32_e32 v1, v0, v1
	v_and_b32_e32 v1, 0xfffffc00, v1
	v_sub_u32_e32 v0, v0, v1
	s_mul_i32 s2, s6, 0x2e00000
	v_lshrrev_b32_e32 v1, 4, v0
	v_ashrrev_i32_e32 v2, 31, v14
	s_mul_hi_i32 s1, s6, 0x2e00000
	s_waitcnt lgkmcnt(0)
	s_add_u32 s2, s20, s2
	v_bitop3_b32 v0, v1, v0, 32 bitop3:0x6c
	v_lshrrev_b32_e32 v2, 26, v2
	s_addc_u32 s3, s21, s1
	v_ashrrev_i32_e32 v1, 31, v0
	v_add_u32_e32 v2, v14, v2
	s_add_u32 s1, s2, 0x8800000
	v_lshrrev_b32_e32 v1, 26, v1
	v_ashrrev_i32_e32 v12, 6, v2
	s_addc_u32 s5, s3, 0
	s_add_i32 s6, s6, s7
	v_add_u32_e32 v1, v0, v1
	v_lshlrev_b32_e32 v2, 3, v12
	s_bitcmp0_b32 s6, 0
	s_mov_b32 s2, 0x4f200000
	v_ashrrev_i32_e32 v11, 6, v1
	v_and_b32_e32 v2, -16, v2
	s_cselect_b32 s2, 0x28000000, s2
	v_add_u32_e32 v2, v11, v2
	s_add_u32 s8, s20, s2
	v_lshrrev_b32_e32 v4, 2, v2
	v_lshlrev_b32_e32 v5, 1, v2
	v_and_b32_e32 v1, 0xc0, v1
	s_addc_u32 s10, s21, 0
	s_ashr_i32 s23, s22, 6
	v_and_b32_e32 v3, 0xfffe3, v2
	v_and_b32_e32 v4, 4, v4
	v_and_b32_e32 v5, 24, v5
	v_sub_u32_e32 v0, v0, v1
	s_ashr_i32 s24, s22, 8
	s_lshl_b32 s19, s23, 10
	v_or3_b32 v3, v3, v4, v5
	v_lshlrev_b32_e32 v4, 5, v12
	v_ashrrev_i16_sdwa v0, v6, sext(v0) dst_sel:DWORD dst_unused:UNUSED_PAD src0_sel:DWORD src1_sel:BYTE_0
	v_readlane_b32 s2, v254, 17
	v_and_b32_e32 v4, 32, v4
	v_bfe_i32 v13, v0, 0, 16
	v_readlane_b32 s3, v254, 18
	s_add_u32 s38, s8, s2
	v_add_lshl_u32 v0, v4, v13, 1
	s_addc_u32 s39, s10, s3
	s_add_i32 s44, s19, 0
	v_lshl_add_u32 v134, v3, 12, v0
	s_add_i32 m0, s44, 0x10000
	v_lshl_add_u32 v136, v2, 12, v0
	global_load_lds_dwordx4 v134, s[38:39]
	s_add_i32 m0, s44, 0x12000
	s_add_u32 s2, s38, 0x80000
	global_load_lds_dwordx4 v130, s[38:39]
	s_addc_u32 s3, s39, 0
	s_add_i32 m0, s44, 0x14000
	v_mov_b32_e32 v135, v20
	global_load_lds_dwordx4 v134, s[2:3]
	s_add_i32 m0, s44, 0x16000
	v_mov_b32_e32 v131, v20
	global_load_lds_dwordx4 v130, s[2:3]
	v_readlane_b32 s2, v254, 15
	v_readlane_b32 s3, v254, 16
	s_add_u32 s34, s1, s2
	s_addc_u32 s35, s5, s3
	s_add_i32 s45, s44, 0x2000
	s_mov_b32 m0, s44
	s_add_u32 s2, s34, 0x80000
	global_load_lds_dwordx4 v136, s[34:35]
	s_mov_b32 m0, s45
	s_addc_u32 s3, s35, 0
	s_add_i32 s46, s44, 0x4000
	global_load_lds_dwordx4 v132, s[34:35]
	s_mov_b32 m0, s46
	s_add_i32 s47, s44, 0x6000
	global_load_lds_dwordx4 v136, s[2:3]
	s_mov_b32 m0, s47
	v_mov_b32_e32 v137, v20
	global_load_lds_dwordx4 v132, s[2:3]
	v_mov_b32_e32 v133, v20
	s_cmp_eq_u32 s24, 1
	v_lshl_add_u64 v[6:7], s[38:39], 0, v[134:135]
	v_lshl_add_u64 v[4:5], s[38:39], 0, v[130:131]
	v_lshl_add_u64 v[0:1], s[34:35], 0, v[136:137]
	s_cselect_b64 s[2:3], -1, 0
	s_cmp_lg_u32 s24, 1
	v_lshl_add_u64 v[2:3], s[34:35], 0, v[132:133]
	s_cbranch_scc1 .LBB0_346
.LBB0_346:
	s_add_u32 s6, s20, 0x35000000
	s_addc_u32 s7, s21, 0
	s_add_u32 s20, s20, 0x3b000000
	v_lshrrev_b32_e32 v16, 1, v14
	s_addc_u32 s21, s21, 0
	v_and_b32_e32 v16, 24, v16
	s_lshl_b32 s23, s23, 5
	v_and_b32_e32 v15, 15, v14
	v_lshlrev_b32_e32 v17, 1, v16
	v_lshlrev_b32_e32 v14, 2, v14
	s_and_b32 s26, s23, 0x60
	s_add_i32 m0, s44, 0x18000
	v_lshl_add_u64 v[6:7], v[6:7], 0, s[12:13]
	v_lshl_or_b32 v21, s24, 6, v15
	v_lshl_or_b32 v15, v15, 6, v17
	s_lshl_b32 s24, s24, 13
	v_and_b32_e32 v14, 32, v14
	s_lshl_b32 s23, s26, 7
	s_waitcnt vmcnt(2)
	s_barrier
	global_load_lds_dwordx4 v[6:7], off
	v_lshl_add_u64 v[4:5], v[4:5], 0, s[12:13]
	s_add_i32 m0, s44, 0x1a000
	s_add_i32 s48, s44, 0x8000
	s_add_i32 s49, s44, 0xa000
	v_bitop3_b32 v17, v15, s24, v14 bitop3:0xde
	global_load_lds_dwordx4 v[4:5], off
	v_lshl_add_u64 v[0:1], v[0:1], 0, s[12:13]
	s_mov_b32 m0, s48
	s_add_u32 s100, s34, 0x80
	s_addc_u32 s101, s35, 0
	s_add_u32 s24, s38, 0x80080
	global_load_lds_dwordx4 v[0:1], off
	v_lshl_add_u64 v[0:1], v[2:3], 0, s[12:13]
	s_mov_b32 m0, s49
	s_addc_u32 s25, s39, 0
	global_load_lds_dwordx4 v[0:1], off
	s_add_i32 m0, s44, 0x1c000
	v_lshl_add_u64 v[0:1], s[24:25], 0, v[134:135]
	global_load_lds_dwordx4 v[0:1], off
	v_lshl_add_u64 v[0:1], s[24:25], 0, v[130:131]
	s_add_i32 m0, s44, 0x1e000
	s_cmpk_lt_u32 s22, 0x100
	global_load_lds_dwordx4 v[0:1], off
	v_lshlrev_b32_e32 v0, 15, v12
	v_and_b32_e32 v0, 0xffff0000, v0
	v_lshl_add_u32 v0, v11, 12, v0
	v_and_b32_e32 v1, 1, v12
	v_lshl_or_b32 v0, v1, 6, v0
	v_lshl_add_u32 v138, v13, 1, v0
	v_lshlrev_b32_e32 v0, 15, v8
	v_and_b32_e32 v0, 0xffff0000, v0
	s_waitcnt vmcnt(6)
	v_lshl_add_u32 v0, v9, 12, v0
	v_and_b32_e32 v1, 1, v8
	v_lshl_or_b32 v0, v1, 6, v0
	v_readlane_b32 s24, v254, 13
	v_bitop3_b32 v142, v15, s23, v14 bitop3:0xde
	s_cselect_b64 s[22:23], -1, 0
	v_or_b32_e32 v143, s26, v16
	v_mov_b32_e32 v139, v20
	v_lshl_add_u32 v140, v10, 1, v0
	v_mov_b32_e32 v141, v20
	s_mov_b32 s50, 0
	v_add_u32_e32 v144, 0, v17
	v_readlane_b32 s52, v254, 27
	s_mov_b32 s51, s24
	s_barrier
	v_readlane_b32 s25, v254, 14
	s_branch .LBB0_349

; #define PG8_STAGE(bufoff, gbase, voff) do { _Pragma("unroll") for (int _i = 0; _i < 2; ++_i) \
;         __builtin_amdgcn_global_load_lds((const unsigned*)((const char*)(gbase) + (voff)[_i]), (PG8_LAS unsigned*)(lds + (bufoff) + ldsw + _i * 8192), 16, 0, 0); } while (0)
; #define PG8_LDA(dst, b, h) do { _Pragma("unroll") for (int m = 0; m < 4; ++m) _Pragma("unroll") for (int k = 0; k < 2; ++k) dst[m][k] = *(const PG8_LAS bf16x8*)(lds + PG8_SA(b, h) + aoff + m * 2048 + k * 1024); } while (0)
; #define PG8_LDB(dst, b, h) do { _Pragma("unroll") for (int n = 0; n < 2; ++n) _Pragma("unroll") for (int k = 0; k < 2; ++k) dst[n][k] = *(const PG8_LAS bf16x8*)(lds + PG8_SB(b, h) + boff + n * 2048 + k * 1024); } while (0)
; #define PG8_WAIT_V(n) asm volatile("s_waitcnt vmcnt(" #n ")" ::: "memory")
; #define PG8_WAIT_L(n) asm volatile("s_waitcnt lgkmcnt(" #n ")" ::: "memory")
; template <class Epi, class Sched, bool ALIGN_EPI = false, bool SP2 = false>
; __device__ __forceinline__ void gemm_phase(PG8_LAS unsigned char* lds, const Gemm g, const Sched& S, const Epi& E, const int tid_in) {
;     ...
;         const bool has_next = S.next(ui + 1, nxt);
;         const char* nA = has_next ? (const char*)g.A + (size_t)nxt.pm * tstep : cA; const char* nB = has_next ? (const char*)g.Bt + (size_t)nxt.pn * tstep : cB;
;         for (int t = 0; t < nt; t += 2) {
;             if constexpr (Epi::KSPLIT > 0) { if (t == Epi::KSPLIT / BK) E.midk(acc, cur, wr, wc, fr, fq); }
;             const bool last = (t == nt - 2);
;             const char* a1 = cA + (size_t)(t + 1) * kstep;
;             const char* a2 = last ? nA : cA + (size_t)(t + 2) * kstep; const char* b2 = last ? nB : cB + (size_t)(t + 2) * kstep;
;             const char* a3 = a2 + kstep; const char* b3 = b2 + kstep;
;             if (last && has_next) S.a_ready(nxt);
;             if constexpr (SP2) {
;             PG8_LDB(B0, 0, 0); PG8_LDB(B1, 0, 1); PG8_SCHED; PG8_LDA(At, 0, 0); PG8_STAGE(PG8_SA(1, 1), a1 + hstep, voffA);
;             PG8_WAIT_V(8); PG8_WAIT_L(0); PG8_BAR; PG8_MMA(0, 0, At, B0); PG8_MMA(0, 1, At, B1); PG8_BAR; PG8_SCHED;
;             PG8_LDA(At, 0, 1); PG8_STAGE(PG8_SB(0, 0), b2, voffB); PG8_STAGE(PG8_SB(0, 1), b2 + hstep, voffB); PG8_STAGE(PG8_SA(0, 0), a2, voffA);
;             PG8_WAIT_V(8); PG8_WAIT_L(0); PG8_BAR; PG8_MMA(1, 0, At, B0); PG8_MMA(1, 1, At, B1); PG8_BAR; PG8_SCHED;
.LBB0_351:
	s_ashr_i32 s27, s26, 31
	s_lshl_b64 s[28:29], s[26:27], 20
	s_add_u32 s28, s1, s28
	s_addc_u32 s29, s5, s29
	s_and_b64 s[30:31], s[36:37], exec
	s_cselect_b32 s27, s29, s35
	s_cselect_b32 s53, s28, s34
	s_ashr_i32 s25, s24, 31
	s_lshl_b64 s[30:31], s[24:25], 20
	s_add_u32 s30, s8, s30
	s_addc_u32 s31, s10, s31
	s_and_b64 s[42:43], s[36:37], exec
	s_cselect_b32 s25, s31, s39
	s_cselect_b32 s54, s30, s38
	s_add_u32 s34, s34, 0x80080
	s_addc_u32 s35, s35, 0
	s_add_u32 s55, s38, 0x100
	v_mov_b32_e32 v0, 0
	s_addc_u32 s56, s39, 0
	s_mov_b32 s57, -2
	s_cmp_lt_u32 s19, 0x1000
	s_cbranch_scc1 .LCB_352
	s_barrier
.LCB_352:
	s_mov_b32 m0, s49
	s_nop 0
	global_load_lds_dwordx4 v132, s[100:101]
	s_add_u32 s38, s34, 0xfff80080
	s_addc_u32 s39, s35, -1
	s_add_i32 s58, 0, 0x10000
	s_cmp_eq_u32 s57, 28
	s_cselect_b32 s43, s27, s39
	s_cselect_b32 s42, s53, s38
	v_add_u32_e32 v145, s58, v142
	s_cselect_b32 s39, s25, s56
	s_cselect_b32 s38, s54, s55
	s_add_i32 s60, 0, 0x14000
	ds_read_b128 v[146:149], v145
	ds_read_b128 v[150:153], v145 offset:1024
	ds_read_b128 v[154:157], v145 offset:2048
	ds_read_b128 v[158:161], v145 offset:3072
	v_add_u32_e32 v145, s60, v142
	ds_read_b128 v[162:165], v145
	ds_read_b128 v[166:169], v145 offset:1024
	ds_read_b128 v[170:173], v145 offset:2048
	ds_read_b128 v[174:177], v145 offset:3072
	s_add_i32 m0, s44, 0xc000
	ds_read_b128 v[178:181], v144
	ds_read_b128 v[182:185], v144 offset:1024
	ds_read_b128 v[186:189], v144 offset:2048
	ds_read_b128 v[190:193], v144 offset:3072
	ds_read_b128 v[194:197], v144 offset:4096
	ds_read_b128 v[198:201], v144 offset:5120
	ds_read_b128 v[202:205], v144 offset:6144
	ds_read_b128 v[208:211], v144 offset:7168
	global_load_lds_dwordx4 v138, s[34:35]
	s_add_i32 m0, s44, 0xe000
	s_nop 0
	global_load_lds_dwordx4 v140, s[34:35]
	s_waitcnt vmcnt(8)
	s_waitcnt lgkmcnt(0)
	s_barrier
	s_setprio 1
	v_mfma_f32_16x16x32_bf16 v[126:129], v[146:149], v[178:181], 0
	v_mfma_f32_16x16x32_bf16 v[122:125], v[154:157], v[178:181], 0
	v_mfma_f32_16x16x32_bf16 v[114:117], v[146:149], v[186:189], 0
	v_mfma_f32_16x16x32_bf16 v[106:109], v[154:157], v[186:189], 0
	v_mfma_f32_16x16x32_bf16 v[98:101], v[146:149], v[194:197], 0
	v_mfma_f32_16x16x32_bf16 v[90:93], v[154:157], v[194:197], 0
	v_mfma_f32_16x16x32_bf16 v[82:85], v[146:149], v[202:205], 0
	v_mfma_f32_16x16x32_bf16 v[74:77], v[154:157], v[202:205], 0
	v_mfma_f32_16x16x32_bf16 v[126:129], v[150:153], v[182:185], v[126:129]
	v_mfma_f32_16x16x32_bf16 v[122:125], v[158:161], v[182:185], v[122:125]
	v_mfma_f32_16x16x32_bf16 v[114:117], v[150:153], v[190:193], v[114:117]
	v_mfma_f32_16x16x32_bf16 v[106:109], v[158:161], v[190:193], v[106:109]
	v_mfma_f32_16x16x32_bf16 v[98:101], v[150:153], v[198:201], v[98:101]
	v_mfma_f32_16x16x32_bf16 v[90:93], v[158:161], v[198:201], v[90:93]
	v_mfma_f32_16x16x32_bf16 v[82:85], v[150:153], v[208:211], v[82:85]
	v_mfma_f32_16x16x32_bf16 v[74:77], v[158:161], v[208:211], v[74:77]
	s_setprio 0
	s_setprio 1
	v_mfma_f32_16x16x32_bf16 v[118:121], v[162:165], v[178:181], 0
	v_mfma_f32_16x16x32_bf16 v[110:113], v[170:173], v[178:181], 0
	v_mfma_f32_16x16x32_bf16 v[102:105], v[162:165], v[186:189], 0
	v_mfma_f32_16x16x32_bf16 v[94:97], v[170:173], v[186:189], 0
	v_mfma_f32_16x16x32_bf16 v[86:89], v[162:165], v[194:197], 0
	v_mfma_f32_16x16x32_bf16 v[78:81], v[170:173], v[194:197], 0
	v_mfma_f32_16x16x32_bf16 v[70:73], v[162:165], v[202:205], 0
	v_mfma_f32_16x16x32_bf16 v[66:69], v[170:173], v[202:205], 0
	v_mfma_f32_16x16x32_bf16 v[118:121], v[166:169], v[182:185], v[118:121]
	v_mfma_f32_16x16x32_bf16 v[110:113], v[174:177], v[182:185], v[110:113]
	v_mfma_f32_16x16x32_bf16 v[102:105], v[166:169], v[190:193], v[102:105]
	v_mfma_f32_16x16x32_bf16 v[94:97], v[174:177], v[190:193], v[94:97]
	v_mfma_f32_16x16x32_bf16 v[86:89], v[166:169], v[198:201], v[86:89]
	v_mfma_f32_16x16x32_bf16 v[78:81], v[174:177], v[198:201], v[78:81]
	v_mfma_f32_16x16x32_bf16 v[70:73], v[166:169], v[208:211], v[70:73]
	v_mfma_f32_16x16x32_bf16 v[66:69], v[174:177], v[208:211], v[66:69]
	s_setprio 0
	s_barrier
	s_add_i32 s58, s58, s19
	s_add_u32 s98, s38, 0x80
	s_addc_u32 s99, s39, 0
	s_mov_b32 m0, s58
	ds_read_b128 v[178:181], v144 offset:16384
	ds_read_b128 v[182:185], v144 offset:17408
	ds_read_b128 v[186:189], v144 offset:18432
	ds_read_b128 v[190:193], v144 offset:19456
	ds_read_b128 v[194:197], v144 offset:20480
	ds_read_b128 v[198:201], v144 offset:21504
	ds_read_b128 v[202:205], v144 offset:22528
	ds_read_b128 v[208:211], v144 offset:23552
	global_load_lds_dwordx4 v134, s[38:39]
	s_add_i32 m0, s58, 0x2000
	s_add_u32 s58, s38, 0x80000
	s_addc_u32 s59, s39, 0
	s_add_i32 s60, s60, s19
	global_load_lds_dwordx4 v130, s[38:39]
	s_mov_b32 m0, s60
	s_add_u32 s100, s42, 0x80
	s_addc_u32 s101, s43, 0
	global_load_lds_dwordx4 v134, s[58:59]
	s_add_i32 m0, s60, 0x2000
	s_nop 0
	global_load_lds_dwordx4 v130, s[58:59]
	s_mov_b32 m0, s44
	s_nop 0
	global_load_lds_dwordx4 v136, s[42:43]
	s_waitcnt vmcnt(7)
	s_waitcnt lgkmcnt(0)
	s_barrier
; #define PG8_STAGE(bufoff, gbase, voff) do { _Pragma("unroll") for (int _i = 0; _i < 2; ++_i) \
;         __builtin_amdgcn_global_load_lds((const unsigned*)((const char*)(gbase) + (voff)[_i]), (PG8_LAS unsigned*)(lds + (bufoff) + ldsw + _i * 8192), 16, 0, 0); } while (0)
; #define PG8_LDA(dst, b, h) do { _Pragma("unroll") for (int m = 0; m < 4; ++m) _Pragma("unroll") for (int k = 0; k < 2; ++k) dst[m][k] = *(const PG8_LAS bf16x8*)(lds + PG8_SA(b, h) + aoff + m * 2048 + k * 1024); } while (0)
; #define PG8_LDB(dst, b, h) do { _Pragma("unroll") for (int n = 0; n < 2; ++n) _Pragma("unroll") for (int k = 0; k < 2; ++k) dst[n][k] = *(const PG8_LAS bf16x8*)(lds + PG8_SB(b, h) + boff + n * 2048 + k * 1024); } while (0)
; #define PG8_MMA(ai, bj, At, Bt) do { __builtin_amdgcn_s_setprio(1); _Pragma("unroll") for (int m = 0; m < 4; ++m) _Pragma("unroll") for (int n = 0; n < 2; ++n) _Pragma("unroll") for (int k = 0; k < 2; ++k) \
;         acc[ai][bj][m][n] = __builtin_amdgcn_mfma_f32_16x16x32_bf16(Bt[n][k], At[m][k], acc[ai][bj][m][n], 0, 0, 0); __builtin_amdgcn_s_setprio(0); } while (0)
; #define PG8_WAIT_V(n) asm volatile("s_waitcnt vmcnt(" #n ")" ::: "memory")
; #define PG8_WAIT_L(n) asm volatile("s_waitcnt lgkmcnt(" #n ")" ::: "memory")
; #define PG8_BAR __builtin_amdgcn_s_barrier()
; #define PG8_SCHED __builtin_amdgcn_sched_barrier(0)
; template <class Epi, class Sched, bool ALIGN_EPI = false, bool SP2 = false>
; __device__ __forceinline__ void gemm_phase(PG8_LAS unsigned char* lds, const Gemm g, const Sched& S, const Epi& E, const int tid_in) {
;     ...
;             PG8_WAIT_V(8); PG8_WAIT_L(0); PG8_BAR; PG8_MMA(1, 0, At, B0); PG8_MMA(1, 1, At, B1); PG8_BAR; PG8_SCHED;
;             PG8_LDB(B0, 1, 0); PG8_LDB(B1, 1, 1); PG8_SCHED; PG8_LDA(At, 1, 0); PG8_STAGE(PG8_SA(0, 1), a2 + hstep, voffA);
;             PG8_WAIT_V(8); PG8_WAIT_L(0); PG8_BAR; PG8_MMA(0, 0, At, B0); PG8_MMA(0, 1, At, B1); PG8_BAR; PG8_SCHED;
;             PG8_LDA(At, 1, 1); PG8_STAGE(PG8_SB(1, 0), b3, voffB); PG8_STAGE(PG8_SB(1, 1), b3 + hstep, voffB); PG8_STAGE(PG8_SA(1, 0), a3, voffA);
	s_setprio 1
	v_mfma_f32_16x16x32_bf16 v[62:65], v[146:149], v[178:181], 0
	v_mfma_f32_16x16x32_bf16 v[58:61], v[154:157], v[178:181], 0
	v_mfma_f32_16x16x32_bf16 v[50:53], v[146:149], v[186:189], 0
	v_mfma_f32_16x16x32_bf16 v[42:45], v[154:157], v[186:189], 0
	v_mfma_f32_16x16x32_bf16 v[34:37], v[146:149], v[194:197], 0
	v_mfma_f32_16x16x32_bf16 v[26:29], v[154:157], v[194:197], 0
	v_mfma_f32_16x16x32_bf16 v[16:19], v[146:149], v[202:205], 0
	v_mfma_f32_16x16x32_bf16 v[8:11], v[154:157], v[202:205], 0
	v_mfma_f32_16x16x32_bf16 v[62:65], v[150:153], v[182:185], v[62:65]
	v_mfma_f32_16x16x32_bf16 v[58:61], v[158:161], v[182:185], v[58:61]
	v_mfma_f32_16x16x32_bf16 v[50:53], v[150:153], v[190:193], v[50:53]
	v_mfma_f32_16x16x32_bf16 v[42:45], v[158:161], v[190:193], v[42:45]
	v_mfma_f32_16x16x32_bf16 v[34:37], v[150:153], v[198:201], v[34:37]
	v_mfma_f32_16x16x32_bf16 v[26:29], v[158:161], v[198:201], v[26:29]
	v_mfma_f32_16x16x32_bf16 v[16:19], v[150:153], v[208:211], v[16:19]
	v_mfma_f32_16x16x32_bf16 v[8:11], v[158:161], v[208:211], v[8:11]
	s_setprio 0
	s_setprio 1
	v_mfma_f32_16x16x32_bf16 v[54:57], v[162:165], v[178:181], 0
	v_mfma_f32_16x16x32_bf16 v[46:49], v[170:173], v[178:181], 0
	v_mfma_f32_16x16x32_bf16 v[38:41], v[162:165], v[186:189], 0
	v_mfma_f32_16x16x32_bf16 v[30:33], v[170:173], v[186:189], 0
	v_mfma_f32_16x16x32_bf16 v[22:25], v[162:165], v[194:197], 0
	v_mfma_f32_16x16x32_bf16 v[12:15], v[170:173], v[194:197], 0
	v_mfma_f32_16x16x32_bf16 v[4:7], v[162:165], v[202:205], 0
	v_mfma_f32_16x16x32_bf16 v[0:3], v[170:173], v[202:205], 0
	v_mfma_f32_16x16x32_bf16 v[54:57], v[166:169], v[182:185], v[54:57]
	v_mfma_f32_16x16x32_bf16 v[46:49], v[174:177], v[182:185], v[46:49]
	v_mfma_f32_16x16x32_bf16 v[38:41], v[166:169], v[190:193], v[38:41]
	v_mfma_f32_16x16x32_bf16 v[30:33], v[174:177], v[190:193], v[30:33]
	v_mfma_f32_16x16x32_bf16 v[22:25], v[166:169], v[198:201], v[22:25]
	v_mfma_f32_16x16x32_bf16 v[12:15], v[174:177], v[198:201], v[12:15]
	v_mfma_f32_16x16x32_bf16 v[4:7], v[166:169], v[208:211], v[4:7]
	v_mfma_f32_16x16x32_bf16 v[0:3], v[174:177], v[208:211], v[0:3]
	s_setprio 0
	s_barrier
	s_add_i32 s58, 0, 0x18000
	v_add_u32_e32 v145, s58, v142
	s_add_i32 s59, 0, 0x1c000
	ds_read_b128 v[146:149], v145
	ds_read_b128 v[150:153], v145 offset:1024
	ds_read_b128 v[154:157], v145 offset:2048
	ds_read_b128 v[158:161], v145 offset:3072
	v_add_u32_e32 v145, s59, v142
	ds_read_b128 v[162:165], v145
	ds_read_b128 v[166:169], v145 offset:1024
	ds_read_b128 v[170:173], v145 offset:2048
	ds_read_b128 v[174:177], v145 offset:3072
	s_mov_b32 m0, s45
	s_nop 0
	global_load_lds_dwordx4 v132, s[42:43]
	s_add_u32 s42, s42, 0x80000
	s_addc_u32 s43, s43, 0
	s_mov_b32 m0, s46
	ds_read_b128 v[178:181], v144 offset:32768
	ds_read_b128 v[182:185], v144 offset:33792
	ds_read_b128 v[186:189], v144 offset:34816
	ds_read_b128 v[190:193], v144 offset:35840
	ds_read_b128 v[194:197], v144 offset:36864
	ds_read_b128 v[198:201], v144 offset:37888
	ds_read_b128 v[202:205], v144 offset:38912
	ds_read_b128 v[208:211], v144 offset:39936
	global_load_lds_dwordx4 v136, s[42:43]
	s_mov_b32 m0, s47
	s_nop 0
	global_load_lds_dwordx4 v132, s[42:43]
	s_waitcnt vmcnt(8)
	s_waitcnt lgkmcnt(0)
	s_barrier
	s_setprio 1
	v_mfma_f32_16x16x32_bf16 v[126:129], v[146:149], v[178:181], v[126:129]
	v_mfma_f32_16x16x32_bf16 v[122:125], v[154:157], v[178:181], v[122:125]
	v_mfma_f32_16x16x32_bf16 v[114:117], v[146:149], v[186:189], v[114:117]
	v_mfma_f32_16x16x32_bf16 v[106:109], v[154:157], v[186:189], v[106:109]
	v_mfma_f32_16x16x32_bf16 v[98:101], v[146:149], v[194:197], v[98:101]
	v_mfma_f32_16x16x32_bf16 v[90:93], v[154:157], v[194:197], v[90:93]
	v_mfma_f32_16x16x32_bf16 v[82:85], v[146:149], v[202:205], v[82:85]
	v_mfma_f32_16x16x32_bf16 v[74:77], v[154:157], v[202:205], v[74:77]
	v_mfma_f32_16x16x32_bf16 v[126:129], v[150:153], v[182:185], v[126:129]
	v_mfma_f32_16x16x32_bf16 v[122:125], v[158:161], v[182:185], v[122:125]
	v_mfma_f32_16x16x32_bf16 v[114:117], v[150:153], v[190:193], v[114:117]
	v_mfma_f32_16x16x32_bf16 v[106:109], v[158:161], v[190:193], v[106:109]
	v_mfma_f32_16x16x32_bf16 v[98:101], v[150:153], v[198:201], v[98:101]
	v_mfma_f32_16x16x32_bf16 v[90:93], v[158:161], v[198:201], v[90:93]
	v_mfma_f32_16x16x32_bf16 v[82:85], v[150:153], v[208:211], v[82:85]
	v_mfma_f32_16x16x32_bf16 v[74:77], v[158:161], v[208:211], v[74:77]
	s_setprio 0
	s_setprio 1
	v_mfma_f32_16x16x32_bf16 v[118:121], v[162:165], v[178:181], v[118:121]
	v_mfma_f32_16x16x32_bf16 v[110:113], v[170:173], v[178:181], v[110:113]
	v_mfma_f32_16x16x32_bf16 v[102:105], v[162:165], v[186:189], v[102:105]
	v_mfma_f32_16x16x32_bf16 v[94:97], v[170:173], v[186:189], v[94:97]
	v_mfma_f32_16x16x32_bf16 v[86:89], v[162:165], v[194:197], v[86:89]
	v_mfma_f32_16x16x32_bf16 v[78:81], v[170:173], v[194:197], v[78:81]
	v_mfma_f32_16x16x32_bf16 v[70:73], v[162:165], v[202:205], v[70:73]
	v_mfma_f32_16x16x32_bf16 v[66:69], v[170:173], v[202:205], v[66:69]
	v_mfma_f32_16x16x32_bf16 v[118:121], v[166:169], v[182:185], v[118:121]
	v_mfma_f32_16x16x32_bf16 v[110:113], v[174:177], v[182:185], v[110:113]
	v_mfma_f32_16x16x32_bf16 v[102:105], v[166:169], v[190:193], v[102:105]
	v_mfma_f32_16x16x32_bf16 v[94:97], v[174:177], v[190:193], v[94:97]
	v_mfma_f32_16x16x32_bf16 v[86:89], v[166:169], v[198:201], v[86:89]
	v_mfma_f32_16x16x32_bf16 v[78:81], v[174:177], v[198:201], v[78:81]
	v_mfma_f32_16x16x32_bf16 v[70:73], v[166:169], v[208:211], v[70:73]
	v_mfma_f32_16x16x32_bf16 v[66:69], v[174:177], v[208:211], v[66:69]
	s_setprio 0
	s_barrier
; #define PG8_STAGE(bufoff, gbase, voff) do { _Pragma("unroll") for (int _i = 0; _i < 2; ++_i) \
;         __builtin_amdgcn_global_load_lds((const unsigned*)((const char*)(gbase) + (voff)[_i]), (PG8_LAS unsigned*)(lds + (bufoff) + ldsw + _i * 8192), 16, 0, 0); } while (0)
; #define PG8_LDA(dst, b, h) do { _Pragma("unroll") for (int m = 0; m < 4; ++m) _Pragma("unroll") for (int k = 0; k < 2; ++k) dst[m][k] = *(const PG8_LAS bf16x8*)(lds + PG8_SA(b, h) + aoff + m * 2048 + k * 1024); } while (0)
; #define PG8_MMA(ai, bj, At, Bt) do { __builtin_amdgcn_s_setprio(1); _Pragma("unroll") for (int m = 0; m < 4; ++m) _Pragma("unroll") for (int n = 0; n < 2; ++n) _Pragma("unroll") for (int k = 0; k < 2; ++k) \
;         acc[ai][bj][m][n] = __builtin_amdgcn_mfma_f32_16x16x32_bf16(Bt[n][k], At[m][k], acc[ai][bj][m][n], 0, 0, 0); __builtin_amdgcn_s_setprio(0); } while (0)
; #define PG8_WAIT_V(n) asm volatile("s_waitcnt vmcnt(" #n ")" ::: "memory")
; #define PG8_WAIT_L(n) asm volatile("s_waitcnt lgkmcnt(" #n ")" ::: "memory")
; #define PG8_BAR __builtin_amdgcn_s_barrier()
; #define PG8_SCHED __builtin_amdgcn_sched_barrier(0)
; template <class Epi, class Sched, bool ALIGN_EPI = false, bool SP2 = false>
; __device__ __forceinline__ void gemm_phase(PG8_LAS unsigned char* lds, const Gemm g, const Sched& S, const Epi& E, const int tid_in) {
;     ...
;             PG8_LDA(At, 1, 1); PG8_STAGE(PG8_SB(1, 0), b3, voffB); PG8_STAGE(PG8_SB(1, 1), b3 + hstep, voffB); PG8_STAGE(PG8_SA(1, 0), a3, voffA);
;             PG8_WAIT_V(8); PG8_WAIT_L(0); PG8_BAR; PG8_MMA(1, 0, At, B0); PG8_MMA(1, 1, At, B1); PG8_BAR; PG8_SCHED;
	s_add_i32 s42, s58, s19
	s_mov_b32 m0, s42
	ds_read_b128 v[178:181], v144 offset:49152
	ds_read_b128 v[182:185], v144 offset:50176
	ds_read_b128 v[186:189], v144 offset:51200
	ds_read_b128 v[190:193], v144 offset:52224
	ds_read_b128 v[194:197], v144 offset:53248
	ds_read_b128 v[198:201], v144 offset:54272
	ds_read_b128 v[202:205], v144 offset:55296
	ds_read_b128 v[208:211], v144 offset:56320
	global_load_lds_dwordx4 v134, s[98:99]
	s_add_i32 m0, s42, 0x2000
	s_add_u32 s38, s38, 0x80080
	s_addc_u32 s39, s39, 0
	s_add_i32 s42, s59, s19
	global_load_lds_dwordx4 v130, s[98:99]
	s_mov_b32 m0, s42
	s_nop 0
	global_load_lds_dwordx4 v134, s[38:39]
	s_add_i32 m0, s42, 0x2000
	s_nop 0
	global_load_lds_dwordx4 v130, s[38:39]
	s_mov_b32 m0, s48
	s_nop 0
	global_load_lds_dwordx4 v136, s[100:101]
	s_waitcnt vmcnt(7)
	s_waitcnt lgkmcnt(0)
	s_barrier
	s_setprio 1
	v_mfma_f32_16x16x32_bf16 v[62:65], v[146:149], v[178:181], v[62:65]
	v_mfma_f32_16x16x32_bf16 v[58:61], v[154:157], v[178:181], v[58:61]
	v_mfma_f32_16x16x32_bf16 v[50:53], v[146:149], v[186:189], v[50:53]
	v_mfma_f32_16x16x32_bf16 v[42:45], v[154:157], v[186:189], v[42:45]
	v_mfma_f32_16x16x32_bf16 v[34:37], v[146:149], v[194:197], v[34:37]
	v_mfma_f32_16x16x32_bf16 v[26:29], v[154:157], v[194:197], v[26:29]
	v_mfma_f32_16x16x32_bf16 v[16:19], v[146:149], v[202:205], v[16:19]
	v_mfma_f32_16x16x32_bf16 v[8:11], v[154:157], v[202:205], v[8:11]
	v_mfma_f32_16x16x32_bf16 v[62:65], v[150:153], v[182:185], v[62:65]
	v_mfma_f32_16x16x32_bf16 v[58:61], v[158:161], v[182:185], v[58:61]
	v_mfma_f32_16x16x32_bf16 v[50:53], v[150:153], v[190:193], v[50:53]
	v_mfma_f32_16x16x32_bf16 v[42:45], v[158:161], v[190:193], v[42:45]
	v_mfma_f32_16x16x32_bf16 v[34:37], v[150:153], v[198:201], v[34:37]
	v_mfma_f32_16x16x32_bf16 v[26:29], v[158:161], v[198:201], v[26:29]
	v_mfma_f32_16x16x32_bf16 v[16:19], v[150:153], v[208:211], v[16:19]
	v_mfma_f32_16x16x32_bf16 v[8:11], v[158:161], v[208:211], v[8:11]
	s_setprio 0
	s_setprio 1
	v_mfma_f32_16x16x32_bf16 v[54:57], v[162:165], v[178:181], v[54:57]
	v_mfma_f32_16x16x32_bf16 v[46:49], v[170:173], v[178:181], v[46:49]
	v_mfma_f32_16x16x32_bf16 v[38:41], v[162:165], v[186:189], v[38:41]
	v_mfma_f32_16x16x32_bf16 v[30:33], v[170:173], v[186:189], v[30:33]
	v_mfma_f32_16x16x32_bf16 v[22:25], v[162:165], v[194:197], v[22:25]
	v_mfma_f32_16x16x32_bf16 v[12:15], v[170:173], v[194:197], v[12:15]
	v_mfma_f32_16x16x32_bf16 v[4:7], v[162:165], v[202:205], v[4:7]
	v_mfma_f32_16x16x32_bf16 v[0:3], v[170:173], v[202:205], v[0:3]
	v_mfma_f32_16x16x32_bf16 v[54:57], v[166:169], v[182:185], v[54:57]
	v_mfma_f32_16x16x32_bf16 v[46:49], v[174:177], v[182:185], v[46:49]
	v_mfma_f32_16x16x32_bf16 v[38:41], v[166:169], v[190:193], v[38:41]
	v_mfma_f32_16x16x32_bf16 v[30:33], v[174:177], v[190:193], v[30:33]
	v_mfma_f32_16x16x32_bf16 v[22:25], v[166:169], v[198:201], v[22:25]
	v_mfma_f32_16x16x32_bf16 v[12:15], v[174:177], v[198:201], v[12:15]
	v_mfma_f32_16x16x32_bf16 v[4:7], v[166:169], v[208:211], v[4:7]
	v_mfma_f32_16x16x32_bf16 v[0:3], v[174:177], v[208:211], v[0:3]
	s_setprio 0
	s_barrier
	s_add_i32 s57, s57, 2
	s_add_u32 s34, s34, 0x100
	s_addc_u32 s35, s35, 0
	s_add_u32 s55, s55, 0x100
	s_addc_u32 s56, s56, 0
	s_cmp_gt_u32 s57, 29

; __device__ __forceinline__ unsigned cvt_pk_bf16(float lo, float hi) { unsigned r; asm volatile("v_cvt_pk_bf16_f32 %0, %1, %2" : "=v"(r) : "v"(lo), "v"(hi)); return r; }
;     __device__ __forceinline__ void operator()(const f32x4 (&acc)[2][2][4][2], const Unit& u, int wr, int wc, int fr, int fq) const {
;         const int row0 = u.pm * BM + wr * 64 + fr;
;         const int T0 = u.pn * BM, bseq = T0 >> 12, t0 = T0 & 4095;
; #pragma unroll
;         for (int ai = 0; ai < 2; ++ai)
; #pragma unroll
;             for (int m = 0; m < 4; ++m) {
;                 const int nn = row0 + ai * HALF + m * 16;
; #pragma unroll
;                 for (int bj = 0; bj < 2; ++bj) {
;                     const f32x4 v0 = acc[ai][bj][m][0], v1 = acc[ai][bj][m][1];
;                     u32x4 w; w.x = cvt_pk_bf16(v0[0], v0[1]); w.y = cvt_pk_bf16(v0[2], v0[3]); w.z = cvt_pk_bf16(v1[0], v1[1]); w.w = cvt_pk_bf16(v1[2], v1[3]);
;                     const int th = t0 + bj * HALF;
;                     if (VM == 0) {
;                         const int t = th + wc * 32 + 8 * fq;
;                         if (u.pm < 12) *(u32x4*)(UT + ((size_t)(bseq * 3072 + nn)) * 4096 + t) = w;
;                         else *(u32x4*)(VT + ((size_t)(bseq * 1536 + (nn - 3072))) * 4096 + t) = w;
;                     } else if (VM == 1) {
;                         *(u32x4*)(VT + ((size_t)(bseq * 1536 + 512 + nn)) * 4096 + fq * 1024 + (th >> 2) + 8 * wc) = w;
;                     } else {
;                         *(u32x4*)(VT + ((size_t)(bseq * 1536 + 1024 + nn)) * 4096 + (4 * wc + fq) * 256 + (th >> 4)) = w;
;                     }
;                 }
;             }
;     }
.LBB0_355:
	s_lshl_b32 s25, s52, 8
	s_ashr_i32 s34, s52, 4
	s_and_b32 s25, s25, 0xf00
	s_mul_i32 s27, s34, 0x600
	v_lshl_add_u32 v145, s51, 8, v21
	v_or_b32_e32 v150, s25, v143
	s_addk_i32 s27, 0xf400
	s_mul_i32 s25, s34, 0xc00
	v_add_u32_e32 v146, s27, v145
	v_add_u32_e32 v148, s25, v145
	v_ashrrev_i32_e32 v147, 31, v146
	v_ashrrev_i32_e32 v149, 31, v148
	v_lshlrev_b64 v[146:147], 13, v[146:147]
	v_lshlrev_b64 v[148:149], 13, v[148:149]
	s_cmp_lt_i32 s51, 12
	v_cvt_pk_bf16_f32 v126, v126, v127
	v_cvt_pk_bf16_f32 v127, v128, v129
	v_cvt_pk_bf16_f32 v128, v122, v123
	v_cvt_pk_bf16_f32 v129, v124, v125
	v_lshl_add_u64 v[122:123], s[20:21], 0, v[146:147]
	v_lshl_add_u64 v[124:125], s[6:7], 0, v[148:149]
	s_cselect_b64 vcc, -1, 0
	v_cndmask_b32_e32 v125, v123, v125, vcc
	v_cndmask_b32_e32 v124, v122, v124, vcc
	v_lshlrev_b32_e32 v122, 1, v150
	v_mov_b32_e32 v123, v20
	v_lshl_add_u64 v[124:125], v[124:125], 0, v[122:123]
	global_store_dwordx4 v[124:125], v[126:129], off
	v_cvt_pk_bf16_f32 v118, v118, v119
	v_cvt_pk_bf16_f32 v119, v120, v121
	v_cvt_pk_bf16_f32 v120, v110, v111
	v_cvt_pk_bf16_f32 v121, v112, v113
	v_or_b32_e32 v112, 16, v145
	v_add_u32_e32 v110, s27, v112
	v_ashrrev_i32_e32 v111, 31, v110
	global_store_dwordx4 v[124:125], v[118:121], off offset:256
	s_mov_b64 s[34:35], -1
	v_readlane_b32 s53, v255, 10
	v_lshlrev_b64 v[118:119], 13, v[110:111]
	v_add_u32_e32 v110, s25, v112
	v_ashrrev_i32_e32 v111, 31, v110
	v_lshlrev_b64 v[120:121], 13, v[110:111]
	v_cvt_pk_bf16_f32 v110, v114, v115
	v_cvt_pk_bf16_f32 v111, v116, v117
	v_cvt_pk_bf16_f32 v112, v106, v107
	v_cvt_pk_bf16_f32 v113, v108, v109
	v_lshl_add_u64 v[106:107], s[6:7], 0, v[120:121]
	v_lshl_add_u64 v[108:109], s[20:21], 0, v[118:119]
	v_cndmask_b32_e32 v107, v109, v107, vcc
	v_cndmask_b32_e32 v106, v108, v106, vcc
	v_lshl_add_u64 v[106:107], v[106:107], 0, v[122:123]
	global_store_dwordx4 v[106:107], v[110:113], off
	v_cvt_pk_bf16_f32 v102, v102, v103
	v_cvt_pk_bf16_f32 v103, v104, v105
	v_cvt_pk_bf16_f32 v104, v94, v95
	v_cvt_pk_bf16_f32 v105, v96, v97
	v_or_b32_e32 v96, 32, v145
	v_add_u32_e32 v94, s27, v96
	v_ashrrev_i32_e32 v95, 31, v94
	global_store_dwordx4 v[106:107], v[102:105], off offset:256
	v_readlane_b32 s57, v255, 11
	s_movk_i32 s54, 0xffc0
	v_lshlrev_b64 v[102:103], 13, v[94:95]
	v_add_u32_e32 v94, s25, v96
	v_ashrrev_i32_e32 v95, 31, v94
	v_lshlrev_b64 v[104:105], 13, v[94:95]
	v_cvt_pk_bf16_f32 v94, v98, v99
	v_cvt_pk_bf16_f32 v95, v100, v101
	v_cvt_pk_bf16_f32 v96, v90, v91
	v_cvt_pk_bf16_f32 v97, v92, v93
	v_lshl_add_u64 v[90:91], s[6:7], 0, v[104:105]
	v_lshl_add_u64 v[92:93], s[20:21], 0, v[102:103]
	v_cndmask_b32_e32 v91, v93, v91, vcc
	v_cndmask_b32_e32 v90, v92, v90, vcc
	v_lshl_add_u64 v[90:91], v[90:91], 0, v[122:123]
	global_store_dwordx4 v[90:91], v[94:97], off
	v_cvt_pk_bf16_f32 v86, v86, v87
	v_cvt_pk_bf16_f32 v87, v88, v89
	v_cvt_pk_bf16_f32 v88, v78, v79
	v_cvt_pk_bf16_f32 v89, v80, v81
	v_or_b32_e32 v80, 48, v145
	v_add_u32_e32 v78, s27, v80
	v_ashrrev_i32_e32 v79, 31, v78
	global_store_dwordx4 v[90:91], v[86:89], off offset:256
	s_movk_i32 s55, 0xc00
	s_mov_b32 s56, 0xfe03f81
	v_lshlrev_b64 v[86:87], 13, v[78:79]
	v_add_u32_e32 v78, s25, v80
	v_ashrrev_i32_e32 v79, 31, v78
	v_lshlrev_b64 v[88:89], 13, v[78:79]
	v_cvt_pk_bf16_f32 v78, v82, v83
	v_cvt_pk_bf16_f32 v79, v84, v85
	v_cvt_pk_bf16_f32 v80, v74, v75
	v_cvt_pk_bf16_f32 v81, v76, v77
	v_lshl_add_u64 v[74:75], s[6:7], 0, v[88:89]
	v_lshl_add_u64 v[76:77], s[20:21], 0, v[86:87]
	v_cndmask_b32_e32 v75, v77, v75, vcc
	v_cndmask_b32_e32 v74, v76, v74, vcc
	v_lshl_add_u64 v[74:75], v[74:75], 0, v[122:123]
; __device__ __forceinline__ unsigned cvt_pk_bf16(float lo, float hi) { unsigned r; asm volatile("v_cvt_pk_bf16_f32 %0, %1, %2" : "=v"(r) : "v"(lo), "v"(hi)); return r; }
; #define PG8_BAR __builtin_amdgcn_s_barrier()
;     __device__ __forceinline__ void operator()(const f32x4 (&acc)[2][2][4][2], const Unit& u, int wr, int wc, int fr, int fq) const {
;         const int row0 = u.pm * BM + wr * 64 + fr;
;         const int T0 = u.pn * BM, bseq = T0 >> 12, t0 = T0 & 4095;
; #pragma unroll
;         for (int ai = 0; ai < 2; ++ai)
; #pragma unroll
;             for (int m = 0; m < 4; ++m) {
;                 const int nn = row0 + ai * HALF + m * 16;
; #pragma unroll
;                 for (int bj = 0; bj < 2; ++bj) {
;                     const f32x4 v0 = acc[ai][bj][m][0], v1 = acc[ai][bj][m][1];
;                     u32x4 w; w.x = cvt_pk_bf16(v0[0], v0[1]); w.y = cvt_pk_bf16(v0[2], v0[3]); w.z = cvt_pk_bf16(v1[0], v1[1]); w.w = cvt_pk_bf16(v1[2], v1[3]);
;                     const int th = t0 + bj * HALF;
;                     if (VM == 0) {
;                         const int t = th + wc * 32 + 8 * fq;
;                         if (u.pm < 12) *(u32x4*)(UT + ((size_t)(bseq * 3072 + nn)) * 4096 + t) = w;
;                         else *(u32x4*)(VT + ((size_t)(bseq * 1536 + (nn - 3072))) * 4096 + t) = w;
;                     } else if (VM == 1) {
;                         *(u32x4*)(VT + ((size_t)(bseq * 1536 + 512 + nn)) * 4096 + fq * 1024 + (th >> 2) + 8 * wc) = w;
;                     } else {
;                         *(u32x4*)(VT + ((size_t)(bseq * 1536 + 1024 + nn)) * 4096 + (4 * wc + fq) * 256 + (th >> 4)) = w;
;                     }
;                 }
;             }
;     }
; template <class Epi, class Sched, bool ALIGN_EPI = false, bool SP2 = false>
; __device__ __forceinline__ void gemm_phase(PG8_LAS unsigned char* lds, const Gemm g, const Sched& S, const Epi& E, const int tid_in) {
;     ...
;         if (!has_next) break;
; #pragma unroll
;         for (int a = 0; a < 2; ++a)
; #pragma unroll
;             for (int b = 0; b < 2; ++b)
; #pragma unroll
;                 for (int m = 0; m < 4; ++m)
; #pragma unroll
;                     for (int n = 0; n < 2; ++n) acc[a][b][m][n] = (f32x4){0.f, 0.f, 0.f, 0.f};
;         cur = nxt; cA = nA; cB = nB; ++ui;
;         if constexpr (ALIGN_EPI) { if (wr == 1) PG8_BAR; }
	global_store_dwordx4 v[74:75], v[78:81], off
	v_cvt_pk_bf16_f32 v70, v70, v71
	v_cvt_pk_bf16_f32 v71, v72, v73
	v_cvt_pk_bf16_f32 v72, v66, v67
	v_cvt_pk_bf16_f32 v73, v68, v69
	v_add_u32_e32 v68, 0x80, v145
	v_add_u32_e32 v66, s27, v68
	v_add_u32_e32 v68, s25, v68
	v_ashrrev_i32_e32 v67, 31, v66
	v_ashrrev_i32_e32 v69, 31, v68
	v_lshlrev_b64 v[66:67], 13, v[66:67]
	v_lshlrev_b64 v[68:69], 13, v[68:69]
	global_store_dwordx4 v[74:75], v[70:73], off offset:256
	v_cvt_pk_bf16_f32 v62, v62, v63
	v_cvt_pk_bf16_f32 v63, v64, v65
	v_cvt_pk_bf16_f32 v64, v58, v59
	v_cvt_pk_bf16_f32 v65, v60, v61
	v_lshl_add_u64 v[58:59], s[6:7], 0, v[68:69]
	v_lshl_add_u64 v[60:61], s[20:21], 0, v[66:67]
	v_cndmask_b32_e32 v59, v61, v59, vcc
	v_cndmask_b32_e32 v58, v60, v58, vcc
	v_lshl_add_u64 v[58:59], v[58:59], 0, v[122:123]
	global_store_dwordx4 v[58:59], v[62:65], off
	v_cvt_pk_bf16_f32 v54, v54, v55
	v_cvt_pk_bf16_f32 v55, v56, v57
	v_cvt_pk_bf16_f32 v56, v46, v47
	v_cvt_pk_bf16_f32 v57, v48, v49
	v_add_u32_e32 v48, 0x90, v145
	v_add_u32_e32 v46, s27, v48
	v_ashrrev_i32_e32 v47, 31, v46
	global_store_dwordx4 v[58:59], v[54:57], off offset:256
	s_nop 1
	v_lshlrev_b64 v[54:55], 13, v[46:47]
	v_add_u32_e32 v46, s25, v48
	v_ashrrev_i32_e32 v47, 31, v46
	v_lshlrev_b64 v[56:57], 13, v[46:47]
	v_cvt_pk_bf16_f32 v46, v50, v51
	v_cvt_pk_bf16_f32 v47, v52, v53
	v_cvt_pk_bf16_f32 v48, v42, v43
	v_cvt_pk_bf16_f32 v49, v44, v45
	v_lshl_add_u64 v[42:43], s[6:7], 0, v[56:57]
	v_lshl_add_u64 v[44:45], s[20:21], 0, v[54:55]
	v_cndmask_b32_e32 v43, v45, v43, vcc
	v_cndmask_b32_e32 v42, v44, v42, vcc
	v_lshl_add_u64 v[42:43], v[42:43], 0, v[122:123]
	global_store_dwordx4 v[42:43], v[46:49], off
	v_cvt_pk_bf16_f32 v38, v38, v39
	v_cvt_pk_bf16_f32 v39, v40, v41
	v_cvt_pk_bf16_f32 v40, v30, v31
	v_cvt_pk_bf16_f32 v41, v32, v33
	v_add_u32_e32 v32, 0xa0, v145
	v_add_u32_e32 v30, s27, v32
	v_ashrrev_i32_e32 v31, 31, v30
	global_store_dwordx4 v[42:43], v[38:41], off offset:256
	s_nop 1
	v_lshlrev_b64 v[38:39], 13, v[30:31]
	v_add_u32_e32 v30, s25, v32
	v_ashrrev_i32_e32 v31, 31, v30
	v_lshlrev_b64 v[40:41], 13, v[30:31]
	v_cvt_pk_bf16_f32 v30, v34, v35
	v_cvt_pk_bf16_f32 v31, v36, v37
	v_cvt_pk_bf16_f32 v32, v26, v27
	v_cvt_pk_bf16_f32 v33, v28, v29
	v_lshl_add_u64 v[26:27], s[6:7], 0, v[40:41]
	v_lshl_add_u64 v[28:29], s[20:21], 0, v[38:39]
	v_cndmask_b32_e32 v27, v29, v27, vcc
	v_cndmask_b32_e32 v26, v28, v26, vcc
	v_lshl_add_u64 v[26:27], v[26:27], 0, v[122:123]
	global_store_dwordx4 v[26:27], v[30:33], off
	v_cvt_pk_bf16_f32 v22, v22, v23
	v_cvt_pk_bf16_f32 v23, v24, v25
	v_cvt_pk_bf16_f32 v24, v12, v13
	v_cvt_pk_bf16_f32 v25, v14, v15
	v_add_u32_e32 v14, 0xb0, v145
	v_add_u32_e32 v12, s27, v14
	v_ashrrev_i32_e32 v13, 31, v12
	global_store_dwordx4 v[26:27], v[22:25], off offset:256
	s_nop 1
	v_lshlrev_b64 v[22:23], 13, v[12:13]
	v_add_u32_e32 v12, s25, v14
	v_ashrrev_i32_e32 v13, 31, v12
	v_lshlrev_b64 v[24:25], 13, v[12:13]
	v_cvt_pk_bf16_f32 v12, v16, v17
	v_cvt_pk_bf16_f32 v13, v18, v19
	v_cvt_pk_bf16_f32 v14, v8, v9
	v_cvt_pk_bf16_f32 v15, v10, v11
	v_lshl_add_u64 v[8:9], s[6:7], 0, v[24:25]
	v_lshl_add_u64 v[10:11], s[20:21], 0, v[22:23]
	v_cndmask_b32_e32 v9, v11, v9, vcc
	v_cndmask_b32_e32 v8, v10, v8, vcc
	v_lshl_add_u64 v[8:9], v[8:9], 0, v[122:123]
	s_andn2_b64 vcc, exec, s[36:37]
	global_store_dwordx4 v[8:9], v[12:15], off
	v_cvt_pk_bf16_f32 v4, v4, v5
	v_cvt_pk_bf16_f32 v5, v6, v7
	v_cvt_pk_bf16_f32 v6, v0, v1
	v_cvt_pk_bf16_f32 v7, v2, v3
	global_store_dwordx4 v[8:9], v[4:7], off offset:256
	s_cbranch_vccnz .LBB0_348
	s_andn2_b64 vcc, exec, s[2:3]
	s_cbranch_vccnz .LBB0_347
	s_branch .LBB0_347

; #define PG8_BAR __builtin_amdgcn_s_barrier()
;     __host__ __device__ bool next(int i, Unit& u) const {
;         const long L = (long)i * G + c; if (L >= nwg) return false;
;         int wgid = (int)L; { const int q = nwg / NXCD, r = nwg % NXCD, xcd = wgid % NXCD, off = wgid / NXCD; wgid = (xcd < r ? xcd * (q + 1) : r * (q + 1) + (xcd - r) * q) + off; }
; template <class Epi, class Sched, bool ALIGN_EPI = false, bool SP2 = false>
; __device__ __forceinline__ void gemm_phase(PG8_LAS unsigned char* lds, const Gemm g, const Sched& S, const Epi& E, const int tid_in) {
;     ...
;     const int tid = tid_l, wid = __builtin_amdgcn_readfirstlane(tid >> 6), lane = tid & 63, wr = wid >> 2, wc = wid & 3, fr = lane & 15, fq = lane >> 4;
;     const int K = g.K, nt = K / BK;
;     unsigned voffA[2], voffB[2];
; #pragma unroll
;     for (int i = 0; i < 2; ++i) { int R, C; stage_rc(tid * 16 + i * 8192, R, C); const int Rb = perm_row<Epi::PMODE>(R);
;         voffA[i] = (unsigned)(R * K + C) * 2u; voffB[i] = (unsigned)(Rb * K + C) * 2u; }
;     const size_t kstep = (size_t)(BK * 2);
;     const size_t hstep = (size_t)HALF * K * 2;
;     const size_t tstep = 2 * hstep;
;     const unsigned ldsw = (unsigned)wid * 1024u;
;     const int aoff = lds_byte(wr * 64 + fr, fq * 8), boff = lds_byte(wc * 32 + fr, fq * 8);
;     ...
;     Unit cur, nxt; int ui = 0;
;     if (!S.next(0, cur)) return;
;     f32x4 acc[2][2][4][2];
; #pragma unroll
;     for (int a = 0; a < 2; ++a)
; #pragma unroll
;         for (int b = 0; b < 2; ++b)
; #pragma unroll
;             for (int m = 0; m < 4; ++m)
; #pragma unroll
;                 for (int n = 0; n < 2; ++n) acc[a][b][m][n] = (f32x4){0.f, 0.f, 0.f, 0.f};
;     bf16x8 At[4][2], B0[2][2], B1[2][2];
;     const char* cA = (const char*)g.A + (size_t)cur.pm * tstep; const char* cB = (const char*)g.Bt + (size_t)cur.pn * tstep;
;     S.a_ready(cur);
;     if constexpr (Epi::PREF) E.prefetch(cur, 0, lds, wid, lane);
;     if constexpr (SP2) {
;         PG8_STAGE(PG8_SB(0, 0), cB, voffB); PG8_STAGE(PG8_SB(0, 1), cB + hstep, voffB); PG8_STAGE(PG8_SA(0, 0), cA, voffA); PG8_STAGE(PG8_SA(0, 1), cA + hstep, voffA);
;         if (wr == 1) PG8_BAR;
;         PG8_WAIT_V(2); PG8_BAR;
;         PG8_STAGE(PG8_SB(1, 0), cB + kstep, voffB); PG8_STAGE(PG8_SA(1, 0), cA + kstep, voffA); PG8_STAGE(PG8_SB(1, 1), cB + hstep + kstep, voffB);
;         PG8_WAIT_V(6); PG8_BAR;
.LBB0_362:
	v_ashrrev_i32_e32 v1, 31, v14
	v_lshrrev_b32_e32 v1, 26, v1
	v_add_u32_e32 v1, v14, v1
	v_ashrrev_i32_e32 v8, 6, v1
	v_bfe_i32 v1, v14, 27, 1
	v_lshlrev_b32_e32 v0, 4, v14
	v_lshrrev_b32_e32 v1, 22, v1
	v_add_u32_e32 v1, v0, v1
	v_and_b32_e32 v1, 0xfffffc00, v1
	v_sub_u32_e32 v1, v0, v1
	v_lshrrev_b32_e32 v2, 4, v1
	s_mul_i32 s3, s6, 0x2e00000
	v_bitop3_b32 v1, v2, v1, 32 bitop3:0x6c
	s_mul_hi_i32 s1, s6, 0x2e00000
	s_waitcnt lgkmcnt(0)
	s_add_u32 s3, s20, s3
	v_ashrrev_i32_e32 v3, 31, v1
	s_addc_u32 s5, s21, s1
	v_lshrrev_b32_e32 v3, 26, v3
	s_add_u32 s1, s3, 0x9600000
	v_add_u32_e32 v3, v1, v3
	s_addc_u32 s5, s5, 0
	s_add_i32 s6, s6, s8
	v_lshlrev_b32_e32 v2, 3, v8
	v_ashrrev_i32_e32 v9, 6, v3
	v_and_b32_e32 v3, 0xc0, v3
	s_bitcmp0_b32 s6, 0
	s_mov_b32 s3, 0x4f200000
	v_and_b32_e32 v2, -16, v2
	v_sub_u32_e32 v1, v1, v3
	v_mov_b32_e32 v5, 1
	s_cselect_b32 s3, 0x28000000, s3
	v_add_u32_e32 v2, v9, v2
	v_lshlrev_b32_e32 v4, 5, v8
	v_ashrrev_i16_sdwa v1, v5, sext(v1) dst_sel:DWORD dst_unused:UNUSED_PAD src0_sel:DWORD src1_sel:BYTE_0
	s_add_u32 s8, s20, s3
	v_and_b32_e32 v4, 32, v4
	v_bfe_i32 v10, v1, 0, 16
	v_lshrrev_b32_e32 v1, 2, v2
	v_and_b32_e32 v3, 3, v9
	s_mov_b32 s3, 0x3fffc
	v_and_or_b32 v1, v1, s3, v3
	v_add_lshl_u32 v3, v4, v10, 1
	v_lshl_add_u32 v130, v2, 12, v3
	v_lshlrev_b32_e32 v2, 10, v2
	v_lshlrev_b32_e32 v1, 14, v1
	v_and_b32_e32 v2, 0x3000, v2
	v_add_u32_e32 v0, 0x2000, v0
	v_add3_u32 v132, v3, v2, v1
	v_ashrrev_i32_e32 v1, 31, v0
	v_lshrrev_b32_e32 v1, 22, v1
	v_add_u32_e32 v1, v0, v1
	v_ashrrev_i32_e32 v11, 10, v1
	v_mul_i32_i24_e32 v1, 0x400, v11
	v_sub_u32_e32 v0, v0, v1
	v_lshrrev_b32_e32 v1, 4, v0
	v_bitop3_b32 v0, v1, v0, 32 bitop3:0x6c
	v_ashrrev_i32_e32 v2, 31, v0
	v_lshrrev_b32_e32 v2, 26, v2
	v_add_u32_e32 v2, v0, v2
	v_lshlrev_b32_e32 v1, 3, v11
	v_ashrrev_i32_e32 v12, 6, v2
	v_and_b32_e32 v2, 0xc0, v2
	v_and_b32_e32 v1, -16, v1
	v_sub_u32_e32 v0, v0, v2
	v_add_u32_e32 v1, v12, v1
	v_ashrrev_i16_sdwa v0, v5, sext(v0) dst_sel:DWORD dst_unused:UNUSED_PAD src0_sel:DWORD src1_sel:BYTE_0
	v_bfe_i32 v13, v0, 0, 16
	v_lshrrev_b32_e32 v0, 2, v1
	v_and_b32_e32 v2, 3, v12
	v_and_or_b32 v0, v0, s3, v2
	v_readlane_b32 s3, v254, 22
	s_addc_u32 s10, s21, 0
	s_add_i32 s2, s2, s3
	s_ashr_i32 s3, s2, 31
	s_lshr_b32 s3, s3, 23
	v_lshlrev_b32_e32 v3, 5, v11
	s_add_i32 s3, s2, s3
	v_and_b32_e32 v3, 32, v3
	s_ashr_i32 s6, s3, 9
	v_add_lshl_u32 v2, v3, v13, 1
	s_lshl_b32 s24, s6, 3
	v_lshl_add_u32 v134, v1, 12, v2
	v_lshlrev_b32_e32 v1, 10, v1
	s_sub_i32 s6, 2, s24
	v_lshlrev_b32_e32 v0, 14, v0
	v_and_b32_e32 v1, 0x3000, v1
	s_min_u32 s25, s6, 8
	s_and_b32 s3, s3, 0xfffffe00
	v_add3_u32 v136, v2, v1, v0
	s_sub_i32 s26, s2, s3
	v_cvt_f32_ubyte0_e32 v1, s25
	v_cvt_f32_i32_e32 v0, s26
	v_rcp_iflag_f32_e32 v2, v1
	s_ashr_i32 s22, s7, 6
	s_ashr_i32 s2, s26, 30
	s_ashr_i32 s23, s7, 8
	v_mul_f32_e32 v2, v0, v2
	v_trunc_f32_e32 v2, v2
	v_fma_f32 v0, -v2, v1, v0
	v_cvt_i32_f32_e32 v2, v2
	s_lshl_b32 s19, s22, 10
	s_or_b32 s6, s2, 1
	v_cmp_ge_f32_e64 s[2:3], |v0|, v1
	s_and_b64 s[2:3], s[2:3], exec
	s_cselect_b32 s2, s6, 0
	v_readfirstlane_b32 s3, v2
	s_add_i32 s6, s3, s2
	s_mul_i32 s2, s6, s25
	s_sub_i32 s2, s26, s2
	s_sext_i32_i16 s2, s2
	s_add_i32 s30, s24, s2
	s_ashr_i32 s31, s30, 31
	s_bfe_i64 s[24:25], s[6:7], 0x100000
	s_lshl_b64 s[2:3], s[30:31], 20
	s_lshl_b64 s[24:25], s[24:25], 20
	s_add_u32 s38, s8, s24
	s_addc_u32 s39, s10, s25
	s_add_i32 s44, s19, 0
	s_add_i32 m0, s44, 0x10000
	v_mov_b32_e32 v133, v20
	global_load_lds_dwordx4 v132, s[38:39]
	s_add_i32 m0, s44, 0x12000
	s_add_u32 s24, s38, 0x80000
	global_load_lds_dwordx4 v136, s[38:39]
	s_addc_u32 s25, s39, 0
	s_add_i32 m0, s44, 0x14000
	v_mov_b32_e32 v137, v20
	global_load_lds_dwordx4 v132, s[24:25]
	s_add_i32 m0, s44, 0x16000
	s_add_u32 s34, s1, s2
	s_addc_u32 s35, s5, s3
	s_add_i32 s45, s44, 0x2000
	global_load_lds_dwordx4 v136, s[24:25]
	s_mov_b32 m0, s44
	s_add_u32 s2, s34, 0x80000
	global_load_lds_dwordx4 v130, s[34:35]
	s_mov_b32 m0, s45
	s_addc_u32 s3, s35, 0
	s_add_i32 s46, s44, 0x4000
	global_load_lds_dwordx4 v134, s[34:35]
	s_mov_b32 m0, s46
	s_add_i32 s47, s44, 0x6000
	global_load_lds_dwordx4 v130, s[2:3]
	s_mov_b32 m0, s47
	v_mov_b32_e32 v131, v20
	global_load_lds_dwordx4 v134, s[2:3]
	v_mov_b32_e32 v135, v20
	s_cmp_eq_u32 s23, 1
	v_lshl_add_u64 v[6:7], s[38:39], 0, v[132:133]
	v_lshl_add_u64 v[4:5], s[38:39], 0, v[136:137]
	v_lshl_add_u64 v[0:1], s[34:35], 0, v[130:131]
	s_cselect_b64 s[2:3], -1, 0
	s_cmp_lg_u32 s23, 1
	v_lshl_add_u64 v[2:3], s[34:35], 0, v[134:135]
	s_cbranch_scc1 .LBB0_364
.LBB0_364:
	v_bfe_u32 v16, v14, 4, 2
	v_and_b32_e32 v15, 15, v14
	v_lshlrev_b32_e32 v18, 4, v16
	v_lshlrev_b32_e32 v14, 2, v14
	s_sext_i32_i16 s31, s6
	s_and_b32 s24, s22, 3
	v_lshl_or_b32 v17, s23, 6, v15
	v_lshl_or_b32 v15, v15, 6, v18
	s_lshl_b32 s6, s23, 13
	v_and_b32_e32 v14, 32, v14
	s_add_i32 m0, s44, 0x18000
	v_lshl_add_u64 v[6:7], v[6:7], 0, s[12:13]
	v_bitop3_b32 v18, v15, s6, v14 bitop3:0xde
	s_lshl_b32 s6, s24, 12
	s_waitcnt vmcnt(2)
	s_barrier
	global_load_lds_dwordx4 v[6:7], off
	v_lshl_add_u64 v[4:5], v[4:5], 0, s[12:13]
	s_add_i32 m0, s44, 0x1a000
	s_add_i32 s48, s44, 0x8000
	s_add_i32 s49, s44, 0xa000
	global_load_lds_dwordx4 v[4:5], off
	v_lshl_add_u64 v[0:1], v[0:1], 0, s[12:13]
	s_mov_b32 m0, s48
	s_add_u32 s100, s34, 0x80
	s_addc_u32 s101, s35, 0
	s_add_u32 s22, s38, 0x80080
	global_load_lds_dwordx4 v[0:1], off
	v_lshl_add_u64 v[0:1], v[2:3], 0, s[12:13]
	s_mov_b32 m0, s49
	s_addc_u32 s23, s39, 0
	global_load_lds_dwordx4 v[0:1], off
	s_add_i32 m0, s44, 0x1c000
	v_lshl_add_u64 v[0:1], s[22:23], 0, v[132:133]
	global_load_lds_dwordx4 v[0:1], off
	v_lshl_add_u64 v[0:1], s[22:23], 0, v[136:137]
	s_add_i32 m0, s44, 0x1e000
	s_cmpk_lt_u32 s7, 0x100
	global_load_lds_dwordx4 v[0:1], off
	v_lshlrev_b32_e32 v0, 11, v16
	v_mov_b32_e32 v1, v20
	v_lshl_add_u64 v[0:1], s[20:21], 0, v[0:1]
	s_mov_b64 s[20:21], 0x3b000000
	v_lshl_add_u64 v[138:139], v[0:1], 0, s[20:21]
	v_lshlrev_b32_e32 v0, 15, v8
	v_and_b32_e32 v0, 0xffff0000, v0
	v_lshl_add_u32 v0, v9, 12, v0
	v_and_b32_e32 v1, 1, v8
	v_lshl_or_b32 v0, v1, 6, v0
	v_lshl_add_u32 v140, v10, 1, v0
	v_lshlrev_b32_e32 v0, 15, v11
	v_and_b32_e32 v0, 0xffff0000, v0
	s_waitcnt vmcnt(6)
	v_lshl_add_u32 v0, v12, 12, v0
	v_and_b32_e32 v1, 1, v11
	v_bitop3_b32 v21, v15, s6, v14 bitop3:0xde
	s_cselect_b64 s[6:7], -1, 0
	s_lshl_b32 s22, s24, 3
	v_lshl_or_b32 v0, v1, 6, v0
	v_add_u32_e32 v146, 0x200, v17
	v_mov_b32_e32 v141, v20
	v_lshl_add_u32 v142, v13, 1, v0
	v_mov_b32_e32 v143, v20
	s_mov_b32 s50, 0
	v_add_u32_e32 v147, 0, v18
	s_lshl_b32 s20, s22, 1
	s_barrier
	s_branch .LBB0_367

; #define PG8_STAGE(bufoff, gbase, voff) do { _Pragma("unroll") for (int _i = 0; _i < 2; ++_i) \
;         __builtin_amdgcn_global_load_lds((const unsigned*)((const char*)(gbase) + (voff)[_i]), (PG8_LAS unsigned*)(lds + (bufoff) + ldsw + _i * 8192), 16, 0, 0); } while (0)
; #define PG8_LDA(dst, b, h) do { _Pragma("unroll") for (int m = 0; m < 4; ++m) _Pragma("unroll") for (int k = 0; k < 2; ++k) dst[m][k] = *(const PG8_LAS bf16x8*)(lds + PG8_SA(b, h) + aoff + m * 2048 + k * 1024); } while (0)
; #define PG8_LDB(dst, b, h) do { _Pragma("unroll") for (int n = 0; n < 2; ++n) _Pragma("unroll") for (int k = 0; k < 2; ++k) dst[n][k] = *(const PG8_LAS bf16x8*)(lds + PG8_SB(b, h) + boff + n * 2048 + k * 1024); } while (0)
; #define PG8_WAIT_V(n) asm volatile("s_waitcnt vmcnt(" #n ")" ::: "memory")
; #define PG8_WAIT_L(n) asm volatile("s_waitcnt lgkmcnt(" #n ")" ::: "memory")
; template <class Epi, class Sched, bool ALIGN_EPI = false, bool SP2 = false>
; __device__ __forceinline__ void gemm_phase(PG8_LAS unsigned char* lds, const Gemm g, const Sched& S, const Epi& E, const int tid_in) {
;     ...
;         const bool has_next = S.next(ui + 1, nxt);
;         const char* nA = has_next ? (const char*)g.A + (size_t)nxt.pm * tstep : cA; const char* nB = has_next ? (const char*)g.Bt + (size_t)nxt.pn * tstep : cB;
;         for (int t = 0; t < nt; t += 2) {
;             if constexpr (Epi::KSPLIT > 0) { if (t == Epi::KSPLIT / BK) E.midk(acc, cur, wr, wc, fr, fq); }
;             const bool last = (t == nt - 2);
;             const char* a1 = cA + (size_t)(t + 1) * kstep;
;             const char* a2 = last ? nA : cA + (size_t)(t + 2) * kstep; const char* b2 = last ? nB : cB + (size_t)(t + 2) * kstep;
;             const char* a3 = a2 + kstep; const char* b3 = b2 + kstep;
;             if (last && has_next) S.a_ready(nxt);
;             if constexpr (SP2) {
;             PG8_LDB(B0, 0, 0); PG8_LDB(B1, 0, 1); PG8_SCHED; PG8_LDA(At, 0, 0); PG8_STAGE(PG8_SA(1, 1), a1 + hstep, voffA);
;             PG8_WAIT_V(8); PG8_WAIT_L(0); PG8_BAR; PG8_MMA(0, 0, At, B0); PG8_MMA(0, 1, At, B1); PG8_BAR; PG8_SCHED;
;             PG8_LDA(At, 0, 1); PG8_STAGE(PG8_SB(0, 0), b2, voffB); PG8_STAGE(PG8_SB(0, 1), b2 + hstep, voffB); PG8_STAGE(PG8_SA(0, 0), a2, voffA);
;             PG8_WAIT_V(8); PG8_WAIT_L(0); PG8_BAR; PG8_MMA(1, 0, At, B0); PG8_MMA(1, 1, At, B1); PG8_BAR; PG8_SCHED;
.LBB0_373:
	s_ashr_i32 s25, s24, 31
	s_lshl_b64 s[26:27], s[24:25], 20
	s_add_u32 s26, s1, s26
	s_addc_u32 s27, s5, s27
	s_and_b64 s[28:29], s[36:37], exec
	s_cselect_b32 s21, s27, s35
	s_cselect_b32 s25, s26, s34
	s_ashr_i32 s23, s22, 31
	s_lshl_b64 s[28:29], s[22:23], 20
	s_add_u32 s28, s8, s28
	s_addc_u32 s29, s10, s29
	s_and_b64 s[42:43], s[36:37], exec
	s_cselect_b32 s23, s29, s39
	s_cselect_b32 s51, s28, s38
	s_add_u32 s34, s34, 0x80080
	s_addc_u32 s35, s35, 0
	s_add_u32 s52, s38, 0x100
	v_mov_b32_e32 v0, 0
	s_addc_u32 s53, s39, 0
	s_mov_b32 s54, -2
	s_cmp_lt_u32 s19, 0x1000
	s_cbranch_scc1 .LCB_374
	s_barrier
.LCB_374:
	s_mov_b32 m0, s49
	s_nop 0
	global_load_lds_dwordx4 v134, s[100:101]
	s_add_u32 s38, s34, 0xfff80080
	s_addc_u32 s39, s35, -1
	s_add_i32 s55, 0, 0x10000
	s_cmp_eq_u32 s54, 28
	s_cselect_b32 s43, s21, s39
	s_cselect_b32 s42, s25, s38
	v_add_u32_e32 v144, s55, v21
	s_cselect_b32 s39, s23, s53
	s_cselect_b32 s38, s51, s52
	s_add_i32 s58, 0, 0x14000
	ds_read_b128 v[148:151], v144
	ds_read_b128 v[152:155], v144 offset:1024
	ds_read_b128 v[156:159], v144 offset:2048
	ds_read_b128 v[160:163], v144 offset:3072
	v_add_u32_e32 v144, s58, v21
	ds_read_b128 v[164:167], v144
	ds_read_b128 v[168:171], v144 offset:1024
	ds_read_b128 v[172:175], v144 offset:2048
	ds_read_b128 v[176:179], v144 offset:3072
	s_add_i32 m0, s44, 0xc000
	ds_read_b128 v[180:183], v147
	ds_read_b128 v[184:187], v147 offset:1024
	ds_read_b128 v[188:191], v147 offset:2048
	ds_read_b128 v[192:195], v147 offset:3072
	ds_read_b128 v[196:199], v147 offset:4096
	ds_read_b128 v[200:203], v147 offset:5120
	ds_read_b128 v[208:211], v147 offset:6144
	ds_read_b128 v[212:215], v147 offset:7168
	global_load_lds_dwordx4 v140, s[34:35]
	s_add_i32 m0, s44, 0xe000
	s_nop 0
	global_load_lds_dwordx4 v142, s[34:35]
	s_waitcnt vmcnt(8)
	s_waitcnt lgkmcnt(0)
	s_barrier
	s_setprio 1
	v_mfma_f32_16x16x32_bf16 v[126:129], v[148:151], v[180:183], 0
	v_mfma_f32_16x16x32_bf16 v[122:125], v[156:159], v[180:183], 0
	v_mfma_f32_16x16x32_bf16 v[118:121], v[148:151], v[188:191], 0
	v_mfma_f32_16x16x32_bf16 v[110:113], v[156:159], v[188:191], 0
	v_mfma_f32_16x16x32_bf16 v[102:105], v[148:151], v[196:199], 0
	v_mfma_f32_16x16x32_bf16 v[94:97], v[156:159], v[196:199], 0
	v_mfma_f32_16x16x32_bf16 v[86:89], v[148:151], v[208:211], 0
	v_mfma_f32_16x16x32_bf16 v[78:81], v[156:159], v[208:211], 0
	v_mfma_f32_16x16x32_bf16 v[126:129], v[152:155], v[184:187], v[126:129]
	v_mfma_f32_16x16x32_bf16 v[122:125], v[160:163], v[184:187], v[122:125]
	v_mfma_f32_16x16x32_bf16 v[118:121], v[152:155], v[192:195], v[118:121]
	v_mfma_f32_16x16x32_bf16 v[110:113], v[160:163], v[192:195], v[110:113]
	v_mfma_f32_16x16x32_bf16 v[102:105], v[152:155], v[200:203], v[102:105]
	v_mfma_f32_16x16x32_bf16 v[94:97], v[160:163], v[200:203], v[94:97]
	v_mfma_f32_16x16x32_bf16 v[86:89], v[152:155], v[212:215], v[86:89]
	v_mfma_f32_16x16x32_bf16 v[78:81], v[160:163], v[212:215], v[78:81]
	s_setprio 0
	s_setprio 1
	v_mfma_f32_16x16x32_bf16 v[114:117], v[164:167], v[180:183], 0
	v_mfma_f32_16x16x32_bf16 v[106:109], v[172:175], v[180:183], 0
	v_mfma_f32_16x16x32_bf16 v[98:101], v[164:167], v[188:191], 0
	v_mfma_f32_16x16x32_bf16 v[90:93], v[172:175], v[188:191], 0
	v_mfma_f32_16x16x32_bf16 v[82:85], v[164:167], v[196:199], 0
	v_mfma_f32_16x16x32_bf16 v[74:77], v[172:175], v[196:199], 0
	v_mfma_f32_16x16x32_bf16 v[70:73], v[164:167], v[208:211], 0
	v_mfma_f32_16x16x32_bf16 v[66:69], v[172:175], v[208:211], 0
	v_mfma_f32_16x16x32_bf16 v[114:117], v[168:171], v[184:187], v[114:117]
	v_mfma_f32_16x16x32_bf16 v[106:109], v[176:179], v[184:187], v[106:109]
	v_mfma_f32_16x16x32_bf16 v[98:101], v[168:171], v[192:195], v[98:101]
	v_mfma_f32_16x16x32_bf16 v[90:93], v[176:179], v[192:195], v[90:93]
	v_mfma_f32_16x16x32_bf16 v[82:85], v[168:171], v[200:203], v[82:85]
	v_mfma_f32_16x16x32_bf16 v[74:77], v[176:179], v[200:203], v[74:77]
	v_mfma_f32_16x16x32_bf16 v[70:73], v[168:171], v[212:215], v[70:73]
	v_mfma_f32_16x16x32_bf16 v[66:69], v[176:179], v[212:215], v[66:69]
	s_setprio 0
	s_barrier
	s_add_i32 s55, s55, s19
	s_add_u32 s98, s38, 0x80
	s_addc_u32 s99, s39, 0
	s_mov_b32 m0, s55
	ds_read_b128 v[180:183], v147 offset:16384
	ds_read_b128 v[184:187], v147 offset:17408
	ds_read_b128 v[188:191], v147 offset:18432
	ds_read_b128 v[192:195], v147 offset:19456
	ds_read_b128 v[196:199], v147 offset:20480
	ds_read_b128 v[200:203], v147 offset:21504
	ds_read_b128 v[208:211], v147 offset:22528
	ds_read_b128 v[212:215], v147 offset:23552
	global_load_lds_dwordx4 v132, s[38:39]
	s_add_i32 m0, s55, 0x2000
	s_add_u32 s56, s38, 0x80000
	s_addc_u32 s57, s39, 0
	s_add_i32 s55, s58, s19
	global_load_lds_dwordx4 v136, s[38:39]
	s_mov_b32 m0, s55
	s_add_u32 s100, s42, 0x80
	s_addc_u32 s101, s43, 0
	global_load_lds_dwordx4 v132, s[56:57]
	s_add_i32 m0, s55, 0x2000
	s_nop 0
	global_load_lds_dwordx4 v136, s[56:57]
	s_mov_b32 m0, s44
	s_nop 0
	global_load_lds_dwordx4 v130, s[42:43]
	s_waitcnt vmcnt(7)
	s_waitcnt lgkmcnt(0)
	s_barrier
; #define PG8_STAGE(bufoff, gbase, voff) do { _Pragma("unroll") for (int _i = 0; _i < 2; ++_i) \
;         __builtin_amdgcn_global_load_lds((const unsigned*)((const char*)(gbase) + (voff)[_i]), (PG8_LAS unsigned*)(lds + (bufoff) + ldsw + _i * 8192), 16, 0, 0); } while (0)
; #define PG8_LDA(dst, b, h) do { _Pragma("unroll") for (int m = 0; m < 4; ++m) _Pragma("unroll") for (int k = 0; k < 2; ++k) dst[m][k] = *(const PG8_LAS bf16x8*)(lds + PG8_SA(b, h) + aoff + m * 2048 + k * 1024); } while (0)
; #define PG8_LDB(dst, b, h) do { _Pragma("unroll") for (int n = 0; n < 2; ++n) _Pragma("unroll") for (int k = 0; k < 2; ++k) dst[n][k] = *(const PG8_LAS bf16x8*)(lds + PG8_SB(b, h) + boff + n * 2048 + k * 1024); } while (0)
; #define PG8_MMA(ai, bj, At, Bt) do { __builtin_amdgcn_s_setprio(1); _Pragma("unroll") for (int m = 0; m < 4; ++m) _Pragma("unroll") for (int n = 0; n < 2; ++n) _Pragma("unroll") for (int k = 0; k < 2; ++k) \
;         acc[ai][bj][m][n] = __builtin_amdgcn_mfma_f32_16x16x32_bf16(Bt[n][k], At[m][k], acc[ai][bj][m][n], 0, 0, 0); __builtin_amdgcn_s_setprio(0); } while (0)
; #define PG8_WAIT_V(n) asm volatile("s_waitcnt vmcnt(" #n ")" ::: "memory")
; #define PG8_WAIT_L(n) asm volatile("s_waitcnt lgkmcnt(" #n ")" ::: "memory")
; #define PG8_BAR __builtin_amdgcn_s_barrier()
; #define PG8_SCHED __builtin_amdgcn_sched_barrier(0)
; template <class Epi, class Sched, bool ALIGN_EPI = false, bool SP2 = false>
; __device__ __forceinline__ void gemm_phase(PG8_LAS unsigned char* lds, const Gemm g, const Sched& S, const Epi& E, const int tid_in) {
;     ...
;             PG8_WAIT_V(8); PG8_WAIT_L(0); PG8_BAR; PG8_MMA(1, 0, At, B0); PG8_MMA(1, 1, At, B1); PG8_BAR; PG8_SCHED;
;             PG8_LDB(B0, 1, 0); PG8_LDB(B1, 1, 1); PG8_SCHED; PG8_LDA(At, 1, 0); PG8_STAGE(PG8_SA(0, 1), a2 + hstep, voffA);
;             PG8_WAIT_V(8); PG8_WAIT_L(0); PG8_BAR; PG8_MMA(0, 0, At, B0); PG8_MMA(0, 1, At, B1); PG8_BAR; PG8_SCHED;
;             PG8_LDA(At, 1, 1); PG8_STAGE(PG8_SB(1, 0), b3, voffB); PG8_STAGE(PG8_SB(1, 1), b3 + hstep, voffB); PG8_STAGE(PG8_SA(1, 0), a3, voffA);
	s_setprio 1
	v_mfma_f32_16x16x32_bf16 v[62:65], v[148:151], v[180:183], 0
	v_mfma_f32_16x16x32_bf16 v[58:61], v[156:159], v[180:183], 0
	v_mfma_f32_16x16x32_bf16 v[54:57], v[148:151], v[188:191], 0
	v_mfma_f32_16x16x32_bf16 v[46:49], v[156:159], v[188:191], 0
	v_mfma_f32_16x16x32_bf16 v[38:41], v[148:151], v[196:199], 0
	v_mfma_f32_16x16x32_bf16 v[30:33], v[156:159], v[196:199], 0
	v_mfma_f32_16x16x32_bf16 v[22:25], v[148:151], v[208:211], 0
	v_mfma_f32_16x16x32_bf16 v[12:15], v[156:159], v[208:211], 0
	v_mfma_f32_16x16x32_bf16 v[62:65], v[152:155], v[184:187], v[62:65]
	v_mfma_f32_16x16x32_bf16 v[58:61], v[160:163], v[184:187], v[58:61]
	v_mfma_f32_16x16x32_bf16 v[54:57], v[152:155], v[192:195], v[54:57]
	v_mfma_f32_16x16x32_bf16 v[46:49], v[160:163], v[192:195], v[46:49]
	v_mfma_f32_16x16x32_bf16 v[38:41], v[152:155], v[200:203], v[38:41]
	v_mfma_f32_16x16x32_bf16 v[30:33], v[160:163], v[200:203], v[30:33]
	v_mfma_f32_16x16x32_bf16 v[22:25], v[152:155], v[212:215], v[22:25]
	v_mfma_f32_16x16x32_bf16 v[12:15], v[160:163], v[212:215], v[12:15]
	s_setprio 0
	s_setprio 1
	v_mfma_f32_16x16x32_bf16 v[50:53], v[164:167], v[180:183], 0
	v_mfma_f32_16x16x32_bf16 v[42:45], v[172:175], v[180:183], 0
	v_mfma_f32_16x16x32_bf16 v[34:37], v[164:167], v[188:191], 0
	v_mfma_f32_16x16x32_bf16 v[26:29], v[172:175], v[188:191], 0
	v_mfma_f32_16x16x32_bf16 v[16:19], v[164:167], v[196:199], 0
	v_mfma_f32_16x16x32_bf16 v[8:11], v[172:175], v[196:199], 0
	v_mfma_f32_16x16x32_bf16 v[4:7], v[164:167], v[208:211], 0
	v_mfma_f32_16x16x32_bf16 v[0:3], v[172:175], v[208:211], 0
	v_mfma_f32_16x16x32_bf16 v[50:53], v[168:171], v[184:187], v[50:53]
	v_mfma_f32_16x16x32_bf16 v[42:45], v[176:179], v[184:187], v[42:45]
	v_mfma_f32_16x16x32_bf16 v[34:37], v[168:171], v[192:195], v[34:37]
	v_mfma_f32_16x16x32_bf16 v[26:29], v[176:179], v[192:195], v[26:29]
	v_mfma_f32_16x16x32_bf16 v[16:19], v[168:171], v[200:203], v[16:19]
	v_mfma_f32_16x16x32_bf16 v[8:11], v[176:179], v[200:203], v[8:11]
	v_mfma_f32_16x16x32_bf16 v[4:7], v[168:171], v[212:215], v[4:7]
	v_mfma_f32_16x16x32_bf16 v[0:3], v[176:179], v[212:215], v[0:3]
	s_setprio 0
	s_barrier
	s_add_i32 s55, 0, 0x18000
	s_add_i32 s56, 0, 0x1c000
	v_add_u32_e32 v160, s55, v21
	v_add_u32_e32 v176, s56, v21
	ds_read_b128 v[148:151], v160
	ds_read_b128 v[152:155], v160 offset:1024
	ds_read_b128 v[156:159], v160 offset:2048
	ds_read_b128 v[160:163], v160 offset:3072
	ds_read_b128 v[164:167], v176
	ds_read_b128 v[168:171], v176 offset:1024
	ds_read_b128 v[172:175], v176 offset:2048
	ds_read_b128 v[176:179], v176 offset:3072
	s_mov_b32 m0, s45
	s_nop 0
	global_load_lds_dwordx4 v134, s[42:43]
	s_add_u32 s42, s42, 0x80000
	s_addc_u32 s43, s43, 0
	s_mov_b32 m0, s46
	ds_read_b128 v[180:183], v147 offset:32768
	ds_read_b128 v[184:187], v147 offset:33792
	ds_read_b128 v[188:191], v147 offset:34816
	ds_read_b128 v[192:195], v147 offset:35840
	ds_read_b128 v[196:199], v147 offset:36864
	ds_read_b128 v[200:203], v147 offset:37888
	ds_read_b128 v[208:211], v147 offset:38912
	ds_read_b128 v[212:215], v147 offset:39936
	global_load_lds_dwordx4 v130, s[42:43]
	s_mov_b32 m0, s47
	s_nop 0
	global_load_lds_dwordx4 v134, s[42:43]
	s_waitcnt vmcnt(8)
	s_waitcnt lgkmcnt(0)
	s_barrier
	s_setprio 1
	v_mfma_f32_16x16x32_bf16 v[126:129], v[148:151], v[180:183], v[126:129]
	v_mfma_f32_16x16x32_bf16 v[122:125], v[156:159], v[180:183], v[122:125]
	v_mfma_f32_16x16x32_bf16 v[118:121], v[148:151], v[188:191], v[118:121]
	v_mfma_f32_16x16x32_bf16 v[110:113], v[156:159], v[188:191], v[110:113]
	v_mfma_f32_16x16x32_bf16 v[102:105], v[148:151], v[196:199], v[102:105]
	v_mfma_f32_16x16x32_bf16 v[94:97], v[156:159], v[196:199], v[94:97]
	v_mfma_f32_16x16x32_bf16 v[86:89], v[148:151], v[208:211], v[86:89]
	v_mfma_f32_16x16x32_bf16 v[78:81], v[156:159], v[208:211], v[78:81]
	v_mfma_f32_16x16x32_bf16 v[126:129], v[152:155], v[184:187], v[126:129]
	v_mfma_f32_16x16x32_bf16 v[122:125], v[160:163], v[184:187], v[122:125]
	v_mfma_f32_16x16x32_bf16 v[118:121], v[152:155], v[192:195], v[118:121]
	v_mfma_f32_16x16x32_bf16 v[110:113], v[160:163], v[192:195], v[110:113]
	v_mfma_f32_16x16x32_bf16 v[102:105], v[152:155], v[200:203], v[102:105]
	v_mfma_f32_16x16x32_bf16 v[94:97], v[160:163], v[200:203], v[94:97]
	v_mfma_f32_16x16x32_bf16 v[86:89], v[152:155], v[212:215], v[86:89]
	v_mfma_f32_16x16x32_bf16 v[78:81], v[160:163], v[212:215], v[78:81]
	s_setprio 0
	s_setprio 1
	v_mfma_f32_16x16x32_bf16 v[114:117], v[164:167], v[180:183], v[114:117]
	v_mfma_f32_16x16x32_bf16 v[106:109], v[172:175], v[180:183], v[106:109]
	v_mfma_f32_16x16x32_bf16 v[98:101], v[164:167], v[188:191], v[98:101]
	v_mfma_f32_16x16x32_bf16 v[90:93], v[172:175], v[188:191], v[90:93]
	v_mfma_f32_16x16x32_bf16 v[82:85], v[164:167], v[196:199], v[82:85]
	v_mfma_f32_16x16x32_bf16 v[74:77], v[172:175], v[196:199], v[74:77]
	v_mfma_f32_16x16x32_bf16 v[70:73], v[164:167], v[208:211], v[70:73]
	v_mfma_f32_16x16x32_bf16 v[66:69], v[172:175], v[208:211], v[66:69]
	v_mfma_f32_16x16x32_bf16 v[114:117], v[168:171], v[184:187], v[114:117]
	v_mfma_f32_16x16x32_bf16 v[106:109], v[176:179], v[184:187], v[106:109]
	v_mfma_f32_16x16x32_bf16 v[98:101], v[168:171], v[192:195], v[98:101]
	v_mfma_f32_16x16x32_bf16 v[90:93], v[176:179], v[192:195], v[90:93]
	v_mfma_f32_16x16x32_bf16 v[82:85], v[168:171], v[200:203], v[82:85]
	v_mfma_f32_16x16x32_bf16 v[74:77], v[176:179], v[200:203], v[74:77]
	v_mfma_f32_16x16x32_bf16 v[70:73], v[168:171], v[212:215], v[70:73]
	v_mfma_f32_16x16x32_bf16 v[66:69], v[176:179], v[212:215], v[66:69]
	s_setprio 0
	s_barrier
; #define PG8_STAGE(bufoff, gbase, voff) do { _Pragma("unroll") for (int _i = 0; _i < 2; ++_i) \
;         __builtin_amdgcn_global_load_lds((const unsigned*)((const char*)(gbase) + (voff)[_i]), (PG8_LAS unsigned*)(lds + (bufoff) + ldsw + _i * 8192), 16, 0, 0); } while (0)
; #define PG8_LDA(dst, b, h) do { _Pragma("unroll") for (int m = 0; m < 4; ++m) _Pragma("unroll") for (int k = 0; k < 2; ++k) dst[m][k] = *(const PG8_LAS bf16x8*)(lds + PG8_SA(b, h) + aoff + m * 2048 + k * 1024); } while (0)
; #define PG8_MMA(ai, bj, At, Bt) do { __builtin_amdgcn_s_setprio(1); _Pragma("unroll") for (int m = 0; m < 4; ++m) _Pragma("unroll") for (int n = 0; n < 2; ++n) _Pragma("unroll") for (int k = 0; k < 2; ++k) \
;         acc[ai][bj][m][n] = __builtin_amdgcn_mfma_f32_16x16x32_bf16(Bt[n][k], At[m][k], acc[ai][bj][m][n], 0, 0, 0); __builtin_amdgcn_s_setprio(0); } while (0)
; #define PG8_WAIT_V(n) asm volatile("s_waitcnt vmcnt(" #n ")" ::: "memory")
; #define PG8_WAIT_L(n) asm volatile("s_waitcnt lgkmcnt(" #n ")" ::: "memory")
; #define PG8_BAR __builtin_amdgcn_s_barrier()
; #define PG8_SCHED __builtin_amdgcn_sched_barrier(0)
; template <class Epi, class Sched, bool ALIGN_EPI = false, bool SP2 = false>
; __device__ __forceinline__ void gemm_phase(PG8_LAS unsigned char* lds, const Gemm g, const Sched& S, const Epi& E, const int tid_in) {
;     ...
;             PG8_LDA(At, 1, 1); PG8_STAGE(PG8_SB(1, 0), b3, voffB); PG8_STAGE(PG8_SB(1, 1), b3 + hstep, voffB); PG8_STAGE(PG8_SA(1, 0), a3, voffA);
;             PG8_WAIT_V(8); PG8_WAIT_L(0); PG8_BAR; PG8_MMA(1, 0, At, B0); PG8_MMA(1, 1, At, B1); PG8_BAR; PG8_SCHED;
	s_add_i32 s42, s55, s19
	s_mov_b32 m0, s42
	ds_read_b128 v[180:183], v147 offset:49152
	ds_read_b128 v[184:187], v147 offset:50176
	ds_read_b128 v[188:191], v147 offset:51200
	ds_read_b128 v[192:195], v147 offset:52224
	ds_read_b128 v[196:199], v147 offset:53248
	ds_read_b128 v[200:203], v147 offset:54272
	ds_read_b128 v[208:211], v147 offset:55296
	ds_read_b128 v[212:215], v147 offset:56320
	global_load_lds_dwordx4 v132, s[98:99]
	s_add_i32 m0, s42, 0x2000
	s_add_u32 s38, s38, 0x80080
	s_addc_u32 s39, s39, 0
	s_add_i32 s42, s56, s19
	global_load_lds_dwordx4 v136, s[98:99]
	s_mov_b32 m0, s42
	s_nop 0
	global_load_lds_dwordx4 v132, s[38:39]
	s_add_i32 m0, s42, 0x2000
	s_nop 0
	global_load_lds_dwordx4 v136, s[38:39]
	s_mov_b32 m0, s48
	s_nop 0
	global_load_lds_dwordx4 v130, s[100:101]
	s_waitcnt vmcnt(7)
	s_waitcnt lgkmcnt(0)
	s_barrier
	s_setprio 1
	v_mfma_f32_16x16x32_bf16 v[62:65], v[148:151], v[180:183], v[62:65]
	v_mfma_f32_16x16x32_bf16 v[58:61], v[156:159], v[180:183], v[58:61]
	v_mfma_f32_16x16x32_bf16 v[54:57], v[148:151], v[188:191], v[54:57]
	v_mfma_f32_16x16x32_bf16 v[46:49], v[156:159], v[188:191], v[46:49]
	v_mfma_f32_16x16x32_bf16 v[38:41], v[148:151], v[196:199], v[38:41]
	v_mfma_f32_16x16x32_bf16 v[30:33], v[156:159], v[196:199], v[30:33]
	v_mfma_f32_16x16x32_bf16 v[22:25], v[148:151], v[208:211], v[22:25]
	v_mfma_f32_16x16x32_bf16 v[12:15], v[156:159], v[208:211], v[12:15]
	v_mfma_f32_16x16x32_bf16 v[62:65], v[152:155], v[184:187], v[62:65]
	v_mfma_f32_16x16x32_bf16 v[58:61], v[160:163], v[184:187], v[58:61]
	v_mfma_f32_16x16x32_bf16 v[54:57], v[152:155], v[192:195], v[54:57]
	v_mfma_f32_16x16x32_bf16 v[46:49], v[160:163], v[192:195], v[46:49]
	v_mfma_f32_16x16x32_bf16 v[38:41], v[152:155], v[200:203], v[38:41]
	v_mfma_f32_16x16x32_bf16 v[30:33], v[160:163], v[200:203], v[30:33]
	v_mfma_f32_16x16x32_bf16 v[22:25], v[152:155], v[212:215], v[22:25]
	v_mfma_f32_16x16x32_bf16 v[12:15], v[160:163], v[212:215], v[12:15]
	s_setprio 0
	s_setprio 1
	v_mfma_f32_16x16x32_bf16 v[50:53], v[164:167], v[180:183], v[50:53]
	v_mfma_f32_16x16x32_bf16 v[42:45], v[172:175], v[180:183], v[42:45]
	v_mfma_f32_16x16x32_bf16 v[34:37], v[164:167], v[188:191], v[34:37]
	v_mfma_f32_16x16x32_bf16 v[26:29], v[172:175], v[188:191], v[26:29]
	v_mfma_f32_16x16x32_bf16 v[16:19], v[164:167], v[196:199], v[16:19]
	v_mfma_f32_16x16x32_bf16 v[8:11], v[172:175], v[196:199], v[8:11]
	v_mfma_f32_16x16x32_bf16 v[4:7], v[164:167], v[208:211], v[4:7]
	v_mfma_f32_16x16x32_bf16 v[0:3], v[172:175], v[208:211], v[0:3]
	v_mfma_f32_16x16x32_bf16 v[50:53], v[168:171], v[184:187], v[50:53]
	v_mfma_f32_16x16x32_bf16 v[42:45], v[176:179], v[184:187], v[42:45]
	v_mfma_f32_16x16x32_bf16 v[34:37], v[168:171], v[192:195], v[34:37]
	v_mfma_f32_16x16x32_bf16 v[26:29], v[176:179], v[192:195], v[26:29]
	v_mfma_f32_16x16x32_bf16 v[16:19], v[168:171], v[200:203], v[16:19]
	v_mfma_f32_16x16x32_bf16 v[8:11], v[176:179], v[200:203], v[8:11]
	v_mfma_f32_16x16x32_bf16 v[4:7], v[168:171], v[212:215], v[4:7]
	v_mfma_f32_16x16x32_bf16 v[0:3], v[176:179], v[212:215], v[0:3]
	s_setprio 0
	s_barrier
	s_add_i32 s54, s54, 2
	s_add_u32 s34, s34, 0x100
	s_addc_u32 s35, s35, 0
	s_add_u32 s52, s52, 0x100
	s_addc_u32 s53, s53, 0
	s_cmp_gt_u32 s54, 29

; __device__ __forceinline__ unsigned cvt_pk_bf16(float lo, float hi) { unsigned r; asm volatile("v_cvt_pk_bf16_f32 %0, %1, %2" : "=v"(r) : "v"(lo), "v"(hi)); return r; }
; #define PG8_BAR __builtin_amdgcn_s_barrier()
;     __device__ __forceinline__ void operator()(const f32x4 (&acc)[2][2][4][2], const Unit& u, int wr, int wc, int fr, int fq) const {
;         const int row0 = u.pm * BM + wr * 64 + fr;
;         const int T0 = u.pn * BM, bseq = T0 >> 12, t0 = T0 & 4095;
; #pragma unroll
;         for (int ai = 0; ai < 2; ++ai)
; #pragma unroll
;             for (int m = 0; m < 4; ++m) {
;                 const int nn = row0 + ai * HALF + m * 16;
; #pragma unroll
;                 for (int bj = 0; bj < 2; ++bj) {
;                     const f32x4 v0 = acc[ai][bj][m][0], v1 = acc[ai][bj][m][1];
;                     u32x4 w; w.x = cvt_pk_bf16(v0[0], v0[1]); w.y = cvt_pk_bf16(v0[2], v0[3]); w.z = cvt_pk_bf16(v1[0], v1[1]); w.w = cvt_pk_bf16(v1[2], v1[3]);
;                     const int th = t0 + bj * HALF;
;                     if (VM == 0) {
;                         const int t = th + wc * 32 + 8 * fq;
;                         if (u.pm < 12) *(u32x4*)(UT + ((size_t)(bseq * 3072 + nn)) * 4096 + t) = w;
;                         else *(u32x4*)(VT + ((size_t)(bseq * 1536 + (nn - 3072))) * 4096 + t) = w;
;                     } else if (VM == 1) {
;                         *(u32x4*)(VT + ((size_t)(bseq * 1536 + 512 + nn)) * 4096 + fq * 1024 + (th >> 2) + 8 * wc) = w;
;                     } else {
;                         *(u32x4*)(VT + ((size_t)(bseq * 1536 + 1024 + nn)) * 4096 + (4 * wc + fq) * 256 + (th >> 4)) = w;
;                     }
;                 }
;             }
;     }
; template <class Epi, class Sched, bool ALIGN_EPI = false, bool SP2 = false>
; __device__ __forceinline__ void gemm_phase(PG8_LAS unsigned char* lds, const Gemm g, const Sched& S, const Epi& E, const int tid_in) {
;     ...
;         if (!has_next) break;
; #pragma unroll
;         for (int a = 0; a < 2; ++a)
; #pragma unroll
;             for (int b = 0; b < 2; ++b)
; #pragma unroll
;                 for (int m = 0; m < 4; ++m)
; #pragma unroll
;                     for (int n = 0; n < 2; ++n) acc[a][b][m][n] = (f32x4){0.f, 0.f, 0.f, 0.f};
;         cur = nxt; cA = nA; cB = nB; ++ui;
;         if constexpr (ALIGN_EPI) { if (wr == 1) PG8_BAR; }
.LBB0_377:
	s_lshr_b32 s23, s31, 4
	s_lshl_b32 s21, s30, 8
	s_mulk_i32 s23, 0x600
	s_add_i32 s23, s23, s21
	v_add_u32_e32 v144, s23, v146
	v_ashrrev_i32_e32 v145, 31, v144
	v_lshlrev_b64 v[148:149], 13, v[144:145]
	s_lshl_b32 s21, s31, 7
	v_cvt_pk_bf16_f32 v126, v126, v127
	v_cvt_pk_bf16_f32 v127, v128, v129
	v_cvt_pk_bf16_f32 v128, v122, v123
	v_lshl_add_u64 v[122:123], v[138:139], 0, v[148:149]
	s_and_b32 s92, s21, 0x780
	v_lshl_add_u64 v[122:123], v[122:123], 0, s[92:93]
	s_mov_b32 s21, s93
	v_lshl_add_u64 v[122:123], v[122:123], 0, s[20:21]
	v_cvt_pk_bf16_f32 v129, v124, v125
	global_store_dwordx4 v[122:123], v[126:129], off
	v_cvt_pk_bf16_f32 v114, v114, v115
	v_cvt_pk_bf16_f32 v115, v116, v117
	v_cvt_pk_bf16_f32 v116, v106, v107
	v_or_b32_e32 v106, 16, v144
	v_ashrrev_i32_e32 v107, 31, v106
	v_cvt_pk_bf16_f32 v117, v108, v109
	global_store_dwordx4 v[122:123], v[114:117], off offset:64
	s_andn2_b64 vcc, exec, s[36:37]
	s_mov_b64 s[30:31], -1
	v_lshlrev_b64 v[114:115], 13, v[106:107]
	v_cvt_pk_bf16_f32 v106, v118, v119
	v_cvt_pk_bf16_f32 v107, v120, v121
	v_cvt_pk_bf16_f32 v108, v110, v111
	v_lshl_add_u64 v[110:111], v[138:139], 0, v[114:115]
	v_lshl_add_u64 v[110:111], v[110:111], 0, s[92:93]
	v_lshl_add_u64 v[110:111], v[110:111], 0, s[20:21]
	v_cvt_pk_bf16_f32 v109, v112, v113
	global_store_dwordx4 v[110:111], v[106:109], off
	v_cvt_pk_bf16_f32 v98, v98, v99
	v_cvt_pk_bf16_f32 v99, v100, v101
	v_cvt_pk_bf16_f32 v100, v90, v91
	v_or_b32_e32 v90, 32, v144
	v_ashrrev_i32_e32 v91, 31, v90
	v_cvt_pk_bf16_f32 v101, v92, v93
	global_store_dwordx4 v[110:111], v[98:101], off offset:64
	v_readlane_b32 s57, v255, 11
	s_movk_i32 s54, 0xffc0
	v_lshlrev_b64 v[98:99], 13, v[90:91]
	v_cvt_pk_bf16_f32 v90, v102, v103
	v_cvt_pk_bf16_f32 v91, v104, v105
	v_cvt_pk_bf16_f32 v92, v94, v95
	v_lshl_add_u64 v[94:95], v[138:139], 0, v[98:99]
	v_lshl_add_u64 v[94:95], v[94:95], 0, s[92:93]
	v_lshl_add_u64 v[94:95], v[94:95], 0, s[20:21]
	v_cvt_pk_bf16_f32 v93, v96, v97
	global_store_dwordx4 v[94:95], v[90:93], off
	v_cvt_pk_bf16_f32 v82, v82, v83
	v_cvt_pk_bf16_f32 v83, v84, v85
	v_cvt_pk_bf16_f32 v84, v74, v75
	v_or_b32_e32 v74, 48, v144
	v_ashrrev_i32_e32 v75, 31, v74
	v_cvt_pk_bf16_f32 v85, v76, v77
	global_store_dwordx4 v[94:95], v[82:85], off offset:64
	s_movk_i32 s55, 0xc00
	s_mov_b32 s56, 0xfe03f81
	v_lshlrev_b64 v[82:83], 13, v[74:75]
	v_cvt_pk_bf16_f32 v74, v86, v87
	v_cvt_pk_bf16_f32 v75, v88, v89
	v_cvt_pk_bf16_f32 v76, v78, v79
	v_lshl_add_u64 v[78:79], v[138:139], 0, v[82:83]
	v_lshl_add_u64 v[78:79], v[78:79], 0, s[92:93]
	v_lshl_add_u64 v[78:79], v[78:79], 0, s[20:21]
	v_cvt_pk_bf16_f32 v77, v80, v81
	global_store_dwordx4 v[78:79], v[74:77], off
	v_cvt_pk_bf16_f32 v70, v70, v71
	v_cvt_pk_bf16_f32 v71, v72, v73
	v_cvt_pk_bf16_f32 v72, v66, v67
	v_add_u32_e32 v66, 0x80, v144
	v_ashrrev_i32_e32 v67, 31, v66
	v_lshlrev_b64 v[66:67], 13, v[66:67]
	v_cvt_pk_bf16_f32 v73, v68, v69
	global_store_dwordx4 v[78:79], v[70:73], off offset:64
	v_cvt_pk_bf16_f32 v62, v62, v63
	v_cvt_pk_bf16_f32 v63, v64, v65
	v_cvt_pk_bf16_f32 v64, v58, v59
	v_lshl_add_u64 v[58:59], v[138:139], 0, v[66:67]
	v_lshl_add_u64 v[58:59], v[58:59], 0, s[92:93]
	v_lshl_add_u64 v[58:59], v[58:59], 0, s[20:21]
	v_cvt_pk_bf16_f32 v65, v60, v61
	global_store_dwordx4 v[58:59], v[62:65], off
	v_cvt_pk_bf16_f32 v50, v50, v51
	v_cvt_pk_bf16_f32 v51, v52, v53
	v_cvt_pk_bf16_f32 v52, v42, v43
	v_add_u32_e32 v42, 0x90, v144
	v_ashrrev_i32_e32 v43, 31, v42
	v_cvt_pk_bf16_f32 v53, v44, v45
	global_store_dwordx4 v[58:59], v[50:53], off offset:64
	s_nop 1
	v_lshlrev_b64 v[50:51], 13, v[42:43]
	v_cvt_pk_bf16_f32 v42, v54, v55
	v_cvt_pk_bf16_f32 v43, v56, v57
	v_cvt_pk_bf16_f32 v44, v46, v47
	v_lshl_add_u64 v[46:47], v[138:139], 0, v[50:51]
	v_lshl_add_u64 v[46:47], v[46:47], 0, s[92:93]
	v_lshl_add_u64 v[46:47], v[46:47], 0, s[20:21]
	v_cvt_pk_bf16_f32 v45, v48, v49
	global_store_dwordx4 v[46:47], v[42:45], off
	v_cvt_pk_bf16_f32 v34, v34, v35
	v_cvt_pk_bf16_f32 v35, v36, v37
	v_cvt_pk_bf16_f32 v36, v26, v27
	v_add_u32_e32 v26, 0xa0, v144
	v_ashrrev_i32_e32 v27, 31, v26
	v_cvt_pk_bf16_f32 v37, v28, v29
	global_store_dwordx4 v[46:47], v[34:37], off offset:64
	s_nop 1
	v_lshlrev_b64 v[34:35], 13, v[26:27]
	v_cvt_pk_bf16_f32 v26, v38, v39
	v_cvt_pk_bf16_f32 v27, v40, v41
	v_cvt_pk_bf16_f32 v28, v30, v31
	v_lshl_add_u64 v[30:31], v[138:139], 0, v[34:35]
	v_lshl_add_u64 v[30:31], v[30:31], 0, s[92:93]
	v_lshl_add_u64 v[30:31], v[30:31], 0, s[20:21]
	v_cvt_pk_bf16_f32 v29, v32, v33
	global_store_dwordx4 v[30:31], v[26:29], off
	v_cvt_pk_bf16_f32 v16, v16, v17
	v_cvt_pk_bf16_f32 v17, v18, v19
	v_cvt_pk_bf16_f32 v18, v8, v9
	v_add_u32_e32 v8, 0xb0, v144
	v_ashrrev_i32_e32 v9, 31, v8
	v_cvt_pk_bf16_f32 v19, v10, v11
	global_store_dwordx4 v[30:31], v[16:19], off offset:64
	s_nop 1
	v_lshlrev_b64 v[16:17], 13, v[8:9]
	v_cvt_pk_bf16_f32 v8, v22, v23
	v_cvt_pk_bf16_f32 v9, v24, v25
	v_cvt_pk_bf16_f32 v10, v12, v13
	v_lshl_add_u64 v[12:13], v[138:139], 0, v[16:17]
	v_lshl_add_u64 v[12:13], v[12:13], 0, s[92:93]
	v_lshl_add_u64 v[12:13], v[12:13], 0, s[20:21]
	v_cvt_pk_bf16_f32 v11, v14, v15
	global_store_dwordx4 v[12:13], v[8:11], off
	v_cvt_pk_bf16_f32 v4, v4, v5
	v_cvt_pk_bf16_f32 v5, v6, v7
	v_cvt_pk_bf16_f32 v6, v0, v1
	v_cvt_pk_bf16_f32 v7, v2, v3
	global_store_dwordx4 v[12:13], v[4:7], off offset:64
	s_cbranch_vccnz .LBB0_366
	s_andn2_b64 vcc, exec, s[2:3]
	s_cbranch_vccnz .LBB0_365
	s_branch .LBB0_365

; template <class Epi, class Sched, bool ALIGN_EPI = false, bool SP2 = false>
; __device__ __forceinline__ void gemm_phase(PG8_LAS unsigned char* lds, const Gemm g, const Sched& S, const Epi& E, const int tid_in) {
;     ...
;     const int tid = tid_l, wid = __builtin_amdgcn_readfirstlane(tid >> 6), lane = tid & 63, wr = wid >> 2, wc = wid & 3, fr = lane & 15, fq = lane >> 4;
;     const int K = g.K, nt = K / BK;
;     unsigned voffA[2], voffB[2];
; #pragma unroll
;     for (int i = 0; i < 2; ++i) { int R, C; stage_rc(tid * 16 + i * 8192, R, C); const int Rb = perm_row<Epi::PMODE>(R);
;         voffA[i] = (unsigned)(R * K + C) * 2u; voffB[i] = (unsigned)(Rb * K + C) * 2u; }
;     const size_t kstep = (size_t)(BK * 2);
;     const size_t hstep = (size_t)HALF * K * 2;
;     const size_t tstep = 2 * hstep;
;     const unsigned ldsw = (unsigned)wid * 1024u;
;     const int aoff = lds_byte(wr * 64 + fr, fq * 8), boff = lds_byte(wc * 32 + fr, fq * 8);
;     ...
;     Unit cur, nxt; int ui = 0;
;     if (!S.next(0, cur)) return;
;     f32x4 acc[2][2][4][2];
; #pragma unroll
;     for (int a = 0; a < 2; ++a)
; #pragma unroll
;         for (int b = 0; b < 2; ++b)
; #pragma unroll
;             for (int m = 0; m < 4; ++m)
; #pragma unroll
;                 for (int n = 0; n < 2; ++n) acc[a][b][m][n] = (f32x4){0.f, 0.f, 0.f, 0.f};
;     bf16x8 At[4][2], B0[2][2], B1[2][2];
;     const char* cA = (const char*)g.A + (size_t)cur.pm * tstep; const char* cB = (const char*)g.Bt + (size_t)cur.pn * tstep;
;     S.a_ready(cur);
;     if constexpr (Epi::PREF) E.prefetch(cur, 0, lds, wid, lane);
;     if constexpr (SP2) {
;         PG8_STAGE(PG8_SB(0, 0), cB, voffB); PG8_STAGE(PG8_SB(0, 1), cB + hstep, voffB); PG8_STAGE(PG8_SA(0, 0), cA, voffA); PG8_STAGE(PG8_SA(0, 1), cA + hstep, voffA);
;         if (wr == 1) PG8_BAR;
;         PG8_WAIT_V(2); PG8_BAR;
;         PG8_STAGE(PG8_SB(1, 0), cB + kstep, voffB); PG8_STAGE(PG8_SA(1, 0), cA + kstep, voffA); PG8_STAGE(PG8_SB(1, 1), cB + hstep + kstep, voffB);
;         PG8_WAIT_V(6); PG8_BAR;
; __global__ void __launch_bounds__(512, 2) mega_fwd(Args args) {
;     ...
;                 { PH_CTX const bf16_t* Win = WSP(const bf16_t, WS_WIN) + (size_t)pl * 11776 * 2048 + (size_t)4096 * 2048;
;                   pg8::Gemm g{Win, HB_CUR, 512, MROWS, 2048}; pg8::StaticOrder S; S.init(512, MROWS, G, bx); pg8::EpiG1a<2> E{WSP(bf16_t, WS_UT), WSP(bf16_t, WS_VT)};
.LBB0_381:
	v_readlane_b32 s1, v252, 7
	v_readlane_b32 s22, v253, 26
	v_mbcnt_lo_u32_b32 v0, -1, 0
	v_mbcnt_hi_u32_b32 v0, -1, v0
	s_mov_b64 s[2:3], s[20:21]
	v_or_b32_e32 v13, s1, v0
	v_readlane_b32 s7, v255, 12
	v_readlane_b32 s8, v254, 59
	v_readlane_b32 s23, v253, 27
	s_andn2_b64 vcc, exec, s[22:23]
	v_readfirstlane_b32 s6, v13
	s_cbranch_vccnz .LBB0_401
	v_lshlrev_b32_e32 v0, 4, v13
	v_add_u32_e32 v1, 0x2000, v0
	v_ashrrev_i32_e32 v2, 31, v1
	v_lshrrev_b32_e32 v2, 22, v2
	v_add_u32_e32 v2, v1, v2
	s_load_dwordx2 s[20:21], s[2:3], 0xf0
	v_ashrrev_i32_e32 v8, 10, v2
	v_mul_i32_i24_e32 v2, 0x400, v8
	v_sub_u32_e32 v1, v1, v2
	v_lshrrev_b32_e32 v2, 4, v1
	s_mul_i32 s2, s8, 0x2e00000
	v_bitop3_b32 v1, v2, v1, 32 bitop3:0x6c
	s_mul_hi_i32 s1, s8, 0x2e00000
	s_waitcnt lgkmcnt(0)
	s_add_u32 s2, s20, s2
	v_ashrrev_i32_e32 v2, 31, v1
	s_addc_u32 s3, s21, s1
	v_lshrrev_b32_e32 v2, 26, v2
	s_add_u32 s1, s2, 0x9800000
	v_add_u32_e32 v2, v1, v2
	v_lshlrev_b32_e32 v3, 3, v8
	s_addc_u32 s5, s3, 0
	s_add_i32 s8, s8, s7
	v_ashrrev_i32_e32 v9, 6, v2
	v_and_b32_e32 v3, -16, v3
	s_bitcmp0_b32 s8, 0
	s_mov_b32 s2, 0x4f200000
	v_add_u32_e32 v3, v9, v3
	s_cselect_b32 s2, 0x28000000, s2
	v_lshrrev_b32_e32 v4, 2, v3
	v_and_b32_e32 v5, 3, v9
	v_and_b32_e32 v2, 0xc0, v2
	s_add_u32 s8, s20, s2
	v_and_or_b32 v4, v4, 4, v5
	v_lshrrev_b32_e32 v5, 3, v3
	v_bfe_u32 v6, v3, 2, 2
	s_mov_b32 s2, 0xffffc
	v_sub_u32_e32 v1, v1, v2
	v_mov_b32_e32 v7, 1
	v_and_or_b32 v5, v5, s2, v6
	v_lshlrev_b32_e32 v6, 5, v8
	v_ashrrev_i16_sdwa v1, v7, sext(v1) dst_sel:DWORD dst_unused:UNUSED_PAD src0_sel:DWORD src1_sel:BYTE_0
	v_and_b32_e32 v6, 32, v6
	v_bfe_i32 v10, v1, 0, 16
	v_lshlrev_b32_e32 v4, 16, v4
	v_lshlrev_b32_e32 v5, 12, v5
	v_add_lshl_u32 v1, v6, v10, 1
	v_add3_u32 v130, v4, v5, v1
	v_lshl_add_u32 v132, v3, 12, v1
	v_bfe_i32 v1, v13, 27, 1
	v_lshrrev_b32_e32 v1, 22, v1
	v_add_u32_e32 v1, v0, v1
	v_and_b32_e32 v1, 0xfffffc00, v1
	v_sub_u32_e32 v0, v0, v1
	v_lshrrev_b32_e32 v1, 4, v0
	v_ashrrev_i32_e32 v2, 31, v13
	v_bitop3_b32 v0, v1, v0, 32 bitop3:0x6c
	v_lshrrev_b32_e32 v2, 26, v2
	v_ashrrev_i32_e32 v1, 31, v0
	v_add_u32_e32 v2, v13, v2
	v_lshrrev_b32_e32 v1, 26, v1
	v_ashrrev_i32_e32 v12, 6, v2
	v_add_u32_e32 v1, v0, v1
	v_lshlrev_b32_e32 v2, 3, v12
	v_ashrrev_i32_e32 v11, 6, v1
	v_and_b32_e32 v2, -16, v2
	v_add_u32_e32 v2, v11, v2
	v_lshrrev_b32_e32 v3, 2, v2
	v_and_b32_e32 v4, 3, v11
	v_and_b32_e32 v1, 0xc0, v1
	s_addc_u32 s10, s21, 0
	s_ashr_i32 s22, s6, 6
	v_and_or_b32 v3, v3, 4, v4
	v_lshrrev_b32_e32 v4, 3, v2
	v_bfe_u32 v5, v2, 2, 2
	v_sub_u32_e32 v0, v0, v1
	s_ashr_i32 s7, s6, 8
	s_lshl_b32 s19, s22, 10
	v_and_or_b32 v4, v4, s2, v5
	v_lshlrev_b32_e32 v5, 5, v12
	v_ashrrev_i16_sdwa v0, v7, sext(v0) dst_sel:DWORD dst_unused:UNUSED_PAD src0_sel:DWORD src1_sel:BYTE_0
	v_readlane_b32 s2, v254, 29
	v_and_b32_e32 v5, 32, v5
	v_bfe_i32 v14, v0, 0, 16
	v_readlane_b32 s3, v254, 30
	s_add_u32 s30, s8, s2
	v_lshlrev_b32_e32 v3, 16, v3
	v_lshlrev_b32_e32 v4, 12, v4
	v_add_lshl_u32 v0, v5, v14, 1
	s_addc_u32 s31, s10, s3
	s_add_i32 s38, s19, 0
	v_add3_u32 v134, v3, v4, v0
	s_add_i32 m0, s38, 0x10000
	v_lshl_add_u32 v136, v2, 12, v0
	global_load_lds_dwordx4 v134, s[30:31]
	s_add_i32 m0, s38, 0x12000
	s_add_u32 s2, s30, 0x80000
	global_load_lds_dwordx4 v130, s[30:31]
	s_addc_u32 s3, s31, 0
	s_add_i32 m0, s38, 0x14000
	v_mov_b32_e32 v135, v20
	global_load_lds_dwordx4 v134, s[2:3]
	s_add_i32 m0, s38, 0x16000
	v_mov_b32_e32 v131, v20
	global_load_lds_dwordx4 v130, s[2:3]
	v_readlane_b32 s2, v254, 33
	v_readlane_b32 s3, v254, 34
	s_add_u32 s28, s1, s2
	s_addc_u32 s29, s5, s3
	s_add_i32 s39, s38, 0x2000
	s_mov_b32 m0, s38
	s_add_u32 s2, s28, 0x80000
	global_load_lds_dwordx4 v136, s[28:29]
	s_mov_b32 m0, s39
	s_addc_u32 s3, s29, 0
	s_add_i32 s42, s38, 0x4000
	global_load_lds_dwordx4 v132, s[28:29]
	s_mov_b32 m0, s42
	s_add_i32 s43, s38, 0x6000
	global_load_lds_dwordx4 v136, s[2:3]
	s_mov_b32 m0, s43
	v_mov_b32_e32 v137, v20
	global_load_lds_dwordx4 v132, s[2:3]
	v_mov_b32_e32 v133, v20
	s_cmp_eq_u32 s7, 1
	v_lshl_add_u64 v[6:7], s[30:31], 0, v[134:135]
	v_lshl_add_u64 v[4:5], s[30:31], 0, v[130:131]
	v_lshl_add_u64 v[0:1], s[28:29], 0, v[136:137]
	s_cselect_b64 s[2:3], -1, 0
	s_cmp_lg_u32 s7, 1
	v_lshl_add_u64 v[2:3], s[28:29], 0, v[132:133]
	s_cbranch_scc1 .LBB0_384
.LBB0_384:
	v_bfe_u32 v16, v13, 4, 2
	v_and_b32_e32 v15, 15, v13
	v_lshlrev_b32_e32 v18, 4, v16
	v_lshlrev_b32_e32 v13, 2, v13
	s_and_b32 s24, s22, 3
	v_lshl_or_b32 v17, s7, 6, v15
	v_lshl_or_b32 v15, v15, 6, v18
	s_lshl_b32 s7, s7, 13
	v_and_b32_e32 v13, 32, v13
	s_add_i32 m0, s38, 0x18000
	v_lshl_add_u64 v[6:7], v[6:7], 0, s[12:13]
	v_bitop3_b32 v18, v15, s7, v13 bitop3:0xde
	s_lshl_b32 s7, s24, 12
	s_waitcnt vmcnt(2)
	s_barrier
	global_load_lds_dwordx4 v[6:7], off
	v_lshl_add_u64 v[4:5], v[4:5], 0, s[12:13]
	s_add_i32 m0, s38, 0x1a000
	s_add_i32 s44, s38, 0x8000
	s_add_i32 s45, s38, 0xa000
	global_load_lds_dwordx4 v[4:5], off
	v_lshl_add_u64 v[0:1], v[0:1], 0, s[12:13]
	s_mov_b32 m0, s44
	s_add_u32 s100, s28, 0x80
	s_addc_u32 s101, s29, 0
	s_add_u32 s22, s30, 0x80080
	global_load_lds_dwordx4 v[0:1], off
	v_lshl_add_u64 v[0:1], v[2:3], 0, s[12:13]
	s_mov_b32 m0, s45
	s_addc_u32 s23, s31, 0
	global_load_lds_dwordx4 v[0:1], off
	s_add_i32 m0, s38, 0x1c000
	v_lshl_add_u64 v[0:1], s[22:23], 0, v[134:135]
	global_load_lds_dwordx4 v[0:1], off
	v_lshl_add_u64 v[0:1], s[22:23], 0, v[130:131]
	s_add_i32 m0, s38, 0x1e000
	s_cmpk_lt_u32 s6, 0x100
	global_load_lds_dwordx4 v[0:1], off
	v_lshlrev_b32_e32 v0, 9, v16
	v_lshl_or_b32 v0, s24, 11, v0
	v_mov_b32_e32 v1, v20
	v_lshl_add_u64 v[0:1], s[20:21], 0, v[0:1]
	s_mov_b64 s[20:21], 0x3b000000
	v_lshl_add_u64 v[138:139], v[0:1], 0, s[20:21]
	v_lshlrev_b32_e32 v0, 15, v12
	v_and_b32_e32 v0, 0xffff0000, v0
	v_lshl_add_u32 v0, v11, 12, v0
	v_and_b32_e32 v1, 1, v12
	v_lshl_or_b32 v0, v1, 6, v0
	v_lshl_add_u32 v140, v14, 1, v0
	v_lshlrev_b32_e32 v0, 15, v8
	v_and_b32_e32 v0, 0xffff0000, v0
	s_waitcnt vmcnt(6)
	v_lshl_add_u32 v0, v9, 12, v0
	v_and_b32_e32 v1, 1, v8
	v_lshl_or_b32 v0, v1, 6, v0
	v_readlane_b32 s20, v254, 31
	v_bitop3_b32 v21, v15, s7, v13 bitop3:0xde
	s_cselect_b64 s[6:7], -1, 0
	v_add_u32_e32 v146, 0x400, v17
	v_mov_b32_e32 v141, v20
	v_lshl_add_u32 v142, v10, 1, v0
	v_mov_b32_e32 v143, v20
	s_mov_b32 s46, 0
	v_add_u32_e32 v147, 0, v18
	v_readlane_b32 s47, v254, 28
	s_mov_b32 s48, s20
	s_barrier
	v_readlane_b32 s21, v254, 32
	s_branch .LBB0_387

; #define PG8_STAGE(bufoff, gbase, voff) do { _Pragma("unroll") for (int _i = 0; _i < 2; ++_i) \
;         __builtin_amdgcn_global_load_lds((const unsigned*)((const char*)(gbase) + (voff)[_i]), (PG8_LAS unsigned*)(lds + (bufoff) + ldsw + _i * 8192), 16, 0, 0); } while (0)
; #define PG8_LDA(dst, b, h) do { _Pragma("unroll") for (int m = 0; m < 4; ++m) _Pragma("unroll") for (int k = 0; k < 2; ++k) dst[m][k] = *(const PG8_LAS bf16x8*)(lds + PG8_SA(b, h) + aoff + m * 2048 + k * 1024); } while (0)
; #define PG8_LDB(dst, b, h) do { _Pragma("unroll") for (int n = 0; n < 2; ++n) _Pragma("unroll") for (int k = 0; k < 2; ++k) dst[n][k] = *(const PG8_LAS bf16x8*)(lds + PG8_SB(b, h) + boff + n * 2048 + k * 1024); } while (0)
; #define PG8_WAIT_V(n) asm volatile("s_waitcnt vmcnt(" #n ")" ::: "memory")
; #define PG8_WAIT_L(n) asm volatile("s_waitcnt lgkmcnt(" #n ")" ::: "memory")
; template <class Epi, class Sched, bool ALIGN_EPI = false, bool SP2 = false>
; __device__ __forceinline__ void gemm_phase(PG8_LAS unsigned char* lds, const Gemm g, const Sched& S, const Epi& E, const int tid_in) {
;     ...
;         const bool has_next = S.next(ui + 1, nxt);
;         const char* nA = has_next ? (const char*)g.A + (size_t)nxt.pm * tstep : cA; const char* nB = has_next ? (const char*)g.Bt + (size_t)nxt.pn * tstep : cB;
;         for (int t = 0; t < nt; t += 2) {
;             if constexpr (Epi::KSPLIT > 0) { if (t == Epi::KSPLIT / BK) E.midk(acc, cur, wr, wc, fr, fq); }
;             const bool last = (t == nt - 2);
;             const char* a1 = cA + (size_t)(t + 1) * kstep;
;             const char* a2 = last ? nA : cA + (size_t)(t + 2) * kstep; const char* b2 = last ? nB : cB + (size_t)(t + 2) * kstep;
;             const char* a3 = a2 + kstep; const char* b3 = b2 + kstep;
;             if (last && has_next) S.a_ready(nxt);
;             if constexpr (SP2) {
;             PG8_LDB(B0, 0, 0); PG8_LDB(B1, 0, 1); PG8_SCHED; PG8_LDA(At, 0, 0); PG8_STAGE(PG8_SA(1, 1), a1 + hstep, voffA);
;             PG8_WAIT_V(8); PG8_WAIT_L(0); PG8_BAR; PG8_MMA(0, 0, At, B0); PG8_MMA(0, 1, At, B1); PG8_BAR; PG8_SCHED;
;             PG8_LDA(At, 0, 1); PG8_STAGE(PG8_SB(0, 0), b2, voffB); PG8_STAGE(PG8_SB(0, 1), b2 + hstep, voffB); PG8_STAGE(PG8_SA(0, 0), a2, voffA);
;             PG8_WAIT_V(8); PG8_WAIT_L(0); PG8_BAR; PG8_MMA(1, 0, At, B0); PG8_MMA(1, 1, At, B1); PG8_BAR; PG8_SCHED;
.LBB0_393:
	s_ashr_i32 s23, s22, 31
	s_lshl_b64 s[24:25], s[22:23], 20
	s_add_u32 s24, s1, s24
	s_addc_u32 s25, s5, s25
	s_and_b64 s[26:27], s[36:37], exec
	s_cselect_b32 s23, s25, s29
	s_cselect_b32 s49, s24, s28
	s_ashr_i32 s21, s20, 31
	s_lshl_b64 s[26:27], s[20:21], 20
	s_add_u32 s26, s8, s26
	s_addc_u32 s27, s10, s27
	s_and_b64 s[34:35], s[36:37], exec
	s_cselect_b32 s21, s27, s31
	s_cselect_b32 s50, s26, s30
	s_add_u32 s28, s28, 0x80080
	s_addc_u32 s29, s29, 0
	s_add_u32 s51, s30, 0x100
	v_mov_b32_e32 v0, 0
	s_addc_u32 s52, s31, 0
	s_mov_b32 s53, -2
	s_cmp_lt_u32 s19, 0x1000
	s_cbranch_scc1 .LCB_394
	s_barrier
.LCB_394:
	s_mov_b32 m0, s45
	s_nop 0
	global_load_lds_dwordx4 v132, s[100:101]
	s_add_u32 s30, s28, 0xfff80080
	s_addc_u32 s31, s29, -1
	s_add_i32 s54, 0, 0x10000
	s_cmp_eq_u32 s53, 28
	s_cselect_b32 s35, s23, s31
	s_cselect_b32 s34, s49, s30
	v_add_u32_e32 v144, s54, v21
	s_cselect_b32 s31, s21, s52
	s_cselect_b32 s30, s50, s51
	s_add_i32 s56, 0, 0x14000
	ds_read_b128 v[148:151], v144
	ds_read_b128 v[152:155], v144 offset:1024
	ds_read_b128 v[156:159], v144 offset:2048
	ds_read_b128 v[160:163], v144 offset:3072
	v_add_u32_e32 v144, s56, v21
	ds_read_b128 v[164:167], v144
	ds_read_b128 v[168:171], v144 offset:1024
	ds_read_b128 v[172:175], v144 offset:2048
	ds_read_b128 v[176:179], v144 offset:3072
	s_add_i32 m0, s38, 0xc000
	ds_read_b128 v[180:183], v147
	ds_read_b128 v[184:187], v147 offset:1024
	ds_read_b128 v[188:191], v147 offset:2048
	ds_read_b128 v[192:195], v147 offset:3072
	ds_read_b128 v[196:199], v147 offset:4096
	ds_read_b128 v[200:203], v147 offset:5120
	ds_read_b128 v[208:211], v147 offset:6144
	ds_read_b128 v[212:215], v147 offset:7168
	global_load_lds_dwordx4 v140, s[28:29]
	s_add_i32 m0, s38, 0xe000
	s_nop 0
	global_load_lds_dwordx4 v142, s[28:29]
	s_waitcnt vmcnt(8)
	s_waitcnt lgkmcnt(0)
	s_barrier
	s_setprio 1
	v_mfma_f32_16x16x32_bf16 v[126:129], v[148:151], v[180:183], 0
	v_mfma_f32_16x16x32_bf16 v[122:125], v[156:159], v[180:183], 0
	v_mfma_f32_16x16x32_bf16 v[118:121], v[148:151], v[188:191], 0
	v_mfma_f32_16x16x32_bf16 v[110:113], v[156:159], v[188:191], 0
	v_mfma_f32_16x16x32_bf16 v[102:105], v[148:151], v[196:199], 0
	v_mfma_f32_16x16x32_bf16 v[94:97], v[156:159], v[196:199], 0
	v_mfma_f32_16x16x32_bf16 v[86:89], v[148:151], v[208:211], 0
	v_mfma_f32_16x16x32_bf16 v[78:81], v[156:159], v[208:211], 0
	v_mfma_f32_16x16x32_bf16 v[126:129], v[152:155], v[184:187], v[126:129]
	v_mfma_f32_16x16x32_bf16 v[122:125], v[160:163], v[184:187], v[122:125]
	v_mfma_f32_16x16x32_bf16 v[118:121], v[152:155], v[192:195], v[118:121]
	v_mfma_f32_16x16x32_bf16 v[110:113], v[160:163], v[192:195], v[110:113]
	v_mfma_f32_16x16x32_bf16 v[102:105], v[152:155], v[200:203], v[102:105]
	v_mfma_f32_16x16x32_bf16 v[94:97], v[160:163], v[200:203], v[94:97]
	v_mfma_f32_16x16x32_bf16 v[86:89], v[152:155], v[212:215], v[86:89]
	v_mfma_f32_16x16x32_bf16 v[78:81], v[160:163], v[212:215], v[78:81]
	s_setprio 0
	s_setprio 1
	v_mfma_f32_16x16x32_bf16 v[114:117], v[164:167], v[180:183], 0
	v_mfma_f32_16x16x32_bf16 v[106:109], v[172:175], v[180:183], 0
	v_mfma_f32_16x16x32_bf16 v[98:101], v[164:167], v[188:191], 0
	v_mfma_f32_16x16x32_bf16 v[90:93], v[172:175], v[188:191], 0
	v_mfma_f32_16x16x32_bf16 v[82:85], v[164:167], v[196:199], 0
	v_mfma_f32_16x16x32_bf16 v[74:77], v[172:175], v[196:199], 0
	v_mfma_f32_16x16x32_bf16 v[70:73], v[164:167], v[208:211], 0
	v_mfma_f32_16x16x32_bf16 v[66:69], v[172:175], v[208:211], 0
	v_mfma_f32_16x16x32_bf16 v[114:117], v[168:171], v[184:187], v[114:117]
	v_mfma_f32_16x16x32_bf16 v[106:109], v[176:179], v[184:187], v[106:109]
	v_mfma_f32_16x16x32_bf16 v[98:101], v[168:171], v[192:195], v[98:101]
	v_mfma_f32_16x16x32_bf16 v[90:93], v[176:179], v[192:195], v[90:93]
	v_mfma_f32_16x16x32_bf16 v[82:85], v[168:171], v[200:203], v[82:85]
	v_mfma_f32_16x16x32_bf16 v[74:77], v[176:179], v[200:203], v[74:77]
	v_mfma_f32_16x16x32_bf16 v[70:73], v[168:171], v[212:215], v[70:73]
	v_mfma_f32_16x16x32_bf16 v[66:69], v[176:179], v[212:215], v[66:69]
	s_setprio 0
	s_barrier
	s_add_i32 s54, s54, s19
	s_add_u32 s98, s30, 0x80
	s_addc_u32 s99, s31, 0
	s_mov_b32 m0, s54
	ds_read_b128 v[180:183], v147 offset:16384
	ds_read_b128 v[184:187], v147 offset:17408
	ds_read_b128 v[188:191], v147 offset:18432
	ds_read_b128 v[192:195], v147 offset:19456
	ds_read_b128 v[196:199], v147 offset:20480
	ds_read_b128 v[200:203], v147 offset:21504
	ds_read_b128 v[208:211], v147 offset:22528
	ds_read_b128 v[212:215], v147 offset:23552
	global_load_lds_dwordx4 v134, s[30:31]
	s_add_i32 m0, s54, 0x2000
	s_add_u32 s54, s30, 0x80000
	s_addc_u32 s55, s31, 0
	s_add_i32 s56, s56, s19
	global_load_lds_dwordx4 v130, s[30:31]
	s_mov_b32 m0, s56
	s_add_u32 s100, s34, 0x80
	s_addc_u32 s101, s35, 0
	global_load_lds_dwordx4 v134, s[54:55]
	s_add_i32 m0, s56, 0x2000
	s_nop 0
	global_load_lds_dwordx4 v130, s[54:55]
	s_mov_b32 m0, s38
	s_nop 0
	global_load_lds_dwordx4 v136, s[34:35]
	s_waitcnt vmcnt(7)
	s_waitcnt lgkmcnt(0)
	s_barrier
; #define PG8_STAGE(bufoff, gbase, voff) do { _Pragma("unroll") for (int _i = 0; _i < 2; ++_i) \
;         __builtin_amdgcn_global_load_lds((const unsigned*)((const char*)(gbase) + (voff)[_i]), (PG8_LAS unsigned*)(lds + (bufoff) + ldsw + _i * 8192), 16, 0, 0); } while (0)
; #define PG8_LDA(dst, b, h) do { _Pragma("unroll") for (int m = 0; m < 4; ++m) _Pragma("unroll") for (int k = 0; k < 2; ++k) dst[m][k] = *(const PG8_LAS bf16x8*)(lds + PG8_SA(b, h) + aoff + m * 2048 + k * 1024); } while (0)
; #define PG8_LDB(dst, b, h) do { _Pragma("unroll") for (int n = 0; n < 2; ++n) _Pragma("unroll") for (int k = 0; k < 2; ++k) dst[n][k] = *(const PG8_LAS bf16x8*)(lds + PG8_SB(b, h) + boff + n * 2048 + k * 1024); } while (0)
; #define PG8_MMA(ai, bj, At, Bt) do { __builtin_amdgcn_s_setprio(1); _Pragma("unroll") for (int m = 0; m < 4; ++m) _Pragma("unroll") for (int n = 0; n < 2; ++n) _Pragma("unroll") for (int k = 0; k < 2; ++k) \
;         acc[ai][bj][m][n] = __builtin_amdgcn_mfma_f32_16x16x32_bf16(Bt[n][k], At[m][k], acc[ai][bj][m][n], 0, 0, 0); __builtin_amdgcn_s_setprio(0); } while (0)
; #define PG8_WAIT_V(n) asm volatile("s_waitcnt vmcnt(" #n ")" ::: "memory")
; #define PG8_WAIT_L(n) asm volatile("s_waitcnt lgkmcnt(" #n ")" ::: "memory")
; #define PG8_BAR __builtin_amdgcn_s_barrier()
; #define PG8_SCHED __builtin_amdgcn_sched_barrier(0)
; template <class Epi, class Sched, bool ALIGN_EPI = false, bool SP2 = false>
; __device__ __forceinline__ void gemm_phase(PG8_LAS unsigned char* lds, const Gemm g, const Sched& S, const Epi& E, const int tid_in) {
;     ...
;             PG8_WAIT_V(8); PG8_WAIT_L(0); PG8_BAR; PG8_MMA(1, 0, At, B0); PG8_MMA(1, 1, At, B1); PG8_BAR; PG8_SCHED;
;             PG8_LDB(B0, 1, 0); PG8_LDB(B1, 1, 1); PG8_SCHED; PG8_LDA(At, 1, 0); PG8_STAGE(PG8_SA(0, 1), a2 + hstep, voffA);
;             PG8_WAIT_V(8); PG8_WAIT_L(0); PG8_BAR; PG8_MMA(0, 0, At, B0); PG8_MMA(0, 1, At, B1); PG8_BAR; PG8_SCHED;
;             PG8_LDA(At, 1, 1); PG8_STAGE(PG8_SB(1, 0), b3, voffB); PG8_STAGE(PG8_SB(1, 1), b3 + hstep, voffB); PG8_STAGE(PG8_SA(1, 0), a3, voffA);
	s_setprio 1
	v_mfma_f32_16x16x32_bf16 v[62:65], v[148:151], v[180:183], 0
	v_mfma_f32_16x16x32_bf16 v[58:61], v[156:159], v[180:183], 0
	v_mfma_f32_16x16x32_bf16 v[54:57], v[148:151], v[188:191], 0
	v_mfma_f32_16x16x32_bf16 v[46:49], v[156:159], v[188:191], 0
	v_mfma_f32_16x16x32_bf16 v[38:41], v[148:151], v[196:199], 0
	v_mfma_f32_16x16x32_bf16 v[30:33], v[156:159], v[196:199], 0
	v_mfma_f32_16x16x32_bf16 v[22:25], v[148:151], v[208:211], 0
	v_mfma_f32_16x16x32_bf16 v[12:15], v[156:159], v[208:211], 0
	v_mfma_f32_16x16x32_bf16 v[62:65], v[152:155], v[184:187], v[62:65]
	v_mfma_f32_16x16x32_bf16 v[58:61], v[160:163], v[184:187], v[58:61]
	v_mfma_f32_16x16x32_bf16 v[54:57], v[152:155], v[192:195], v[54:57]
	v_mfma_f32_16x16x32_bf16 v[46:49], v[160:163], v[192:195], v[46:49]
	v_mfma_f32_16x16x32_bf16 v[38:41], v[152:155], v[200:203], v[38:41]
	v_mfma_f32_16x16x32_bf16 v[30:33], v[160:163], v[200:203], v[30:33]
	v_mfma_f32_16x16x32_bf16 v[22:25], v[152:155], v[212:215], v[22:25]
	v_mfma_f32_16x16x32_bf16 v[12:15], v[160:163], v[212:215], v[12:15]
	s_setprio 0
	s_setprio 1
	v_mfma_f32_16x16x32_bf16 v[50:53], v[164:167], v[180:183], 0
	v_mfma_f32_16x16x32_bf16 v[42:45], v[172:175], v[180:183], 0
	v_mfma_f32_16x16x32_bf16 v[34:37], v[164:167], v[188:191], 0
	v_mfma_f32_16x16x32_bf16 v[26:29], v[172:175], v[188:191], 0
	v_mfma_f32_16x16x32_bf16 v[16:19], v[164:167], v[196:199], 0
	v_mfma_f32_16x16x32_bf16 v[8:11], v[172:175], v[196:199], 0
	v_mfma_f32_16x16x32_bf16 v[4:7], v[164:167], v[208:211], 0
	v_mfma_f32_16x16x32_bf16 v[0:3], v[172:175], v[208:211], 0
	v_mfma_f32_16x16x32_bf16 v[50:53], v[168:171], v[184:187], v[50:53]
	v_mfma_f32_16x16x32_bf16 v[42:45], v[176:179], v[184:187], v[42:45]
	v_mfma_f32_16x16x32_bf16 v[34:37], v[168:171], v[192:195], v[34:37]
	v_mfma_f32_16x16x32_bf16 v[26:29], v[176:179], v[192:195], v[26:29]
	v_mfma_f32_16x16x32_bf16 v[16:19], v[168:171], v[200:203], v[16:19]
	v_mfma_f32_16x16x32_bf16 v[8:11], v[176:179], v[200:203], v[8:11]
	v_mfma_f32_16x16x32_bf16 v[4:7], v[168:171], v[212:215], v[4:7]
	v_mfma_f32_16x16x32_bf16 v[0:3], v[176:179], v[212:215], v[0:3]
	s_setprio 0
	s_barrier
	s_add_i32 s54, 0, 0x18000
	s_add_i32 s55, 0, 0x1c000
	v_add_u32_e32 v160, s54, v21
	v_add_u32_e32 v176, s55, v21
	ds_read_b128 v[148:151], v160
	ds_read_b128 v[152:155], v160 offset:1024
	ds_read_b128 v[156:159], v160 offset:2048
	ds_read_b128 v[160:163], v160 offset:3072
	ds_read_b128 v[164:167], v176
	ds_read_b128 v[168:171], v176 offset:1024
	ds_read_b128 v[172:175], v176 offset:2048
	ds_read_b128 v[176:179], v176 offset:3072
	s_mov_b32 m0, s39
	s_nop 0
	global_load_lds_dwordx4 v132, s[34:35]
	s_add_u32 s34, s34, 0x80000
	s_addc_u32 s35, s35, 0
	s_mov_b32 m0, s42
	ds_read_b128 v[180:183], v147 offset:32768
	ds_read_b128 v[184:187], v147 offset:33792
	ds_read_b128 v[188:191], v147 offset:34816
	ds_read_b128 v[192:195], v147 offset:35840
	ds_read_b128 v[196:199], v147 offset:36864
	ds_read_b128 v[200:203], v147 offset:37888
	ds_read_b128 v[208:211], v147 offset:38912
	ds_read_b128 v[212:215], v147 offset:39936
	global_load_lds_dwordx4 v136, s[34:35]
	s_mov_b32 m0, s43
	s_nop 0
	global_load_lds_dwordx4 v132, s[34:35]
	s_waitcnt vmcnt(8)
	s_waitcnt lgkmcnt(0)
	s_barrier
	s_setprio 1
	v_mfma_f32_16x16x32_bf16 v[126:129], v[148:151], v[180:183], v[126:129]
	v_mfma_f32_16x16x32_bf16 v[122:125], v[156:159], v[180:183], v[122:125]
	v_mfma_f32_16x16x32_bf16 v[118:121], v[148:151], v[188:191], v[118:121]
	v_mfma_f32_16x16x32_bf16 v[110:113], v[156:159], v[188:191], v[110:113]
	v_mfma_f32_16x16x32_bf16 v[102:105], v[148:151], v[196:199], v[102:105]
	v_mfma_f32_16x16x32_bf16 v[94:97], v[156:159], v[196:199], v[94:97]
	v_mfma_f32_16x16x32_bf16 v[86:89], v[148:151], v[208:211], v[86:89]
	v_mfma_f32_16x16x32_bf16 v[78:81], v[156:159], v[208:211], v[78:81]
	v_mfma_f32_16x16x32_bf16 v[126:129], v[152:155], v[184:187], v[126:129]
	v_mfma_f32_16x16x32_bf16 v[122:125], v[160:163], v[184:187], v[122:125]
	v_mfma_f32_16x16x32_bf16 v[118:121], v[152:155], v[192:195], v[118:121]
	v_mfma_f32_16x16x32_bf16 v[110:113], v[160:163], v[192:195], v[110:113]
	v_mfma_f32_16x16x32_bf16 v[102:105], v[152:155], v[200:203], v[102:105]
	v_mfma_f32_16x16x32_bf16 v[94:97], v[160:163], v[200:203], v[94:97]
	v_mfma_f32_16x16x32_bf16 v[86:89], v[152:155], v[212:215], v[86:89]
	v_mfma_f32_16x16x32_bf16 v[78:81], v[160:163], v[212:215], v[78:81]
	s_setprio 0
	s_setprio 1
	v_mfma_f32_16x16x32_bf16 v[114:117], v[164:167], v[180:183], v[114:117]
	v_mfma_f32_16x16x32_bf16 v[106:109], v[172:175], v[180:183], v[106:109]
	v_mfma_f32_16x16x32_bf16 v[98:101], v[164:167], v[188:191], v[98:101]
	v_mfma_f32_16x16x32_bf16 v[90:93], v[172:175], v[188:191], v[90:93]
	v_mfma_f32_16x16x32_bf16 v[82:85], v[164:167], v[196:199], v[82:85]
	v_mfma_f32_16x16x32_bf16 v[74:77], v[172:175], v[196:199], v[74:77]
	v_mfma_f32_16x16x32_bf16 v[70:73], v[164:167], v[208:211], v[70:73]
	v_mfma_f32_16x16x32_bf16 v[66:69], v[172:175], v[208:211], v[66:69]
	v_mfma_f32_16x16x32_bf16 v[114:117], v[168:171], v[184:187], v[114:117]
	v_mfma_f32_16x16x32_bf16 v[106:109], v[176:179], v[184:187], v[106:109]
	v_mfma_f32_16x16x32_bf16 v[98:101], v[168:171], v[192:195], v[98:101]
	v_mfma_f32_16x16x32_bf16 v[90:93], v[176:179], v[192:195], v[90:93]
	v_mfma_f32_16x16x32_bf16 v[82:85], v[168:171], v[200:203], v[82:85]
	v_mfma_f32_16x16x32_bf16 v[74:77], v[176:179], v[200:203], v[74:77]
	v_mfma_f32_16x16x32_bf16 v[70:73], v[168:171], v[212:215], v[70:73]
	v_mfma_f32_16x16x32_bf16 v[66:69], v[176:179], v[212:215], v[66:69]
	s_setprio 0
	s_barrier
; #define PG8_STAGE(bufoff, gbase, voff) do { _Pragma("unroll") for (int _i = 0; _i < 2; ++_i) \
;         __builtin_amdgcn_global_load_lds((const unsigned*)((const char*)(gbase) + (voff)[_i]), (PG8_LAS unsigned*)(lds + (bufoff) + ldsw + _i * 8192), 16, 0, 0); } while (0)
; #define PG8_LDA(dst, b, h) do { _Pragma("unroll") for (int m = 0; m < 4; ++m) _Pragma("unroll") for (int k = 0; k < 2; ++k) dst[m][k] = *(const PG8_LAS bf16x8*)(lds + PG8_SA(b, h) + aoff + m * 2048 + k * 1024); } while (0)
; #define PG8_MMA(ai, bj, At, Bt) do { __builtin_amdgcn_s_setprio(1); _Pragma("unroll") for (int m = 0; m < 4; ++m) _Pragma("unroll") for (int n = 0; n < 2; ++n) _Pragma("unroll") for (int k = 0; k < 2; ++k) \
;         acc[ai][bj][m][n] = __builtin_amdgcn_mfma_f32_16x16x32_bf16(Bt[n][k], At[m][k], acc[ai][bj][m][n], 0, 0, 0); __builtin_amdgcn_s_setprio(0); } while (0)
; #define PG8_WAIT_V(n) asm volatile("s_waitcnt vmcnt(" #n ")" ::: "memory")
; #define PG8_WAIT_L(n) asm volatile("s_waitcnt lgkmcnt(" #n ")" ::: "memory")
; #define PG8_BAR __builtin_amdgcn_s_barrier()
; #define PG8_SCHED __builtin_amdgcn_sched_barrier(0)
; template <class Epi, class Sched, bool ALIGN_EPI = false, bool SP2 = false>
; __device__ __forceinline__ void gemm_phase(PG8_LAS unsigned char* lds, const Gemm g, const Sched& S, const Epi& E, const int tid_in) {
;     ...
;             PG8_LDA(At, 1, 1); PG8_STAGE(PG8_SB(1, 0), b3, voffB); PG8_STAGE(PG8_SB(1, 1), b3 + hstep, voffB); PG8_STAGE(PG8_SA(1, 0), a3, voffA);
;             PG8_WAIT_V(8); PG8_WAIT_L(0); PG8_BAR; PG8_MMA(1, 0, At, B0); PG8_MMA(1, 1, At, B1); PG8_BAR; PG8_SCHED;
	s_add_i32 s34, s54, s19
	s_mov_b32 m0, s34
	ds_read_b128 v[180:183], v147 offset:49152
	ds_read_b128 v[184:187], v147 offset:50176
	ds_read_b128 v[188:191], v147 offset:51200
	ds_read_b128 v[192:195], v147 offset:52224
	ds_read_b128 v[196:199], v147 offset:53248
	ds_read_b128 v[200:203], v147 offset:54272
	ds_read_b128 v[208:211], v147 offset:55296
	ds_read_b128 v[212:215], v147 offset:56320
	global_load_lds_dwordx4 v134, s[98:99]
	s_add_i32 m0, s34, 0x2000
	s_add_u32 s30, s30, 0x80080
	s_addc_u32 s31, s31, 0
	s_add_i32 s34, s55, s19
	global_load_lds_dwordx4 v130, s[98:99]
	s_mov_b32 m0, s34
	s_nop 0
	global_load_lds_dwordx4 v134, s[30:31]
	s_add_i32 m0, s34, 0x2000
	s_nop 0
	global_load_lds_dwordx4 v130, s[30:31]
	s_mov_b32 m0, s44
	s_nop 0
	global_load_lds_dwordx4 v136, s[100:101]
	s_waitcnt vmcnt(7)
	s_waitcnt lgkmcnt(0)
	s_barrier
	s_setprio 1
	v_mfma_f32_16x16x32_bf16 v[62:65], v[148:151], v[180:183], v[62:65]
	v_mfma_f32_16x16x32_bf16 v[58:61], v[156:159], v[180:183], v[58:61]
	v_mfma_f32_16x16x32_bf16 v[54:57], v[148:151], v[188:191], v[54:57]
	v_mfma_f32_16x16x32_bf16 v[46:49], v[156:159], v[188:191], v[46:49]
	v_mfma_f32_16x16x32_bf16 v[38:41], v[148:151], v[196:199], v[38:41]
	v_mfma_f32_16x16x32_bf16 v[30:33], v[156:159], v[196:199], v[30:33]
	v_mfma_f32_16x16x32_bf16 v[22:25], v[148:151], v[208:211], v[22:25]
	v_mfma_f32_16x16x32_bf16 v[12:15], v[156:159], v[208:211], v[12:15]
	v_mfma_f32_16x16x32_bf16 v[62:65], v[152:155], v[184:187], v[62:65]
	v_mfma_f32_16x16x32_bf16 v[58:61], v[160:163], v[184:187], v[58:61]
	v_mfma_f32_16x16x32_bf16 v[54:57], v[152:155], v[192:195], v[54:57]
	v_mfma_f32_16x16x32_bf16 v[46:49], v[160:163], v[192:195], v[46:49]
	v_mfma_f32_16x16x32_bf16 v[38:41], v[152:155], v[200:203], v[38:41]
	v_mfma_f32_16x16x32_bf16 v[30:33], v[160:163], v[200:203], v[30:33]
	v_mfma_f32_16x16x32_bf16 v[22:25], v[152:155], v[212:215], v[22:25]
	v_mfma_f32_16x16x32_bf16 v[12:15], v[160:163], v[212:215], v[12:15]
	s_setprio 0
	s_setprio 1
	v_mfma_f32_16x16x32_bf16 v[50:53], v[164:167], v[180:183], v[50:53]
	v_mfma_f32_16x16x32_bf16 v[42:45], v[172:175], v[180:183], v[42:45]
	v_mfma_f32_16x16x32_bf16 v[34:37], v[164:167], v[188:191], v[34:37]
	v_mfma_f32_16x16x32_bf16 v[26:29], v[172:175], v[188:191], v[26:29]
	v_mfma_f32_16x16x32_bf16 v[16:19], v[164:167], v[196:199], v[16:19]
	v_mfma_f32_16x16x32_bf16 v[8:11], v[172:175], v[196:199], v[8:11]
	v_mfma_f32_16x16x32_bf16 v[4:7], v[164:167], v[208:211], v[4:7]
	v_mfma_f32_16x16x32_bf16 v[0:3], v[172:175], v[208:211], v[0:3]
	v_mfma_f32_16x16x32_bf16 v[50:53], v[168:171], v[184:187], v[50:53]
	v_mfma_f32_16x16x32_bf16 v[42:45], v[176:179], v[184:187], v[42:45]
	v_mfma_f32_16x16x32_bf16 v[34:37], v[168:171], v[192:195], v[34:37]
	v_mfma_f32_16x16x32_bf16 v[26:29], v[176:179], v[192:195], v[26:29]
	v_mfma_f32_16x16x32_bf16 v[16:19], v[168:171], v[200:203], v[16:19]
	v_mfma_f32_16x16x32_bf16 v[8:11], v[176:179], v[200:203], v[8:11]
	v_mfma_f32_16x16x32_bf16 v[4:7], v[168:171], v[212:215], v[4:7]
	v_mfma_f32_16x16x32_bf16 v[0:3], v[176:179], v[212:215], v[0:3]
	s_setprio 0
	s_barrier
	s_add_i32 s53, s53, 2
	s_add_u32 s28, s28, 0x100
	s_addc_u32 s29, s29, 0
	s_add_u32 s51, s51, 0x100
	s_addc_u32 s52, s52, 0
	s_cmp_gt_u32 s53, 29

; __device__ __forceinline__ unsigned cvt_pk_bf16(float lo, float hi) { unsigned r; asm volatile("v_cvt_pk_bf16_f32 %0, %1, %2" : "=v"(r) : "v"(lo), "v"(hi)); return r; }
; #define PG8_BAR __builtin_amdgcn_s_barrier()
;     __device__ __forceinline__ void operator()(const f32x4 (&acc)[2][2][4][2], const Unit& u, int wr, int wc, int fr, int fq) const {
;         const int row0 = u.pm * BM + wr * 64 + fr;
;         const int T0 = u.pn * BM, bseq = T0 >> 12, t0 = T0 & 4095;
; #pragma unroll
;         for (int ai = 0; ai < 2; ++ai)
; #pragma unroll
;             for (int m = 0; m < 4; ++m) {
;                 const int nn = row0 + ai * HALF + m * 16;
; #pragma unroll
;                 for (int bj = 0; bj < 2; ++bj) {
;                     const f32x4 v0 = acc[ai][bj][m][0], v1 = acc[ai][bj][m][1];
;                     u32x4 w; w.x = cvt_pk_bf16(v0[0], v0[1]); w.y = cvt_pk_bf16(v0[2], v0[3]); w.z = cvt_pk_bf16(v1[0], v1[1]); w.w = cvt_pk_bf16(v1[2], v1[3]);
;                     const int th = t0 + bj * HALF;
;                     if (VM == 0) {
;                         const int t = th + wc * 32 + 8 * fq;
;                         if (u.pm < 12) *(u32x4*)(UT + ((size_t)(bseq * 3072 + nn)) * 4096 + t) = w;
;                         else *(u32x4*)(VT + ((size_t)(bseq * 1536 + (nn - 3072))) * 4096 + t) = w;
;                     } else if (VM == 1) {
;                         *(u32x4*)(VT + ((size_t)(bseq * 1536 + 512 + nn)) * 4096 + fq * 1024 + (th >> 2) + 8 * wc) = w;
;                     } else {
;                         *(u32x4*)(VT + ((size_t)(bseq * 1536 + 1024 + nn)) * 4096 + (4 * wc + fq) * 256 + (th >> 4)) = w;
;                     }
;                 }
;             }
;     }
; template <class Epi, class Sched, bool ALIGN_EPI = false, bool SP2 = false>
; __device__ __forceinline__ void gemm_phase(PG8_LAS unsigned char* lds, const Gemm g, const Sched& S, const Epi& E, const int tid_in) {
;     ...
;         if (!has_next) break;
; #pragma unroll
;         for (int a = 0; a < 2; ++a)
; #pragma unroll
;             for (int b = 0; b < 2; ++b)
; #pragma unroll
;                 for (int m = 0; m < 4; ++m)
; #pragma unroll
;                     for (int n = 0; n < 2; ++n) acc[a][b][m][n] = (f32x4){0.f, 0.f, 0.f, 0.f};
;         cur = nxt; cA = nA; cB = nB; ++ui;
;         if constexpr (ALIGN_EPI) { if (wr == 1) PG8_BAR; }
.LBB0_397:
	s_lshr_b32 s23, s47, 4
	s_lshl_b32 s21, s48, 8
	s_mulk_i32 s23, 0x600
	s_add_i32 s23, s23, s21
	v_add_u32_e32 v144, s23, v146
	v_ashrrev_i32_e32 v145, 31, v144
	v_lshlrev_b64 v[148:149], 13, v[144:145]
	s_lshl_b32 s21, s47, 5
	v_cvt_pk_bf16_f32 v126, v126, v127
	v_cvt_pk_bf16_f32 v127, v128, v129
	v_cvt_pk_bf16_f32 v128, v122, v123
	v_lshl_add_u64 v[122:123], v[138:139], 0, v[148:149]
	s_and_b32 s92, s21, 0x1e0
	v_lshl_add_u64 v[122:123], v[122:123], 0, s[92:93]
	v_cvt_pk_bf16_f32 v129, v124, v125
	global_store_dwordx4 v[122:123], v[126:129], off
	v_cvt_pk_bf16_f32 v114, v114, v115
	v_cvt_pk_bf16_f32 v115, v116, v117
	v_cvt_pk_bf16_f32 v116, v106, v107
	v_or_b32_e32 v106, 16, v144
	v_ashrrev_i32_e32 v107, 31, v106
	v_cvt_pk_bf16_f32 v117, v108, v109
	global_store_dwordx4 v[122:123], v[114:117], off offset:16
	s_andn2_b64 vcc, exec, s[36:37]
	s_mov_b64 s[28:29], -1
	v_lshlrev_b64 v[114:115], 13, v[106:107]
	v_cvt_pk_bf16_f32 v106, v118, v119
	v_cvt_pk_bf16_f32 v107, v120, v121
	v_cvt_pk_bf16_f32 v108, v110, v111
	v_lshl_add_u64 v[110:111], v[138:139], 0, v[114:115]
	v_lshl_add_u64 v[110:111], v[110:111], 0, s[92:93]
	v_cvt_pk_bf16_f32 v109, v112, v113
	global_store_dwordx4 v[110:111], v[106:109], off
	v_cvt_pk_bf16_f32 v98, v98, v99
	v_cvt_pk_bf16_f32 v99, v100, v101
	v_cvt_pk_bf16_f32 v100, v90, v91
	v_or_b32_e32 v90, 32, v144
	v_ashrrev_i32_e32 v91, 31, v90
	v_cvt_pk_bf16_f32 v101, v92, v93
	global_store_dwordx4 v[110:111], v[98:101], off offset:16
	s_movk_i32 s54, 0xffc0
	s_movk_i32 s55, 0xc00
	v_lshlrev_b64 v[98:99], 13, v[90:91]
	v_cvt_pk_bf16_f32 v90, v102, v103
	v_cvt_pk_bf16_f32 v91, v104, v105
	v_cvt_pk_bf16_f32 v92, v94, v95
	v_lshl_add_u64 v[94:95], v[138:139], 0, v[98:99]
	v_lshl_add_u64 v[94:95], v[94:95], 0, s[92:93]
	v_cvt_pk_bf16_f32 v93, v96, v97
	global_store_dwordx4 v[94:95], v[90:93], off
	v_cvt_pk_bf16_f32 v82, v82, v83
	v_cvt_pk_bf16_f32 v83, v84, v85
	v_cvt_pk_bf16_f32 v84, v74, v75
	v_or_b32_e32 v74, 48, v144
	v_ashrrev_i32_e32 v75, 31, v74
	v_cvt_pk_bf16_f32 v85, v76, v77
	global_store_dwordx4 v[94:95], v[82:85], off offset:16
	s_mov_b32 s56, 0xfe03f81
	s_nop 0
	v_lshlrev_b64 v[82:83], 13, v[74:75]
	v_cvt_pk_bf16_f32 v74, v86, v87
	v_cvt_pk_bf16_f32 v75, v88, v89
	v_cvt_pk_bf16_f32 v76, v78, v79
	v_lshl_add_u64 v[78:79], v[138:139], 0, v[82:83]
	v_lshl_add_u64 v[78:79], v[78:79], 0, s[92:93]
	v_cvt_pk_bf16_f32 v77, v80, v81
	global_store_dwordx4 v[78:79], v[74:77], off
	v_cvt_pk_bf16_f32 v70, v70, v71
	v_cvt_pk_bf16_f32 v71, v72, v73
	v_cvt_pk_bf16_f32 v72, v66, v67
	v_add_u32_e32 v66, 0x80, v144
	v_ashrrev_i32_e32 v67, 31, v66
	v_lshlrev_b64 v[66:67], 13, v[66:67]
	v_cvt_pk_bf16_f32 v73, v68, v69
	global_store_dwordx4 v[78:79], v[70:73], off offset:16
	v_cvt_pk_bf16_f32 v62, v62, v63
	v_cvt_pk_bf16_f32 v63, v64, v65
	v_cvt_pk_bf16_f32 v64, v58, v59
	v_lshl_add_u64 v[58:59], v[138:139], 0, v[66:67]
	v_lshl_add_u64 v[58:59], v[58:59], 0, s[92:93]
	v_cvt_pk_bf16_f32 v65, v60, v61
	global_store_dwordx4 v[58:59], v[62:65], off
	v_cvt_pk_bf16_f32 v50, v50, v51
	v_cvt_pk_bf16_f32 v51, v52, v53
	v_cvt_pk_bf16_f32 v52, v42, v43
	v_add_u32_e32 v42, 0x90, v144
	v_ashrrev_i32_e32 v43, 31, v42
	v_cvt_pk_bf16_f32 v53, v44, v45
	global_store_dwordx4 v[58:59], v[50:53], off offset:16
	s_nop 1
	v_lshlrev_b64 v[50:51], 13, v[42:43]
	v_cvt_pk_bf16_f32 v42, v54, v55
	v_cvt_pk_bf16_f32 v43, v56, v57
	v_cvt_pk_bf16_f32 v44, v46, v47
	v_lshl_add_u64 v[46:47], v[138:139], 0, v[50:51]
	v_lshl_add_u64 v[46:47], v[46:47], 0, s[92:93]
	v_cvt_pk_bf16_f32 v45, v48, v49
	global_store_dwordx4 v[46:47], v[42:45], off
	v_cvt_pk_bf16_f32 v34, v34, v35
	v_cvt_pk_bf16_f32 v35, v36, v37
	v_cvt_pk_bf16_f32 v36, v26, v27
	v_add_u32_e32 v26, 0xa0, v144
	v_ashrrev_i32_e32 v27, 31, v26
	v_cvt_pk_bf16_f32 v37, v28, v29
	global_store_dwordx4 v[46:47], v[34:37], off offset:16
	s_nop 1
	v_lshlrev_b64 v[34:35], 13, v[26:27]
	v_cvt_pk_bf16_f32 v26, v38, v39
	v_cvt_pk_bf16_f32 v27, v40, v41
	v_cvt_pk_bf16_f32 v28, v30, v31
	v_lshl_add_u64 v[30:31], v[138:139], 0, v[34:35]
	v_lshl_add_u64 v[30:31], v[30:31], 0, s[92:93]
	v_cvt_pk_bf16_f32 v29, v32, v33
	global_store_dwordx4 v[30:31], v[26:29], off
	v_cvt_pk_bf16_f32 v16, v16, v17
	v_cvt_pk_bf16_f32 v17, v18, v19
	v_cvt_pk_bf16_f32 v18, v8, v9
	v_add_u32_e32 v8, 0xb0, v144
	v_ashrrev_i32_e32 v9, 31, v8
	v_cvt_pk_bf16_f32 v19, v10, v11
	global_store_dwordx4 v[30:31], v[16:19], off offset:16
	s_nop 1
	v_lshlrev_b64 v[16:17], 13, v[8:9]
	v_cvt_pk_bf16_f32 v8, v22, v23
	v_cvt_pk_bf16_f32 v9, v24, v25
	v_cvt_pk_bf16_f32 v10, v12, v13
	v_lshl_add_u64 v[12:13], v[138:139], 0, v[16:17]
	v_lshl_add_u64 v[12:13], v[12:13], 0, s[92:93]
	v_cvt_pk_bf16_f32 v11, v14, v15
	global_store_dwordx4 v[12:13], v[8:11], off
	v_cvt_pk_bf16_f32 v4, v4, v5
	v_cvt_pk_bf16_f32 v5, v6, v7
	v_cvt_pk_bf16_f32 v6, v0, v1
	v_cvt_pk_bf16_f32 v7, v2, v3
	global_store_dwordx4 v[12:13], v[4:7], off offset:16
	s_cbranch_vccnz .LBB0_386
	s_andn2_b64 vcc, exec, s[2:3]
	s_cbranch_vccnz .LBB0_385
	s_branch .LBB0_385

;     __device__ __forceinline__ void prefetch(const Unit& u, int buf, PG8_LAS unsigned char* lds, int wid, int lane) const {
;         if (u.pn >= 12 && wid == 0) __builtin_amdgcn_global_load_lds((const unsigned*)(bgate + (lane >> 5) * 2048 + (u.pn - 12) * 128 + (lane & 31) * 4), (PG8_LAS unsigned*)(lds + EPI_LDS_OFF + buf * 2048), 16, 0, 0);
;     }
; template <class Epi, class Sched, bool ALIGN_EPI = false, bool SP2 = false>
; __device__ __forceinline__ void gemm_phase(PG8_LAS unsigned char* lds, const Gemm g, const Sched& S, const Epi& E, const int tid_in) {
;     ...
;     const int tid = tid_l, wid = __builtin_amdgcn_readfirstlane(tid >> 6), lane = tid & 63, wr = wid >> 2, wc = wid & 3, fr = lane & 15, fq = lane >> 4;
;     const int K = g.K, nt = K / BK;
;     unsigned voffA[2], voffB[2];
; #pragma unroll
;     for (int i = 0; i < 2; ++i) { int R, C; stage_rc(tid * 16 + i * 8192, R, C); const int Rb = perm_row<Epi::PMODE>(R);
;         voffA[i] = (unsigned)(R * K + C) * 2u; voffB[i] = (unsigned)(Rb * K + C) * 2u; }
;     const size_t kstep = (size_t)(BK * 2);
;     const size_t hstep = (size_t)HALF * K * 2;
;     const size_t tstep = 2 * hstep;
;     const unsigned ldsw = (unsigned)wid * 1024u;
;     const int aoff = lds_byte(wr * 64 + fr, fq * 8), boff = lds_byte(wc * 32 + fr, fq * 8);
;     ...
;     Unit cur, nxt; int ui = 0;
;     if (!S.next(0, cur)) return;
;     f32x4 acc[2][2][4][2];
; #pragma unroll
;     for (int a = 0; a < 2; ++a)
; #pragma unroll
;         for (int b = 0; b < 2; ++b)
; #pragma unroll
;             for (int m = 0; m < 4; ++m)
; #pragma unroll
;                 for (int n = 0; n < 2; ++n) acc[a][b][m][n] = (f32x4){0.f, 0.f, 0.f, 0.f};
;     bf16x8 At[4][2], B0[2][2], B1[2][2];
;     const char* cA = (const char*)g.A + (size_t)cur.pm * tstep; const char* cB = (const char*)g.Bt + (size_t)cur.pn * tstep;
;     S.a_ready(cur);
;     if constexpr (Epi::PREF) E.prefetch(cur, 0, lds, wid, lane);
;     if constexpr (SP2) {
;         PG8_STAGE(PG8_SB(0, 0), cB, voffB); PG8_STAGE(PG8_SB(0, 1), cB + hstep, voffB); PG8_STAGE(PG8_SA(0, 0), cA, voffA); PG8_STAGE(PG8_SA(0, 1), cA + hstep, voffA);
;         if (wr == 1) PG8_BAR;
;         PG8_WAIT_V(2); PG8_BAR;
;         PG8_STAGE(PG8_SB(1, 0), cB + kstep, voffB); PG8_STAGE(PG8_SA(1, 0), cA + kstep, voffA); PG8_STAGE(PG8_SB(1, 1), cB + hstep + kstep, voffB);
;         PG8_WAIT_V(6); PG8_BAR;
.LBB0_404:
	v_ashrrev_i32_e32 v3, 31, v13
	v_lshrrev_b32_e32 v3, 26, v3
	v_add_u32_e32 v3, v13, v3
	v_ashrrev_i32_e32 v12, 6, v3
	v_bfe_i32 v3, v13, 27, 1
	v_lshlrev_b32_e32 v1, 4, v13
	v_lshrrev_b32_e32 v3, 22, v3
	v_add_u32_e32 v3, v1, v3
	v_and_b32_e32 v3, 0xfffffc00, v3
	v_sub_u32_e32 v3, v1, v3
	v_lshrrev_b32_e32 v4, 4, v3
	v_bitop3_b32 v3, v4, v3, 32 bitop3:0x6c
	v_ashrrev_i32_e32 v5, 31, v3
	v_lshrrev_b32_e32 v5, 26, v5
	v_add_u32_e32 v5, v3, v5
	v_lshlrev_b32_e32 v4, 3, v12
	v_ashrrev_i32_e32 v14, 6, v5
	v_and_b32_e32 v5, 0xc0, v5
	v_and_b32_e32 v4, -16, v4
	v_sub_u32_e32 v3, v3, v5
	v_mov_b32_e32 v8, 1
	v_add_u32_e32 v4, v14, v4
	v_ashrrev_i16_sdwa v3, v8, sext(v3) dst_sel:DWORD dst_unused:UNUSED_PAD src0_sel:DWORD src1_sel:BYTE_0
	v_lshlrev_b32_e32 v6, 5, v12
	v_bfe_i32 v15, v3, 0, 16
	v_lshlrev_b32_e32 v3, 1, v4
	v_lshrrev_b32_e32 v5, 2, v4
	v_and_b32_e32 v6, 32, v6
	v_and_b32_e32 v3, 24, v3
	v_and_b32_e32 v5, 4, v5
	v_and_b32_e32 v7, 0xfffe3, v4
	v_or3_b32 v3, v7, v5, v3
	v_add_lshl_u32 v5, v6, v15, 1
	v_add_u32_e32 v1, 0x2000, v1
	s_mul_i32 s10, s1, 0x2e00000
	v_lshl_add_u32 v148, v3, 12, v5
	v_ashrrev_i32_e32 v3, 31, v1
	s_mul_hi_i32 s8, s1, 0x2e00000
	s_add_u32 s10, s2, s10
	v_lshrrev_b32_e32 v3, 22, v3
	s_addc_u32 s19, s3, s8
	s_add_i32 s1, s1, s5
	v_add_u32_e32 v3, v1, v3
	s_bitcmp0_b32 s1, 0
	s_mov_b32 s1, 0x4f200000
	v_ashrrev_i32_e32 v16, 10, v3
	s_cselect_b32 s1, 0x28000000, s1
	v_mul_i32_i24_e32 v3, 0x400, v16
	s_add_u32 s1, s2, s1
	v_sub_u32_e32 v1, v1, v3
	s_addc_u32 s5, s3, 0
	v_lshrrev_b32_e32 v3, 4, v1
	s_add_u32 s8, s10, 0x9a00000
	v_bitop3_b32 v1, v3, v1, 32 bitop3:0x6c
	s_addc_u32 s10, s19, 0
	v_readlane_b32 s22, v253, 61
	v_lshl_add_u32 v146, v4, 12, v5
	v_ashrrev_i32_e32 v4, 31, v1
	v_readlane_b32 s23, v253, 62
	s_add_u32 s34, s1, s22
	v_lshrrev_b32_e32 v4, 26, v4
	s_addc_u32 s35, s5, s23
	v_readlane_b32 s22, v253, 63
	v_add_u32_e32 v4, v1, v4
	v_readlane_b32 s23, v254, 0
	s_add_u32 s38, s8, s22
	v_lshlrev_b32_e32 v3, 3, v16
	v_ashrrev_i32_e32 v17, 6, v4
	v_and_b32_e32 v4, 0xc0, v4
	s_addc_u32 s39, s10, s23
	s_ashr_i32 s27, s26, 6
	v_and_b32_e32 v3, -16, v3
	v_sub_u32_e32 v1, v1, v4
	v_add_u32_e32 v3, v17, v3
	v_ashrrev_i16_sdwa v1, v8, sext(v1) dst_sel:DWORD dst_unused:UNUSED_PAD src0_sel:DWORD src1_sel:BYTE_0
	s_lshl_b32 s19, s27, 10
	v_lshlrev_b32_e32 v5, 5, v16
	v_bfe_i32 v18, v1, 0, 16
	v_lshlrev_b32_e32 v1, 1, v3
	v_lshrrev_b32_e32 v4, 2, v3
	s_add_i32 s44, s19, 0
	v_and_b32_e32 v5, 32, v5
	v_and_b32_e32 v1, 24, v1
	v_and_b32_e32 v4, 4, v4
	v_and_b32_e32 v6, 0xfffe3, v3
	s_add_i32 m0, s44, 0x10000
	s_ashr_i32 s28, s26, 8
	v_or3_b32 v1, v6, v4, v1
	v_add_lshl_u32 v4, v5, v18, 1
	global_load_lds_dwordx4 v148, s[38:39]
	s_add_i32 m0, s44, 0x12000
	v_lshl_add_u32 v152, v1, 12, v4
	s_add_u32 s22, s38, 0x80000
	global_load_lds_dwordx4 v152, s[38:39]
	s_addc_u32 s23, s39, 0
	s_add_i32 m0, s44, 0x14000
	s_add_i32 s45, s44, 0x2000
	global_load_lds_dwordx4 v148, s[22:23]
	s_add_i32 m0, s44, 0x16000
	v_lshl_add_u32 v150, v3, 12, v4
	global_load_lds_dwordx4 v152, s[22:23]
	s_mov_b32 m0, s44
	s_add_u32 s22, s34, 0x80000
	global_load_lds_dwordx4 v146, s[34:35]
	s_mov_b32 m0, s45
	s_addc_u32 s23, s35, 0
	s_add_i32 s46, s44, 0x4000
	global_load_lds_dwordx4 v150, s[34:35]
	s_mov_b32 m0, s46
	s_add_i32 s47, s44, 0x6000
	global_load_lds_dwordx4 v146, s[22:23]
	s_mov_b32 m0, s47
	v_mov_b32_e32 v149, v20
	global_load_lds_dwordx4 v150, s[22:23]
	v_mov_b32_e32 v153, v20
	v_mov_b32_e32 v147, v20
	v_mov_b32_e32 v151, v20
	s_cmp_eq_u32 s28, 1
	v_lshl_add_u64 v[10:11], s[38:39], 0, v[148:149]
	v_lshl_add_u64 v[8:9], s[38:39], 0, v[152:153]
	v_lshl_add_u64 v[4:5], s[34:35], 0, v[146:147]
	s_cselect_b64 s[22:23], -1, 0
	s_cmp_lg_u32 s28, 1
	v_lshl_add_u64 v[6:7], s[34:35], 0, v[150:151]
	s_cbranch_scc1 .LBB0_406
.LBB0_406:
	v_lshrrev_b32_e32 v3, 1, v13
	v_and_b32_e32 v19, 24, v3
	v_and_b32_e32 v1, 15, v13
	v_lshlrev_b32_e32 v3, 1, v19
	s_add_u32 s24, s2, 0x3e000000
	v_lshl_or_b32 v21, s28, 6, v1
	v_lshl_or_b32 v1, v1, 6, v3
	v_lshlrev_b32_e32 v3, 2, v13
	s_addc_u32 s25, s3, 0
	s_lshl_b32 s2, s28, 13
	v_and_b32_e32 v3, 32, v3
	v_bitop3_b32 v13, v1, s2, v3 bitop3:0xde
	s_lshl_b32 s2, s27, 5
	s_and_b32 s27, s2, 0x60
	s_add_i32 m0, s44, 0x18000
	v_lshl_add_u64 v[10:11], v[10:11], 0, s[12:13]
	s_lshl_b32 s2, s27, 7
	s_waitcnt vmcnt(2)
	s_barrier
	global_load_lds_dwordx4 v[10:11], off
	v_lshl_add_u64 v[8:9], v[8:9], 0, s[12:13]
	s_add_i32 m0, s44, 0x1a000
	s_add_i32 s48, s44, 0x8000
	s_add_i32 s49, s44, 0xa000
	v_bitop3_b32 v162, v1, s2, v3 bitop3:0xde
	global_load_lds_dwordx4 v[8:9], off
	v_lshl_add_u64 v[4:5], v[4:5], 0, s[12:13]
	s_mov_b32 m0, s48
	s_add_u32 s100, s34, 0x80
	s_addc_u32 s101, s35, 0
	s_add_u32 s2, s38, 0x80080
	global_load_lds_dwordx4 v[4:5], off
	v_lshl_add_u64 v[4:5], v[6:7], 0, s[12:13]
	s_mov_b32 m0, s49
	s_addc_u32 s3, s39, 0
	global_load_lds_dwordx4 v[4:5], off
	s_add_i32 m0, s44, 0x1c000
	v_lshl_add_u64 v[4:5], s[2:3], 0, v[148:149]
	global_load_lds_dwordx4 v[4:5], off
	v_lshl_add_u64 v[4:5], s[2:3], 0, v[152:153]
	s_add_i32 m0, s44, 0x1e000
	v_mov_b32_e32 v3, v20
	global_load_lds_dwordx4 v[4:5], off
	v_lshl_add_u64 v[2:3], s[6:7], 0, v[2:3]
	v_mov_b32_e32 v1, v20
	v_lshl_add_u64 v[154:155], v[2:3], 0, v[0:1]
	v_lshlrev_b32_e32 v0, 15, v12
	v_and_b32_e32 v0, 0xffff0000, v0
	v_lshl_add_u32 v0, v14, 12, v0
	v_and_b32_e32 v1, 1, v12
	v_lshl_or_b32 v0, v1, 6, v0
	s_lshl_b32 s2, s27, 2
	v_lshl_add_u32 v156, v15, 1, v0
	v_lshlrev_b32_e32 v0, 15, v16
	s_add_i32 s2, s2, 0
	v_and_b32_e32 v0, 0xffff0000, v0
	s_waitcnt vmcnt(6)
	s_add_i32 s2, s2, 0x22400
	v_lshl_add_u32 v0, v17, 12, v0
	v_and_b32_e32 v1, 1, v16
	s_cmpk_lt_u32 s26, 0x100
	v_lshl_or_b32 v0, v1, 6, v0
	v_readlane_b32 s6, v253, 59
	v_lshl_add_u32 v163, v19, 2, s2
	s_cselect_b64 s[2:3], -1, 0
	v_or_b32_e32 v164, s27, v19
	v_mov_b32_e32 v157, v20
	v_lshl_add_u32 v158, v18, 1, v0
	v_mov_b32_e32 v159, v20
	s_mov_b32 s53, 0
	v_add_u32_e32 v165, 0, v13
	v_readlane_b32 s51, v254, 3
	s_mov_b32 s52, s6
	s_barrier
	v_readlane_b32 s7, v253, 60
	s_branch .LBB0_409

; #define PG8_STAGE(bufoff, gbase, voff) do { _Pragma("unroll") for (int _i = 0; _i < 2; ++_i) \
;         __builtin_amdgcn_global_load_lds((const unsigned*)((const char*)(gbase) + (voff)[_i]), (PG8_LAS unsigned*)(lds + (bufoff) + ldsw + _i * 8192), 16, 0, 0); } while (0)
; #define PG8_LDA(dst, b, h) do { _Pragma("unroll") for (int m = 0; m < 4; ++m) _Pragma("unroll") for (int k = 0; k < 2; ++k) dst[m][k] = *(const PG8_LAS bf16x8*)(lds + PG8_SA(b, h) + aoff + m * 2048 + k * 1024); } while (0)
; #define PG8_LDB(dst, b, h) do { _Pragma("unroll") for (int n = 0; n < 2; ++n) _Pragma("unroll") for (int k = 0; k < 2; ++k) dst[n][k] = *(const PG8_LAS bf16x8*)(lds + PG8_SB(b, h) + boff + n * 2048 + k * 1024); } while (0)
; #define PG8_WAIT_V(n) asm volatile("s_waitcnt vmcnt(" #n ")" ::: "memory")
; #define PG8_WAIT_L(n) asm volatile("s_waitcnt lgkmcnt(" #n ")" ::: "memory")
; template <class Epi, class Sched, bool ALIGN_EPI = false, bool SP2 = false>
; __device__ __forceinline__ void gemm_phase(PG8_LAS unsigned char* lds, const Gemm g, const Sched& S, const Epi& E, const int tid_in) {
;     ...
;         const bool has_next = S.next(ui + 1, nxt);
;         const char* nA = has_next ? (const char*)g.A + (size_t)nxt.pm * tstep : cA; const char* nB = has_next ? (const char*)g.Bt + (size_t)nxt.pn * tstep : cB;
;         for (int t = 0; t < nt; t += 2) {
;             if constexpr (Epi::KSPLIT > 0) { if (t == Epi::KSPLIT / BK) E.midk(acc, cur, wr, wc, fr, fq); }
;             const bool last = (t == nt - 2);
;             const char* a1 = cA + (size_t)(t + 1) * kstep;
;             const char* a2 = last ? nA : cA + (size_t)(t + 2) * kstep; const char* b2 = last ? nB : cB + (size_t)(t + 2) * kstep;
;             const char* a3 = a2 + kstep; const char* b3 = b2 + kstep;
;             if (last && has_next) S.a_ready(nxt);
;             if constexpr (SP2) {
;             PG8_LDB(B0, 0, 0); PG8_LDB(B1, 0, 1); PG8_SCHED; PG8_LDA(At, 0, 0); PG8_STAGE(PG8_SA(1, 1), a1 + hstep, voffA);
;             PG8_WAIT_V(8); PG8_WAIT_L(0); PG8_BAR; PG8_MMA(0, 0, At, B0); PG8_MMA(0, 1, At, B1); PG8_BAR; PG8_SCHED;
;             PG8_LDA(At, 0, 1); PG8_STAGE(PG8_SB(0, 0), b2, voffB); PG8_STAGE(PG8_SB(0, 1), b2 + hstep, voffB); PG8_STAGE(PG8_SA(0, 0), a2, voffA);
;             PG8_WAIT_V(8); PG8_WAIT_L(0); PG8_BAR; PG8_MMA(1, 0, At, B0); PG8_MMA(1, 1, At, B1); PG8_BAR; PG8_SCHED;
.LBB0_411:
	s_ashr_i32 s27, s26, 31
	s_lshl_b64 s[28:29], s[26:27], 20
	s_add_u32 s28, s1, s28
	s_addc_u32 s29, s5, s29
	s_and_b64 s[30:31], s[36:37], exec
	s_cselect_b32 s27, s29, s35
	s_cselect_b32 s54, s28, s34
	s_ashr_i32 s7, s6, 31
	s_lshl_b64 s[30:31], s[6:7], 20
	s_add_u32 s30, s8, s30
	s_addc_u32 s31, s10, s31
	s_and_b64 s[42:43], s[36:37], exec
	s_cselect_b32 s7, s31, s39
	s_cselect_b32 s55, s30, s38
	s_add_u32 s34, s34, 0x80080
	s_addc_u32 s35, s35, 0
	s_add_u32 s56, s38, 0x100
	v_mov_b32_e32 v0, 0
	s_addc_u32 s57, s39, 0
	s_mov_b32 s58, -2
	s_cmp_lt_u32 s19, 0x1000
	s_cbranch_scc1 .LCB_412
	s_barrier
.LCB_412:
	s_mov_b32 m0, s49
	s_nop 0
	global_load_lds_dwordx4 v150, s[100:101]
	s_add_u32 s38, s34, 0xfff80080
	s_addc_u32 s39, s35, -1
	s_add_i32 s59, 0, 0x10000
	s_cmp_eq_u32 s58, 28
	s_cselect_b32 s43, s27, s39
	s_cselect_b32 s42, s54, s38
	s_cselect_b32 s39, s7, s57
	s_cselect_b32 s38, s55, s56
	s_add_i32 s62, 0, 0x14000
	v_add_u32_e32 v78, s59, v162
	v_add_u32_e32 v160, s62, v162
	ds_read_b128 v[66:69], v78
	ds_read_b128 v[70:73], v78 offset:1024
	ds_read_b128 v[74:77], v78 offset:2048
	ds_read_b128 v[78:81], v78 offset:3072
	ds_read_b128 v[166:169], v160
	ds_read_b128 v[170:173], v160 offset:1024
	ds_read_b128 v[174:177], v160 offset:2048
	ds_read_b128 v[178:181], v160 offset:3072
	s_add_i32 m0, s44, 0xc000
	ds_read_b128 v[182:185], v165
	ds_read_b128 v[186:189], v165 offset:1024
	ds_read_b128 v[190:193], v165 offset:2048
	ds_read_b128 v[194:197], v165 offset:3072
	ds_read_b128 v[198:201], v165 offset:4096
	ds_read_b128 v[202:205], v165 offset:5120
	ds_read_b128 v[208:211], v165 offset:6144
	ds_read_b128 v[212:215], v165 offset:7168
	global_load_lds_dwordx4 v156, s[34:35]
	s_add_i32 m0, s44, 0xe000
	s_nop 0
	global_load_lds_dwordx4 v158, s[34:35]
	s_waitcnt vmcnt(8)
	s_waitcnt lgkmcnt(0)
	s_barrier
	s_setprio 1
	v_mfma_f32_16x16x32_bf16 v[142:145], v[66:69], v[182:185], 0
	v_mfma_f32_16x16x32_bf16 v[138:141], v[74:77], v[182:185], 0
	v_mfma_f32_16x16x32_bf16 v[126:129], v[66:69], v[190:193], 0
	v_mfma_f32_16x16x32_bf16 v[122:125], v[74:77], v[190:193], 0
	v_mfma_f32_16x16x32_bf16 v[110:113], v[66:69], v[198:201], 0
	v_mfma_f32_16x16x32_bf16 v[106:109], v[74:77], v[198:201], 0
	v_mfma_f32_16x16x32_bf16 v[94:97], v[66:69], v[208:211], 0
	v_mfma_f32_16x16x32_bf16 v[90:93], v[74:77], v[208:211], 0
	v_mfma_f32_16x16x32_bf16 v[142:145], v[70:73], v[186:189], v[142:145]
	v_mfma_f32_16x16x32_bf16 v[138:141], v[78:81], v[186:189], v[138:141]
	v_mfma_f32_16x16x32_bf16 v[126:129], v[70:73], v[194:197], v[126:129]
	v_mfma_f32_16x16x32_bf16 v[122:125], v[78:81], v[194:197], v[122:125]
	v_mfma_f32_16x16x32_bf16 v[110:113], v[70:73], v[202:205], v[110:113]
	v_mfma_f32_16x16x32_bf16 v[106:109], v[78:81], v[202:205], v[106:109]
	v_mfma_f32_16x16x32_bf16 v[94:97], v[70:73], v[212:215], v[94:97]
	v_mfma_f32_16x16x32_bf16 v[90:93], v[78:81], v[212:215], v[90:93]
	s_setprio 0
	s_setprio 1
	v_mfma_f32_16x16x32_bf16 v[134:137], v[166:169], v[182:185], 0
	v_mfma_f32_16x16x32_bf16 v[130:133], v[174:177], v[182:185], 0
	v_mfma_f32_16x16x32_bf16 v[118:121], v[166:169], v[190:193], 0
	v_mfma_f32_16x16x32_bf16 v[114:117], v[174:177], v[190:193], 0
	v_mfma_f32_16x16x32_bf16 v[102:105], v[166:169], v[198:201], 0
	v_mfma_f32_16x16x32_bf16 v[98:101], v[174:177], v[198:201], 0
	v_mfma_f32_16x16x32_bf16 v[86:89], v[166:169], v[208:211], 0
	v_mfma_f32_16x16x32_bf16 v[82:85], v[174:177], v[208:211], 0
	v_mfma_f32_16x16x32_bf16 v[134:137], v[170:173], v[186:189], v[134:137]
	v_mfma_f32_16x16x32_bf16 v[130:133], v[178:181], v[186:189], v[130:133]
	v_mfma_f32_16x16x32_bf16 v[118:121], v[170:173], v[194:197], v[118:121]
	v_mfma_f32_16x16x32_bf16 v[114:117], v[178:181], v[194:197], v[114:117]
	v_mfma_f32_16x16x32_bf16 v[102:105], v[170:173], v[202:205], v[102:105]
	v_mfma_f32_16x16x32_bf16 v[98:101], v[178:181], v[202:205], v[98:101]
	v_mfma_f32_16x16x32_bf16 v[86:89], v[170:173], v[212:215], v[86:89]
	v_mfma_f32_16x16x32_bf16 v[82:85], v[178:181], v[212:215], v[82:85]
	s_setprio 0
	s_barrier
	s_add_i32 s59, s59, s19
	s_add_u32 s98, s38, 0x80
	s_addc_u32 s99, s39, 0
	s_mov_b32 m0, s59
	ds_read_b128 v[182:185], v165 offset:16384
	ds_read_b128 v[186:189], v165 offset:17408
	ds_read_b128 v[190:193], v165 offset:18432
	ds_read_b128 v[194:197], v165 offset:19456
	ds_read_b128 v[198:201], v165 offset:20480
	ds_read_b128 v[202:205], v165 offset:21504
	ds_read_b128 v[208:211], v165 offset:22528
	ds_read_b128 v[212:215], v165 offset:23552
	global_load_lds_dwordx4 v148, s[38:39]
	s_add_i32 m0, s59, 0x2000
	s_add_u32 s60, s38, 0x80000
	s_addc_u32 s61, s39, 0
	s_add_i32 s59, s62, s19
	global_load_lds_dwordx4 v152, s[38:39]
	s_mov_b32 m0, s59
	s_add_u32 s100, s42, 0x80
	s_addc_u32 s101, s43, 0
	global_load_lds_dwordx4 v148, s[60:61]
	s_add_i32 m0, s59, 0x2000
	s_nop 0
	global_load_lds_dwordx4 v152, s[60:61]
	s_mov_b32 m0, s44
	s_nop 0
	global_load_lds_dwordx4 v146, s[42:43]
	s_waitcnt vmcnt(7)
	s_waitcnt lgkmcnt(0)
	s_barrier
; #define PG8_STAGE(bufoff, gbase, voff) do { _Pragma("unroll") for (int _i = 0; _i < 2; ++_i) \
;         __builtin_amdgcn_global_load_lds((const unsigned*)((const char*)(gbase) + (voff)[_i]), (PG8_LAS unsigned*)(lds + (bufoff) + ldsw + _i * 8192), 16, 0, 0); } while (0)
; #define PG8_LDA(dst, b, h) do { _Pragma("unroll") for (int m = 0; m < 4; ++m) _Pragma("unroll") for (int k = 0; k < 2; ++k) dst[m][k] = *(const PG8_LAS bf16x8*)(lds + PG8_SA(b, h) + aoff + m * 2048 + k * 1024); } while (0)
; #define PG8_LDB(dst, b, h) do { _Pragma("unroll") for (int n = 0; n < 2; ++n) _Pragma("unroll") for (int k = 0; k < 2; ++k) dst[n][k] = *(const PG8_LAS bf16x8*)(lds + PG8_SB(b, h) + boff + n * 2048 + k * 1024); } while (0)
; #define PG8_MMA(ai, bj, At, Bt) do { __builtin_amdgcn_s_setprio(1); _Pragma("unroll") for (int m = 0; m < 4; ++m) _Pragma("unroll") for (int n = 0; n < 2; ++n) _Pragma("unroll") for (int k = 0; k < 2; ++k) \
;         acc[ai][bj][m][n] = __builtin_amdgcn_mfma_f32_16x16x32_bf16(Bt[n][k], At[m][k], acc[ai][bj][m][n], 0, 0, 0); __builtin_amdgcn_s_setprio(0); } while (0)
; #define PG8_WAIT_V(n) asm volatile("s_waitcnt vmcnt(" #n ")" ::: "memory")
; #define PG8_WAIT_L(n) asm volatile("s_waitcnt lgkmcnt(" #n ")" ::: "memory")
; #define PG8_BAR __builtin_amdgcn_s_barrier()
; #define PG8_SCHED __builtin_amdgcn_sched_barrier(0)
; template <class Epi, class Sched, bool ALIGN_EPI = false, bool SP2 = false>
; __device__ __forceinline__ void gemm_phase(PG8_LAS unsigned char* lds, const Gemm g, const Sched& S, const Epi& E, const int tid_in) {
;     ...
;             PG8_WAIT_V(8); PG8_WAIT_L(0); PG8_BAR; PG8_MMA(1, 0, At, B0); PG8_MMA(1, 1, At, B1); PG8_BAR; PG8_SCHED;
;             PG8_LDB(B0, 1, 0); PG8_LDB(B1, 1, 1); PG8_SCHED; PG8_LDA(At, 1, 0); PG8_STAGE(PG8_SA(0, 1), a2 + hstep, voffA);
;             PG8_WAIT_V(8); PG8_WAIT_L(0); PG8_BAR; PG8_MMA(0, 0, At, B0); PG8_MMA(0, 1, At, B1); PG8_BAR; PG8_SCHED;
;             PG8_LDA(At, 1, 1); PG8_STAGE(PG8_SB(1, 0), b3, voffB); PG8_STAGE(PG8_SB(1, 1), b3 + hstep, voffB); PG8_STAGE(PG8_SA(1, 0), a3, voffA);
	s_setprio 1
	v_mfma_f32_16x16x32_bf16 v[62:65], v[66:69], v[182:185], 0
	v_mfma_f32_16x16x32_bf16 v[58:61], v[74:77], v[182:185], 0
	v_mfma_f32_16x16x32_bf16 v[46:49], v[66:69], v[190:193], 0
	v_mfma_f32_16x16x32_bf16 v[42:45], v[74:77], v[190:193], 0
	v_mfma_f32_16x16x32_bf16 v[30:33], v[66:69], v[198:201], 0
	v_mfma_f32_16x16x32_bf16 v[26:29], v[74:77], v[198:201], 0
	v_mfma_f32_16x16x32_bf16 v[12:15], v[66:69], v[208:211], 0
	v_mfma_f32_16x16x32_bf16 v[8:11], v[74:77], v[208:211], 0
	v_mfma_f32_16x16x32_bf16 v[62:65], v[70:73], v[186:189], v[62:65]
	v_mfma_f32_16x16x32_bf16 v[58:61], v[78:81], v[186:189], v[58:61]
	v_mfma_f32_16x16x32_bf16 v[46:49], v[70:73], v[194:197], v[46:49]
	v_mfma_f32_16x16x32_bf16 v[42:45], v[78:81], v[194:197], v[42:45]
	v_mfma_f32_16x16x32_bf16 v[30:33], v[70:73], v[202:205], v[30:33]
	v_mfma_f32_16x16x32_bf16 v[26:29], v[78:81], v[202:205], v[26:29]
	v_mfma_f32_16x16x32_bf16 v[12:15], v[70:73], v[212:215], v[12:15]
	v_mfma_f32_16x16x32_bf16 v[8:11], v[78:81], v[212:215], v[8:11]
	s_setprio 0
	s_setprio 1
	v_mfma_f32_16x16x32_bf16 v[54:57], v[166:169], v[182:185], 0
	v_mfma_f32_16x16x32_bf16 v[50:53], v[174:177], v[182:185], 0
	v_mfma_f32_16x16x32_bf16 v[38:41], v[166:169], v[190:193], 0
	v_mfma_f32_16x16x32_bf16 v[34:37], v[174:177], v[190:193], 0
	v_mfma_f32_16x16x32_bf16 v[22:25], v[166:169], v[198:201], 0
	v_mfma_f32_16x16x32_bf16 v[16:19], v[174:177], v[198:201], 0
	v_mfma_f32_16x16x32_bf16 v[4:7], v[166:169], v[208:211], 0
	v_mfma_f32_16x16x32_bf16 v[0:3], v[174:177], v[208:211], 0
	v_mfma_f32_16x16x32_bf16 v[54:57], v[170:173], v[186:189], v[54:57]
	v_mfma_f32_16x16x32_bf16 v[50:53], v[178:181], v[186:189], v[50:53]
	v_mfma_f32_16x16x32_bf16 v[38:41], v[170:173], v[194:197], v[38:41]
	v_mfma_f32_16x16x32_bf16 v[34:37], v[178:181], v[194:197], v[34:37]
	v_mfma_f32_16x16x32_bf16 v[22:25], v[170:173], v[202:205], v[22:25]
	v_mfma_f32_16x16x32_bf16 v[16:19], v[178:181], v[202:205], v[16:19]
	v_mfma_f32_16x16x32_bf16 v[4:7], v[170:173], v[212:215], v[4:7]
	v_mfma_f32_16x16x32_bf16 v[0:3], v[178:181], v[212:215], v[0:3]
	s_setprio 0
	s_barrier
	s_add_i32 s59, 0, 0x18000
	s_add_i32 s60, 0, 0x1c000
	v_add_u32_e32 v78, s59, v162
	v_add_u32_e32 v178, s60, v162
	ds_read_b128 v[66:69], v78
	ds_read_b128 v[70:73], v78 offset:1024
	ds_read_b128 v[74:77], v78 offset:2048
	ds_read_b128 v[78:81], v78 offset:3072
	ds_read_b128 v[166:169], v178
	ds_read_b128 v[170:173], v178 offset:1024
	ds_read_b128 v[174:177], v178 offset:2048
	ds_read_b128 v[178:181], v178 offset:3072
	s_mov_b32 m0, s45
	s_nop 0
	global_load_lds_dwordx4 v150, s[42:43]
	s_add_u32 s42, s42, 0x80000
	s_addc_u32 s43, s43, 0
	s_mov_b32 m0, s46
	ds_read_b128 v[182:185], v165 offset:32768
	ds_read_b128 v[186:189], v165 offset:33792
	ds_read_b128 v[190:193], v165 offset:34816
	ds_read_b128 v[194:197], v165 offset:35840
	ds_read_b128 v[198:201], v165 offset:36864
	ds_read_b128 v[202:205], v165 offset:37888
	ds_read_b128 v[208:211], v165 offset:38912
	ds_read_b128 v[212:215], v165 offset:39936
	global_load_lds_dwordx4 v146, s[42:43]
	s_mov_b32 m0, s47
	s_nop 0
	global_load_lds_dwordx4 v150, s[42:43]
	s_waitcnt vmcnt(8)
	s_waitcnt lgkmcnt(0)
	s_barrier
	s_setprio 1
	v_mfma_f32_16x16x32_bf16 v[142:145], v[66:69], v[182:185], v[142:145]
	v_mfma_f32_16x16x32_bf16 v[138:141], v[74:77], v[182:185], v[138:141]
	v_mfma_f32_16x16x32_bf16 v[126:129], v[66:69], v[190:193], v[126:129]
	v_mfma_f32_16x16x32_bf16 v[122:125], v[74:77], v[190:193], v[122:125]
	v_mfma_f32_16x16x32_bf16 v[110:113], v[66:69], v[198:201], v[110:113]
	v_mfma_f32_16x16x32_bf16 v[106:109], v[74:77], v[198:201], v[106:109]
	v_mfma_f32_16x16x32_bf16 v[94:97], v[66:69], v[208:211], v[94:97]
	v_mfma_f32_16x16x32_bf16 v[90:93], v[74:77], v[208:211], v[90:93]
	v_mfma_f32_16x16x32_bf16 v[142:145], v[70:73], v[186:189], v[142:145]
	v_mfma_f32_16x16x32_bf16 v[138:141], v[78:81], v[186:189], v[138:141]
	v_mfma_f32_16x16x32_bf16 v[126:129], v[70:73], v[194:197], v[126:129]
	v_mfma_f32_16x16x32_bf16 v[122:125], v[78:81], v[194:197], v[122:125]
	v_mfma_f32_16x16x32_bf16 v[110:113], v[70:73], v[202:205], v[110:113]
	v_mfma_f32_16x16x32_bf16 v[106:109], v[78:81], v[202:205], v[106:109]
	v_mfma_f32_16x16x32_bf16 v[94:97], v[70:73], v[212:215], v[94:97]
	v_mfma_f32_16x16x32_bf16 v[90:93], v[78:81], v[212:215], v[90:93]
	s_setprio 0
	s_setprio 1
	v_mfma_f32_16x16x32_bf16 v[134:137], v[166:169], v[182:185], v[134:137]
	v_mfma_f32_16x16x32_bf16 v[130:133], v[174:177], v[182:185], v[130:133]
	v_mfma_f32_16x16x32_bf16 v[118:121], v[166:169], v[190:193], v[118:121]
	v_mfma_f32_16x16x32_bf16 v[114:117], v[174:177], v[190:193], v[114:117]
	v_mfma_f32_16x16x32_bf16 v[102:105], v[166:169], v[198:201], v[102:105]
	v_mfma_f32_16x16x32_bf16 v[98:101], v[174:177], v[198:201], v[98:101]
	v_mfma_f32_16x16x32_bf16 v[86:89], v[166:169], v[208:211], v[86:89]
	v_mfma_f32_16x16x32_bf16 v[82:85], v[174:177], v[208:211], v[82:85]
	v_mfma_f32_16x16x32_bf16 v[134:137], v[170:173], v[186:189], v[134:137]
	v_mfma_f32_16x16x32_bf16 v[130:133], v[178:181], v[186:189], v[130:133]
	v_mfma_f32_16x16x32_bf16 v[118:121], v[170:173], v[194:197], v[118:121]
	v_mfma_f32_16x16x32_bf16 v[114:117], v[178:181], v[194:197], v[114:117]
	v_mfma_f32_16x16x32_bf16 v[102:105], v[170:173], v[202:205], v[102:105]
	v_mfma_f32_16x16x32_bf16 v[98:101], v[178:181], v[202:205], v[98:101]
	v_mfma_f32_16x16x32_bf16 v[86:89], v[170:173], v[212:215], v[86:89]
	v_mfma_f32_16x16x32_bf16 v[82:85], v[178:181], v[212:215], v[82:85]
	s_setprio 0
	s_barrier
; #define PG8_STAGE(bufoff, gbase, voff) do { _Pragma("unroll") for (int _i = 0; _i < 2; ++_i) \
;         __builtin_amdgcn_global_load_lds((const unsigned*)((const char*)(gbase) + (voff)[_i]), (PG8_LAS unsigned*)(lds + (bufoff) + ldsw + _i * 8192), 16, 0, 0); } while (0)
; #define PG8_LDA(dst, b, h) do { _Pragma("unroll") for (int m = 0; m < 4; ++m) _Pragma("unroll") for (int k = 0; k < 2; ++k) dst[m][k] = *(const PG8_LAS bf16x8*)(lds + PG8_SA(b, h) + aoff + m * 2048 + k * 1024); } while (0)
; #define PG8_WAIT_V(n) asm volatile("s_waitcnt vmcnt(" #n ")" ::: "memory")
; template <class Epi, class Sched, bool ALIGN_EPI = false, bool SP2 = false>
; __device__ __forceinline__ void gemm_phase(PG8_LAS unsigned char* lds, const Gemm g, const Sched& S, const Epi& E, const int tid_in) {
;     ...
;         for (int t = 0; t < nt; t += 2) {
;             if constexpr (Epi::KSPLIT > 0) { if (t == Epi::KSPLIT / BK) E.midk(acc, cur, wr, wc, fr, fq); }
;             const bool last = (t == nt - 2);
;             const char* a1 = cA + (size_t)(t + 1) * kstep;
;             const char* a2 = last ? nA : cA + (size_t)(t + 2) * kstep; const char* b2 = last ? nB : cB + (size_t)(t + 2) * kstep;
;             const char* a3 = a2 + kstep; const char* b3 = b2 + kstep;
;             if (last && has_next) S.a_ready(nxt);
;             if constexpr (SP2) {
;             PG8_LDB(B0, 0, 0); PG8_LDB(B1, 0, 1); PG8_SCHED; PG8_LDA(At, 0, 0); PG8_STAGE(PG8_SA(1, 1), a1 + hstep, voffA);
;             PG8_WAIT_V(8); PG8_WAIT_L(0); PG8_BAR; PG8_MMA(0, 0, At, B0); PG8_MMA(0, 1, At, B1); PG8_BAR; PG8_SCHED;
;             PG8_LDA(At, 0, 1); PG8_STAGE(PG8_SB(0, 0), b2, voffB); PG8_STAGE(PG8_SB(0, 1), b2 + hstep, voffB); PG8_STAGE(PG8_SA(0, 0), a2, voffA);
;             PG8_WAIT_V(8); PG8_WAIT_L(0); PG8_BAR; PG8_MMA(1, 0, At, B0); PG8_MMA(1, 1, At, B1); PG8_BAR; PG8_SCHED;
;             PG8_LDB(B0, 1, 0); PG8_LDB(B1, 1, 1); PG8_SCHED; PG8_LDA(At, 1, 0); PG8_STAGE(PG8_SA(0, 1), a2 + hstep, voffA);
;             PG8_WAIT_V(8); PG8_WAIT_L(0); PG8_BAR; PG8_MMA(0, 0, At, B0); PG8_MMA(0, 1, At, B1); PG8_BAR; PG8_SCHED;
;             PG8_LDA(At, 1, 1); PG8_STAGE(PG8_SB(1, 0), b3, voffB); PG8_STAGE(PG8_SB(1, 1), b3 + hstep, voffB); PG8_STAGE(PG8_SA(1, 0), a3, voffA);
;             PG8_WAIT_V(8); PG8_WAIT_L(0); PG8_BAR; PG8_MMA(1, 0, At, B0); PG8_MMA(1, 1, At, B1); PG8_BAR; PG8_SCHED;
	s_add_i32 s42, s59, s19
	s_mov_b32 m0, s42
	ds_read_b128 v[182:185], v165 offset:49152
	ds_read_b128 v[186:189], v165 offset:50176
	ds_read_b128 v[190:193], v165 offset:51200
	ds_read_b128 v[194:197], v165 offset:52224
	ds_read_b128 v[198:201], v165 offset:53248
	ds_read_b128 v[202:205], v165 offset:54272
	ds_read_b128 v[208:211], v165 offset:55296
	ds_read_b128 v[212:215], v165 offset:56320
	global_load_lds_dwordx4 v148, s[98:99]
	s_add_i32 m0, s42, 0x2000
	s_add_u32 s38, s38, 0x80080
	s_addc_u32 s39, s39, 0
	s_add_i32 s42, s60, s19
	global_load_lds_dwordx4 v152, s[98:99]
	s_mov_b32 m0, s42
	s_nop 0
	global_load_lds_dwordx4 v148, s[38:39]
	s_add_i32 m0, s42, 0x2000
	s_nop 0
	global_load_lds_dwordx4 v152, s[38:39]
	s_mov_b32 m0, s48
	s_nop 0
	global_load_lds_dwordx4 v146, s[100:101]
	s_waitcnt vmcnt(7)
	s_waitcnt lgkmcnt(0)
	s_barrier
	s_setprio 1
	v_mfma_f32_16x16x32_bf16 v[62:65], v[66:69], v[182:185], v[62:65]
	v_mfma_f32_16x16x32_bf16 v[58:61], v[74:77], v[182:185], v[58:61]
	v_mfma_f32_16x16x32_bf16 v[46:49], v[66:69], v[190:193], v[46:49]
	v_mfma_f32_16x16x32_bf16 v[42:45], v[74:77], v[190:193], v[42:45]
	v_mfma_f32_16x16x32_bf16 v[30:33], v[66:69], v[198:201], v[30:33]
	v_mfma_f32_16x16x32_bf16 v[26:29], v[74:77], v[198:201], v[26:29]
	v_mfma_f32_16x16x32_bf16 v[12:15], v[66:69], v[208:211], v[12:15]
	v_mfma_f32_16x16x32_bf16 v[8:11], v[74:77], v[208:211], v[8:11]
	v_mfma_f32_16x16x32_bf16 v[62:65], v[70:73], v[186:189], v[62:65]
	v_mfma_f32_16x16x32_bf16 v[58:61], v[78:81], v[186:189], v[58:61]
	v_mfma_f32_16x16x32_bf16 v[46:49], v[70:73], v[194:197], v[46:49]
	v_mfma_f32_16x16x32_bf16 v[42:45], v[78:81], v[194:197], v[42:45]
	v_mfma_f32_16x16x32_bf16 v[30:33], v[70:73], v[202:205], v[30:33]
	v_mfma_f32_16x16x32_bf16 v[26:29], v[78:81], v[202:205], v[26:29]
	v_mfma_f32_16x16x32_bf16 v[12:15], v[70:73], v[212:215], v[12:15]
	v_mfma_f32_16x16x32_bf16 v[8:11], v[78:81], v[212:215], v[8:11]
	s_setprio 0
	s_setprio 1
	v_mfma_f32_16x16x32_bf16 v[54:57], v[166:169], v[182:185], v[54:57]
	v_mfma_f32_16x16x32_bf16 v[50:53], v[174:177], v[182:185], v[50:53]
	v_mfma_f32_16x16x32_bf16 v[38:41], v[166:169], v[190:193], v[38:41]
	v_mfma_f32_16x16x32_bf16 v[34:37], v[174:177], v[190:193], v[34:37]
	v_mfma_f32_16x16x32_bf16 v[22:25], v[166:169], v[198:201], v[22:25]
	v_mfma_f32_16x16x32_bf16 v[16:19], v[174:177], v[198:201], v[16:19]
	v_mfma_f32_16x16x32_bf16 v[4:7], v[166:169], v[208:211], v[4:7]
	v_mfma_f32_16x16x32_bf16 v[0:3], v[174:177], v[208:211], v[0:3]
	v_mfma_f32_16x16x32_bf16 v[54:57], v[170:173], v[186:189], v[54:57]
	v_mfma_f32_16x16x32_bf16 v[50:53], v[178:181], v[186:189], v[50:53]
	v_mfma_f32_16x16x32_bf16 v[38:41], v[170:173], v[194:197], v[38:41]
	v_mfma_f32_16x16x32_bf16 v[34:37], v[178:181], v[194:197], v[34:37]
	v_mfma_f32_16x16x32_bf16 v[22:25], v[170:173], v[202:205], v[22:25]
	v_mfma_f32_16x16x32_bf16 v[16:19], v[178:181], v[202:205], v[16:19]
	v_mfma_f32_16x16x32_bf16 v[4:7], v[170:173], v[212:215], v[4:7]
	v_mfma_f32_16x16x32_bf16 v[0:3], v[178:181], v[212:215], v[0:3]
	s_setprio 0
	s_barrier
	s_add_i32 s58, s58, 2
	s_add_u32 s34, s34, 0x100
	s_addc_u32 s35, s35, 0
	s_add_u32 s56, s56, 0x100
	s_addc_u32 s57, s57, 0
	s_cmp_gt_u32 s58, 29

; __device__ __forceinline__ unsigned cvt_pk_bf16(float lo, float hi) { unsigned r; asm volatile("v_cvt_pk_bf16_f32 %0, %1, %2" : "=v"(r) : "v"(lo), "v"(hi)); return r; }
; #define PG8_BAR __builtin_amdgcn_s_barrier()
;     __device__ __forceinline__ void run(const f32x4 (&acc)[2][2][4][2], const Unit& u, int wr, int wc, int fr, int fq, PG8_LAS unsigned char* lds, int buf) const {
;     ...
;             for (int m = 0; m < 4; ++m) { bf16_t* rowp = O + (size_t)(row0 + ai * HALF + m * 16) * 7168 + col0;
;                 {
;                     f32x4 h0 = acc[ai][0][m][0] + bv[0][0], h1 = acc[ai][0][m][1] + bv[0][1], a0 = acc[ai][1][m][0] + bv[1][0], a1 = acc[ai][1][m][1] + bv[1][1];
;                     if (gate) {
;                         const float nl2e = -1.4426950408889634f;
;                         const f32x4 pa0 = exp2_4(a0 * nl2e) + 1.0f, pa1 = exp2_4(a1 * nl2e) + 1.0f, ph0 = exp2_4(h0 * nl2e) + 1.0f, ph1 = exp2_4(h1 * nl2e) + 1.0f;
;                         const f32x4 r0 = rcp_4(pa0 * ph0), r1 = rcp_4(pa1 * ph1);
;                         h0 = r0 * pa0 * pa0; h1 = r1 * pa1 * pa1; a0 = r0 * ph0; a1 = r1 * ph1; }
;                     u32x4 w; w.x = cvt_pk_bf16(h0[0], h0[1]); w.y = cvt_pk_bf16(h0[2], h0[3]); w.z = cvt_pk_bf16(h1[0], h1[1]); w.w = cvt_pk_bf16(h1[2], h1[3]);
;                     *(u32x4*)(rowp) = w;
;                     w.x = cvt_pk_bf16(a0[0], a0[1]); w.y = cvt_pk_bf16(a0[2], a0[3]); w.z = cvt_pk_bf16(a1[0], a1[1]); w.w = cvt_pk_bf16(a1[2], a1[3]);
;                     *(u32x4*)(rowp + HALF) = w; } }
; template <class Epi, class Sched, bool ALIGN_EPI = false, bool SP2 = false>
; __device__ __forceinline__ void gemm_phase(PG8_LAS unsigned char* lds, const Gemm g, const Sched& S, const Epi& E, const int tid_in) {
;     ...
;         if (!has_next) break;
; #pragma unroll
;         for (int a = 0; a < 2; ++a)
; #pragma unroll
;             for (int b = 0; b < 2; ++b)
; #pragma unroll
;                 for (int m = 0; m < 4; ++m)
; #pragma unroll
;                     for (int n = 0; n < 2; ++n) acc[a][b][m][n] = (f32x4){0.f, 0.f, 0.f, 0.f};
;         cur = nxt; cA = nA; cB = nB; ++ui;
;         if constexpr (ALIGN_EPI) { if (wr == 1) PG8_BAR; }
.LBB0_441:
	v_add_u32_e32 v18, 0xb0, v166
	v_mov_b64_e32 v[16:17], s[24:25]
	v_mad_i64_i32 v[16:17], s[34:35], v18, s14, v[16:17]
	v_lshl_add_u64 v[16:17], v[130:131], 1, v[16:17]
	s_andn2_b64 vcc, exec, s[36:37]
	s_mov_b64 s[34:35], -1
	v_cvt_pk_bf16_f32 v12, v12, v13
	v_cvt_pk_bf16_f32 v13, v14, v15
	v_cvt_pk_bf16_f32 v14, v8, v9
	v_cvt_pk_bf16_f32 v15, v10, v11
	global_store_dwordx4 v[16:17], v[12:15], off
	v_cvt_pk_bf16_f32 v4, v4, v5
	v_cvt_pk_bf16_f32 v5, v6, v7
	v_cvt_pk_bf16_f32 v6, v0, v1
	v_cvt_pk_bf16_f32 v7, v2, v3
	global_store_dwordx4 v[16:17], v[4:7], off offset:256
	s_cbranch_vccnz .LBB0_408
	s_andn2_b64 vcc, exec, s[22:23]
	s_cbranch_vccnz .LBB0_407
	s_branch .LBB0_407

; #define PG8_WAIT_V(n) asm volatile("s_waitcnt vmcnt(" #n ")" ::: "memory")
; template <class Epi, class Sched, bool ALIGN_EPI = false, bool SP2 = false>
; __device__ __forceinline__ void gemm_phase(PG8_LAS unsigned char* lds, const Gemm g, const Sched& S, const Epi& E, const int tid_in) {
;     ...
;     const int tid = tid_l, wid = __builtin_amdgcn_readfirstlane(tid >> 6), lane = tid & 63, wr = wid >> 2, wc = wid & 3, fr = lane & 15, fq = lane >> 4;
;     const int K = g.K, nt = K / BK;
;     unsigned voffA[2], voffB[2];
; #pragma unroll
;     for (int i = 0; i < 2; ++i) { int R, C; stage_rc(tid * 16 + i * 8192, R, C); const int Rb = perm_row<Epi::PMODE>(R);
;         voffA[i] = (unsigned)(R * K + C) * 2u; voffB[i] = (unsigned)(Rb * K + C) * 2u; }
;     const size_t kstep = (size_t)(BK * 2);
;     const size_t hstep = (size_t)HALF * K * 2;
;     const size_t tstep = 2 * hstep;
;     const unsigned ldsw = (unsigned)wid * 1024u;
;     const int aoff = lds_byte(wr * 64 + fr, fq * 8), boff = lds_byte(wc * 32 + fr, fq * 8);
;     ...
;     Unit cur, nxt; int ui = 0;
;     if (!S.next(0, cur)) return;
;     f32x4 acc[2][2][4][2];
; #pragma unroll
;     for (int a = 0; a < 2; ++a)
; #pragma unroll
;         for (int b = 0; b < 2; ++b)
; #pragma unroll
;             for (int m = 0; m < 4; ++m)
; #pragma unroll
;                 for (int n = 0; n < 2; ++n) acc[a][b][m][n] = (f32x4){0.f, 0.f, 0.f, 0.f};
;     bf16x8 At[4][2], B0[2][2], B1[2][2];
;     const char* cA = (const char*)g.A + (size_t)cur.pm * tstep; const char* cB = (const char*)g.Bt + (size_t)cur.pn * tstep;
;     S.a_ready(cur);
;     if constexpr (Epi::PREF) E.prefetch(cur, 0, lds, wid, lane);
;     if constexpr (SP2) {
;         PG8_STAGE(PG8_SB(0, 0), cB, voffB); PG8_STAGE(PG8_SB(0, 1), cB + hstep, voffB); PG8_STAGE(PG8_SA(0, 0), cA, voffA); PG8_STAGE(PG8_SA(0, 1), cA + hstep, voffA);
;         if (wr == 1) PG8_BAR;
;         PG8_WAIT_V(2); PG8_BAR;
;         PG8_STAGE(PG8_SB(1, 0), cB + kstep, voffB); PG8_STAGE(PG8_SA(1, 0), cA + kstep, voffA); PG8_STAGE(PG8_SB(1, 1), cB + hstep + kstep, voffB);
;         PG8_WAIT_V(6); PG8_BAR;
;     } else {
;         PG8_STAGE(PG8_SB(0, 0), cB, voffB); PG8_STAGE(PG8_SA(0, 0), cA, voffA); PG8_STAGE(PG8_SB(0, 1), cB + hstep, voffB); PG8_STAGE(PG8_SA(0, 1), cA + hstep, voffA);
;         if (wr == 1) PG8_BAR;
;         PG8_WAIT_V(4); PG8_BAR;
.LBB0_942:
	s_cmp_ge_i32 s1, s50
	s_cselect_b64 s[2:3], -1, 0
	s_and_b64 s[6:7], s[2:3], s[6:7]
	s_andn2_b64 vcc, exec, s[6:7]
	v_readlane_b32 s6, v253, 53
	v_readlane_b32 s7, v253, 54
	s_nop 1
	v_cndmask_b32_e64 v0, 0, 1, s[6:7]
	v_cmp_ne_u32_e64 s[42:43], 1, v0
	s_cbranch_vccnz .LBB0_969
	v_readlane_b32 s1, v252, 7
	v_readlane_b32 s6, v252, 10
	v_mbcnt_lo_u32_b32 v0, -1, 0
	v_mbcnt_hi_u32_b32 v0, -1, v0
	v_readlane_b32 s7, v252, 11
	v_or_b32_e32 v8, s1, v0
	v_readlane_b32 s1, v254, 59
	v_readlane_b32 s5, v255, 12
	s_and_b64 vcc, exec, s[42:43]
	v_readfirstlane_b32 s24, v8
	s_cbranch_vccnz .LBB0_969
	v_lshlrev_b32_e32 v0, 4, v8
	v_add_u32_e32 v1, 0x2000, v0
	v_ashrrev_i32_e32 v2, 31, v1
	v_lshrrev_b32_e32 v2, 22, v2
	v_add_u32_e32 v2, v1, v2
	v_ashrrev_i32_e32 v9, 10, v2
	v_mul_i32_i24_e32 v2, 0x400, v9
	v_sub_u32_e32 v1, v1, v2
	v_lshrrev_b32_e32 v2, 4, v1
	s_load_dwordx2 s[22:23], s[6:7], 0xf0
	v_bitop3_b32 v1, v2, v1, 32 bitop3:0x6c
	v_ashrrev_i32_e32 v2, 31, v1
	v_lshrrev_b32_e32 v2, 26, v2
	v_add_u32_e32 v2, v1, v2
	v_lshlrev_b32_e32 v3, 3, v9
	v_ashrrev_i32_e32 v10, 6, v2
	v_and_b32_e32 v3, -16, v3
	s_mul_hi_i32 s6, s1, 0x600000
	s_mul_i32 s7, s1, 0x600000
	s_waitcnt lgkmcnt(0)
	s_add_u32 s1, s22, 0x2e000000
	v_add_u32_e32 v3, v10, v3
	s_addc_u32 s5, s23, 0
	v_lshrrev_b32_e32 v5, 2, v3
	v_lshlrev_b32_e32 v6, 1, v3
	s_add_u32 s7, s22, s7
	v_and_b32_e32 v4, 0x7fffe3, v3
	v_and_b32_e32 v5, 4, v5
	v_and_b32_e32 v6, 24, v6
	v_and_b32_e32 v2, 0xc0, v2
	s_addc_u32 s6, s23, s6
	v_or3_b32 v4, v4, v5, v6
	v_sub_u32_e32 v1, v1, v2
	v_mov_b32_e32 v6, 1
	s_add_u32 s8, s7, 0x26800000
	v_lshlrev_b32_e32 v5, 5, v9
	v_ashrrev_i16_sdwa v1, v6, sext(v1) dst_sel:DWORD dst_unused:UNUSED_PAD src0_sel:DWORD src1_sel:BYTE_0
	s_addc_u32 s10, s6, 0
	v_and_b32_e32 v11, 32, v5
	v_bfe_i32 v12, v1, 0, 16
	s_movk_i32 s6, 0x600
	v_mul_u32_u24_e32 v4, 0x600, v4
	v_add_u32_e32 v1, v11, v12
	v_mul_lo_u32 v2, v3, s6
	v_add_lshl_u32 v194, v4, v1, 1
	v_add_lshl_u32 v196, v1, v2, 1
	v_bfe_i32 v1, v8, 27, 1
	v_lshrrev_b32_e32 v1, 22, v1
	v_add_u32_e32 v1, v0, v1
	v_and_b32_e32 v1, 0xfffffc00, v1
	v_sub_u32_e32 v0, v0, v1
	v_lshrrev_b32_e32 v1, 4, v0
	v_ashrrev_i32_e32 v2, 31, v8
	v_bitop3_b32 v0, v1, v0, 32 bitop3:0x6c
	v_lshrrev_b32_e32 v2, 26, v2
	v_ashrrev_i32_e32 v1, 31, v0
	v_add_u32_e32 v2, v8, v2
	v_lshrrev_b32_e32 v1, 26, v1
	v_ashrrev_i32_e32 v14, 6, v2
	v_add_u32_e32 v1, v0, v1
	v_lshlrev_b32_e32 v2, 3, v14
	v_ashrrev_i32_e32 v13, 6, v1
	v_and_b32_e32 v2, -16, v2
	v_add_u32_e32 v2, v13, v2
	v_lshrrev_b32_e32 v4, 2, v2
	v_lshlrev_b32_e32 v5, 1, v2
	v_and_b32_e32 v1, 0xc0, v1
	s_ashr_i32 s25, s24, 6
	v_and_b32_e32 v3, 0x7fffe3, v2
	v_and_b32_e32 v4, 4, v4
	v_and_b32_e32 v5, 24, v5
	v_sub_u32_e32 v0, v0, v1
	v_readlane_b32 s7, v253, 58
	s_ashr_i32 s26, s24, 8
	s_lshl_b32 s19, s25, 10
	v_or3_b32 v3, v3, v4, v5
	v_lshlrev_b32_e32 v4, 5, v14
	v_ashrrev_i16_sdwa v0, v6, sext(v0) dst_sel:DWORD dst_unused:UNUSED_PAD src0_sel:DWORD src1_sel:BYTE_0
	v_mul_lo_u32 v1, v2, s6
	s_mul_i32 s6, s7, 0xc0000
	v_and_b32_e32 v15, 32, v4
	v_bfe_i32 v16, v0, 0, 16
	s_add_u32 s34, s8, s6
	s_mul_hi_i32 s6, s7, 0xc0000
	s_mov_b64 s[66:67], s[42:43]
	v_mul_u32_u24_e32 v3, 0x600, v3
	v_add_u32_e32 v0, v15, v16
	s_addc_u32 s35, s10, s6
	s_add_i32 s42, s19, 0
	v_add_lshl_u32 v198, v3, v0, 1
	s_add_i32 m0, s42, 0x10000
	v_add_lshl_u32 v200, v0, v1, 1
	global_load_lds_dwordx4 v198, s[34:35]
	s_add_i32 m0, s42, 0x12000
	s_add_u32 s6, s34, 0x60000
	global_load_lds_dwordx4 v194, s[34:35]
	s_addc_u32 s7, s35, 0
	s_add_i32 m0, s42, 0x14000
	v_mov_b32_e32 v199, v20
	global_load_lds_dwordx4 v198, s[6:7]
	s_add_i32 m0, s42, 0x16000
	v_mov_b32_e32 v195, v20
	global_load_lds_dwordx4 v194, s[6:7]
	v_readlane_b32 s7, v253, 57
	s_mul_i32 s6, s7, 0xc0000
	s_add_u32 s30, s1, s6
	s_mul_hi_i32 s6, s7, 0xc0000
	s_addc_u32 s31, s5, s6
	s_add_i32 s43, s42, 0x2000
	s_mov_b32 m0, s42
	s_add_u32 s6, s30, 0x60000
	global_load_lds_dwordx4 v200, s[30:31]
	s_mov_b32 m0, s43
	s_addc_u32 s7, s31, 0
	s_add_i32 s44, s42, 0x4000
	global_load_lds_dwordx4 v196, s[30:31]
	s_mov_b32 m0, s44
	s_add_i32 s45, s42, 0x6000
	global_load_lds_dwordx4 v200, s[6:7]
	s_mov_b32 m0, s45
	v_mov_b32_e32 v201, v20
	global_load_lds_dwordx4 v196, s[6:7]
	v_mov_b32_e32 v197, v20
	s_cmp_eq_u32 s26, 1
	v_lshl_add_u64 v[6:7], s[34:35], 0, v[198:199]
	v_lshl_add_u64 v[4:5], s[34:35], 0, v[194:195]
	v_lshl_add_u64 v[0:1], s[30:31], 0, v[200:201]
	s_cselect_b64 s[6:7], -1, 0
	s_cmp_lg_u32 s26, 1
	v_lshl_add_u64 v[2:3], s[30:31], 0, v[196:197]
	s_cbranch_scc1 .LBB0_946
.LBB0_946:
	s_add_u32 s20, s22, 0x3e000000
	s_addc_u32 s21, s23, 0
	s_add_u32 s22, s22, 0x31000000
	s_addc_u32 s23, s23, 0
	s_lshl_b32 s25, s25, 5
	s_and_b32 s25, s25, 0x60
	s_add_i32 m0, s42, 0x18000
	v_lshl_add_u64 v[6:7], v[6:7], 0, s[12:13]
	s_lshl_b32 s46, s26, 6
	s_lshl_b32 s28, s26, 13
	s_lshl_b32 s29, s25, 7
	s_waitcnt vmcnt(2)
	s_barrier
	global_load_lds_dwordx4 v[6:7], off
	v_lshl_add_u64 v[4:5], v[4:5], 0, s[12:13]
	s_add_i32 m0, s42, 0x1a000
	s_add_i32 s47, s42, 0x8000
	s_add_i32 s48, s42, 0xa000
	global_load_lds_dwordx4 v[4:5], off
	v_lshl_add_u64 v[0:1], v[0:1], 0, s[12:13]
	s_mov_b32 m0, s47
	s_add_u32 s100, s30, 0x80
	s_addc_u32 s101, s31, 0
	s_add_u32 s26, s34, 0x60080
	global_load_lds_dwordx4 v[0:1], off
	v_lshl_add_u64 v[0:1], v[2:3], 0, s[12:13]
	s_mov_b32 m0, s48
	s_addc_u32 s27, s35, 0
	global_load_lds_dwordx4 v[0:1], off
	s_add_i32 m0, s42, 0x1c000
	v_lshl_add_u64 v[0:1], s[26:27], 0, v[198:199]
	global_load_lds_dwordx4 v[0:1], off
	v_lshl_add_u64 v[0:1], s[26:27], 0, v[194:195]
	s_add_i32 m0, s42, 0x1e000
	v_bfe_u32 v208, v8, 4, 2
	global_load_lds_dwordx4 v[0:1], off
	v_and_b32_e32 v21, 15, v8
	v_lshlrev_b32_e32 v0, 4, v208
	v_lshlrev_b32_e32 v1, 2, v8
	v_lshl_or_b32 v0, v21, 6, v0
	v_and_b32_e32 v1, 32, v1
	v_bitop3_b32 v2, v0, s28, v1 bitop3:0xde
	s_movk_i32 s28, 0x600
	v_bitop3_b32 v230, v0, s29, v1 bitop3:0xde
	v_lshrrev_b32_e32 v1, 1, v14
	v_mul_lo_u32 v0, v13, s28
	s_movk_i32 s29, 0x6000
	v_mad_u64_u32 v[0:1], s[26:27], v1, s29, v[0:1]
	v_or_b32_e32 v0, v0, v15
	v_add_lshl_u32 v202, v0, v16, 1
	v_lshrrev_b32_e32 v1, 1, v9
	v_mul_lo_u32 v0, v10, s28
	s_waitcnt vmcnt(6)
	s_or_b32 s49, s25, 0xc00
	v_mad_u64_u32 v[0:1], s[26:27], v1, s29, v[0:1]
	v_lshl_or_b32 v231, v208, 3, s25
	s_cmpk_lt_u32 s24, 0x100
	v_or_b32_e32 v0, v0, v11
	v_or_b32_e32 v209, s46, v21
	v_or_b32_e32 v232, 0xc80, v231
	s_cselect_b64 s[24:25], -1, 0
	v_mov_b32_e32 v203, v20
	v_add_lshl_u32 v204, v0, v12, 1
	v_mov_b32_e32 v205, v20
	s_mov_b32 s50, 0
	v_add_u32_e32 v233, 0, v2
	v_readlane_b32 s53, v253, 58
	v_readlane_b32 s36, v253, 57
	s_barrier
	s_branch .LBB0_949

; template <class Epi, class Sched, bool ALIGN_EPI = false, bool SP2 = false>
; __device__ __forceinline__ void gemm_phase(PG8_LAS unsigned char* lds, const Gemm g, const Sched& S, const Epi& E, const int tid_in) {
;     ...
;     for (;;) {
;         const bool has_next = S.next(ui + 1, nxt);
;         const char* nA = has_next ? (const char*)g.A + (size_t)nxt.pm * tstep : cA; const char* nB = has_next ? (const char*)g.Bt + (size_t)nxt.pn * tstep : cB;
;         for (int t = 0; t < nt; t += 2) {
;             if constexpr (Epi::KSPLIT > 0) { if (t == Epi::KSPLIT / BK) E.midk(acc, cur, wr, wc, fr, fq); }
;             const bool last = (t == nt - 2);
;             const char* a1 = cA + (size_t)(t + 1) * kstep;
;             const char* a2 = last ? nA : cA + (size_t)(t + 2) * kstep; const char* b2 = last ? nB : cB + (size_t)(t + 2) * kstep;
;             const char* a3 = a2 + kstep; const char* b3 = b2 + kstep;
;             if (last && has_next) S.a_ready(nxt);
.LBB0_959:
	s_lshl_b32 s54, s36, 8
	s_lshl_b32 s55, s53, 9
	s_add_i32 s56, s54, s46
	s_add_i32 s57, s49, s55
	s_add_u32 s36, s30, 0x60080
	s_addc_u32 s37, s31, 0
	s_add_u32 s58, s34, 0x100
	v_mov_b32_e32 v0, 0
	v_lshl_add_u64 v[182:183], s[36:37], 0, v[202:203]
	v_lshl_add_u64 v[184:185], s[36:37], 0, v[204:205]
	s_addc_u32 s59, s35, 0
	s_mov_b32 s60, -2
	s_mov_b64 s[34:35], 0
	v_mov_b32_e32 v1, v0
	v_mov_b32_e32 v2, v0
	v_mov_b32_e32 v3, v0
	v_mov_b32_e32 v4, v0
	v_mov_b32_e32 v5, v0
	v_mov_b32_e32 v6, v0
	v_mov_b32_e32 v7, v0
	v_mov_b32_e32 v8, v0
	v_mov_b32_e32 v9, v0
	v_mov_b32_e32 v10, v0
	v_mov_b32_e32 v11, v0
	v_mov_b32_e32 v16, v0
	v_mov_b32_e32 v17, v0
	v_mov_b32_e32 v18, v0
	v_mov_b32_e32 v19, v0
	v_mov_b32_e32 v26, v0
	v_mov_b32_e32 v27, v0
	v_mov_b32_e32 v28, v0
	v_mov_b32_e32 v29, v0
	v_mov_b32_e32 v34, v0
	v_mov_b32_e32 v35, v0
	v_mov_b32_e32 v36, v0
	v_mov_b32_e32 v37, v0
	v_mov_b32_e32 v42, v0
	v_mov_b32_e32 v43, v0
	v_mov_b32_e32 v44, v0
	v_mov_b32_e32 v45, v0
	v_mov_b32_e32 v50, v0
	v_mov_b32_e32 v51, v0
	v_mov_b32_e32 v52, v0
	v_mov_b32_e32 v53, v0
	v_mov_b32_e32 v12, v0
	v_mov_b32_e32 v13, v0
	v_mov_b32_e32 v14, v0
	v_mov_b32_e32 v15, v0
	v_mov_b32_e32 v22, v0
	v_mov_b32_e32 v23, v0
	v_mov_b32_e32 v24, v0
	v_mov_b32_e32 v25, v0
	v_mov_b32_e32 v30, v0
	v_mov_b32_e32 v31, v0
	v_mov_b32_e32 v32, v0
	v_mov_b32_e32 v33, v0
	v_mov_b32_e32 v38, v0
	v_mov_b32_e32 v39, v0
	v_mov_b32_e32 v40, v0
	v_mov_b32_e32 v41, v0
	v_mov_b32_e32 v46, v0
	v_mov_b32_e32 v47, v0
	v_mov_b32_e32 v48, v0
	v_mov_b32_e32 v49, v0
	v_mov_b32_e32 v54, v0
	v_mov_b32_e32 v55, v0
	v_mov_b32_e32 v56, v0
	v_mov_b32_e32 v57, v0
	v_mov_b32_e32 v58, v0
	v_mov_b32_e32 v59, v0
	v_mov_b32_e32 v60, v0
	v_mov_b32_e32 v61, v0
	v_mov_b32_e32 v62, v0
	v_mov_b32_e32 v63, v0
	v_mov_b32_e32 v64, v0
	v_mov_b32_e32 v65, v0
	v_mov_b32_e32 v66, v0
	v_mov_b32_e32 v67, v0
	v_mov_b32_e32 v68, v0
	v_mov_b32_e32 v69, v0
	v_mov_b32_e32 v70, v0
	v_mov_b32_e32 v71, v0
	v_mov_b32_e32 v72, v0
	v_mov_b32_e32 v73, v0
	v_mov_b32_e32 v74, v0
	v_mov_b32_e32 v75, v0
	v_mov_b32_e32 v76, v0
	v_mov_b32_e32 v77, v0
	v_mov_b32_e32 v82, v0
	v_mov_b32_e32 v83, v0
	v_mov_b32_e32 v84, v0
	v_mov_b32_e32 v85, v0
	v_mov_b32_e32 v90, v0
	v_mov_b32_e32 v91, v0
	v_mov_b32_e32 v92, v0
	v_mov_b32_e32 v93, v0
	v_mov_b32_e32 v98, v0
	v_mov_b32_e32 v99, v0
	v_mov_b32_e32 v100, v0
	v_mov_b32_e32 v101, v0
	v_mov_b32_e32 v114, v0
	v_mov_b32_e32 v115, v0
	v_mov_b32_e32 v116, v0
	v_mov_b32_e32 v117, v0
	v_mov_b32_e32 v118, v0
	v_mov_b32_e32 v119, v0
	v_mov_b32_e32 v120, v0
	v_mov_b32_e32 v121, v0
	v_mov_b32_e32 v78, v0
	v_mov_b32_e32 v79, v0
	v_mov_b32_e32 v80, v0
	v_mov_b32_e32 v81, v0
	v_mov_b32_e32 v86, v0
	v_mov_b32_e32 v87, v0
	v_mov_b32_e32 v88, v0
	v_mov_b32_e32 v89, v0
	v_mov_b32_e32 v94, v0
	v_mov_b32_e32 v95, v0
	v_mov_b32_e32 v96, v0
	v_mov_b32_e32 v97, v0
	v_mov_b32_e32 v102, v0
	v_mov_b32_e32 v103, v0
	v_mov_b32_e32 v104, v0
	v_mov_b32_e32 v105, v0
	v_mov_b32_e32 v106, v0
	v_mov_b32_e32 v107, v0
	v_mov_b32_e32 v108, v0
	v_mov_b32_e32 v109, v0
	v_mov_b32_e32 v110, v0
	v_mov_b32_e32 v111, v0
	v_mov_b32_e32 v112, v0
	v_mov_b32_e32 v113, v0
	v_mov_b32_e32 v122, v0
	v_mov_b32_e32 v123, v0
	v_mov_b32_e32 v124, v0
	v_mov_b32_e32 v125, v0
	v_mov_b32_e32 v126, v0
	v_mov_b32_e32 v127, v0
	v_mov_b32_e32 v128, v0
	v_mov_b32_e32 v129, v0
	s_cmp_lt_u32 s19, 0x1000
	s_cbranch_scc1 .LCB_960
	s_barrier

; __device__ __forceinline__ float bflo(unsigned w) { return __uint_as_float(w << 16); }
; __device__ __forceinline__ float bfhi(unsigned w) { return __uint_as_float(w & 0xffff0000u); }
;     template <int WHICH> __device__ __forceinline__ void scale(f32x4 (&acc)[2][2][4][2], const Unit& u, int wr, int wc, int fr, int fq) const {
;         const int row0 = u.pm * BM + wr * 64 + fr, gcol = 3072 + u.pn * 512 + WHICH * 128 + wc * 32 + 8 * fq;
;         u32x4 g[2][4][2];
; #pragma unroll
;         for (int ai = 0; ai < 2; ++ai)
; #pragma unroll
;             for (int m = 0; m < 4; ++m)
; #pragma unroll
;                 for (int bj = 0; bj < 2; ++bj) g[ai][m][bj] = *(const u32x4*)(QKG + (size_t)(row0 + ai * HALF + m * 16) * 7168 + gcol + bj * 256);
; #pragma unroll
;         for (int ai = 0; ai < 2; ++ai)
; #pragma unroll
;             for (int m = 0; m < 4; ++m)
; #pragma unroll
;                 for (int bj = 0; bj < 2; ++bj) {
;                     const unsigned gw[4] = {g[ai][m][bj].x, g[ai][m][bj].y, g[ai][m][bj].z, g[ai][m][bj].w};
; #pragma unroll
;                     for (int j = 0; j < 4; ++j) { acc[ai][bj][m][j >> 1][(2 * j) & 3] *= bflo(gw[j]); acc[ai][bj][m][j >> 1][(2 * j + 1) & 3] *= bfhi(gw[j]); }
;                 }
;     }
.LBB0_965:
	v_add_u32_e32 v130, s55, v232
	v_ashrrev_i32_e32 v131, 31, v130
	v_add_u32_e32 v224, s54, v209
	v_lshl_add_u64 v[178:179], v[130:131], 1, s[20:21]
	v_mad_i64_i32 v[130:131], s[30:31], v224, s14, v[178:179]
	global_load_dwordx4 v[190:193], v[130:131], off
	global_load_dwordx4 v[186:189], v[130:131], off offset:512
	v_or_b32_e32 v216, 16, v224
	v_mad_i64_i32 v[130:131], s[30:31], v216, s14, v[178:179]
	global_load_dwordx4 v[174:177], v[130:131], off
	global_load_dwordx4 v[170:173], v[130:131], off offset:512
	v_or_b32_e32 v214, 32, v224
	v_mad_i64_i32 v[130:131], s[30:31], v214, s14, v[178:179]
	global_load_dwordx4 v[166:169], v[130:131], off
	global_load_dwordx4 v[158:161], v[130:131], off offset:512
	v_or_b32_e32 v218, 48, v224
	v_mad_i64_i32 v[130:131], s[30:31], v218, s14, v[178:179]
	global_load_dwordx4 v[162:165], v[130:131], off
	global_load_dwordx4 v[150:153], v[130:131], off offset:512
	v_add_u32_e32 v220, 0x80, v224
	v_mad_i64_i32 v[130:131], s[30:31], v220, s14, v[178:179]
	global_load_dwordx4 v[154:157], v[130:131], off
	global_load_dwordx4 v[142:145], v[130:131], off offset:512
	v_add_u32_e32 v222, 0x90, v224
	v_mad_i64_i32 v[130:131], s[30:31], v222, s14, v[178:179]
	global_load_dwordx4 v[146:149], v[130:131], off
	global_load_dwordx4 v[134:137], v[130:131], off offset:512
	v_add_u32_e32 v226, 0xa0, v224
	v_mad_i64_i32 v[130:131], s[30:31], v226, s14, v[178:179]
	global_load_dwordx4 v[138:141], v[130:131], off
	s_nop 0
	global_load_dwordx4 v[130:133], v[130:131], off offset:512
	v_add_u32_e32 v228, 0xb0, v224
	v_mad_i64_i32 v[178:179], s[30:31], v228, s14, v[178:179]
	global_load_dwordx4 v[182:185], v[178:179], off
	s_nop 0
	global_load_dwordx4 v[178:181], v[178:179], off offset:512
	v_ashrrev_i32_e32 v225, 31, v224
	v_ashrrev_i32_e32 v217, 31, v216
	v_ashrrev_i32_e32 v215, 31, v214
	v_ashrrev_i32_e32 v219, 31, v218
	v_ashrrev_i32_e32 v221, 31, v220
	v_ashrrev_i32_e32 v223, 31, v222
	v_ashrrev_i32_e32 v227, 31, v226
	v_ashrrev_i32_e32 v229, 31, v228
	s_mov_b64 s[30:31], -1
	s_and_b64 vcc, exec, s[38:39]
	v_readlane_b32 s57, v255, 11
	s_movk_i32 s54, 0xffc0
	s_movk_i32 s55, 0xc00
	s_mov_b32 s56, 0xfe03f81
	s_waitcnt vmcnt(0)
	v_lshlrev_b32_e32 v207, 16, v190
	v_and_b32_e32 v190, 0xffff0000, v190
	v_mul_f32_e32 v127, v127, v190
	v_lshlrev_b32_e32 v190, 16, v191
	v_mul_f32_e32 v128, v128, v190
	v_and_b32_e32 v190, 0xffff0000, v191
	v_mul_f32_e32 v129, v129, v190
	v_lshlrev_b32_e32 v190, 16, v192
	v_mul_f32_e32 v122, v122, v190
	v_and_b32_e32 v190, 0xffff0000, v192
	v_mul_f32_e32 v123, v123, v190
	v_lshlrev_b32_e32 v190, 16, v193
	v_mul_f32_e32 v124, v124, v190
	v_and_b32_e32 v190, 0xffff0000, v193
	v_mul_f32_e32 v125, v125, v190
	v_lshlrev_b32_e32 v190, 16, v186
	v_and_b32_e32 v186, 0xffff0000, v186
	v_mul_f32_e32 v119, v119, v186
	v_lshlrev_b32_e32 v186, 16, v187
	v_mul_f32_e32 v120, v120, v186
	v_and_b32_e32 v186, 0xffff0000, v187
	v_mul_f32_e32 v121, v121, v186
	v_lshlrev_b32_e32 v186, 16, v188
	v_mul_f32_e32 v114, v114, v186
	v_and_b32_e32 v186, 0xffff0000, v188
	v_mul_f32_e32 v115, v115, v186
	v_lshlrev_b32_e32 v186, 16, v189
	v_mul_f32_e32 v116, v116, v186
	v_and_b32_e32 v186, 0xffff0000, v189
	v_mul_f32_e32 v117, v117, v186
	v_lshlrev_b32_e32 v186, 16, v174
	v_and_b32_e32 v174, 0xffff0000, v174
	v_mul_f32_e32 v111, v111, v174
	v_lshlrev_b32_e32 v174, 16, v175
	v_mul_f32_e32 v112, v112, v174
	v_and_b32_e32 v174, 0xffff0000, v175
	v_mul_f32_e32 v113, v113, v174
	v_lshlrev_b32_e32 v174, 16, v176
	v_mul_f32_e32 v106, v106, v174
	v_and_b32_e32 v174, 0xffff0000, v176
	v_mul_f32_e32 v107, v107, v174
	v_lshlrev_b32_e32 v174, 16, v177
	v_mul_f32_e32 v108, v108, v174
	v_and_b32_e32 v174, 0xffff0000, v177
	v_mul_f32_e32 v109, v109, v174
	v_lshlrev_b32_e32 v174, 16, v170
	v_and_b32_e32 v170, 0xffff0000, v170
	v_mul_f32_e32 v99, v99, v170
	v_lshlrev_b32_e32 v170, 16, v171
	v_mul_f32_e32 v100, v100, v170
	v_and_b32_e32 v170, 0xffff0000, v171
	v_mul_f32_e32 v101, v101, v170
	v_lshlrev_b32_e32 v170, 16, v172
	v_mul_f32_e32 v90, v90, v170
	v_and_b32_e32 v170, 0xffff0000, v172
	v_mul_f32_e32 v91, v91, v170
	v_lshlrev_b32_e32 v170, 16, v173
	v_mul_f32_e32 v92, v92, v170
	v_and_b32_e32 v170, 0xffff0000, v173
	v_mul_f32_e32 v93, v93, v170
	v_lshlrev_b32_e32 v170, 16, v166
	v_and_b32_e32 v166, 0xffff0000, v166
	v_mul_f32_e32 v103, v103, v166
	v_lshlrev_b32_e32 v166, 16, v167
	v_mul_f32_e32 v104, v104, v166
	v_and_b32_e32 v166, 0xffff0000, v167
	v_mul_f32_e32 v105, v105, v166
	v_lshlrev_b32_e32 v166, 16, v168
	v_mul_f32_e32 v94, v94, v166
	v_and_b32_e32 v166, 0xffff0000, v168
	v_mul_f32_e32 v95, v95, v166
	v_lshlrev_b32_e32 v166, 16, v169
	v_mul_f32_e32 v96, v96, v166
	v_and_b32_e32 v166, 0xffff0000, v169
	v_mul_f32_e32 v97, v97, v166
	v_lshlrev_b32_e32 v166, 16, v158
	v_and_b32_e32 v158, 0xffff0000, v158
	v_mul_f32_e32 v83, v83, v158
	v_lshlrev_b32_e32 v158, 16, v159
	v_mul_f32_e32 v84, v84, v158
	v_and_b32_e32 v158, 0xffff0000, v159
	v_mul_f32_e32 v85, v85, v158
	v_lshlrev_b32_e32 v158, 16, v160
	v_mul_f32_e32 v74, v74, v158
	v_and_b32_e32 v158, 0xffff0000, v160
	v_mul_f32_e32 v75, v75, v158
	v_lshlrev_b32_e32 v158, 16, v161
	v_mul_f32_e32 v76, v76, v158
	v_and_b32_e32 v158, 0xffff0000, v161
	v_mul_f32_e32 v77, v77, v158
	v_lshlrev_b32_e32 v158, 16, v162
	v_mul_f32_e32 v86, v86, v158
	v_and_b32_e32 v158, 0xffff0000, v162
	v_mul_f32_e32 v87, v87, v158
	v_lshlrev_b32_e32 v158, 16, v163
	v_mul_f32_e32 v88, v88, v158
	v_and_b32_e32 v158, 0xffff0000, v163
	v_mul_f32_e32 v89, v89, v158
	v_lshlrev_b32_e32 v158, 16, v164
	v_mul_f32_e32 v78, v78, v158
	v_and_b32_e32 v158, 0xffff0000, v164
	v_mul_f32_e32 v79, v79, v158
	v_lshlrev_b32_e32 v158, 16, v165
; __device__ __forceinline__ float bflo(unsigned w) { return __uint_as_float(w << 16); }
; __device__ __forceinline__ float bfhi(unsigned w) { return __uint_as_float(w & 0xffff0000u); }
;     template <int WHICH> __device__ __forceinline__ void scale(f32x4 (&acc)[2][2][4][2], const Unit& u, int wr, int wc, int fr, int fq) const {
;     ...
;         for (int ai = 0; ai < 2; ++ai)
; #pragma unroll
;             for (int m = 0; m < 4; ++m)
; #pragma unroll
;                 for (int bj = 0; bj < 2; ++bj) {
;                     const unsigned gw[4] = {g[ai][m][bj].x, g[ai][m][bj].y, g[ai][m][bj].z, g[ai][m][bj].w};
; #pragma unroll
;                     for (int j = 0; j < 4; ++j) { acc[ai][bj][m][j >> 1][(2 * j) & 3] *= bflo(gw[j]); acc[ai][bj][m][j >> 1][(2 * j + 1) & 3] *= bfhi(gw[j]); }
;                 }
;     }
	v_mul_f32_e32 v80, v80, v158
	v_and_b32_e32 v158, 0xffff0000, v165
	v_mul_f32_e32 v81, v81, v158
	v_lshlrev_b32_e32 v158, 16, v150
	v_and_b32_e32 v150, 0xffff0000, v150
	v_mul_f32_e32 v71, v71, v150
	v_lshlrev_b32_e32 v150, 16, v151
	v_mul_f32_e32 v72, v72, v150
	v_and_b32_e32 v150, 0xffff0000, v151
	v_mul_f32_e32 v73, v73, v150
	v_lshlrev_b32_e32 v150, 16, v152
	v_mul_f32_e32 v66, v66, v150
	v_and_b32_e32 v150, 0xffff0000, v152
	v_mul_f32_e32 v67, v67, v150
	v_lshlrev_b32_e32 v150, 16, v153
	v_mul_f32_e32 v68, v68, v150
	v_and_b32_e32 v150, 0xffff0000, v153
	v_mul_f32_e32 v69, v69, v150
	v_lshlrev_b32_e32 v150, 16, v154
	v_mul_f32_e32 v62, v62, v150
	v_and_b32_e32 v150, 0xffff0000, v154
	v_mul_f32_e32 v63, v63, v150
	v_lshlrev_b32_e32 v150, 16, v155
	v_mul_f32_e32 v64, v64, v150
	v_and_b32_e32 v150, 0xffff0000, v155
	v_mul_f32_e32 v65, v65, v150
	v_lshlrev_b32_e32 v150, 16, v156
	v_mul_f32_e32 v58, v58, v150
	v_and_b32_e32 v150, 0xffff0000, v156
	v_mul_f32_e32 v59, v59, v150
	v_lshlrev_b32_e32 v150, 16, v157
	v_mul_f32_e32 v60, v60, v150
	v_and_b32_e32 v150, 0xffff0000, v157
	v_mul_f32_e32 v61, v61, v150
	v_lshlrev_b32_e32 v150, 16, v142
	v_and_b32_e32 v142, 0xffff0000, v142
	v_mul_f32_e32 v51, v51, v142
	v_lshlrev_b32_e32 v142, 16, v143
	v_mul_f32_e32 v52, v52, v142
	v_and_b32_e32 v142, 0xffff0000, v143
	v_mul_f32_e32 v53, v53, v142
	v_lshlrev_b32_e32 v142, 16, v144
	v_mul_f32_e32 v42, v42, v142
	v_and_b32_e32 v142, 0xffff0000, v144
	v_mul_f32_e32 v43, v43, v142
	v_lshlrev_b32_e32 v142, 16, v145
	v_mul_f32_e32 v44, v44, v142
	v_and_b32_e32 v142, 0xffff0000, v145
	v_mul_f32_e32 v45, v45, v142
	v_lshlrev_b32_e32 v142, 16, v146
	v_mul_f32_e32 v54, v54, v142
	v_and_b32_e32 v142, 0xffff0000, v146
	v_mul_f32_e32 v55, v55, v142
	v_lshlrev_b32_e32 v142, 16, v147
	v_mul_f32_e32 v56, v56, v142
	v_and_b32_e32 v142, 0xffff0000, v147
	v_mul_f32_e32 v57, v57, v142
	v_lshlrev_b32_e32 v142, 16, v148
	v_mul_f32_e32 v46, v46, v142
	v_and_b32_e32 v142, 0xffff0000, v148
	v_mul_f32_e32 v47, v47, v142
	v_lshlrev_b32_e32 v142, 16, v149
	v_mul_f32_e32 v48, v48, v142
	v_and_b32_e32 v142, 0xffff0000, v149
	v_mul_f32_e32 v49, v49, v142
	v_lshlrev_b32_e32 v142, 16, v134
	v_and_b32_e32 v134, 0xffff0000, v134
	v_mul_f32_e32 v35, v35, v134
	v_lshlrev_b32_e32 v134, 16, v135
	v_mul_f32_e32 v36, v36, v134
	v_and_b32_e32 v134, 0xffff0000, v135
	v_mul_f32_e32 v37, v37, v134
	v_lshlrev_b32_e32 v134, 16, v136
	v_mul_f32_e32 v26, v26, v134
	v_and_b32_e32 v134, 0xffff0000, v136
	v_mul_f32_e32 v27, v27, v134
	v_lshlrev_b32_e32 v134, 16, v137
	v_mul_f32_e32 v28, v28, v134
	v_and_b32_e32 v134, 0xffff0000, v137
	v_mul_f32_e32 v29, v29, v134
	v_lshlrev_b32_e32 v134, 16, v138
	v_mul_f32_e32 v38, v38, v134
	v_and_b32_e32 v134, 0xffff0000, v138
	v_mul_f32_e32 v39, v39, v134
	v_lshlrev_b32_e32 v134, 16, v139
	v_mul_f32_e32 v40, v40, v134
	v_and_b32_e32 v134, 0xffff0000, v139
	v_mul_f32_e32 v41, v41, v134
	v_lshlrev_b32_e32 v134, 16, v140
	v_mul_f32_e32 v30, v30, v134
	v_and_b32_e32 v134, 0xffff0000, v140
	v_mul_f32_e32 v31, v31, v134
	v_lshlrev_b32_e32 v134, 16, v141
	v_mul_f32_e32 v32, v32, v134
	v_and_b32_e32 v134, 0xffff0000, v141
	v_mul_f32_e32 v33, v33, v134
	v_lshlrev_b32_e32 v134, 16, v130
	v_and_b32_e32 v130, 0xffff0000, v130
	v_mul_f32_e32 v17, v17, v130
	v_lshlrev_b32_e32 v130, 16, v131
	v_mul_f32_e32 v18, v18, v130
	v_and_b32_e32 v130, 0xffff0000, v131
	v_mul_f32_e32 v19, v19, v130
	v_lshlrev_b32_e32 v130, 16, v132
	v_mul_f32_e32 v8, v8, v130
	v_and_b32_e32 v130, 0xffff0000, v132
	v_mul_f32_e32 v9, v9, v130
	v_lshlrev_b32_e32 v130, 16, v133
	v_mul_f32_e32 v10, v10, v130
	v_and_b32_e32 v130, 0xffff0000, v133
	v_mul_f32_e32 v11, v11, v130
	v_lshlrev_b32_e32 v130, 16, v182
	v_mul_f32_e32 v22, v22, v130
	v_and_b32_e32 v130, 0xffff0000, v182
	v_mul_f32_e32 v23, v23, v130
	v_lshlrev_b32_e32 v130, 16, v183
	v_mul_f32_e32 v24, v24, v130
	v_and_b32_e32 v130, 0xffff0000, v183
	v_mul_f32_e32 v25, v25, v130
	v_lshlrev_b32_e32 v130, 16, v184
	v_mul_f32_e32 v12, v12, v130
	v_and_b32_e32 v130, 0xffff0000, v184
	v_mul_f32_e32 v13, v13, v130
	v_lshlrev_b32_e32 v130, 16, v185
	v_mul_f32_e32 v14, v14, v130
	v_and_b32_e32 v130, 0xffff0000, v185
	v_mul_f32_e32 v15, v15, v130
	v_lshlrev_b32_e32 v130, 16, v178
	v_mul_f32_e32 v130, v4, v130
	v_and_b32_e32 v4, 0xffff0000, v178
	v_mul_f32_e32 v131, v5, v4
	v_lshlrev_b32_e32 v4, 16, v179
	v_mul_f32_e32 v132, v6, v4
	v_and_b32_e32 v4, 0xffff0000, v179
	v_mul_f32_e32 v133, v7, v4
	v_lshlrev_b32_e32 v4, 16, v180
	v_mul_f32_e32 v16, v16, v134
	v_mul_f32_e32 v134, v0, v4
; __device__ __forceinline__ unsigned cvt_pk_bf16(float lo, float hi) { unsigned r; asm volatile("v_cvt_pk_bf16_f32 %0, %1, %2" : "=v"(r) : "v"(lo), "v"(hi)); return r; }
; #define PG8_BAR __builtin_amdgcn_s_barrier()
;     __device__ __forceinline__ void operator()(f32x4 (&acc)[2][2][4][2], const Unit& u, int wr, int wc, int fr, int fq) const {
;         scale<1>(acc, u, wr, wc, fr, fq);
;         const int row0 = u.pm * BM + wr * 64 + fr, col0 = u.pn * BM + wc * 32 + 8 * fq;
; #pragma unroll
;         for (int ai = 0; ai < 2; ++ai)
; #pragma unroll
;             for (int m = 0; m < 4; ++m)
; #pragma unroll
;                 for (int bj = 0; bj < 2; ++bj) { const f32x4 v0 = acc[ai][bj][m][0], v1 = acc[ai][bj][m][1];
;                     u32x4 w; w.x = cvt_pk_bf16(v0[0], v0[1]); w.y = cvt_pk_bf16(v0[2], v0[3]); w.z = cvt_pk_bf16(v1[0], v1[1]); w.w = cvt_pk_bf16(v1[2], v1[3]);
;                     *(u32x4*)(MB + (size_t)(row0 + ai * HALF + m * 16) * 2048 + col0 + bj * HALF) = w; }
;     }
; template <class Epi, class Sched, bool ALIGN_EPI = false, bool SP2 = false>
; __device__ __forceinline__ void gemm_phase(PG8_LAS unsigned char* lds, const Gemm g, const Sched& S, const Epi& E, const int tid_in) {
;     ...
;         if (!has_next) break;
; #pragma unroll
;         for (int a = 0; a < 2; ++a)
; #pragma unroll
;             for (int b = 0; b < 2; ++b)
; #pragma unroll
;                 for (int m = 0; m < 4; ++m)
; #pragma unroll
;                     for (int n = 0; n < 2; ++n) acc[a][b][m][n] = (f32x4){0.f, 0.f, 0.f, 0.f};
;         cur = nxt; cA = nA; cB = nB; ++ui;
;         if constexpr (ALIGN_EPI) { if (wr == 1) PG8_BAR; }
	v_and_b32_e32 v0, 0xffff0000, v180
	v_lshl_or_b32 v4, s53, 8, v231
	v_mul_f32_e32 v135, v1, v0
	v_lshlrev_b32_e32 v0, 16, v181
	v_ashrrev_i32_e32 v5, 31, v4
	v_lshlrev_b64 v[6:7], 12, v[224:225]
	v_mul_f32_e32 v136, v2, v0
	v_and_b32_e32 v0, 0xffff0000, v181
	v_lshl_add_u64 v[6:7], s[22:23], 0, v[6:7]
	v_lshlrev_b64 v[4:5], 1, v[4:5]
	v_mul_f32_e32 v126, v126, v207
	v_mul_f32_e32 v137, v3, v0
	v_cvt_pk_bf16_f32 v0, v126, v127
	v_cvt_pk_bf16_f32 v1, v128, v129
	v_cvt_pk_bf16_f32 v2, v122, v123
	v_cvt_pk_bf16_f32 v3, v124, v125
	v_lshl_add_u64 v[6:7], v[6:7], 0, v[4:5]
	v_mul_f32_e32 v118, v118, v190
	global_store_dwordx4 v[6:7], v[0:3], off
	v_mul_f32_e32 v110, v110, v186
	v_mul_f32_e32 v98, v98, v174
	v_cvt_pk_bf16_f32 v0, v118, v119
	v_cvt_pk_bf16_f32 v1, v120, v121
	v_cvt_pk_bf16_f32 v2, v114, v115
	v_cvt_pk_bf16_f32 v3, v116, v117
	global_store_dwordx4 v[6:7], v[0:3], off offset:256
	v_lshlrev_b64 v[6:7], 12, v[216:217]
	v_lshl_add_u64 v[6:7], s[22:23], 0, v[6:7]
	v_cvt_pk_bf16_f32 v0, v110, v111
	v_cvt_pk_bf16_f32 v1, v112, v113
	v_cvt_pk_bf16_f32 v2, v106, v107
	v_cvt_pk_bf16_f32 v3, v108, v109
	v_lshl_add_u64 v[6:7], v[6:7], 0, v[4:5]
	global_store_dwordx4 v[6:7], v[0:3], off
	v_mul_f32_e32 v102, v102, v170
	v_mul_f32_e32 v82, v82, v166
	v_cvt_pk_bf16_f32 v0, v98, v99
	v_cvt_pk_bf16_f32 v1, v100, v101
	v_cvt_pk_bf16_f32 v2, v90, v91
	v_cvt_pk_bf16_f32 v3, v92, v93
	global_store_dwordx4 v[6:7], v[0:3], off offset:256
	v_lshlrev_b64 v[6:7], 12, v[214:215]
	v_lshl_add_u64 v[6:7], s[22:23], 0, v[6:7]
	v_cvt_pk_bf16_f32 v0, v102, v103
	v_cvt_pk_bf16_f32 v1, v104, v105
	v_cvt_pk_bf16_f32 v2, v94, v95
	v_cvt_pk_bf16_f32 v3, v96, v97
	v_lshl_add_u64 v[6:7], v[6:7], 0, v[4:5]
	global_store_dwordx4 v[6:7], v[0:3], off
	v_mul_f32_e32 v70, v70, v158
	v_mul_f32_e32 v50, v50, v150
	v_cvt_pk_bf16_f32 v0, v82, v83
	v_cvt_pk_bf16_f32 v1, v84, v85
	v_cvt_pk_bf16_f32 v2, v74, v75
	v_cvt_pk_bf16_f32 v3, v76, v77
	global_store_dwordx4 v[6:7], v[0:3], off offset:256
	v_lshlrev_b64 v[6:7], 12, v[218:219]
	v_lshl_add_u64 v[6:7], s[22:23], 0, v[6:7]
	v_cvt_pk_bf16_f32 v0, v86, v87
	v_cvt_pk_bf16_f32 v1, v88, v89
	v_cvt_pk_bf16_f32 v2, v78, v79
	v_cvt_pk_bf16_f32 v3, v80, v81
	v_lshl_add_u64 v[6:7], v[6:7], 0, v[4:5]
	global_store_dwordx4 v[6:7], v[0:3], off
	v_mul_f32_e32 v34, v34, v142
	s_nop 0
	v_cvt_pk_bf16_f32 v0, v70, v71
	v_cvt_pk_bf16_f32 v1, v72, v73
	v_cvt_pk_bf16_f32 v2, v66, v67
	v_cvt_pk_bf16_f32 v3, v68, v69
	global_store_dwordx4 v[6:7], v[0:3], off offset:256
	v_lshlrev_b64 v[6:7], 12, v[220:221]
	v_lshl_add_u64 v[6:7], s[22:23], 0, v[6:7]
	v_cvt_pk_bf16_f32 v0, v62, v63
	v_cvt_pk_bf16_f32 v1, v64, v65
	v_cvt_pk_bf16_f32 v2, v58, v59
	v_cvt_pk_bf16_f32 v3, v60, v61
	v_lshl_add_u64 v[6:7], v[6:7], 0, v[4:5]
	global_store_dwordx4 v[6:7], v[0:3], off
	s_nop 1
	v_cvt_pk_bf16_f32 v0, v50, v51
	v_cvt_pk_bf16_f32 v1, v52, v53
	v_cvt_pk_bf16_f32 v2, v42, v43
	v_cvt_pk_bf16_f32 v3, v44, v45
	global_store_dwordx4 v[6:7], v[0:3], off offset:256
	v_lshlrev_b64 v[6:7], 12, v[222:223]
	v_lshl_add_u64 v[6:7], s[22:23], 0, v[6:7]
	v_cvt_pk_bf16_f32 v0, v54, v55
	v_cvt_pk_bf16_f32 v1, v56, v57
	v_cvt_pk_bf16_f32 v2, v46, v47
	v_cvt_pk_bf16_f32 v3, v48, v49
	v_lshl_add_u64 v[6:7], v[6:7], 0, v[4:5]
	global_store_dwordx4 v[6:7], v[0:3], off
	s_nop 1
	v_cvt_pk_bf16_f32 v0, v34, v35
	v_cvt_pk_bf16_f32 v1, v36, v37
	v_cvt_pk_bf16_f32 v2, v26, v27
	v_cvt_pk_bf16_f32 v3, v28, v29
	global_store_dwordx4 v[6:7], v[0:3], off offset:256
	v_lshlrev_b64 v[6:7], 12, v[226:227]
	v_lshl_add_u64 v[6:7], s[22:23], 0, v[6:7]
	v_cvt_pk_bf16_f32 v0, v38, v39
	v_cvt_pk_bf16_f32 v1, v40, v41
	v_cvt_pk_bf16_f32 v2, v30, v31
	v_cvt_pk_bf16_f32 v3, v32, v33
	v_lshl_add_u64 v[6:7], v[6:7], 0, v[4:5]
	global_store_dwordx4 v[6:7], v[0:3], off
	s_nop 1
	v_cvt_pk_bf16_f32 v0, v16, v17
	v_cvt_pk_bf16_f32 v1, v18, v19
	v_cvt_pk_bf16_f32 v2, v8, v9
	v_cvt_pk_bf16_f32 v3, v10, v11
	global_store_dwordx4 v[6:7], v[0:3], off offset:256
	v_lshlrev_b64 v[6:7], 12, v[228:229]
	v_lshl_add_u64 v[6:7], s[22:23], 0, v[6:7]
	v_cvt_pk_bf16_f32 v0, v22, v23
	v_cvt_pk_bf16_f32 v1, v24, v25
	v_cvt_pk_bf16_f32 v2, v12, v13
	v_cvt_pk_bf16_f32 v3, v14, v15
	v_lshl_add_u64 v[4:5], v[6:7], 0, v[4:5]
	global_store_dwordx4 v[4:5], v[0:3], off
	s_nop 1
	v_cvt_pk_bf16_f32 v0, v130, v131
	v_cvt_pk_bf16_f32 v1, v132, v133
	v_cvt_pk_bf16_f32 v2, v134, v135
	v_cvt_pk_bf16_f32 v3, v136, v137
	global_store_dwordx4 v[4:5], v[0:3], off offset:256
	s_cbranch_vccnz .LBB0_948
	s_andn2_b64 vcc, exec, s[6:7]
	s_cbranch_vccnz .LBB0_947
	s_branch .LBB0_947

; #define PG8_WAIT_V(n) asm volatile("s_waitcnt vmcnt(" #n ")" ::: "memory")
; template <class Epi, class Sched, bool ALIGN_EPI = false, bool SP2 = false>
; __device__ __forceinline__ void gemm_phase(PG8_LAS unsigned char* lds, const Gemm g, const Sched& S, const Epi& E, const int tid_in) {
;     ...
;     const int tid = tid_l, wid = __builtin_amdgcn_readfirstlane(tid >> 6), lane = tid & 63, wr = wid >> 2, wc = wid & 3, fr = lane & 15, fq = lane >> 4;
;     const int K = g.K, nt = K / BK;
;     unsigned voffA[2], voffB[2];
; #pragma unroll
;     for (int i = 0; i < 2; ++i) { int R, C; stage_rc(tid * 16 + i * 8192, R, C); const int Rb = perm_row<Epi::PMODE>(R);
;         voffA[i] = (unsigned)(R * K + C) * 2u; voffB[i] = (unsigned)(Rb * K + C) * 2u; }
;     const size_t kstep = (size_t)(BK * 2);
;     const size_t hstep = (size_t)HALF * K * 2;
;     const size_t tstep = 2 * hstep;
;     const unsigned ldsw = (unsigned)wid * 1024u;
;     const int aoff = lds_byte(wr * 64 + fr, fq * 8), boff = lds_byte(wc * 32 + fr, fq * 8);
;     ...
;     Unit cur, nxt; int ui = 0;
;     if (!S.next(0, cur)) return;
;     f32x4 acc[2][2][4][2];
; #pragma unroll
;     for (int a = 0; a < 2; ++a)
; #pragma unroll
;         for (int b = 0; b < 2; ++b)
; #pragma unroll
;             for (int m = 0; m < 4; ++m)
; #pragma unroll
;                 for (int n = 0; n < 2; ++n) acc[a][b][m][n] = (f32x4){0.f, 0.f, 0.f, 0.f};
;     bf16x8 At[4][2], B0[2][2], B1[2][2];
;     const char* cA = (const char*)g.A + (size_t)cur.pm * tstep; const char* cB = (const char*)g.Bt + (size_t)cur.pn * tstep;
;     S.a_ready(cur);
;     if constexpr (Epi::PREF) E.prefetch(cur, 0, lds, wid, lane);
;     if constexpr (SP2) {
;         PG8_STAGE(PG8_SB(0, 0), cB, voffB); PG8_STAGE(PG8_SB(0, 1), cB + hstep, voffB); PG8_STAGE(PG8_SA(0, 0), cA, voffA); PG8_STAGE(PG8_SA(0, 1), cA + hstep, voffA);
;         if (wr == 1) PG8_BAR;
;         PG8_WAIT_V(2); PG8_BAR;
;         PG8_STAGE(PG8_SB(1, 0), cB + kstep, voffB); PG8_STAGE(PG8_SA(1, 0), cA + kstep, voffA); PG8_STAGE(PG8_SB(1, 1), cB + hstep + kstep, voffB);
;         PG8_WAIT_V(6); PG8_BAR;
;     } else {
;         PG8_STAGE(PG8_SB(0, 0), cB, voffB); PG8_STAGE(PG8_SA(0, 0), cA, voffA); PG8_STAGE(PG8_SB(0, 1), cB + hstep, voffB); PG8_STAGE(PG8_SA(0, 1), cA + hstep, voffA);
;         if (wr == 1) PG8_BAR;
;         PG8_WAIT_V(4); PG8_BAR;
.LBB0_1029:
	v_ashrrev_i32_e32 v1, 31, v8
	v_lshrrev_b32_e32 v1, 26, v1
	v_add_u32_e32 v1, v8, v1
	v_ashrrev_i32_e32 v9, 6, v1
	v_bfe_i32 v1, v8, 27, 1
	v_lshlrev_b32_e32 v0, 4, v8
	v_lshrrev_b32_e32 v1, 22, v1
	v_add_u32_e32 v1, v0, v1
	v_and_b32_e32 v1, 0xfffffc00, v1
	v_sub_u32_e32 v1, v0, v1
	v_lshrrev_b32_e32 v2, 4, v1
	v_bitop3_b32 v1, v2, v1, 32 bitop3:0x6c
	v_ashrrev_i32_e32 v3, 31, v1
	v_lshrrev_b32_e32 v3, 26, v3
	v_add_u32_e32 v3, v1, v3
	v_lshlrev_b32_e32 v2, 3, v9
	v_ashrrev_i32_e32 v10, 6, v3
	v_and_b32_e32 v3, 0xc0, v3
	v_and_b32_e32 v2, -16, v2
	v_sub_u32_e32 v1, v1, v3
	v_mov_b32_e32 v6, 1
	v_add_u32_e32 v2, v10, v2
	v_ashrrev_i16_sdwa v1, v6, sext(v1) dst_sel:DWORD dst_unused:UNUSED_PAD src0_sel:DWORD src1_sel:BYTE_0
	v_lshlrev_b32_e32 v4, 5, v9
	v_bfe_i32 v11, v1, 0, 16
	v_lshlrev_b32_e32 v1, 1, v2
	v_lshrrev_b32_e32 v3, 2, v2
	v_and_b32_e32 v4, 32, v4
	v_and_b32_e32 v1, 24, v1
	v_and_b32_e32 v3, 4, v3
	v_and_b32_e32 v5, 0xfffe3, v2
	v_or3_b32 v1, v5, v3, v1
	v_add_lshl_u32 v3, v4, v11, 1
	v_add_u32_e32 v0, 0x2000, v0
	v_lshl_add_u32 v204, v1, 12, v3
	v_ashrrev_i32_e32 v1, 31, v0
	s_add_u32 s10, s36, 0x31000000
	v_lshrrev_b32_e32 v1, 22, v1
	s_addc_u32 s19, s37, 0
	s_lshl_b64 s[26:27], s[34:35], 23
	v_add_u32_e32 v1, v0, v1
	s_add_u32 s3, s36, s26
	v_ashrrev_i32_e32 v12, 10, v1
	s_addc_u32 s7, s37, s27
	v_mul_i32_i24_e32 v1, 0x400, v12
	s_add_u32 s62, s3, 0x24800000
	v_sub_u32_e32 v0, v0, v1
	s_addc_u32 s63, s7, 0
	s_ashr_i32 s3, s2, 31
	v_lshrrev_b32_e32 v1, 4, v0
	s_lshl_b64 s[26:27], s[2:3], 20
	v_bitop3_b32 v0, v1, v0, 32 bitop3:0x6c
	s_add_u32 s28, s10, s26
	v_lshl_add_u32 v202, v2, 12, v3
	v_ashrrev_i32_e32 v2, 31, v0
	s_addc_u32 s29, s19, s27
	v_readlane_b32 s26, v254, 36
	v_lshrrev_b32_e32 v2, 26, v2
	v_readlane_b32 s27, v254, 37
	v_add_u32_e32 v2, v0, v2
	s_mov_b32 s30, s26
	s_ashr_i32 s31, s26, 31
	v_writelane_b32 v254, s26, 36
	v_lshlrev_b32_e32 v1, 3, v12
	v_ashrrev_i32_e32 v13, 6, v2
	v_and_b32_e32 v2, 0xc0, v2
	v_writelane_b32 v254, s27, 37
	s_lshl_b64 s[26:27], s[30:31], 20
	v_and_b32_e32 v1, -16, v1
	v_sub_u32_e32 v0, v0, v2
	s_add_u32 s30, s62, s26
	v_add_u32_e32 v1, v13, v1
	v_ashrrev_i16_sdwa v0, v6, sext(v0) dst_sel:DWORD dst_unused:UNUSED_PAD src0_sel:DWORD src1_sel:BYTE_0
	s_addc_u32 s31, s63, s27
	v_lshlrev_b32_e32 v3, 5, v12
	v_bfe_i32 v14, v0, 0, 16
	v_lshlrev_b32_e32 v0, 1, v1
	v_lshrrev_b32_e32 v2, 2, v1
	s_add_i32 s64, s8, 0
	v_and_b32_e32 v3, 32, v3
	v_and_b32_e32 v0, 24, v0
	v_and_b32_e32 v2, 4, v2
	v_and_b32_e32 v4, 0xfffe3, v1
	s_add_i32 m0, s64, 0x10000
	v_or3_b32 v0, v4, v2, v0
	v_add_lshl_u32 v2, v3, v14, 1
	s_ashr_i32 s35, s38, 8
	global_load_lds_dwordx4 v204, s[30:31]
	s_add_i32 m0, s64, 0x12000
	v_lshl_add_u32 v216, v0, 12, v2
	s_add_u32 s26, s30, 0x80000
	global_load_lds_dwordx4 v216, s[30:31]
	s_addc_u32 s27, s31, 0
	s_add_i32 m0, s64, 0x14000
	s_add_i32 s65, s64, 0x2000
	global_load_lds_dwordx4 v204, s[26:27]
	s_add_i32 m0, s64, 0x16000
	v_lshl_add_u32 v214, v1, 12, v2
	global_load_lds_dwordx4 v216, s[26:27]
	s_mov_b32 m0, s64
	s_add_u32 s26, s28, 0x80000
	global_load_lds_dwordx4 v202, s[28:29]
	s_mov_b32 m0, s65
	s_addc_u32 s27, s29, 0
	s_add_i32 s66, s64, 0x4000
	global_load_lds_dwordx4 v214, s[28:29]
	s_mov_b32 m0, s66
	s_add_i32 s67, s64, 0x6000
	global_load_lds_dwordx4 v202, s[26:27]
	s_mov_b32 m0, s67
	v_writelane_b32 v255, s42, 22
	global_load_lds_dwordx4 v214, s[26:27]
	v_mov_b32_e32 v205, v20
	v_mov_b32_e32 v217, v20
	v_mov_b32_e32 v203, v20
	v_mov_b32_e32 v215, v20
	s_cmp_eq_u32 s35, 1
	v_writelane_b32 v255, s43, 23
	v_lshl_add_u64 v[6:7], s[30:31], 0, v[204:205]
	v_lshl_add_u64 v[4:5], s[30:31], 0, v[216:217]
	v_lshl_add_u64 v[0:1], s[28:29], 0, v[202:203]
	s_cselect_b64 s[26:27], -1, 0
	s_cmp_lg_u32 s35, 1
	v_lshl_add_u64 v[2:3], s[28:29], 0, v[214:215]
	s_cbranch_scc1 .LBB0_1031
.LBB0_1031:
	s_ashr_i32 s7, s6, 31
	s_lshl_b64 s[40:41], s[6:7], 26
	s_add_u32 s3, s36, s40
	s_addc_u32 s7, s37, s41
	s_add_u32 s42, s3, 0x53200000
	s_mul_i32 s3, s34, 3
	s_addc_u32 s43, s7, 0
	s_add_i32 s6, s3, s6
	s_bitcmp0_b32 s6, 0
	s_mov_b32 s7, 0x4f200000
	s_cselect_b32 s7, 0x28000000, s7
	s_add_u32 s44, s36, s7
	s_addc_u32 s45, s37, 0
	s_add_u32 s68, s36, 0x6a200000
	s_addc_u32 s69, s37, 0
	s_add_u32 s70, s36, 0x80000
	s_addc_u32 s71, s37, 0
	s_lshl_b32 s6, s6, 5
	s_add_i32 s72, s6, 32
	s_add_u32 s6, s36, 0x84000
	s_addc_u32 s7, s37, 0
	v_writelane_b32 v255, s6, 26
	v_and_b32_e32 v15, 48, v8
	v_lshlrev_b32_e32 v16, 6, v8
	v_writelane_b32 v255, s7, 27
	s_movk_i32 s7, 0x3c0
	v_lshlrev_b32_e32 v8, 2, v8
	s_and_b32 s34, s39, 3
	s_lshl_b32 s6, s35, 13
	v_and_or_b32 v15, v16, s7, v15
	v_and_b32_e32 v8, 32, v8
	s_add_i32 m0, s64, 0x18000
	v_lshl_add_u64 v[6:7], v[6:7], 0, s[12:13]
	s_lshl_b32 s73, s35, 6
	v_bitop3_b32 v16, v15, s6, v8 bitop3:0xde
	s_lshl_b32 s74, s34, 5
	s_lshl_b32 s6, s34, 12
	s_waitcnt vmcnt(2)
	s_barrier
	global_load_lds_dwordx4 v[6:7], off
	v_lshl_add_u64 v[4:5], v[4:5], 0, s[12:13]
	s_add_i32 m0, s64, 0x1a000
	s_add_i32 s75, s64, 0x8000
	s_add_i32 s76, s64, 0xa000
	v_bitop3_b32 v21, v15, s6, v8 bitop3:0xde
	global_load_lds_dwordx4 v[4:5], off
	v_lshl_add_u64 v[0:1], v[0:1], 0, s[12:13]
	s_mov_b32 m0, s75
	s_add_u32 s100, s28, 0x80
	s_addc_u32 s101, s29, 0
	s_add_u32 s6, s30, 0x80080
	global_load_lds_dwordx4 v[0:1], off
	v_lshl_add_u64 v[0:1], v[2:3], 0, s[12:13]
	s_mov_b32 m0, s76
	s_addc_u32 s7, s31, 0
	global_load_lds_dwordx4 v[0:1], off
	s_add_i32 m0, s64, 0x1c000
	v_lshl_add_u64 v[0:1], s[6:7], 0, v[204:205]
	global_load_lds_dwordx4 v[0:1], off
	v_lshl_add_u64 v[0:1], s[6:7], 0, v[216:217]
	s_add_i32 m0, s64, 0x1e000
	v_readlane_b32 s6, v254, 55
	global_load_lds_dwordx4 v[0:1], off
	s_mov_b32 s7, s6
	s_add_i32 s77, s6, s8
	s_lshl_b32 s6, s34, 7
	s_add_i32 s78, s7, s6
	s_cmpk_lt_u32 s38, 0x100
	s_cselect_b64 s[48:49], -1, 0
	s_cmp_lg_u32 s39, 1
	s_cselect_b64 s[50:51], -1, 0
	s_cmp_eq_u32 s39, 2
	s_movk_i32 s6, 0x2000
	s_cselect_b32 s6, s6, 0x1800
	s_lshl_b32 s7, s35, 2
	s_lshl_b32 s36, s34, 2
	s_add_i32 s79, s36, 0
	s_or_b32 s7, s7, s34
	v_lshlrev_b32_e32 v0, 15, v9
	s_add_i32 s79, s79, 0x24400
	s_lshl_b32 s80, s7, 6
	v_and_b32_e32 v0, 0xffff0000, v0
	s_cmp_lt_i32 s7, 4
	v_lshl_add_u32 v0, v10, 12, v0
	v_and_b32_e32 v1, 1, v9
	s_cselect_b64 s[52:53], -1, 0
	s_cmp_eq_u32 s7, 0
	v_lshl_or_b32 v0, v1, 6, v0
	s_cselect_b64 s[54:55], -1, 0
	s_lshl_b32 s7, s35, 8
	v_lshl_add_u32 v218, v11, 1, v0
	v_lshlrev_b32_e32 v0, 15, v12
	s_add_i32 s81, s7, 0
	v_and_b32_e32 v0, 0xffff0000, v0
	s_waitcnt vmcnt(6)
	s_add_i32 s81, s81, 0x25400
	v_lshl_add_u32 v0, v13, 12, v0
	v_and_b32_e32 v1, 1, v12
	s_cmp_gt_u32 s38, 63
	v_lshl_or_b32 v0, v1, 6, v0
	s_mov_b32 s3, 0
	s_cselect_b32 s83, s6, 0x1000
	v_mov_b32_e32 v219, v20
	v_lshl_add_u32 v220, v14, 1, v0
	v_mov_b32_e32 v221, v20
	v_add_u32_e32 v208, 0, v16
	s_barrier
	s_branch .LBB0_1034

; #define PG8_STAGE(bufoff, gbase, voff) do { _Pragma("unroll") for (int _i = 0; _i < 2; ++_i) \
;         __builtin_amdgcn_global_load_lds((const unsigned*)((const char*)(gbase) + (voff)[_i]), (PG8_LAS unsigned*)(lds + (bufoff) + ldsw + _i * 8192), 16, 0, 0); } while (0)
; #define PG8_LDA(dst, b, h) do { _Pragma("unroll") for (int m = 0; m < 4; ++m) _Pragma("unroll") for (int k = 0; k < 2; ++k) dst[m][k] = *(const PG8_LAS bf16x8*)(lds + PG8_SA(b, h) + aoff + m * 2048 + k * 1024); } while (0)
; #define PG8_LDB(dst, b, h) do { _Pragma("unroll") for (int n = 0; n < 2; ++n) _Pragma("unroll") for (int k = 0; k < 2; ++k) dst[n][k] = *(const PG8_LAS bf16x8*)(lds + PG8_SB(b, h) + boff + n * 2048 + k * 1024); } while (0)
; #define PG8_WAIT_V(n) asm volatile("s_waitcnt vmcnt(" #n ")" ::: "memory")
; #define PG8_WAIT_L(n) asm volatile("s_waitcnt lgkmcnt(" #n ")" ::: "memory")
; template <class Epi, class Sched, bool ALIGN_EPI = false, bool SP2 = false>
; __device__ __forceinline__ void gemm_phase(PG8_LAS unsigned char* lds, const Gemm g, const Sched& S, const Epi& E, const int tid_in) {
;     ...
;     for (;;) {
;         const bool has_next = S.next(ui + 1, nxt);
;         const char* nA = has_next ? (const char*)g.A + (size_t)nxt.pm * tstep : cA; const char* nB = has_next ? (const char*)g.Bt + (size_t)nxt.pn * tstep : cB;
;         for (int t = 0; t < nt; t += 2) {
;             if constexpr (Epi::KSPLIT > 0) { if (t == Epi::KSPLIT / BK) E.midk(acc, cur, wr, wc, fr, fq); }
;             const bool last = (t == nt - 2);
;             const char* a1 = cA + (size_t)(t + 1) * kstep;
;             const char* a2 = last ? nA : cA + (size_t)(t + 2) * kstep; const char* b2 = last ? nB : cB + (size_t)(t + 2) * kstep;
;             const char* a3 = a2 + kstep; const char* b3 = b2 + kstep;
;             if (last && has_next) S.a_ready(nxt);
;             if constexpr (SP2) {
;             PG8_LDB(B0, 0, 0); PG8_LDB(B1, 0, 1); PG8_SCHED; PG8_LDA(At, 0, 0); PG8_STAGE(PG8_SA(1, 1), a1 + hstep, voffA);
;             PG8_WAIT_V(8); PG8_WAIT_L(0); PG8_BAR; PG8_MMA(0, 0, At, B0); PG8_MMA(0, 1, At, B1); PG8_BAR; PG8_SCHED;
;             PG8_LDA(At, 0, 1); PG8_STAGE(PG8_SB(0, 0), b2, voffB); PG8_STAGE(PG8_SB(0, 1), b2 + hstep, voffB); PG8_STAGE(PG8_SA(0, 0), a2, voffA);
;             PG8_WAIT_V(8); PG8_WAIT_L(0); PG8_BAR; PG8_MMA(1, 0, At, B0); PG8_MMA(1, 1, At, B1); PG8_BAR; PG8_SCHED;
.LBB0_1036:
	s_ashr_i32 s57, s56, 31
	s_lshl_b64 s[34:35], s[56:57], 20
	s_add_u32 s36, s10, s34
	s_addc_u32 s37, s19, s35
	s_and_b64 s[34:35], exec, s[6:7]
	v_readlane_b32 s34, v254, 36
	v_readlane_b32 s35, v254, 37
	s_cselect_b32 s38, s29, s37
	s_cselect_b32 s39, s28, s36
	s_mov_b32 s40, s34
	s_ashr_i32 s41, s34, 31
	v_writelane_b32 v254, s34, 36
	v_mov_b32_e32 v0, 0
	s_mov_b32 vcc_lo, -2
	v_writelane_b32 v254, s35, 37
	s_lshl_b64 s[34:35], s[40:41], 20
	s_add_u32 s60, s62, s34
	s_addc_u32 s61, s63, s35
	s_and_b64 s[34:35], exec, s[6:7]
	s_cselect_b32 s40, s31, s61
	s_cselect_b32 s41, s30, s60
	s_add_u32 s28, s28, 0x80080
	s_addc_u32 s29, s29, 0
	s_add_u32 s57, s30, 0x100
	s_addc_u32 s92, s31, 0
	s_cmp_lt_u32 s8, 0x1000
	s_cbranch_scc1 .LCB_1037
	s_barrier
.LCB_1037:
	s_mov_b32 m0, s76
	s_nop 0
	global_load_lds_dwordx4 v214, s[100:101]
	s_add_u32 s30, s28, 0xfff80080
	s_addc_u32 s31, s29, -1
	s_add_i32 s46, 0, 0x10000
	s_cmp_eq_u32 vcc_lo, 28
	s_cselect_b32 s35, s38, s31
	s_cselect_b32 s34, s39, s30
	s_cselect_b32 s31, s40, s92
	s_cselect_b32 s30, s41, s57
	s_add_i32 vcc_hi, 0, 0x14000
	v_add_u32_e32 v142, s46, v21
	v_add_u32_e32 v158, vcc_hi, v21
	ds_read_b128 v[130:133], v142
	ds_read_b128 v[134:137], v142 offset:1024
	ds_read_b128 v[138:141], v142 offset:2048
	ds_read_b128 v[142:145], v142 offset:3072
	ds_read_b128 v[146:149], v158
	ds_read_b128 v[150:153], v158 offset:1024
	ds_read_b128 v[154:157], v158 offset:2048
	ds_read_b128 v[158:161], v158 offset:3072
	s_add_i32 m0, s64, 0xc000
	ds_read_b128 v[162:165], v208
	ds_read_b128 v[166:169], v208 offset:1024
	ds_read_b128 v[170:173], v208 offset:2048
	ds_read_b128 v[174:177], v208 offset:3072
	ds_read_b128 v[178:181], v208 offset:4096
	ds_read_b128 v[182:185], v208 offset:5120
	ds_read_b128 v[186:189], v208 offset:6144
	ds_read_b128 v[190:193], v208 offset:7168
	global_load_lds_dwordx4 v218, s[28:29]
	s_add_i32 m0, s64, 0xe000
	s_nop 0
	global_load_lds_dwordx4 v220, s[28:29]
	s_waitcnt vmcnt(8)
	s_waitcnt lgkmcnt(0)
	s_barrier
	s_setprio 1
	v_mfma_f32_16x16x32_bf16 v[126:129], v[130:133], v[162:165], 0
	v_mfma_f32_16x16x32_bf16 v[122:125], v[138:141], v[162:165], 0
	v_mfma_f32_16x16x32_bf16 v[110:113], v[130:133], v[170:173], 0
	v_mfma_f32_16x16x32_bf16 v[106:109], v[138:141], v[170:173], 0
	v_mfma_f32_16x16x32_bf16 v[94:97], v[130:133], v[178:181], 0
	v_mfma_f32_16x16x32_bf16 v[90:93], v[138:141], v[178:181], 0
	v_mfma_f32_16x16x32_bf16 v[78:81], v[130:133], v[186:189], 0
	v_mfma_f32_16x16x32_bf16 v[74:77], v[138:141], v[186:189], 0
	v_mfma_f32_16x16x32_bf16 v[126:129], v[134:137], v[166:169], v[126:129]
	v_mfma_f32_16x16x32_bf16 v[122:125], v[142:145], v[166:169], v[122:125]
	v_mfma_f32_16x16x32_bf16 v[110:113], v[134:137], v[174:177], v[110:113]
	v_mfma_f32_16x16x32_bf16 v[106:109], v[142:145], v[174:177], v[106:109]
	v_mfma_f32_16x16x32_bf16 v[94:97], v[134:137], v[182:185], v[94:97]
	v_mfma_f32_16x16x32_bf16 v[90:93], v[142:145], v[182:185], v[90:93]
	v_mfma_f32_16x16x32_bf16 v[78:81], v[134:137], v[190:193], v[78:81]
	v_mfma_f32_16x16x32_bf16 v[74:77], v[142:145], v[190:193], v[74:77]
	s_setprio 0
	s_setprio 1
	v_mfma_f32_16x16x32_bf16 v[118:121], v[146:149], v[162:165], 0
	v_mfma_f32_16x16x32_bf16 v[114:117], v[154:157], v[162:165], 0
	v_mfma_f32_16x16x32_bf16 v[102:105], v[146:149], v[170:173], 0
	v_mfma_f32_16x16x32_bf16 v[98:101], v[154:157], v[170:173], 0
	v_mfma_f32_16x16x32_bf16 v[86:89], v[146:149], v[178:181], 0
	v_mfma_f32_16x16x32_bf16 v[82:85], v[154:157], v[178:181], 0
	v_mfma_f32_16x16x32_bf16 v[70:73], v[146:149], v[186:189], 0
	v_mfma_f32_16x16x32_bf16 v[66:69], v[154:157], v[186:189], 0
	v_mfma_f32_16x16x32_bf16 v[118:121], v[150:153], v[166:169], v[118:121]
	v_mfma_f32_16x16x32_bf16 v[114:117], v[158:161], v[166:169], v[114:117]
	v_mfma_f32_16x16x32_bf16 v[102:105], v[150:153], v[174:177], v[102:105]
	v_mfma_f32_16x16x32_bf16 v[98:101], v[158:161], v[174:177], v[98:101]
	v_mfma_f32_16x16x32_bf16 v[86:89], v[150:153], v[182:185], v[86:89]
	v_mfma_f32_16x16x32_bf16 v[82:85], v[158:161], v[182:185], v[82:85]
	v_mfma_f32_16x16x32_bf16 v[70:73], v[150:153], v[190:193], v[70:73]
	v_mfma_f32_16x16x32_bf16 v[66:69], v[158:161], v[190:193], v[66:69]
	s_setprio 0
	s_barrier
	s_add_i32 s46, s46, s8
	s_add_u32 s98, s30, 0x80
	s_addc_u32 s99, s31, 0
	s_mov_b32 m0, s46
	ds_read_b128 v[162:165], v208 offset:16384
	ds_read_b128 v[166:169], v208 offset:17408
	ds_read_b128 v[170:173], v208 offset:18432
	ds_read_b128 v[174:177], v208 offset:19456
	ds_read_b128 v[178:181], v208 offset:20480
	ds_read_b128 v[182:185], v208 offset:21504
	ds_read_b128 v[186:189], v208 offset:22528
	ds_read_b128 v[190:193], v208 offset:23552
	global_load_lds_dwordx4 v204, s[30:31]
	s_add_i32 m0, s46, 0x2000
	s_add_u32 s46, s30, 0x80000
	s_addc_u32 s47, s31, 0
	s_add_i32 vcc_hi, vcc_hi, s8
	global_load_lds_dwordx4 v216, s[30:31]
	s_mov_b32 m0, vcc_hi
	s_add_u32 s100, s34, 0x80
	s_addc_u32 s101, s35, 0
	global_load_lds_dwordx4 v204, s[46:47]
	s_add_i32 m0, vcc_hi, 0x2000
	s_nop 0
	global_load_lds_dwordx4 v216, s[46:47]
	s_mov_b32 m0, s64
	s_nop 0
	global_load_lds_dwordx4 v202, s[34:35]
	s_waitcnt vmcnt(7)
	s_waitcnt lgkmcnt(0)
	s_barrier
; #define PG8_STAGE(bufoff, gbase, voff) do { _Pragma("unroll") for (int _i = 0; _i < 2; ++_i) \
;         __builtin_amdgcn_global_load_lds((const unsigned*)((const char*)(gbase) + (voff)[_i]), (PG8_LAS unsigned*)(lds + (bufoff) + ldsw + _i * 8192), 16, 0, 0); } while (0)
; #define PG8_LDA(dst, b, h) do { _Pragma("unroll") for (int m = 0; m < 4; ++m) _Pragma("unroll") for (int k = 0; k < 2; ++k) dst[m][k] = *(const PG8_LAS bf16x8*)(lds + PG8_SA(b, h) + aoff + m * 2048 + k * 1024); } while (0)
; #define PG8_LDB(dst, b, h) do { _Pragma("unroll") for (int n = 0; n < 2; ++n) _Pragma("unroll") for (int k = 0; k < 2; ++k) dst[n][k] = *(const PG8_LAS bf16x8*)(lds + PG8_SB(b, h) + boff + n * 2048 + k * 1024); } while (0)
; #define PG8_MMA(ai, bj, At, Bt) do { __builtin_amdgcn_s_setprio(1); _Pragma("unroll") for (int m = 0; m < 4; ++m) _Pragma("unroll") for (int n = 0; n < 2; ++n) _Pragma("unroll") for (int k = 0; k < 2; ++k) \
;         acc[ai][bj][m][n] = __builtin_amdgcn_mfma_f32_16x16x32_bf16(Bt[n][k], At[m][k], acc[ai][bj][m][n], 0, 0, 0); __builtin_amdgcn_s_setprio(0); } while (0)
; #define PG8_BAR __builtin_amdgcn_s_barrier()
; template <class Epi, class Sched, bool ALIGN_EPI = false, bool SP2 = false>
; __device__ __forceinline__ void gemm_phase(PG8_LAS unsigned char* lds, const Gemm g, const Sched& S, const Epi& E, const int tid_in) {
;     ...
;             PG8_LDB(B0, 0, 0); PG8_LDB(B1, 0, 1); PG8_SCHED; PG8_LDA(At, 0, 0); PG8_STAGE(PG8_SA(1, 1), a1 + hstep, voffA);
;             PG8_WAIT_V(8); PG8_WAIT_L(0); PG8_BAR; PG8_MMA(0, 0, At, B0); PG8_MMA(0, 1, At, B1); PG8_BAR; PG8_SCHED;
;             PG8_LDA(At, 0, 1); PG8_STAGE(PG8_SB(0, 0), b2, voffB); PG8_STAGE(PG8_SB(0, 1), b2 + hstep, voffB); PG8_STAGE(PG8_SA(0, 0), a2, voffA);
;             PG8_WAIT_V(8); PG8_WAIT_L(0); PG8_BAR; PG8_MMA(1, 0, At, B0); PG8_MMA(1, 1, At, B1); PG8_BAR; PG8_SCHED;
;             PG8_LDB(B0, 1, 0); PG8_LDB(B1, 1, 1); PG8_SCHED; PG8_LDA(At, 1, 0); PG8_STAGE(PG8_SA(0, 1), a2 + hstep, voffA);
;             PG8_WAIT_V(8); PG8_WAIT_L(0); PG8_BAR; PG8_MMA(0, 0, At, B0); PG8_MMA(0, 1, At, B1); PG8_BAR; PG8_SCHED;
;             PG8_LDA(At, 1, 1); PG8_STAGE(PG8_SB(1, 0), b3, voffB); PG8_STAGE(PG8_SB(1, 1), b3 + hstep, voffB); PG8_STAGE(PG8_SA(1, 0), a3, voffA);
;             PG8_WAIT_V(8); PG8_WAIT_L(0); PG8_BAR; PG8_MMA(1, 0, At, B0); PG8_MMA(1, 1, At, B1); PG8_BAR; PG8_SCHED;
	s_setprio 1
	v_mfma_f32_16x16x32_bf16 v[62:65], v[130:133], v[162:165], 0
	v_mfma_f32_16x16x32_bf16 v[58:61], v[138:141], v[162:165], 0
	v_mfma_f32_16x16x32_bf16 v[46:49], v[130:133], v[170:173], 0
	v_mfma_f32_16x16x32_bf16 v[42:45], v[138:141], v[170:173], 0
	v_mfma_f32_16x16x32_bf16 v[30:33], v[130:133], v[178:181], 0
	v_mfma_f32_16x16x32_bf16 v[26:29], v[138:141], v[178:181], 0
	v_mfma_f32_16x16x32_bf16 v[12:15], v[130:133], v[186:189], 0
	v_mfma_f32_16x16x32_bf16 v[8:11], v[138:141], v[186:189], 0
	v_mfma_f32_16x16x32_bf16 v[62:65], v[134:137], v[166:169], v[62:65]
	v_mfma_f32_16x16x32_bf16 v[58:61], v[142:145], v[166:169], v[58:61]
	v_mfma_f32_16x16x32_bf16 v[46:49], v[134:137], v[174:177], v[46:49]
	v_mfma_f32_16x16x32_bf16 v[42:45], v[142:145], v[174:177], v[42:45]
	v_mfma_f32_16x16x32_bf16 v[30:33], v[134:137], v[182:185], v[30:33]
	v_mfma_f32_16x16x32_bf16 v[26:29], v[142:145], v[182:185], v[26:29]
	v_mfma_f32_16x16x32_bf16 v[12:15], v[134:137], v[190:193], v[12:15]
	v_mfma_f32_16x16x32_bf16 v[8:11], v[142:145], v[190:193], v[8:11]
	s_setprio 0
	s_setprio 1
	v_mfma_f32_16x16x32_bf16 v[54:57], v[146:149], v[162:165], 0
	v_mfma_f32_16x16x32_bf16 v[50:53], v[154:157], v[162:165], 0
	v_mfma_f32_16x16x32_bf16 v[38:41], v[146:149], v[170:173], 0
	v_mfma_f32_16x16x32_bf16 v[34:37], v[154:157], v[170:173], 0
	v_mfma_f32_16x16x32_bf16 v[22:25], v[146:149], v[178:181], 0
	v_mfma_f32_16x16x32_bf16 v[16:19], v[154:157], v[178:181], 0
	v_mfma_f32_16x16x32_bf16 v[4:7], v[146:149], v[186:189], 0
	v_mfma_f32_16x16x32_bf16 v[0:3], v[154:157], v[186:189], 0
	v_mfma_f32_16x16x32_bf16 v[54:57], v[150:153], v[166:169], v[54:57]
	v_mfma_f32_16x16x32_bf16 v[50:53], v[158:161], v[166:169], v[50:53]
	v_mfma_f32_16x16x32_bf16 v[38:41], v[150:153], v[174:177], v[38:41]
	v_mfma_f32_16x16x32_bf16 v[34:37], v[158:161], v[174:177], v[34:37]
	v_mfma_f32_16x16x32_bf16 v[22:25], v[150:153], v[182:185], v[22:25]
	v_mfma_f32_16x16x32_bf16 v[16:19], v[158:161], v[182:185], v[16:19]
	v_mfma_f32_16x16x32_bf16 v[4:7], v[150:153], v[190:193], v[4:7]
	v_mfma_f32_16x16x32_bf16 v[0:3], v[158:161], v[190:193], v[0:3]
	s_setprio 0
	s_barrier
	s_add_i32 s46, 0, 0x18000
	s_add_i32 s47, 0, 0x1c000
	v_add_u32_e32 v142, s46, v21
	v_add_u32_e32 v158, s47, v21
	ds_read_b128 v[130:133], v142
	ds_read_b128 v[134:137], v142 offset:1024
	ds_read_b128 v[138:141], v142 offset:2048
	ds_read_b128 v[142:145], v142 offset:3072
	ds_read_b128 v[146:149], v158
	ds_read_b128 v[150:153], v158 offset:1024
	ds_read_b128 v[154:157], v158 offset:2048
	ds_read_b128 v[158:161], v158 offset:3072
	s_mov_b32 m0, s65
	s_nop 0
	global_load_lds_dwordx4 v214, s[34:35]
	s_add_u32 s34, s34, 0x80000
	s_addc_u32 s35, s35, 0
	s_mov_b32 m0, s66
	ds_read_b128 v[162:165], v208 offset:32768
	ds_read_b128 v[166:169], v208 offset:33792
	ds_read_b128 v[170:173], v208 offset:34816
	ds_read_b128 v[174:177], v208 offset:35840
	ds_read_b128 v[178:181], v208 offset:36864
	ds_read_b128 v[182:185], v208 offset:37888
	ds_read_b128 v[186:189], v208 offset:38912
	ds_read_b128 v[190:193], v208 offset:39936
	global_load_lds_dwordx4 v202, s[34:35]
	s_mov_b32 m0, s67
	s_nop 0
	global_load_lds_dwordx4 v214, s[34:35]
	s_waitcnt vmcnt(8)
	s_waitcnt lgkmcnt(0)
	s_barrier
	s_setprio 1
	v_mfma_f32_16x16x32_bf16 v[126:129], v[130:133], v[162:165], v[126:129]
	v_mfma_f32_16x16x32_bf16 v[122:125], v[138:141], v[162:165], v[122:125]
	v_mfma_f32_16x16x32_bf16 v[110:113], v[130:133], v[170:173], v[110:113]
	v_mfma_f32_16x16x32_bf16 v[106:109], v[138:141], v[170:173], v[106:109]
	v_mfma_f32_16x16x32_bf16 v[94:97], v[130:133], v[178:181], v[94:97]
	v_mfma_f32_16x16x32_bf16 v[90:93], v[138:141], v[178:181], v[90:93]
	v_mfma_f32_16x16x32_bf16 v[78:81], v[130:133], v[186:189], v[78:81]
	v_mfma_f32_16x16x32_bf16 v[74:77], v[138:141], v[186:189], v[74:77]
	v_mfma_f32_16x16x32_bf16 v[126:129], v[134:137], v[166:169], v[126:129]
	v_mfma_f32_16x16x32_bf16 v[122:125], v[142:145], v[166:169], v[122:125]
	v_mfma_f32_16x16x32_bf16 v[110:113], v[134:137], v[174:177], v[110:113]
	v_mfma_f32_16x16x32_bf16 v[106:109], v[142:145], v[174:177], v[106:109]
	v_mfma_f32_16x16x32_bf16 v[94:97], v[134:137], v[182:185], v[94:97]
	v_mfma_f32_16x16x32_bf16 v[90:93], v[142:145], v[182:185], v[90:93]
	v_mfma_f32_16x16x32_bf16 v[78:81], v[134:137], v[190:193], v[78:81]
	v_mfma_f32_16x16x32_bf16 v[74:77], v[142:145], v[190:193], v[74:77]
	s_setprio 0
	s_setprio 1
	v_mfma_f32_16x16x32_bf16 v[118:121], v[146:149], v[162:165], v[118:121]
	v_mfma_f32_16x16x32_bf16 v[114:117], v[154:157], v[162:165], v[114:117]
	v_mfma_f32_16x16x32_bf16 v[102:105], v[146:149], v[170:173], v[102:105]
	v_mfma_f32_16x16x32_bf16 v[98:101], v[154:157], v[170:173], v[98:101]
	v_mfma_f32_16x16x32_bf16 v[86:89], v[146:149], v[178:181], v[86:89]
	v_mfma_f32_16x16x32_bf16 v[82:85], v[154:157], v[178:181], v[82:85]
	v_mfma_f32_16x16x32_bf16 v[70:73], v[146:149], v[186:189], v[70:73]
	v_mfma_f32_16x16x32_bf16 v[66:69], v[154:157], v[186:189], v[66:69]
	v_mfma_f32_16x16x32_bf16 v[118:121], v[150:153], v[166:169], v[118:121]
	v_mfma_f32_16x16x32_bf16 v[114:117], v[158:161], v[166:169], v[114:117]
	v_mfma_f32_16x16x32_bf16 v[102:105], v[150:153], v[174:177], v[102:105]
	v_mfma_f32_16x16x32_bf16 v[98:101], v[158:161], v[174:177], v[98:101]
	v_mfma_f32_16x16x32_bf16 v[86:89], v[150:153], v[182:185], v[86:89]
	v_mfma_f32_16x16x32_bf16 v[82:85], v[158:161], v[182:185], v[82:85]
	v_mfma_f32_16x16x32_bf16 v[70:73], v[150:153], v[190:193], v[70:73]
	v_mfma_f32_16x16x32_bf16 v[66:69], v[158:161], v[190:193], v[66:69]
	s_setprio 0
	s_barrier
; #define PG8_STAGE(bufoff, gbase, voff) do { _Pragma("unroll") for (int _i = 0; _i < 2; ++_i) \
;         __builtin_amdgcn_global_load_lds((const unsigned*)((const char*)(gbase) + (voff)[_i]), (PG8_LAS unsigned*)(lds + (bufoff) + ldsw + _i * 8192), 16, 0, 0); } while (0)
; #define PG8_LDA(dst, b, h) do { _Pragma("unroll") for (int m = 0; m < 4; ++m) _Pragma("unroll") for (int k = 0; k < 2; ++k) dst[m][k] = *(const PG8_LAS bf16x8*)(lds + PG8_SA(b, h) + aoff + m * 2048 + k * 1024); } while (0)
; #define PG8_WAIT_V(n) asm volatile("s_waitcnt vmcnt(" #n ")" ::: "memory")
; template <class Epi, class Sched, bool ALIGN_EPI = false, bool SP2 = false>
; __device__ __forceinline__ void gemm_phase(PG8_LAS unsigned char* lds, const Gemm g, const Sched& S, const Epi& E, const int tid_in) {
;     ...
;         for (int t = 0; t < nt; t += 2) {
;             if constexpr (Epi::KSPLIT > 0) { if (t == Epi::KSPLIT / BK) E.midk(acc, cur, wr, wc, fr, fq); }
;             const bool last = (t == nt - 2);
;             const char* a1 = cA + (size_t)(t + 1) * kstep;
;             const char* a2 = last ? nA : cA + (size_t)(t + 2) * kstep; const char* b2 = last ? nB : cB + (size_t)(t + 2) * kstep;
;             const char* a3 = a2 + kstep; const char* b3 = b2 + kstep;
;             if (last && has_next) S.a_ready(nxt);
;             if constexpr (SP2) {
;             PG8_LDB(B0, 0, 0); PG8_LDB(B1, 0, 1); PG8_SCHED; PG8_LDA(At, 0, 0); PG8_STAGE(PG8_SA(1, 1), a1 + hstep, voffA);
;             PG8_WAIT_V(8); PG8_WAIT_L(0); PG8_BAR; PG8_MMA(0, 0, At, B0); PG8_MMA(0, 1, At, B1); PG8_BAR; PG8_SCHED;
;             PG8_LDA(At, 0, 1); PG8_STAGE(PG8_SB(0, 0), b2, voffB); PG8_STAGE(PG8_SB(0, 1), b2 + hstep, voffB); PG8_STAGE(PG8_SA(0, 0), a2, voffA);
;             PG8_WAIT_V(8); PG8_WAIT_L(0); PG8_BAR; PG8_MMA(1, 0, At, B0); PG8_MMA(1, 1, At, B1); PG8_BAR; PG8_SCHED;
;             PG8_LDB(B0, 1, 0); PG8_LDB(B1, 1, 1); PG8_SCHED; PG8_LDA(At, 1, 0); PG8_STAGE(PG8_SA(0, 1), a2 + hstep, voffA);
;             PG8_WAIT_V(8); PG8_WAIT_L(0); PG8_BAR; PG8_MMA(0, 0, At, B0); PG8_MMA(0, 1, At, B1); PG8_BAR; PG8_SCHED;
;             PG8_LDA(At, 1, 1); PG8_STAGE(PG8_SB(1, 0), b3, voffB); PG8_STAGE(PG8_SB(1, 1), b3 + hstep, voffB); PG8_STAGE(PG8_SA(1, 0), a3, voffA);
;             PG8_WAIT_V(8); PG8_WAIT_L(0); PG8_BAR; PG8_MMA(1, 0, At, B0); PG8_MMA(1, 1, At, B1); PG8_BAR; PG8_SCHED;
	s_add_i32 s34, s46, s8
	s_mov_b32 m0, s34
	ds_read_b128 v[162:165], v208 offset:49152
	ds_read_b128 v[166:169], v208 offset:50176
	ds_read_b128 v[170:173], v208 offset:51200
	ds_read_b128 v[174:177], v208 offset:52224
	ds_read_b128 v[178:181], v208 offset:53248
	ds_read_b128 v[182:185], v208 offset:54272
	ds_read_b128 v[186:189], v208 offset:55296
	ds_read_b128 v[190:193], v208 offset:56320
	global_load_lds_dwordx4 v204, s[98:99]
	s_add_i32 m0, s34, 0x2000
	s_add_u32 s30, s30, 0x80080
	s_addc_u32 s31, s31, 0
	s_add_i32 s34, s47, s8
	global_load_lds_dwordx4 v216, s[98:99]
	s_mov_b32 m0, s34
	s_nop 0
	global_load_lds_dwordx4 v204, s[30:31]
	s_add_i32 m0, s34, 0x2000
	s_nop 0
	global_load_lds_dwordx4 v216, s[30:31]
	s_mov_b32 m0, s75
	s_nop 0
	global_load_lds_dwordx4 v202, s[100:101]
	s_waitcnt vmcnt(7)
	s_waitcnt lgkmcnt(0)
	s_barrier
	s_setprio 1
	v_mfma_f32_16x16x32_bf16 v[62:65], v[130:133], v[162:165], v[62:65]
	v_mfma_f32_16x16x32_bf16 v[58:61], v[138:141], v[162:165], v[58:61]
	v_mfma_f32_16x16x32_bf16 v[46:49], v[130:133], v[170:173], v[46:49]
	v_mfma_f32_16x16x32_bf16 v[42:45], v[138:141], v[170:173], v[42:45]
	v_mfma_f32_16x16x32_bf16 v[30:33], v[130:133], v[178:181], v[30:33]
	v_mfma_f32_16x16x32_bf16 v[26:29], v[138:141], v[178:181], v[26:29]
	v_mfma_f32_16x16x32_bf16 v[12:15], v[130:133], v[186:189], v[12:15]
	v_mfma_f32_16x16x32_bf16 v[8:11], v[138:141], v[186:189], v[8:11]
	v_mfma_f32_16x16x32_bf16 v[62:65], v[134:137], v[166:169], v[62:65]
	v_mfma_f32_16x16x32_bf16 v[58:61], v[142:145], v[166:169], v[58:61]
	v_mfma_f32_16x16x32_bf16 v[46:49], v[134:137], v[174:177], v[46:49]
	v_mfma_f32_16x16x32_bf16 v[42:45], v[142:145], v[174:177], v[42:45]
	v_mfma_f32_16x16x32_bf16 v[30:33], v[134:137], v[182:185], v[30:33]
	v_mfma_f32_16x16x32_bf16 v[26:29], v[142:145], v[182:185], v[26:29]
	v_mfma_f32_16x16x32_bf16 v[12:15], v[134:137], v[190:193], v[12:15]
	v_mfma_f32_16x16x32_bf16 v[8:11], v[142:145], v[190:193], v[8:11]
	s_setprio 0
	s_setprio 1
	v_mfma_f32_16x16x32_bf16 v[54:57], v[146:149], v[162:165], v[54:57]
	v_mfma_f32_16x16x32_bf16 v[50:53], v[154:157], v[162:165], v[50:53]
	v_mfma_f32_16x16x32_bf16 v[38:41], v[146:149], v[170:173], v[38:41]
	v_mfma_f32_16x16x32_bf16 v[34:37], v[154:157], v[170:173], v[34:37]
	v_mfma_f32_16x16x32_bf16 v[22:25], v[146:149], v[178:181], v[22:25]
	v_mfma_f32_16x16x32_bf16 v[16:19], v[154:157], v[178:181], v[16:19]
	v_mfma_f32_16x16x32_bf16 v[4:7], v[146:149], v[186:189], v[4:7]
	v_mfma_f32_16x16x32_bf16 v[0:3], v[154:157], v[186:189], v[0:3]
	v_mfma_f32_16x16x32_bf16 v[54:57], v[150:153], v[166:169], v[54:57]
	v_mfma_f32_16x16x32_bf16 v[50:53], v[158:161], v[166:169], v[50:53]
	v_mfma_f32_16x16x32_bf16 v[38:41], v[150:153], v[174:177], v[38:41]
	v_mfma_f32_16x16x32_bf16 v[34:37], v[158:161], v[174:177], v[34:37]
	v_mfma_f32_16x16x32_bf16 v[22:25], v[150:153], v[182:185], v[22:25]
	v_mfma_f32_16x16x32_bf16 v[16:19], v[158:161], v[182:185], v[16:19]
	v_mfma_f32_16x16x32_bf16 v[4:7], v[150:153], v[190:193], v[4:7]
	v_mfma_f32_16x16x32_bf16 v[0:3], v[158:161], v[190:193], v[0:3]
	s_setprio 0
	s_barrier
	s_add_i32 vcc_lo, vcc_lo, 2
	s_add_u32 s28, s28, 0x100
	s_addc_u32 s29, s29, 0
	s_add_u32 s57, s57, 0x100
	s_addc_u32 s92, s92, 0
	s_cmp_gt_u32 vcc_lo, 29

; __device__ __forceinline__ unsigned cvt_pk_bf16(float lo, float hi) { unsigned r; asm volatile("v_cvt_pk_bf16_f32 %0, %1, %2" : "=v"(r) : "v"(lo), "v"(hi)); return r; }
; #define PG8_BAR __builtin_amdgcn_s_barrier()
;     __device__ __forceinline__ void run(f32x4 (&acc)[2][2][4][2], const Unit& u, int wr, int wc, int fr, int fq, PG8_LAS unsigned char* lds, int buf) const {
;     ...
;             for (int m = 0; m < 4; ++m) { const float rstd = bad ? qnan : S[ai * HALF + wr * 64 + m * 16 + fr]; const unsigned off = (unsigned)(row0 + ai * HALF + m * 16) * 2048u + (unsigned)col0;
; #pragma unroll
;                 for (int bj = 0; bj < 2; ++bj) { const f32x4 x0 = acc[ai][bj][m][0], x1 = acc[ai][bj][m][1];
;                     u32x4 w; w.x = pkh2(x0[0], x0[1]); w.y = pkh2(x0[2], x0[3]); w.z = pkh2(x1[0], x1[1]); w.w = pkh2(x1[2], x1[3]);
;                     *(u32x4*)(xnew + off + bj * HALF) = w;
;                     const f32x4 h0 = x0 * rstd * gs[bj][0] + sh[bj][0], h1 = x1 * rstd * gs[bj][1] + sh[bj][1];
;                     w.x = cvt_pk_bf16(h0[0], h0[1]); w.y = cvt_pk_bf16(h0[2], h0[3]); w.z = cvt_pk_bf16(h1[0], h1[1]); w.w = cvt_pk_bf16(h1[2], h1[3]);
;                     *(u32x4*)(hout + off + bj * HALF) = w; } }
; template <class Epi, class Sched, bool ALIGN_EPI = false, bool SP2 = false>
; __device__ __forceinline__ void gemm_phase(PG8_LAS unsigned char* lds, const Gemm g, const Sched& S, const Epi& E, const int tid_in) {
;     ...
;         if (!has_next) break;
; #pragma unroll
;         for (int a = 0; a < 2; ++a)
; #pragma unroll
;             for (int b = 0; b < 2; ++b)
; #pragma unroll
;                 for (int m = 0; m < 4; ++m)
; #pragma unroll
;                     for (int n = 0; n < 2; ++n) acc[a][b][m][n] = (f32x4){0.f, 0.f, 0.f, 0.f};
;         cur = nxt; cA = nA; cB = nB; ++ui;
;         if constexpr (ALIGN_EPI) { if (wr == 1) PG8_BAR; }
.LBB0_1091:
	v_add_u32_e32 v26, 0x58000, v26
	v_mov_b32_e32 v27, v20
	v_lshlrev_b64 v[26:27], 1, v[26:27]
	v_cvt_pk_f16_f32 v34, v74, v75
	v_cvt_pk_f16_f32 v35, v70, v71
	v_cvt_pk_f16_f32 v36, v68, v69
	v_cvt_pk_f16_f32 v37, v66, v67
	v_lshl_add_u64 v[42:43], s[42:43], 0, v[26:27]
	global_store_dwordx4 v[42:43], v[34:37], off
	s_andn2_b64 vcc, exec, s[58:59]
	s_mov_b64 s[2:3], -1
	s_waitcnt lgkmcnt(0)
	v_pk_mul_f32 v[34:35], v[70:71], v[28:29] op_sel_hi:[1,0]
	v_pk_mul_f32 v[36:37], v[74:75], v[28:29] op_sel_hi:[1,0]
	v_pk_fma_f32 v[14:15], v[40:41], v[34:35], v[14:15]
	v_pk_fma_f32 v[12:13], v[38:39], v[36:37], v[12:13]
	v_pk_mul_f32 v[34:35], v[66:67], v[28:29] op_sel_hi:[1,0]
	v_pk_mul_f32 v[36:37], v[68:69], v[28:29] op_sel_hi:[1,0]
	v_pk_fma_f32 v[32:33], v[32:33], v[34:35], v[10:11]
	v_pk_fma_f32 v[10:11], v[30:31], v[36:37], v[8:9]
	v_cvt_pk_bf16_f32 v8, v12, v13
	v_cvt_pk_bf16_f32 v9, v14, v15
	v_lshl_add_u64 v[12:13], s[44:45], 0, v[26:27]
	v_cvt_pk_bf16_f32 v10, v10, v11
	v_cvt_pk_bf16_f32 v11, v32, v33
	global_store_dwordx4 v[12:13], v[8:11], off
	s_nop 1
	v_cvt_pk_f16_f32 v8, v56, v57
	v_cvt_pk_f16_f32 v9, v54, v55
	v_cvt_pk_f16_f32 v10, v52, v53
	v_cvt_pk_f16_f32 v11, v50, v51
	global_store_dwordx4 v[42:43], v[8:11], off offset:256
	s_nop 1
	v_pk_mul_f32 v[8:9], v[54:55], v[28:29] op_sel_hi:[1,0]
	v_pk_mul_f32 v[10:11], v[56:57], v[28:29] op_sel_hi:[1,0]
	v_pk_fma_f32 v[6:7], v[24:25], v[8:9], v[6:7]
	v_pk_fma_f32 v[4:5], v[22:23], v[10:11], v[4:5]
	v_pk_mul_f32 v[8:9], v[50:51], v[28:29] op_sel_hi:[1,0]
	v_pk_mul_f32 v[10:11], v[52:53], v[28:29] op_sel_hi:[1,0]
	v_pk_fma_f32 v[8:9], v[18:19], v[8:9], v[2:3]
	v_pk_fma_f32 v[2:3], v[16:17], v[10:11], v[0:1]
	v_cvt_pk_bf16_f32 v0, v4, v5
	v_cvt_pk_bf16_f32 v1, v6, v7
	s_nop 0
	v_cvt_pk_bf16_f32 v2, v2, v3
	v_cvt_pk_bf16_f32 v3, v8, v9
	global_store_dwordx4 v[12:13], v[0:3], off offset:256
	s_cbranch_vccnz .LBB0_1033
	s_andn2_b64 vcc, exec, s[26:27]
	s_cbranch_vccnz .LBB0_1032
	s_branch .LBB0_1032

; #define PG8_WAIT_V(n) asm volatile("s_waitcnt vmcnt(" #n ")" ::: "memory")
; template <class Epi, class Sched, bool ALIGN_EPI = false, bool SP2 = false>
; __device__ __forceinline__ void gemm_phase(PG8_LAS unsigned char* lds, const Gemm g, const Sched& S, const Epi& E, const int tid_in) {
;     ...
;     const int tid = tid_l, wid = __builtin_amdgcn_readfirstlane(tid >> 6), lane = tid & 63, wr = wid >> 2, wc = wid & 3, fr = lane & 15, fq = lane >> 4;
;     const int K = g.K, nt = K / BK;
;     unsigned voffA[2], voffB[2];
; #pragma unroll
;     for (int i = 0; i < 2; ++i) { int R, C; stage_rc(tid * 16 + i * 8192, R, C); const int Rb = perm_row<Epi::PMODE>(R);
;         voffA[i] = (unsigned)(R * K + C) * 2u; voffB[i] = (unsigned)(Rb * K + C) * 2u; }
;     const size_t kstep = (size_t)(BK * 2);
;     const size_t hstep = (size_t)HALF * K * 2;
;     const size_t tstep = 2 * hstep;
;     const unsigned ldsw = (unsigned)wid * 1024u;
;     const int aoff = lds_byte(wr * 64 + fr, fq * 8), boff = lds_byte(wc * 32 + fr, fq * 8);
;     ...
;     Unit cur, nxt; int ui = 0;
;     if (!S.next(0, cur)) return;
;     f32x4 acc[2][2][4][2];
; #pragma unroll
;     for (int a = 0; a < 2; ++a)
; #pragma unroll
;         for (int b = 0; b < 2; ++b)
; #pragma unroll
;             for (int m = 0; m < 4; ++m)
; #pragma unroll
;                 for (int n = 0; n < 2; ++n) acc[a][b][m][n] = (f32x4){0.f, 0.f, 0.f, 0.f};
;     bf16x8 At[4][2], B0[2][2], B1[2][2];
;     const char* cA = (const char*)g.A + (size_t)cur.pm * tstep; const char* cB = (const char*)g.Bt + (size_t)cur.pn * tstep;
;     S.a_ready(cur);
;     if constexpr (Epi::PREF) E.prefetch(cur, 0, lds, wid, lane);
;     if constexpr (SP2) {
;         PG8_STAGE(PG8_SB(0, 0), cB, voffB); PG8_STAGE(PG8_SB(0, 1), cB + hstep, voffB); PG8_STAGE(PG8_SA(0, 0), cA, voffA); PG8_STAGE(PG8_SA(0, 1), cA + hstep, voffA);
;         if (wr == 1) PG8_BAR;
;         PG8_WAIT_V(2); PG8_BAR;
;         PG8_STAGE(PG8_SB(1, 0), cB + kstep, voffB); PG8_STAGE(PG8_SA(1, 0), cA + kstep, voffA); PG8_STAGE(PG8_SB(1, 1), cB + hstep + kstep, voffB);
;         PG8_WAIT_V(6); PG8_BAR;
;     } else {
;         PG8_STAGE(PG8_SB(0, 0), cB, voffB); PG8_STAGE(PG8_SA(0, 0), cA, voffA); PG8_STAGE(PG8_SB(0, 1), cB + hstep, voffB); PG8_STAGE(PG8_SA(0, 1), cA + hstep, voffA);
;         if (wr == 1) PG8_BAR;
;         PG8_WAIT_V(4); PG8_BAR;
.LBB0_1149:
	v_ashrrev_i32_e32 v2, 31, v10
	v_lshrrev_b32_e32 v2, 26, v2
	v_add_u32_e32 v2, v10, v2
	v_ashrrev_i32_e32 v12, 6, v2
	v_bfe_i32 v2, v10, 27, 1
	v_lshlrev_b32_e32 v1, 4, v10
	v_lshrrev_b32_e32 v2, 22, v2
	v_add_u32_e32 v2, v1, v2
	v_and_b32_e32 v2, 0xfffffc00, v2
	v_sub_u32_e32 v2, v1, v2
	v_lshrrev_b32_e32 v3, 4, v2
	v_bitop3_b32 v2, v3, v2, 32 bitop3:0x6c
	v_ashrrev_i32_e32 v4, 31, v2
	v_lshrrev_b32_e32 v4, 26, v4
	v_add_u32_e32 v4, v2, v4
	v_lshlrev_b32_e32 v3, 3, v12
	v_ashrrev_i32_e32 v13, 6, v4
	v_and_b32_e32 v4, 0xc0, v4
	v_and_b32_e32 v3, -16, v3
	v_sub_u32_e32 v2, v2, v4
	v_mov_b32_e32 v7, 1
	v_add_u32_e32 v3, v13, v3
	v_ashrrev_i16_sdwa v2, v7, sext(v2) dst_sel:DWORD dst_unused:UNUSED_PAD src0_sel:DWORD src1_sel:BYTE_0
	v_lshlrev_b32_e32 v5, 5, v12
	v_bfe_i32 v14, v2, 0, 16
	v_lshlrev_b32_e32 v2, 1, v3
	v_lshrrev_b32_e32 v4, 2, v3
	v_and_b32_e32 v5, 32, v5
	v_and_b32_e32 v2, 24, v2
	v_and_b32_e32 v4, 4, v4
	v_and_b32_e32 v6, 0xfffe3, v3
	v_or3_b32 v2, v6, v4, v2
	v_add_lshl_u32 v4, v5, v14, 1
	v_add_u32_e32 v1, 0x2000, v1
	v_lshl_add_u32 v164, v2, 12, v4
	v_ashrrev_i32_e32 v2, 31, v1
	v_lshrrev_b32_e32 v2, 22, v2
	s_add_i32 s3, s2, s3
	v_add_u32_e32 v2, v1, v2
	s_bitcmp0_b32 s3, 0
	s_mov_b32 s3, 0x4f200000
	v_ashrrev_i32_e32 v15, 10, v2
	s_cselect_b32 s3, 0x28000000, s3
	v_mul_i32_i24_e32 v2, 0x400, v15
	s_add_u32 s5, s20, s3
	v_sub_u32_e32 v1, v1, v2
	s_addc_u32 s8, s21, 0
	s_mul_hi_i32 s3, s2, 0x2c00000
	s_mul_i32 s2, s2, 0x2c00000
	v_lshrrev_b32_e32 v2, 4, v1
	s_add_u32 s2, s20, s2
	v_bitop3_b32 v1, v2, v1, 32 bitop3:0x6c
	s_addc_u32 s3, s21, s3
	v_lshl_add_u32 v162, v3, 12, v4
	v_ashrrev_i32_e32 v3, 31, v1
	s_add_u32 s10, s2, 0x14000000
	v_lshrrev_b32_e32 v3, 26, v3
	s_addc_u32 s19, s3, 0
	v_readlane_b32 s2, v254, 6
	v_add_u32_e32 v3, v1, v3
	v_readlane_b32 s3, v254, 7
	s_add_u32 s50, s5, s2
	v_lshlrev_b32_e32 v2, 3, v15
	v_ashrrev_i32_e32 v16, 6, v3
	v_and_b32_e32 v3, 0xc0, v3
	s_addc_u32 s51, s8, s3
	v_readlane_b32 s2, v254, 8
	v_and_b32_e32 v2, -16, v2
	v_sub_u32_e32 v1, v1, v3
	v_readlane_b32 s3, v254, 9
	s_add_u32 s52, s10, s2
	v_add_u32_e32 v2, v16, v2
	v_ashrrev_i16_sdwa v1, v7, sext(v1) dst_sel:DWORD dst_unused:UNUSED_PAD src0_sel:DWORD src1_sel:BYTE_0
	s_addc_u32 s53, s19, s3
	v_lshlrev_b32_e32 v4, 5, v15
	v_bfe_i32 v17, v1, 0, 16
	v_lshlrev_b32_e32 v1, 1, v2
	v_lshrrev_b32_e32 v3, 2, v2
	s_add_i32 s89, s1, 0
	v_and_b32_e32 v4, 32, v4
	v_and_b32_e32 v1, 24, v1
	v_and_b32_e32 v3, 4, v3
	v_and_b32_e32 v5, 0xfffe3, v2
	s_add_i32 m0, s89, 0x10000
	s_ashr_i32 s83, s23, 8
	v_or3_b32 v1, v5, v3, v1
	v_add_lshl_u32 v3, v4, v17, 1
	global_load_lds_dwordx4 v164, s[52:53]
	s_add_i32 m0, s89, 0x12000
	v_lshl_add_u32 v168, v1, 12, v3
	s_add_u32 s2, s52, 0x80000
	global_load_lds_dwordx4 v168, s[52:53]
	s_addc_u32 s3, s53, 0
	s_add_i32 m0, s89, 0x14000
	s_add_i32 s92, s89, 0x2000
	global_load_lds_dwordx4 v164, s[2:3]
	s_add_i32 m0, s89, 0x16000
	s_add_u32 s26, s50, 0x80000
	global_load_lds_dwordx4 v168, s[2:3]
	s_mov_b32 m0, s89
	v_lshl_add_u32 v166, v2, 12, v3
	global_load_lds_dwordx4 v162, s[50:51]
	s_mov_b32 m0, s92
	s_addc_u32 s27, s51, 0
	s_add_i32 s2, s89, 0x4000
	global_load_lds_dwordx4 v166, s[50:51]
	s_mov_b32 m0, s2
	s_add_i32 s3, s89, 0x6000
	global_load_lds_dwordx4 v162, s[26:27]
	s_mov_b32 m0, s3
	v_writelane_b32 v255, s42, 22
	global_load_lds_dwordx4 v166, s[26:27]
	s_cmp_eq_u32 s83, 1
	v_writelane_b32 v255, s43, 23
	s_cselect_b64 s[26:27], -1, 0
	v_mov_b32_e32 v165, v20
	v_mov_b32_e32 v169, v20
	v_mov_b32_e32 v163, v20
	v_mov_b32_e32 v167, v20
	v_writelane_b32 v255, s26, 18
	v_lshl_add_u64 v[6:7], s[52:53], 0, v[164:165]
	v_lshl_add_u64 v[4:5], s[52:53], 0, v[168:169]
	v_lshl_add_u64 v[2:3], s[50:51], 0, v[162:163]
	v_writelane_b32 v255, s27, 19
	s_cmp_lg_u32 s83, 1
	v_lshl_add_u64 v[8:9], s[50:51], 0, v[166:167]
	s_cbranch_scc1 .LBB0_1151
.LBB0_1151:
	s_add_u32 s26, s20, 0x5f200000
	s_addc_u32 s27, s21, 0
	s_add_u32 s36, s20, 0x35000000
	s_addc_u32 s37, s21, 0
	s_lshl_b32 s20, s24, 5
	s_and_b32 s31, s20, 0x60
	s_add_i32 m0, s89, 0x18000
	v_lshl_add_u64 v[6:7], v[6:7], 0, s[12:13]
	s_lshl_b32 s28, s83, 13
	s_lshl_b32 s29, s31, 7
	s_waitcnt vmcnt(2)
	s_barrier
	global_load_lds_dwordx4 v[6:7], off
	v_lshl_add_u64 v[4:5], v[4:5], 0, s[12:13]
	s_add_i32 m0, s89, 0x1a000
	s_add_i32 s24, s89, 0x8000
	s_add_i32 s25, s89, 0xa000
	global_load_lds_dwordx4 v[4:5], off
	v_lshl_add_u64 v[2:3], v[2:3], 0, s[12:13]
	s_mov_b32 m0, s24
	s_add_u32 s100, s50, 0x80
	s_addc_u32 s101, s51, 0
	s_add_u32 s20, s52, 0x80080
	global_load_lds_dwordx4 v[2:3], off
	v_lshl_add_u64 v[2:3], v[8:9], 0, s[12:13]
	s_mov_b32 m0, s25
	s_addc_u32 s21, s53, 0
	global_load_lds_dwordx4 v[2:3], off
	s_add_i32 m0, s89, 0x1c000
	v_lshl_add_u64 v[2:3], s[20:21], 0, v[164:165]
	global_load_lds_dwordx4 v[2:3], off
	v_lshl_add_u64 v[2:3], s[20:21], 0, v[168:169]
	s_add_i32 m0, s89, 0x1e000
	v_readlane_b32 s20, v254, 55
	global_load_lds_dwordx4 v[2:3], off
	v_lshrrev_b32_e32 v1, 1, v10
	s_mov_b32 s21, s20
	s_add_i32 s20, s20, s1
	v_and_b32_e32 v4, 24, v1
	v_writelane_b32 v255, s20, 20
	s_lshl_b32 s20, s31, 2
	v_and_b32_e32 v21, 15, v10
	v_lshlrev_b32_e32 v1, 1, v4
	v_lshlrev_b32_e32 v2, 2, v10
	s_add_i32 s20, s21, s20
	v_lshl_or_b32 v1, v21, 6, v1
	v_and_b32_e32 v2, 32, v2
	v_lshl_add_u32 v179, v4, 2, s20
	s_movk_i32 s20, 0x1600
	v_bitop3_b32 v5, v1, s28, v2 bitop3:0xde
	v_bitop3_b32 v177, v1, s29, v2 bitop3:0xde
	v_mul_lo_u32 v2, v11, s20
	v_ashrrev_i32_e32 v3, 31, v2
	v_lshl_add_u64 v[2:3], v[2:3], 2, s[6:7]
	v_mov_b32_e32 v1, s30
	v_cmp_gt_i32_e32 vcc, 3, v11
	s_waitcnt vmcnt(6)
	s_cmpk_lt_u32 s23, 0x100
	v_cmp_eq_u32_e64 s[42:43], 15, v21
	v_cndmask_b32_e32 v3, v1, v3, vcc
	v_mov_b32_e32 v1, s22
	v_cndmask_b32_e32 v2, v1, v2, vcc
	v_mov_b32_e32 v1, v20
	v_lshl_add_u64 v[182:183], v[2:3], 0, v[0:1]
	v_lshlrev_b32_e32 v0, 15, v12
	v_and_b32_e32 v0, 0xffff0000, v0
	v_lshl_add_u32 v0, v13, 12, v0
	v_and_b32_e32 v1, 1, v12
	v_lshl_or_b32 v0, v1, 6, v0
	v_lshl_add_u32 v184, v14, 1, v0
	v_lshlrev_b32_e32 v0, 15, v15
	v_and_b32_e32 v0, 0xffff0000, v0
	v_lshl_add_u32 v0, v16, 12, v0
	v_and_b32_e32 v1, 1, v15
	v_cmp_ne_u32_e64 s[44:45], 0, v21
	v_lshl_or_b32 v0, v1, 6, v0
	v_readlane_b32 s6, v254, 4
	v_lshl_or_b32 v175, s83, 6, v21
	s_cselect_b64 s[28:29], -1, 0
	s_mov_b32 s23, 0
	v_cmp_gt_u32_e64 s[38:39], 2, v21
	v_cmp_lt_u32_e64 s[40:41], 13, v21
	v_add_u32_e32 v181, -12, v21
	v_cndmask_b32_e64 v170, 0, 1, s[42:43]
	v_mov_b32_e32 v171, s93
	v_cndmask_b32_e64 v172, 0, 1, s[44:45]
	v_mov_b32_e32 v173, s93
	v_cndmask_b32_e64 v174, 1, 2, s[42:43]
	v_cndmask_b32_e64 v176, 1, 2, s[44:45]
	v_cndmask_b32_e64 v178, 2, 3, s[42:43]
	v_cndmask_b32_e64 v180, 2, 3, s[44:45]
	v_or_b32_e32 v192, s31, v4
	v_mov_b32_e32 v185, v20
	v_lshl_add_u32 v186, v17, 1, v0
	v_mov_b32_e32 v187, v20
	v_add_u32_e32 v193, 0, v5
	v_readlane_b32 s57, v254, 10
	s_mov_b32 s56, s6
	s_barrier
	v_readlane_b32 s7, v254, 5
	s_branch .LBB0_1154

; #define PG8_STAGE(bufoff, gbase, voff) do { _Pragma("unroll") for (int _i = 0; _i < 2; ++_i) \
;         __builtin_amdgcn_global_load_lds((const unsigned*)((const char*)(gbase) + (voff)[_i]), (PG8_LAS unsigned*)(lds + (bufoff) + ldsw + _i * 8192), 16, 0, 0); } while (0)
; #define PG8_LDA(dst, b, h) do { _Pragma("unroll") for (int m = 0; m < 4; ++m) _Pragma("unroll") for (int k = 0; k < 2; ++k) dst[m][k] = *(const PG8_LAS bf16x8*)(lds + PG8_SA(b, h) + aoff + m * 2048 + k * 1024); } while (0)
; #define PG8_LDB(dst, b, h) do { _Pragma("unroll") for (int n = 0; n < 2; ++n) _Pragma("unroll") for (int k = 0; k < 2; ++k) dst[n][k] = *(const PG8_LAS bf16x8*)(lds + PG8_SB(b, h) + boff + n * 2048 + k * 1024); } while (0)
; #define PG8_WAIT_V(n) asm volatile("s_waitcnt vmcnt(" #n ")" ::: "memory")
; #define PG8_WAIT_L(n) asm volatile("s_waitcnt lgkmcnt(" #n ")" ::: "memory")
; template <class Epi, class Sched, bool ALIGN_EPI = false, bool SP2 = false>
; __device__ __forceinline__ void gemm_phase(PG8_LAS unsigned char* lds, const Gemm g, const Sched& S, const Epi& E, const int tid_in) {
;     ...
;     for (;;) {
;         const bool has_next = S.next(ui + 1, nxt);
;         const char* nA = has_next ? (const char*)g.A + (size_t)nxt.pm * tstep : cA; const char* nB = has_next ? (const char*)g.Bt + (size_t)nxt.pn * tstep : cB;
;         for (int t = 0; t < nt; t += 2) {
;             if constexpr (Epi::KSPLIT > 0) { if (t == Epi::KSPLIT / BK) E.midk(acc, cur, wr, wc, fr, fq); }
;             const bool last = (t == nt - 2);
;             const char* a1 = cA + (size_t)(t + 1) * kstep;
;             const char* a2 = last ? nA : cA + (size_t)(t + 2) * kstep; const char* b2 = last ? nB : cB + (size_t)(t + 2) * kstep;
;             const char* a3 = a2 + kstep; const char* b3 = b2 + kstep;
;             if (last && has_next) S.a_ready(nxt);
;             if constexpr (SP2) {
;             PG8_LDB(B0, 0, 0); PG8_LDB(B1, 0, 1); PG8_SCHED; PG8_LDA(At, 0, 0); PG8_STAGE(PG8_SA(1, 1), a1 + hstep, voffA);
;             PG8_WAIT_V(8); PG8_WAIT_L(0); PG8_BAR; PG8_MMA(0, 0, At, B0); PG8_MMA(0, 1, At, B1); PG8_BAR; PG8_SCHED;
;             PG8_LDA(At, 0, 1); PG8_STAGE(PG8_SB(0, 0), b2, voffB); PG8_STAGE(PG8_SB(0, 1), b2 + hstep, voffB); PG8_STAGE(PG8_SA(0, 0), a2, voffA);
;             PG8_WAIT_V(8); PG8_WAIT_L(0); PG8_BAR; PG8_MMA(1, 0, At, B0); PG8_MMA(1, 1, At, B1); PG8_BAR; PG8_SCHED;
.LBB0_1156:
	s_ashr_i32 s35, s34, 31
	s_lshl_b64 s[6:7], s[34:35], 20
	s_add_u32 s6, s5, s6
	s_addc_u32 s7, s8, s7
	s_and_b64 s[20:21], exec, s[48:49]
	s_cselect_b32 s35, s51, s7
	s_cselect_b32 s58, s50, s6
	s_ashr_i32 s31, s30, 31
	s_lshl_b64 s[20:21], s[30:31], 20
	s_add_u32 s20, s10, s20
	s_addc_u32 s21, s19, s21
	s_and_b64 s[54:55], exec, s[48:49]
	s_cselect_b32 s31, s53, s21
	s_cselect_b32 s59, s52, s20
	s_add_u32 s50, s50, 0x80080
	s_addc_u32 s51, s51, 0
	s_add_u32 s60, s52, 0x100
	v_mov_b32_e32 v0, 0
	s_addc_u32 s61, s53, 0
	s_mov_b32 s62, -2
	s_cmp_lt_u32 s1, 0x1000
	s_cbranch_scc1 .LCB_1157
	s_barrier
.LCB_1157:
	s_mov_b32 m0, s25
	s_nop 0
	global_load_lds_dwordx4 v166, s[100:101]
	s_add_u32 s52, s50, 0xfff80080
	s_addc_u32 s53, s51, -1
	s_add_i32 s63, 0, 0x10000
	s_cmp_eq_u32 s62, 28
	s_cselect_b32 s55, s35, s53
	s_cselect_b32 s54, s58, s52
	s_cselect_b32 s53, s31, s61
	s_cselect_b32 s52, s59, s60
	s_add_i32 s66, 0, 0x14000
	v_add_u32_e32 v78, s63, v177
	v_add_u32_e32 v134, s66, v177
	ds_read_b128 v[66:69], v78
	ds_read_b128 v[70:73], v78 offset:1024
	ds_read_b128 v[74:77], v78 offset:2048
	ds_read_b128 v[78:81], v78 offset:3072
	ds_read_b128 v[122:125], v134
	ds_read_b128 v[126:129], v134 offset:1024
	ds_read_b128 v[130:133], v134 offset:2048
	ds_read_b128 v[134:137], v134 offset:3072
	s_add_i32 m0, s89, 0xc000
	ds_read_b128 v[188:191], v193
	ds_read_b128 v[194:197], v193 offset:1024
	ds_read_b128 v[198:201], v193 offset:2048
	ds_read_b128 v[202:205], v193 offset:3072
	ds_read_b128 v[208:211], v193 offset:4096
	ds_read_b128 v[212:215], v193 offset:5120
	ds_read_b128 v[216:219], v193 offset:6144
	ds_read_b128 v[220:223], v193 offset:7168
	global_load_lds_dwordx4 v184, s[50:51]
	s_add_i32 m0, s89, 0xe000
	s_nop 0
	global_load_lds_dwordx4 v186, s[50:51]
	s_waitcnt vmcnt(8)
	s_waitcnt lgkmcnt(0)
	s_barrier
	s_setprio 1
	v_mfma_f32_16x16x32_bf16 v[150:153], v[66:69], v[188:191], 0
	v_mfma_f32_16x16x32_bf16 v[110:113], v[74:77], v[188:191], 0
	v_mfma_f32_16x16x32_bf16 v[146:149], v[66:69], v[198:201], 0
	v_mfma_f32_16x16x32_bf16 v[106:109], v[74:77], v[198:201], 0
	v_mfma_f32_16x16x32_bf16 v[142:145], v[66:69], v[208:211], 0
	v_mfma_f32_16x16x32_bf16 v[102:105], v[74:77], v[208:211], 0
	v_mfma_f32_16x16x32_bf16 v[138:141], v[66:69], v[216:219], 0
	v_mfma_f32_16x16x32_bf16 v[98:101], v[74:77], v[216:219], 0
	v_mfma_f32_16x16x32_bf16 v[150:153], v[70:73], v[194:197], v[150:153]
	v_mfma_f32_16x16x32_bf16 v[110:113], v[78:81], v[194:197], v[110:113]
	v_mfma_f32_16x16x32_bf16 v[146:149], v[70:73], v[202:205], v[146:149]
	v_mfma_f32_16x16x32_bf16 v[106:109], v[78:81], v[202:205], v[106:109]
	v_mfma_f32_16x16x32_bf16 v[142:145], v[70:73], v[212:215], v[142:145]
	v_mfma_f32_16x16x32_bf16 v[102:105], v[78:81], v[212:215], v[102:105]
	v_mfma_f32_16x16x32_bf16 v[138:141], v[70:73], v[220:223], v[138:141]
	v_mfma_f32_16x16x32_bf16 v[98:101], v[78:81], v[220:223], v[98:101]
	s_setprio 0
	s_setprio 1
	v_mfma_f32_16x16x32_bf16 v[94:97], v[122:125], v[188:191], 0
	v_mfma_f32_16x16x32_bf16 v[90:93], v[130:133], v[188:191], 0
	v_mfma_f32_16x16x32_bf16 v[158:161], v[122:125], v[198:201], 0
	v_mfma_f32_16x16x32_bf16 v[118:121], v[130:133], v[198:201], 0
	v_mfma_f32_16x16x32_bf16 v[154:157], v[122:125], v[208:211], 0
	v_mfma_f32_16x16x32_bf16 v[114:117], v[130:133], v[208:211], 0
	v_mfma_f32_16x16x32_bf16 v[86:89], v[122:125], v[216:219], 0
	v_mfma_f32_16x16x32_bf16 v[82:85], v[130:133], v[216:219], 0
	v_mfma_f32_16x16x32_bf16 v[94:97], v[126:129], v[194:197], v[94:97]
	v_mfma_f32_16x16x32_bf16 v[90:93], v[134:137], v[194:197], v[90:93]
	v_mfma_f32_16x16x32_bf16 v[158:161], v[126:129], v[202:205], v[158:161]
	v_mfma_f32_16x16x32_bf16 v[118:121], v[134:137], v[202:205], v[118:121]
	v_mfma_f32_16x16x32_bf16 v[154:157], v[126:129], v[212:215], v[154:157]
	v_mfma_f32_16x16x32_bf16 v[114:117], v[134:137], v[212:215], v[114:117]
	v_mfma_f32_16x16x32_bf16 v[86:89], v[126:129], v[220:223], v[86:89]
	v_mfma_f32_16x16x32_bf16 v[82:85], v[134:137], v[220:223], v[82:85]
	s_setprio 0
	s_barrier
	s_add_i32 s63, s63, s1
	s_add_u32 s98, s52, 0x80
	s_addc_u32 s99, s53, 0
	s_mov_b32 m0, s63
	ds_read_b128 v[188:191], v193 offset:16384
	ds_read_b128 v[194:197], v193 offset:17408
	ds_read_b128 v[198:201], v193 offset:18432
	ds_read_b128 v[202:205], v193 offset:19456
	ds_read_b128 v[208:211], v193 offset:20480
	ds_read_b128 v[212:215], v193 offset:21504
	ds_read_b128 v[216:219], v193 offset:22528
	ds_read_b128 v[220:223], v193 offset:23552
	global_load_lds_dwordx4 v164, s[52:53]
	s_add_i32 m0, s63, 0x2000
	s_add_u32 s64, s52, 0x80000
	s_addc_u32 s65, s53, 0
	s_add_i32 s63, s66, s1
	global_load_lds_dwordx4 v168, s[52:53]
	s_mov_b32 m0, s63
	s_add_u32 s100, s54, 0x80
	s_addc_u32 s101, s55, 0
	global_load_lds_dwordx4 v164, s[64:65]
	s_add_i32 m0, s63, 0x2000
	s_nop 0
	global_load_lds_dwordx4 v168, s[64:65]
	s_mov_b32 m0, s89
	s_nop 0
	global_load_lds_dwordx4 v162, s[54:55]
	s_waitcnt vmcnt(7)
	s_waitcnt lgkmcnt(0)
	s_barrier
; #define PG8_STAGE(bufoff, gbase, voff) do { _Pragma("unroll") for (int _i = 0; _i < 2; ++_i) \
;         __builtin_amdgcn_global_load_lds((const unsigned*)((const char*)(gbase) + (voff)[_i]), (PG8_LAS unsigned*)(lds + (bufoff) + ldsw + _i * 8192), 16, 0, 0); } while (0)
; #define PG8_LDA(dst, b, h) do { _Pragma("unroll") for (int m = 0; m < 4; ++m) _Pragma("unroll") for (int k = 0; k < 2; ++k) dst[m][k] = *(const PG8_LAS bf16x8*)(lds + PG8_SA(b, h) + aoff + m * 2048 + k * 1024); } while (0)
; #define PG8_LDB(dst, b, h) do { _Pragma("unroll") for (int n = 0; n < 2; ++n) _Pragma("unroll") for (int k = 0; k < 2; ++k) dst[n][k] = *(const PG8_LAS bf16x8*)(lds + PG8_SB(b, h) + boff + n * 2048 + k * 1024); } while (0)
; #define PG8_MMA(ai, bj, At, Bt) do { __builtin_amdgcn_s_setprio(1); _Pragma("unroll") for (int m = 0; m < 4; ++m) _Pragma("unroll") for (int n = 0; n < 2; ++n) _Pragma("unroll") for (int k = 0; k < 2; ++k) \
;         acc[ai][bj][m][n] = __builtin_amdgcn_mfma_f32_16x16x32_bf16(Bt[n][k], At[m][k], acc[ai][bj][m][n], 0, 0, 0); __builtin_amdgcn_s_setprio(0); } while (0)
; #define PG8_BAR __builtin_amdgcn_s_barrier()
; template <class Epi, class Sched, bool ALIGN_EPI = false, bool SP2 = false>
; __device__ __forceinline__ void gemm_phase(PG8_LAS unsigned char* lds, const Gemm g, const Sched& S, const Epi& E, const int tid_in) {
;     ...
;             PG8_LDB(B0, 0, 0); PG8_LDB(B1, 0, 1); PG8_SCHED; PG8_LDA(At, 0, 0); PG8_STAGE(PG8_SA(1, 1), a1 + hstep, voffA);
;             PG8_WAIT_V(8); PG8_WAIT_L(0); PG8_BAR; PG8_MMA(0, 0, At, B0); PG8_MMA(0, 1, At, B1); PG8_BAR; PG8_SCHED;
;             PG8_LDA(At, 0, 1); PG8_STAGE(PG8_SB(0, 0), b2, voffB); PG8_STAGE(PG8_SB(0, 1), b2 + hstep, voffB); PG8_STAGE(PG8_SA(0, 0), a2, voffA);
;             PG8_WAIT_V(8); PG8_WAIT_L(0); PG8_BAR; PG8_MMA(1, 0, At, B0); PG8_MMA(1, 1, At, B1); PG8_BAR; PG8_SCHED;
;             PG8_LDB(B0, 1, 0); PG8_LDB(B1, 1, 1); PG8_SCHED; PG8_LDA(At, 1, 0); PG8_STAGE(PG8_SA(0, 1), a2 + hstep, voffA);
;             PG8_WAIT_V(8); PG8_WAIT_L(0); PG8_BAR; PG8_MMA(0, 0, At, B0); PG8_MMA(0, 1, At, B1); PG8_BAR; PG8_SCHED;
;             PG8_LDA(At, 1, 1); PG8_STAGE(PG8_SB(1, 0), b3, voffB); PG8_STAGE(PG8_SB(1, 1), b3 + hstep, voffB); PG8_STAGE(PG8_SA(1, 0), a3, voffA);
;             PG8_WAIT_V(8); PG8_WAIT_L(0); PG8_BAR; PG8_MMA(1, 0, At, B0); PG8_MMA(1, 1, At, B1); PG8_BAR; PG8_SCHED;
	s_setprio 1
	v_mfma_f32_16x16x32_bf16 v[54:57], v[66:69], v[188:191], 0
	v_mfma_f32_16x16x32_bf16 v[30:33], v[74:77], v[188:191], 0
	v_mfma_f32_16x16x32_bf16 v[50:53], v[66:69], v[198:201], 0
	v_mfma_f32_16x16x32_bf16 v[26:29], v[74:77], v[198:201], 0
	v_mfma_f32_16x16x32_bf16 v[46:49], v[66:69], v[208:211], 0
	v_mfma_f32_16x16x32_bf16 v[22:25], v[74:77], v[208:211], 0
	v_mfma_f32_16x16x32_bf16 v[42:45], v[66:69], v[216:219], 0
	v_mfma_f32_16x16x32_bf16 v[16:19], v[74:77], v[216:219], 0
	v_mfma_f32_16x16x32_bf16 v[54:57], v[70:73], v[194:197], v[54:57]
	v_mfma_f32_16x16x32_bf16 v[30:33], v[78:81], v[194:197], v[30:33]
	v_mfma_f32_16x16x32_bf16 v[50:53], v[70:73], v[202:205], v[50:53]
	v_mfma_f32_16x16x32_bf16 v[26:29], v[78:81], v[202:205], v[26:29]
	v_mfma_f32_16x16x32_bf16 v[46:49], v[70:73], v[212:215], v[46:49]
	v_mfma_f32_16x16x32_bf16 v[22:25], v[78:81], v[212:215], v[22:25]
	v_mfma_f32_16x16x32_bf16 v[42:45], v[70:73], v[220:223], v[42:45]
	v_mfma_f32_16x16x32_bf16 v[16:19], v[78:81], v[220:223], v[16:19]
	s_setprio 0
	s_setprio 1
	v_mfma_f32_16x16x32_bf16 v[12:15], v[122:125], v[188:191], 0
	v_mfma_f32_16x16x32_bf16 v[8:11], v[130:133], v[188:191], 0
	v_mfma_f32_16x16x32_bf16 v[62:65], v[122:125], v[198:201], 0
	v_mfma_f32_16x16x32_bf16 v[38:41], v[130:133], v[198:201], 0
	v_mfma_f32_16x16x32_bf16 v[58:61], v[122:125], v[208:211], 0
	v_mfma_f32_16x16x32_bf16 v[34:37], v[130:133], v[208:211], 0
	v_mfma_f32_16x16x32_bf16 v[4:7], v[122:125], v[216:219], 0
	v_mfma_f32_16x16x32_bf16 v[0:3], v[130:133], v[216:219], 0
	v_mfma_f32_16x16x32_bf16 v[12:15], v[126:129], v[194:197], v[12:15]
	v_mfma_f32_16x16x32_bf16 v[8:11], v[134:137], v[194:197], v[8:11]
	v_mfma_f32_16x16x32_bf16 v[62:65], v[126:129], v[202:205], v[62:65]
	v_mfma_f32_16x16x32_bf16 v[38:41], v[134:137], v[202:205], v[38:41]
	v_mfma_f32_16x16x32_bf16 v[58:61], v[126:129], v[212:215], v[58:61]
	v_mfma_f32_16x16x32_bf16 v[34:37], v[134:137], v[212:215], v[34:37]
	v_mfma_f32_16x16x32_bf16 v[4:7], v[126:129], v[220:223], v[4:7]
	v_mfma_f32_16x16x32_bf16 v[0:3], v[134:137], v[220:223], v[0:3]
	s_setprio 0
	s_barrier
	s_add_i32 s63, 0, 0x18000
	s_add_i32 s64, 0, 0x1c000
	v_add_u32_e32 v78, s63, v177
	v_add_u32_e32 v134, s64, v177
	ds_read_b128 v[66:69], v78
	ds_read_b128 v[70:73], v78 offset:1024
	ds_read_b128 v[74:77], v78 offset:2048
	ds_read_b128 v[78:81], v78 offset:3072
	ds_read_b128 v[122:125], v134
	ds_read_b128 v[126:129], v134 offset:1024
	ds_read_b128 v[130:133], v134 offset:2048
	ds_read_b128 v[134:137], v134 offset:3072
	s_mov_b32 m0, s92
	s_nop 0
	global_load_lds_dwordx4 v166, s[54:55]
	s_add_u32 s54, s54, 0x80000
	s_addc_u32 s55, s55, 0
	s_mov_b32 m0, s2
	ds_read_b128 v[188:191], v193 offset:32768
	ds_read_b128 v[194:197], v193 offset:33792
	ds_read_b128 v[198:201], v193 offset:34816
	ds_read_b128 v[202:205], v193 offset:35840
	ds_read_b128 v[208:211], v193 offset:36864
	ds_read_b128 v[212:215], v193 offset:37888
	ds_read_b128 v[216:219], v193 offset:38912
	ds_read_b128 v[220:223], v193 offset:39936
	global_load_lds_dwordx4 v162, s[54:55]
	s_mov_b32 m0, s3
	s_nop 0
	global_load_lds_dwordx4 v166, s[54:55]
	s_waitcnt vmcnt(8)
	s_waitcnt lgkmcnt(0)
	s_barrier
	s_setprio 1
	v_mfma_f32_16x16x32_bf16 v[150:153], v[66:69], v[188:191], v[150:153]
	v_mfma_f32_16x16x32_bf16 v[110:113], v[74:77], v[188:191], v[110:113]
	v_mfma_f32_16x16x32_bf16 v[146:149], v[66:69], v[198:201], v[146:149]
	v_mfma_f32_16x16x32_bf16 v[106:109], v[74:77], v[198:201], v[106:109]
	v_mfma_f32_16x16x32_bf16 v[142:145], v[66:69], v[208:211], v[142:145]
	v_mfma_f32_16x16x32_bf16 v[102:105], v[74:77], v[208:211], v[102:105]
	v_mfma_f32_16x16x32_bf16 v[138:141], v[66:69], v[216:219], v[138:141]
	v_mfma_f32_16x16x32_bf16 v[98:101], v[74:77], v[216:219], v[98:101]
	v_mfma_f32_16x16x32_bf16 v[150:153], v[70:73], v[194:197], v[150:153]
	v_mfma_f32_16x16x32_bf16 v[110:113], v[78:81], v[194:197], v[110:113]
	v_mfma_f32_16x16x32_bf16 v[146:149], v[70:73], v[202:205], v[146:149]
	v_mfma_f32_16x16x32_bf16 v[106:109], v[78:81], v[202:205], v[106:109]
	v_mfma_f32_16x16x32_bf16 v[142:145], v[70:73], v[212:215], v[142:145]
	v_mfma_f32_16x16x32_bf16 v[102:105], v[78:81], v[212:215], v[102:105]
	v_mfma_f32_16x16x32_bf16 v[138:141], v[70:73], v[220:223], v[138:141]
	v_mfma_f32_16x16x32_bf16 v[98:101], v[78:81], v[220:223], v[98:101]
	s_setprio 0
	s_setprio 1
	v_mfma_f32_16x16x32_bf16 v[94:97], v[122:125], v[188:191], v[94:97]
	v_mfma_f32_16x16x32_bf16 v[90:93], v[130:133], v[188:191], v[90:93]
	v_mfma_f32_16x16x32_bf16 v[158:161], v[122:125], v[198:201], v[158:161]
	v_mfma_f32_16x16x32_bf16 v[118:121], v[130:133], v[198:201], v[118:121]
	v_mfma_f32_16x16x32_bf16 v[154:157], v[122:125], v[208:211], v[154:157]
	v_mfma_f32_16x16x32_bf16 v[114:117], v[130:133], v[208:211], v[114:117]
	v_mfma_f32_16x16x32_bf16 v[86:89], v[122:125], v[216:219], v[86:89]
	v_mfma_f32_16x16x32_bf16 v[82:85], v[130:133], v[216:219], v[82:85]
	v_mfma_f32_16x16x32_bf16 v[94:97], v[126:129], v[194:197], v[94:97]
	v_mfma_f32_16x16x32_bf16 v[90:93], v[134:137], v[194:197], v[90:93]
	v_mfma_f32_16x16x32_bf16 v[158:161], v[126:129], v[202:205], v[158:161]
	v_mfma_f32_16x16x32_bf16 v[118:121], v[134:137], v[202:205], v[118:121]
	v_mfma_f32_16x16x32_bf16 v[154:157], v[126:129], v[212:215], v[154:157]
	v_mfma_f32_16x16x32_bf16 v[114:117], v[134:137], v[212:215], v[114:117]
	v_mfma_f32_16x16x32_bf16 v[86:89], v[126:129], v[220:223], v[86:89]
	v_mfma_f32_16x16x32_bf16 v[82:85], v[134:137], v[220:223], v[82:85]
	s_setprio 0
	s_barrier
; #define PG8_STAGE(bufoff, gbase, voff) do { _Pragma("unroll") for (int _i = 0; _i < 2; ++_i) \
;         __builtin_amdgcn_global_load_lds((const unsigned*)((const char*)(gbase) + (voff)[_i]), (PG8_LAS unsigned*)(lds + (bufoff) + ldsw + _i * 8192), 16, 0, 0); } while (0)
; #define PG8_LDA(dst, b, h) do { _Pragma("unroll") for (int m = 0; m < 4; ++m) _Pragma("unroll") for (int k = 0; k < 2; ++k) dst[m][k] = *(const PG8_LAS bf16x8*)(lds + PG8_SA(b, h) + aoff + m * 2048 + k * 1024); } while (0)
; #define PG8_WAIT_V(n) asm volatile("s_waitcnt vmcnt(" #n ")" ::: "memory")
; template <class Epi, class Sched, bool ALIGN_EPI = false, bool SP2 = false>
; __device__ __forceinline__ void gemm_phase(PG8_LAS unsigned char* lds, const Gemm g, const Sched& S, const Epi& E, const int tid_in) {
;     ...
;         for (int t = 0; t < nt; t += 2) {
;             if constexpr (Epi::KSPLIT > 0) { if (t == Epi::KSPLIT / BK) E.midk(acc, cur, wr, wc, fr, fq); }
;             const bool last = (t == nt - 2);
;             const char* a1 = cA + (size_t)(t + 1) * kstep;
;             const char* a2 = last ? nA : cA + (size_t)(t + 2) * kstep; const char* b2 = last ? nB : cB + (size_t)(t + 2) * kstep;
;             const char* a3 = a2 + kstep; const char* b3 = b2 + kstep;
;             if (last && has_next) S.a_ready(nxt);
;             if constexpr (SP2) {
;             PG8_LDB(B0, 0, 0); PG8_LDB(B1, 0, 1); PG8_SCHED; PG8_LDA(At, 0, 0); PG8_STAGE(PG8_SA(1, 1), a1 + hstep, voffA);
;             PG8_WAIT_V(8); PG8_WAIT_L(0); PG8_BAR; PG8_MMA(0, 0, At, B0); PG8_MMA(0, 1, At, B1); PG8_BAR; PG8_SCHED;
;             PG8_LDA(At, 0, 1); PG8_STAGE(PG8_SB(0, 0), b2, voffB); PG8_STAGE(PG8_SB(0, 1), b2 + hstep, voffB); PG8_STAGE(PG8_SA(0, 0), a2, voffA);
;             PG8_WAIT_V(8); PG8_WAIT_L(0); PG8_BAR; PG8_MMA(1, 0, At, B0); PG8_MMA(1, 1, At, B1); PG8_BAR; PG8_SCHED;
;             PG8_LDB(B0, 1, 0); PG8_LDB(B1, 1, 1); PG8_SCHED; PG8_LDA(At, 1, 0); PG8_STAGE(PG8_SA(0, 1), a2 + hstep, voffA);
;             PG8_WAIT_V(8); PG8_WAIT_L(0); PG8_BAR; PG8_MMA(0, 0, At, B0); PG8_MMA(0, 1, At, B1); PG8_BAR; PG8_SCHED;
;             PG8_LDA(At, 1, 1); PG8_STAGE(PG8_SB(1, 0), b3, voffB); PG8_STAGE(PG8_SB(1, 1), b3 + hstep, voffB); PG8_STAGE(PG8_SA(1, 0), a3, voffA);
;             PG8_WAIT_V(8); PG8_WAIT_L(0); PG8_BAR; PG8_MMA(1, 0, At, B0); PG8_MMA(1, 1, At, B1); PG8_BAR; PG8_SCHED;
	s_add_i32 s54, s63, s1
	s_mov_b32 m0, s54
	ds_read_b128 v[188:191], v193 offset:49152
	ds_read_b128 v[194:197], v193 offset:50176
	ds_read_b128 v[198:201], v193 offset:51200
	ds_read_b128 v[202:205], v193 offset:52224
	ds_read_b128 v[208:211], v193 offset:53248
	ds_read_b128 v[212:215], v193 offset:54272
	ds_read_b128 v[216:219], v193 offset:55296
	ds_read_b128 v[220:223], v193 offset:56320
	global_load_lds_dwordx4 v164, s[98:99]
	s_add_i32 m0, s54, 0x2000
	s_add_u32 s52, s52, 0x80080
	s_addc_u32 s53, s53, 0
	s_add_i32 s54, s64, s1
	global_load_lds_dwordx4 v168, s[98:99]
	s_mov_b32 m0, s54
	s_nop 0
	global_load_lds_dwordx4 v164, s[52:53]
	s_add_i32 m0, s54, 0x2000
	s_nop 0
	global_load_lds_dwordx4 v168, s[52:53]
	s_mov_b32 m0, s24
	s_nop 0
	global_load_lds_dwordx4 v162, s[100:101]
	s_waitcnt vmcnt(7)
	s_waitcnt lgkmcnt(0)
	s_barrier
	s_setprio 1
	v_mfma_f32_16x16x32_bf16 v[54:57], v[66:69], v[188:191], v[54:57]
	v_mfma_f32_16x16x32_bf16 v[30:33], v[74:77], v[188:191], v[30:33]
	v_mfma_f32_16x16x32_bf16 v[50:53], v[66:69], v[198:201], v[50:53]
	v_mfma_f32_16x16x32_bf16 v[26:29], v[74:77], v[198:201], v[26:29]
	v_mfma_f32_16x16x32_bf16 v[46:49], v[66:69], v[208:211], v[46:49]
	v_mfma_f32_16x16x32_bf16 v[22:25], v[74:77], v[208:211], v[22:25]
	v_mfma_f32_16x16x32_bf16 v[42:45], v[66:69], v[216:219], v[42:45]
	v_mfma_f32_16x16x32_bf16 v[16:19], v[74:77], v[216:219], v[16:19]
	v_mfma_f32_16x16x32_bf16 v[54:57], v[70:73], v[194:197], v[54:57]
	v_mfma_f32_16x16x32_bf16 v[30:33], v[78:81], v[194:197], v[30:33]
	v_mfma_f32_16x16x32_bf16 v[50:53], v[70:73], v[202:205], v[50:53]
	v_mfma_f32_16x16x32_bf16 v[26:29], v[78:81], v[202:205], v[26:29]
	v_mfma_f32_16x16x32_bf16 v[46:49], v[70:73], v[212:215], v[46:49]
	v_mfma_f32_16x16x32_bf16 v[22:25], v[78:81], v[212:215], v[22:25]
	v_mfma_f32_16x16x32_bf16 v[42:45], v[70:73], v[220:223], v[42:45]
	v_mfma_f32_16x16x32_bf16 v[16:19], v[78:81], v[220:223], v[16:19]
	s_setprio 0
	s_setprio 1
	v_mfma_f32_16x16x32_bf16 v[12:15], v[122:125], v[188:191], v[12:15]
	v_mfma_f32_16x16x32_bf16 v[8:11], v[130:133], v[188:191], v[8:11]
	v_mfma_f32_16x16x32_bf16 v[62:65], v[122:125], v[198:201], v[62:65]
	v_mfma_f32_16x16x32_bf16 v[38:41], v[130:133], v[198:201], v[38:41]
	v_mfma_f32_16x16x32_bf16 v[58:61], v[122:125], v[208:211], v[58:61]
	v_mfma_f32_16x16x32_bf16 v[34:37], v[130:133], v[208:211], v[34:37]
	v_mfma_f32_16x16x32_bf16 v[4:7], v[122:125], v[216:219], v[4:7]
	v_mfma_f32_16x16x32_bf16 v[0:3], v[130:133], v[216:219], v[0:3]
	v_mfma_f32_16x16x32_bf16 v[12:15], v[126:129], v[194:197], v[12:15]
	v_mfma_f32_16x16x32_bf16 v[8:11], v[134:137], v[194:197], v[8:11]
	v_mfma_f32_16x16x32_bf16 v[62:65], v[126:129], v[202:205], v[62:65]
	v_mfma_f32_16x16x32_bf16 v[38:41], v[134:137], v[202:205], v[38:41]
	v_mfma_f32_16x16x32_bf16 v[58:61], v[126:129], v[212:215], v[58:61]
	v_mfma_f32_16x16x32_bf16 v[34:37], v[134:137], v[212:215], v[34:37]
	v_mfma_f32_16x16x32_bf16 v[4:7], v[126:129], v[220:223], v[4:7]
	v_mfma_f32_16x16x32_bf16 v[0:3], v[134:137], v[220:223], v[0:3]
	s_setprio 0
	s_barrier
	s_add_i32 s62, s62, 2
	s_add_u32 s50, s50, 0x100
	s_addc_u32 s51, s51, 0
	s_add_u32 s60, s60, 0x100
	s_addc_u32 s61, s61, 0
	s_cmp_gt_u32 s62, 29

; #define PG8_BAR __builtin_amdgcn_s_barrier()
; template <class Epi, class Sched, bool ALIGN_EPI = false, bool SP2 = false>
; __device__ __forceinline__ void gemm_phase(PG8_LAS unsigned char* lds, const Gemm g, const Sched& S, const Epi& E, const int tid_in) {
;     ...
;         if (!has_next) break;
; #pragma unroll
;         for (int a = 0; a < 2; ++a)
; #pragma unroll
;             for (int b = 0; b < 2; ++b)
; #pragma unroll
;                 for (int m = 0; m < 4; ++m)
; #pragma unroll
;                     for (int n = 0; n < 2; ++n) acc[a][b][m][n] = (f32x4){0.f, 0.f, 0.f, 0.f};
;         cur = nxt; cA = nA; cB = nB; ++ui;
;         if constexpr (ALIGN_EPI) { if (wr == 1) PG8_BAR; }
.LBB0_1171:
	v_readlane_b32 s46, v255, 18
	v_readlane_b32 s47, v255, 19
	s_andn2_b64 vcc, exec, s[46:47]
	s_cbranch_vccnz .LBB0_1152
	s_branch .LBB0_1152

; #define PG8_WAIT_V(n) asm volatile("s_waitcnt vmcnt(" #n ")" ::: "memory")
; template <class Epi, class Sched, bool ALIGN_EPI = false, bool SP2 = false>
; __device__ __forceinline__ void gemm_phase(PG8_LAS unsigned char* lds, const Gemm g, const Sched& S, const Epi& E, const int tid_in) {
;     ...
;     const int tid = tid_l, wid = __builtin_amdgcn_readfirstlane(tid >> 6), lane = tid & 63, wr = wid >> 2, wc = wid & 3, fr = lane & 15, fq = lane >> 4;
;     const int K = g.K, nt = K / BK;
;     unsigned voffA[2], voffB[2];
; #pragma unroll
;     for (int i = 0; i < 2; ++i) { int R, C; stage_rc(tid * 16 + i * 8192, R, C); const int Rb = perm_row<Epi::PMODE>(R);
;         voffA[i] = (unsigned)(R * K + C) * 2u; voffB[i] = (unsigned)(Rb * K + C) * 2u; }
;     const size_t kstep = (size_t)(BK * 2);
;     const size_t hstep = (size_t)HALF * K * 2;
;     const size_t tstep = 2 * hstep;
;     const unsigned ldsw = (unsigned)wid * 1024u;
;     const int aoff = lds_byte(wr * 64 + fr, fq * 8), boff = lds_byte(wc * 32 + fr, fq * 8);
;     ...
;     Unit cur, nxt; int ui = 0;
;     if (!S.next(0, cur)) return;
;     f32x4 acc[2][2][4][2];
; #pragma unroll
;     for (int a = 0; a < 2; ++a)
; #pragma unroll
;         for (int b = 0; b < 2; ++b)
; #pragma unroll
;             for (int m = 0; m < 4; ++m)
; #pragma unroll
;                 for (int n = 0; n < 2; ++n) acc[a][b][m][n] = (f32x4){0.f, 0.f, 0.f, 0.f};
;     bf16x8 At[4][2], B0[2][2], B1[2][2];
;     const char* cA = (const char*)g.A + (size_t)cur.pm * tstep; const char* cB = (const char*)g.Bt + (size_t)cur.pn * tstep;
;     S.a_ready(cur);
;     if constexpr (Epi::PREF) E.prefetch(cur, 0, lds, wid, lane);
;     if constexpr (SP2) {
;         PG8_STAGE(PG8_SB(0, 0), cB, voffB); PG8_STAGE(PG8_SB(0, 1), cB + hstep, voffB); PG8_STAGE(PG8_SA(0, 0), cA, voffA); PG8_STAGE(PG8_SA(0, 1), cA + hstep, voffA);
;         if (wr == 1) PG8_BAR;
;         PG8_WAIT_V(2); PG8_BAR;
;         PG8_STAGE(PG8_SB(1, 0), cB + kstep, voffB); PG8_STAGE(PG8_SA(1, 0), cA + kstep, voffA); PG8_STAGE(PG8_SB(1, 1), cB + hstep + kstep, voffB);
;         PG8_WAIT_V(6); PG8_BAR;
;     } else {
;         PG8_STAGE(PG8_SB(0, 0), cB, voffB); PG8_STAGE(PG8_SA(0, 0), cA, voffA); PG8_STAGE(PG8_SB(0, 1), cB + hstep, voffB); PG8_STAGE(PG8_SA(0, 1), cA + hstep, voffA);
;         if (wr == 1) PG8_BAR;
;         PG8_WAIT_V(4); PG8_BAR;
.LBB0_1287:
	s_load_dwordx4 s[20:23], s[50:51], 0xf0
	s_waitcnt lgkmcnt(0)
	s_cmp_ge_i32 s48, s22
	s_cselect_b64 s[20:21], -1, 0
	s_and_b64 s[2:3], s[20:21], s[6:7]
	s_andn2_b64 vcc, exec, s[2:3]
	s_cbranch_vccnz .LBB0_1312
	v_readlane_b32 s1, v252, 7
	v_mbcnt_lo_u32_b32 v0, -1, 0
	v_mbcnt_hi_u32_b32 v0, -1, v0
	s_mov_b64 s[2:3], s[50:51]
	v_readlane_b32 s35, v254, 59
	v_or_b32_e32 v16, s1, v0
	v_readlane_b32 s1, v255, 12
	s_mov_b32 s22, s1
	s_and_b64 vcc, exec, s[42:43]
	v_readfirstlane_b32 s26, v16
	s_cbranch_vccnz .LBB0_1312
	v_lshlrev_b32_e32 v0, 4, v16
	v_add_u32_e32 v1, 0x2000, v0
	v_ashrrev_i32_e32 v2, 31, v1
	v_lshrrev_b32_e32 v2, 22, v2
	v_add_u32_e32 v2, v1, v2
	v_ashrrev_i32_e32 v8, 10, v2
	v_mul_i32_i24_e32 v2, 0x400, v8
	v_sub_u32_e32 v1, v1, v2
	v_lshrrev_b32_e32 v2, 4, v1
	s_load_dwordx2 s[24:25], s[2:3], 0xf0
	v_bitop3_b32 v1, v2, v1, 32 bitop3:0x6c
	v_ashrrev_i32_e32 v2, 31, v1
	v_lshrrev_b32_e32 v2, 26, v2
	v_add_u32_e32 v2, v1, v2
	v_lshlrev_b32_e32 v3, 3, v8
	v_ashrrev_i32_e32 v9, 6, v2
	v_and_b32_e32 v3, -16, v3
	s_waitcnt lgkmcnt(0)
	s_add_u32 s1, s24, 0x5f200000
	v_add_u32_e32 v3, v9, v3
	s_mul_i32 s3, s35, 0x1600000
	s_addc_u32 s5, s25, 0
	v_lshrrev_b32_e32 v5, 2, v3
	v_lshlrev_b32_e32 v6, 1, v3
	s_mul_hi_i32 s2, s35, 0x1600000
	s_add_u32 s3, s24, s3
	v_and_b32_e32 v4, 0x7fffe3, v3
	v_and_b32_e32 v5, 4, v5
	v_and_b32_e32 v6, 24, v6
	v_and_b32_e32 v2, 0xc0, v2
	s_addc_u32 s2, s25, s2
	v_or3_b32 v4, v4, v5, v6
	v_sub_u32_e32 v1, v1, v2
	v_mov_b32_e32 v6, 1
	s_add_u32 s8, s3, 0x1f000000
	v_lshlrev_b32_e32 v5, 5, v8
	v_ashrrev_i16_sdwa v1, v6, sext(v1) dst_sel:DWORD dst_unused:UNUSED_PAD src0_sel:DWORD src1_sel:BYTE_0
	s_addc_u32 s10, s2, 0
	v_and_b32_e32 v10, 32, v5
	v_bfe_i32 v11, v1, 0, 16
	s_movk_i32 s2, 0x1600
	v_mul_u32_u24_e32 v4, 0x1600, v4
	v_add_u32_e32 v1, v10, v11
	v_mul_lo_u32 v2, v3, s2
	v_add_lshl_u32 v214, v4, v1, 1
	v_add_lshl_u32 v216, v1, v2, 1
	v_bfe_i32 v1, v16, 27, 1
	v_lshrrev_b32_e32 v1, 22, v1
	v_add_u32_e32 v1, v0, v1
	v_and_b32_e32 v1, 0xfffffc00, v1
	v_sub_u32_e32 v0, v0, v1
	v_lshrrev_b32_e32 v1, 4, v0
	v_ashrrev_i32_e32 v2, 31, v16
	v_bitop3_b32 v0, v1, v0, 32 bitop3:0x6c
	v_lshrrev_b32_e32 v2, 26, v2
	v_ashrrev_i32_e32 v1, 31, v0
	v_add_u32_e32 v2, v16, v2
	v_lshrrev_b32_e32 v1, 26, v1
	v_ashrrev_i32_e32 v13, 6, v2
	v_add_u32_e32 v1, v0, v1
	v_lshlrev_b32_e32 v2, 3, v13
	v_ashrrev_i32_e32 v12, 6, v1
	v_and_b32_e32 v2, -16, v2
	v_add_u32_e32 v2, v12, v2
	v_lshrrev_b32_e32 v4, 2, v2
	v_lshlrev_b32_e32 v5, 1, v2
	v_and_b32_e32 v1, 0xc0, v1
	s_ashr_i32 s27, s26, 6
	v_and_b32_e32 v3, 0x7fffe3, v2
	v_and_b32_e32 v4, 4, v4
	v_and_b32_e32 v5, 24, v5
	v_sub_u32_e32 v0, v0, v1
	v_readlane_b32 s3, v253, 58
	s_ashr_i32 s34, s26, 8
	s_lshl_b32 s19, s27, 10
	v_or3_b32 v3, v3, v4, v5
	v_lshlrev_b32_e32 v4, 5, v13
	v_ashrrev_i16_sdwa v0, v6, sext(v0) dst_sel:DWORD dst_unused:UNUSED_PAD src0_sel:DWORD src1_sel:BYTE_0
	v_mul_lo_u32 v1, v2, s2
	s_mul_i32 s2, s3, 0x2c0000
	v_and_b32_e32 v14, 32, v4
	v_bfe_i32 v15, v0, 0, 16
	s_add_u32 s30, s8, s2
	s_mul_hi_i32 s2, s3, 0x2c0000
	v_mul_u32_u24_e32 v3, 0x1600, v3
	v_add_u32_e32 v0, v14, v15
	s_addc_u32 s31, s10, s2
	s_add_i32 s40, s19, 0
	v_add_lshl_u32 v218, v3, v0, 1
	s_add_i32 m0, s40, 0x10000
	v_add_lshl_u32 v220, v0, v1, 1
	global_load_lds_dwordx4 v218, s[30:31]
	s_add_i32 m0, s40, 0x12000
	s_add_u32 s2, s30, 0x160000
	global_load_lds_dwordx4 v214, s[30:31]
	s_addc_u32 s3, s31, 0
	s_add_i32 m0, s40, 0x14000
	v_mov_b32_e32 v219, v20
	global_load_lds_dwordx4 v218, s[2:3]
	s_add_i32 m0, s40, 0x16000
	v_mov_b32_e32 v215, v20
	global_load_lds_dwordx4 v214, s[2:3]
	v_readlane_b32 s3, v253, 57
	s_mul_i32 s2, s3, 0x2c0000
	s_add_u32 s28, s1, s2
	s_mul_hi_i32 s2, s3, 0x2c0000
	s_addc_u32 s29, s5, s2
	s_add_i32 s41, s40, 0x2000
	s_mov_b32 m0, s40
	s_add_u32 s2, s28, 0x160000
	global_load_lds_dwordx4 v220, s[28:29]
	s_mov_b32 m0, s41
	s_addc_u32 s3, s29, 0
	s_add_i32 s42, s40, 0x4000
	global_load_lds_dwordx4 v216, s[28:29]
	s_mov_b32 m0, s42
	s_add_i32 s43, s40, 0x6000
	global_load_lds_dwordx4 v220, s[2:3]
	s_mov_b32 m0, s43
	v_mov_b32_e32 v221, v20
	global_load_lds_dwordx4 v216, s[2:3]
	v_mov_b32_e32 v217, v20
	s_cmp_eq_u32 s34, 1
	v_lshl_add_u64 v[6:7], s[30:31], 0, v[218:219]
	v_lshl_add_u64 v[4:5], s[30:31], 0, v[214:215]
	v_lshl_add_u64 v[0:1], s[28:29], 0, v[220:221]
	s_cselect_b64 s[2:3], -1, 0
	s_cmp_lg_u32 s34, 1
	v_lshl_add_u64 v[2:3], s[28:29], 0, v[216:217]
	s_cbranch_scc1 .LBB0_1291
.LBB0_1291:
	s_ashr_i32 s23, s22, 31
	s_lshl_b64 s[6:7], s[22:23], 26
	s_add_u32 s6, s24, s6
	s_addc_u32 s7, s25, s7
	s_add_u32 s6, s6, 0x53200000
	s_addc_u32 s7, s7, 0
	s_lshl_b32 s22, s22, 2
	s_mul_hi_i32 s23, s35, 12
	s_mul_i32 s35, s35, 12
	s_ashr_i32 s36, s22, 31
	s_add_u32 s22, s35, s22
	s_addc_u32 s23, s23, s36
	s_mul_i32 s23, s23, 0xc000
	s_mul_hi_u32 s35, s22, 0xc000
	s_add_i32 s35, s35, s23
	s_mul_i32 s22, s22, 0xc000
	s_add_u32 s22, s24, s22
	v_lshrrev_b32_e32 v18, 1, v16
	s_addc_u32 s23, s25, s35
	v_and_b32_e32 v18, 24, v18
	s_add_u32 s44, s22, 0x10a000
	v_and_b32_e32 v17, 15, v16
	v_lshlrev_b32_e32 v19, 1, v18
	v_lshlrev_b32_e32 v16, 2, v16
	s_addc_u32 s45, s23, 0
	v_lshl_or_b32 v21, s34, 6, v17
	v_lshl_or_b32 v17, v17, 6, v19
	s_lshl_b32 s22, s34, 13
	v_and_b32_e32 v16, 32, v16
	v_bitop3_b32 v19, v17, s22, v16 bitop3:0xde
	s_lshl_b32 s22, s27, 5
	s_and_b32 s24, s22, 0x60
	s_add_i32 m0, s40, 0x18000
	v_lshl_add_u64 v[6:7], v[6:7], 0, s[12:13]
	s_lshl_b32 s22, s24, 7
	s_waitcnt vmcnt(2)
	s_barrier
	global_load_lds_dwordx4 v[6:7], off
	v_lshl_add_u64 v[4:5], v[4:5], 0, s[12:13]
	s_add_i32 m0, s40, 0x1a000
	s_add_i32 s46, s40, 0x8000
	s_add_i32 s47, s40, 0xa000
	v_bitop3_b32 v208, v17, s22, v16 bitop3:0xde
	global_load_lds_dwordx4 v[4:5], off
	v_lshl_add_u64 v[0:1], v[0:1], 0, s[12:13]
	s_mov_b32 m0, s46
	s_add_u32 s100, s28, 0x80
	s_addc_u32 s101, s29, 0
	s_add_u32 s22, s30, 0x160080
	global_load_lds_dwordx4 v[0:1], off
	v_lshl_add_u64 v[0:1], v[2:3], 0, s[12:13]
	s_mov_b32 m0, s47
	s_addc_u32 s23, s31, 0
	global_load_lds_dwordx4 v[0:1], off
	s_add_i32 m0, s40, 0x1c000
	v_lshl_add_u64 v[0:1], s[22:23], 0, v[218:219]
	global_load_lds_dwordx4 v[0:1], off
	v_lshl_add_u64 v[0:1], s[22:23], 0, v[214:215]
	s_add_i32 m0, s40, 0x1e000
	s_cmpk_lt_u32 s26, 0x100
	global_load_lds_dwordx4 v[0:1], off
	s_movk_i32 s26, 0x1600
	v_lshrrev_b32_e32 v1, 1, v13
	v_mul_lo_u32 v0, v12, s26
	s_mov_b32 s27, 0x16000
	v_or_b32_e32 v209, s24, v18
	v_mad_u64_u32 v[0:1], s[24:25], v1, s27, v[0:1]
	v_or_b32_e32 v0, v0, v14
	v_add_lshl_u32 v0, v0, v15, 1
	v_mov_b32_e32 v1, v20
	s_mov_b64 s[34:35], 0x160080
	v_lshl_add_u64 v[222:223], v[0:1], 0, s[34:35]
	v_lshrrev_b32_e32 v1, 1, v8
	v_mul_lo_u32 v0, v9, s26
	v_mad_u64_u32 v[0:1], s[24:25], v1, s27, v[0:1]
	s_waitcnt vmcnt(6)
	v_or_b32_e32 v0, v0, v10
	v_add_lshl_u32 v0, v0, v11, 1
	v_mov_b32_e32 v1, v20
	s_cselect_b64 s[22:23], -1, 0
	v_lshl_add_u64 v[224:225], v[0:1], 0, s[34:35]
	s_mov_b32 s49, 0
	v_add_u32_e32 v244, 0, v19
	v_readlane_b32 s53, v253, 58
	v_readlane_b32 s52, v253, 57
	s_barrier
	s_branch .LBB0_1294

; #define PG8_STAGE(bufoff, gbase, voff) do { _Pragma("unroll") for (int _i = 0; _i < 2; ++_i) \
;         __builtin_amdgcn_global_load_lds((const unsigned*)((const char*)(gbase) + (voff)[_i]), (PG8_LAS unsigned*)(lds + (bufoff) + ldsw + _i * 8192), 16, 0, 0); } while (0)
; #define PG8_LDA(dst, b, h) do { _Pragma("unroll") for (int m = 0; m < 4; ++m) _Pragma("unroll") for (int k = 0; k < 2; ++k) dst[m][k] = *(const PG8_LAS bf16x8*)(lds + PG8_SA(b, h) + aoff + m * 2048 + k * 1024); } while (0)
; #define PG8_LDB(dst, b, h) do { _Pragma("unroll") for (int n = 0; n < 2; ++n) _Pragma("unroll") for (int k = 0; k < 2; ++k) dst[n][k] = *(const PG8_LAS bf16x8*)(lds + PG8_SB(b, h) + boff + n * 2048 + k * 1024); } while (0)
; #define PG8_WAIT_V(n) asm volatile("s_waitcnt vmcnt(" #n ")" ::: "memory")
; #define PG8_WAIT_L(n) asm volatile("s_waitcnt lgkmcnt(" #n ")" ::: "memory")
; template <class Epi, class Sched, bool ALIGN_EPI = false, bool SP2 = false>
; __device__ __forceinline__ void gemm_phase(PG8_LAS unsigned char* lds, const Gemm g, const Sched& S, const Epi& E, const int tid_in) {
;     ...
;     for (;;) {
;         const bool has_next = S.next(ui + 1, nxt);
;         const char* nA = has_next ? (const char*)g.A + (size_t)nxt.pm * tstep : cA; const char* nB = has_next ? (const char*)g.Bt + (size_t)nxt.pn * tstep : cB;
;         for (int t = 0; t < nt; t += 2) {
;             if constexpr (Epi::KSPLIT > 0) { if (t == Epi::KSPLIT / BK) E.midk(acc, cur, wr, wc, fr, fq); }
;             const bool last = (t == nt - 2);
;             const char* a1 = cA + (size_t)(t + 1) * kstep;
;             const char* a2 = last ? nA : cA + (size_t)(t + 2) * kstep; const char* b2 = last ? nB : cB + (size_t)(t + 2) * kstep;
;             const char* a3 = a2 + kstep; const char* b3 = b2 + kstep;
;             if (last && has_next) S.a_ready(nxt);
;             if constexpr (SP2) {
;             PG8_LDB(B0, 0, 0); PG8_LDB(B1, 0, 1); PG8_SCHED; PG8_LDA(At, 0, 0); PG8_STAGE(PG8_SA(1, 1), a1 + hstep, voffA);
;             PG8_WAIT_V(8); PG8_WAIT_L(0); PG8_BAR; PG8_MMA(0, 0, At, B0); PG8_MMA(0, 1, At, B1); PG8_BAR; PG8_SCHED;
;             PG8_LDA(At, 0, 1); PG8_STAGE(PG8_SB(0, 0), b2, voffB); PG8_STAGE(PG8_SB(0, 1), b2 + hstep, voffB); PG8_STAGE(PG8_SA(0, 0), a2, voffA);
;             PG8_WAIT_V(8); PG8_WAIT_L(0); PG8_BAR; PG8_MMA(1, 0, At, B0); PG8_MMA(1, 1, At, B1); PG8_BAR; PG8_SCHED;
.LBB0_1304:
	s_add_u32 s54, s30, 0x100
	v_mov_b32_e32 v0, 0
	s_addc_u32 s55, s31, 0
	s_mov_b32 s56, -2
	s_cmp_lt_u32 s19, 0x1000
	s_cbranch_scc1 .LCB_1305
	s_barrier
.LCB_1305:
	s_mov_b32 m0, s47
	s_nop 0
	global_load_lds_dwordx4 v216, s[100:101]
	s_add_u32 s30, s28, 0x100
	s_addc_u32 s31, s29, 0
	s_add_i32 s57, 0, 0x10000
	s_cmpk_eq_i32 s56, 0x54
	s_cselect_b32 s39, s25, s31
	s_cselect_b32 s38, s24, s30
	s_cselect_b32 s35, s27, s55
	s_cselect_b32 s34, s26, s54
	s_add_i32 s58, 0, 0x14000
	v_add_u32_e32 v102, s57, v208
	v_add_u32_e32 v142, s58, v208
	ds_read_b128 v[78:81], v102
	ds_read_b128 v[86:89], v102 offset:1024
	ds_read_b128 v[94:97], v102 offset:2048
	ds_read_b128 v[102:105], v102 offset:3072
	ds_read_b128 v[118:121], v142
	ds_read_b128 v[126:129], v142 offset:1024
	ds_read_b128 v[134:137], v142 offset:2048
	ds_read_b128 v[142:145], v142 offset:3072
	v_lshl_add_u64 v[194:195], s[28:29], 0, v[222:223]
	s_add_i32 m0, s40, 0xc000
	ds_read_b128 v[154:157], v244
	ds_read_b128 v[158:161], v244 offset:1024
	ds_read_b128 v[162:165], v244 offset:2048
	ds_read_b128 v[166:169], v244 offset:3072
	ds_read_b128 v[170:173], v244 offset:4096
	ds_read_b128 v[182:185], v244 offset:5120
	ds_read_b128 v[186:189], v244 offset:6144
	ds_read_b128 v[190:193], v244 offset:7168
	global_load_lds_dwordx4 v[194:195], off
	v_lshl_add_u64 v[194:195], s[28:29], 0, v[224:225]
	s_add_i32 m0, s40, 0xe000
	s_nop 0
	global_load_lds_dwordx4 v[194:195], off
	s_waitcnt vmcnt(8)
	s_waitcnt lgkmcnt(0)
	s_barrier
	s_setprio 1
	v_mfma_f32_16x16x32_bf16 v[178:181], v[78:81], v[154:157], 0
	v_mfma_f32_16x16x32_bf16 v[174:177], v[94:97], v[154:157], 0
	v_mfma_f32_16x16x32_bf16 v[138:141], v[78:81], v[162:165], 0
	v_mfma_f32_16x16x32_bf16 v[130:133], v[94:97], v[162:165], 0
	v_mfma_f32_16x16x32_bf16 v[110:113], v[78:81], v[170:173], 0
	v_mfma_f32_16x16x32_bf16 v[106:109], v[94:97], v[170:173], 0
	v_mfma_f32_16x16x32_bf16 v[82:85], v[78:81], v[186:189], 0
	v_mfma_f32_16x16x32_bf16 v[74:77], v[94:97], v[186:189], 0
	v_mfma_f32_16x16x32_bf16 v[178:181], v[86:89], v[158:161], v[178:181]
	v_mfma_f32_16x16x32_bf16 v[174:177], v[102:105], v[158:161], v[174:177]
	v_mfma_f32_16x16x32_bf16 v[138:141], v[86:89], v[166:169], v[138:141]
	v_mfma_f32_16x16x32_bf16 v[130:133], v[102:105], v[166:169], v[130:133]
	v_mfma_f32_16x16x32_bf16 v[110:113], v[86:89], v[182:185], v[110:113]
	v_mfma_f32_16x16x32_bf16 v[106:109], v[102:105], v[182:185], v[106:109]
	v_mfma_f32_16x16x32_bf16 v[82:85], v[86:89], v[190:193], v[82:85]
	v_mfma_f32_16x16x32_bf16 v[74:77], v[102:105], v[190:193], v[74:77]
	s_setprio 0
	s_setprio 1
	v_mfma_f32_16x16x32_bf16 v[150:153], v[118:121], v[154:157], 0
	v_mfma_f32_16x16x32_bf16 v[146:149], v[134:137], v[154:157], 0
	v_mfma_f32_16x16x32_bf16 v[122:125], v[118:121], v[162:165], 0
	v_mfma_f32_16x16x32_bf16 v[114:117], v[134:137], v[162:165], 0
	v_mfma_f32_16x16x32_bf16 v[98:101], v[118:121], v[170:173], 0
	v_mfma_f32_16x16x32_bf16 v[90:93], v[134:137], v[170:173], 0
	v_mfma_f32_16x16x32_bf16 v[70:73], v[118:121], v[186:189], 0
	v_mfma_f32_16x16x32_bf16 v[66:69], v[134:137], v[186:189], 0
	v_mfma_f32_16x16x32_bf16 v[150:153], v[126:129], v[158:161], v[150:153]
	v_mfma_f32_16x16x32_bf16 v[146:149], v[142:145], v[158:161], v[146:149]
	v_mfma_f32_16x16x32_bf16 v[122:125], v[126:129], v[166:169], v[122:125]
	v_mfma_f32_16x16x32_bf16 v[114:117], v[142:145], v[166:169], v[114:117]
	v_mfma_f32_16x16x32_bf16 v[98:101], v[126:129], v[182:185], v[98:101]
	v_mfma_f32_16x16x32_bf16 v[90:93], v[142:145], v[182:185], v[90:93]
	v_mfma_f32_16x16x32_bf16 v[70:73], v[126:129], v[190:193], v[70:73]
	v_mfma_f32_16x16x32_bf16 v[66:69], v[142:145], v[190:193], v[66:69]
	s_setprio 0
	s_barrier
	s_add_i32 s28, s57, s19
	s_add_u32 s98, s34, 0x80
	s_addc_u32 s99, s35, 0
	s_mov_b32 m0, s28
	ds_read_b128 v[154:157], v244 offset:16384
	ds_read_b128 v[158:161], v244 offset:17408
	ds_read_b128 v[162:165], v244 offset:18432
	ds_read_b128 v[166:169], v244 offset:19456
	ds_read_b128 v[170:173], v244 offset:20480
	ds_read_b128 v[182:185], v244 offset:21504
	ds_read_b128 v[186:189], v244 offset:22528
	ds_read_b128 v[190:193], v244 offset:23552
	global_load_lds_dwordx4 v218, s[34:35]
	s_add_i32 m0, s28, 0x2000
	s_add_u32 s28, s34, 0x160000
	s_addc_u32 s29, s35, 0
	s_add_i32 s57, s58, s19
	global_load_lds_dwordx4 v214, s[34:35]
	s_mov_b32 m0, s57
	s_add_u32 s100, s38, 0x80
	s_addc_u32 s101, s39, 0
	global_load_lds_dwordx4 v218, s[28:29]
	s_add_i32 m0, s57, 0x2000
	s_nop 0
	global_load_lds_dwordx4 v214, s[28:29]
	s_mov_b32 m0, s40
	s_nop 0
	global_load_lds_dwordx4 v220, s[38:39]
	s_waitcnt vmcnt(7)
	s_waitcnt lgkmcnt(0)
	s_barrier
; #define PG8_STAGE(bufoff, gbase, voff) do { _Pragma("unroll") for (int _i = 0; _i < 2; ++_i) \
;         __builtin_amdgcn_global_load_lds((const unsigned*)((const char*)(gbase) + (voff)[_i]), (PG8_LAS unsigned*)(lds + (bufoff) + ldsw + _i * 8192), 16, 0, 0); } while (0)
; #define PG8_LDA(dst, b, h) do { _Pragma("unroll") for (int m = 0; m < 4; ++m) _Pragma("unroll") for (int k = 0; k < 2; ++k) dst[m][k] = *(const PG8_LAS bf16x8*)(lds + PG8_SA(b, h) + aoff + m * 2048 + k * 1024); } while (0)
; #define PG8_LDB(dst, b, h) do { _Pragma("unroll") for (int n = 0; n < 2; ++n) _Pragma("unroll") for (int k = 0; k < 2; ++k) dst[n][k] = *(const PG8_LAS bf16x8*)(lds + PG8_SB(b, h) + boff + n * 2048 + k * 1024); } while (0)
; #define PG8_MMA(ai, bj, At, Bt) do { __builtin_amdgcn_s_setprio(1); _Pragma("unroll") for (int m = 0; m < 4; ++m) _Pragma("unroll") for (int n = 0; n < 2; ++n) _Pragma("unroll") for (int k = 0; k < 2; ++k) \
;         acc[ai][bj][m][n] = __builtin_amdgcn_mfma_f32_16x16x32_bf16(Bt[n][k], At[m][k], acc[ai][bj][m][n], 0, 0, 0); __builtin_amdgcn_s_setprio(0); } while (0)
; #define PG8_BAR __builtin_amdgcn_s_barrier()
; template <class Epi, class Sched, bool ALIGN_EPI = false, bool SP2 = false>
; __device__ __forceinline__ void gemm_phase(PG8_LAS unsigned char* lds, const Gemm g, const Sched& S, const Epi& E, const int tid_in) {
;     ...
;             PG8_LDB(B0, 0, 0); PG8_LDB(B1, 0, 1); PG8_SCHED; PG8_LDA(At, 0, 0); PG8_STAGE(PG8_SA(1, 1), a1 + hstep, voffA);
;             PG8_WAIT_V(8); PG8_WAIT_L(0); PG8_BAR; PG8_MMA(0, 0, At, B0); PG8_MMA(0, 1, At, B1); PG8_BAR; PG8_SCHED;
;             PG8_LDA(At, 0, 1); PG8_STAGE(PG8_SB(0, 0), b2, voffB); PG8_STAGE(PG8_SB(0, 1), b2 + hstep, voffB); PG8_STAGE(PG8_SA(0, 0), a2, voffA);
;             PG8_WAIT_V(8); PG8_WAIT_L(0); PG8_BAR; PG8_MMA(1, 0, At, B0); PG8_MMA(1, 1, At, B1); PG8_BAR; PG8_SCHED;
;             PG8_LDB(B0, 1, 0); PG8_LDB(B1, 1, 1); PG8_SCHED; PG8_LDA(At, 1, 0); PG8_STAGE(PG8_SA(0, 1), a2 + hstep, voffA);
;             PG8_WAIT_V(8); PG8_WAIT_L(0); PG8_BAR; PG8_MMA(0, 0, At, B0); PG8_MMA(0, 1, At, B1); PG8_BAR; PG8_SCHED;
;             PG8_LDA(At, 1, 1); PG8_STAGE(PG8_SB(1, 0), b3, voffB); PG8_STAGE(PG8_SB(1, 1), b3 + hstep, voffB); PG8_STAGE(PG8_SA(1, 0), a3, voffA);
;             PG8_WAIT_V(8); PG8_WAIT_L(0); PG8_BAR; PG8_MMA(1, 0, At, B0); PG8_MMA(1, 1, At, B1); PG8_BAR; PG8_SCHED;
	s_setprio 1
	v_mfma_f32_16x16x32_bf16 v[62:65], v[78:81], v[154:157], 0
	v_mfma_f32_16x16x32_bf16 v[58:61], v[94:97], v[154:157], 0
	v_mfma_f32_16x16x32_bf16 v[46:49], v[78:81], v[162:165], 0
	v_mfma_f32_16x16x32_bf16 v[42:45], v[94:97], v[162:165], 0
	v_mfma_f32_16x16x32_bf16 v[30:33], v[78:81], v[170:173], 0
	v_mfma_f32_16x16x32_bf16 v[26:29], v[94:97], v[170:173], 0
	v_mfma_f32_16x16x32_bf16 v[12:15], v[78:81], v[186:189], 0
	v_mfma_f32_16x16x32_bf16 v[8:11], v[94:97], v[186:189], 0
	v_mfma_f32_16x16x32_bf16 v[62:65], v[86:89], v[158:161], v[62:65]
	v_mfma_f32_16x16x32_bf16 v[58:61], v[102:105], v[158:161], v[58:61]
	v_mfma_f32_16x16x32_bf16 v[46:49], v[86:89], v[166:169], v[46:49]
	v_mfma_f32_16x16x32_bf16 v[42:45], v[102:105], v[166:169], v[42:45]
	v_mfma_f32_16x16x32_bf16 v[30:33], v[86:89], v[182:185], v[30:33]
	v_mfma_f32_16x16x32_bf16 v[26:29], v[102:105], v[182:185], v[26:29]
	v_mfma_f32_16x16x32_bf16 v[12:15], v[86:89], v[190:193], v[12:15]
	v_mfma_f32_16x16x32_bf16 v[8:11], v[102:105], v[190:193], v[8:11]
	s_setprio 0
	s_setprio 1
	v_mfma_f32_16x16x32_bf16 v[54:57], v[118:121], v[154:157], 0
	v_mfma_f32_16x16x32_bf16 v[50:53], v[134:137], v[154:157], 0
	v_mfma_f32_16x16x32_bf16 v[38:41], v[118:121], v[162:165], 0
	v_mfma_f32_16x16x32_bf16 v[34:37], v[134:137], v[162:165], 0
	v_mfma_f32_16x16x32_bf16 v[22:25], v[118:121], v[170:173], 0
	v_mfma_f32_16x16x32_bf16 v[16:19], v[134:137], v[170:173], 0
	v_mfma_f32_16x16x32_bf16 v[4:7], v[118:121], v[186:189], 0
	v_mfma_f32_16x16x32_bf16 v[0:3], v[134:137], v[186:189], 0
	v_mfma_f32_16x16x32_bf16 v[54:57], v[126:129], v[158:161], v[54:57]
	v_mfma_f32_16x16x32_bf16 v[50:53], v[142:145], v[158:161], v[50:53]
	v_mfma_f32_16x16x32_bf16 v[38:41], v[126:129], v[166:169], v[38:41]
	v_mfma_f32_16x16x32_bf16 v[34:37], v[142:145], v[166:169], v[34:37]
	v_mfma_f32_16x16x32_bf16 v[22:25], v[126:129], v[182:185], v[22:25]
	v_mfma_f32_16x16x32_bf16 v[16:19], v[142:145], v[182:185], v[16:19]
	v_mfma_f32_16x16x32_bf16 v[4:7], v[126:129], v[190:193], v[4:7]
	v_mfma_f32_16x16x32_bf16 v[0:3], v[142:145], v[190:193], v[0:3]
	s_setprio 0
	s_barrier
	s_add_i32 s57, 0, 0x18000
	s_add_i32 s58, 0, 0x1c000
	v_add_u32_e32 v102, s57, v208
	v_add_u32_e32 v142, s58, v208
	ds_read_b128 v[78:81], v102
	ds_read_b128 v[86:89], v102 offset:1024
	ds_read_b128 v[94:97], v102 offset:2048
	ds_read_b128 v[102:105], v102 offset:3072
	ds_read_b128 v[118:121], v142
	ds_read_b128 v[126:129], v142 offset:1024
	ds_read_b128 v[134:137], v142 offset:2048
	ds_read_b128 v[142:145], v142 offset:3072
	s_add_u32 s28, s38, 0x160000
	s_addc_u32 s29, s39, 0
	s_mov_b32 m0, s41
	s_nop 0
	global_load_lds_dwordx4 v216, s[38:39]
	s_mov_b32 m0, s42
	ds_read_b128 v[154:157], v244 offset:32768
	ds_read_b128 v[158:161], v244 offset:33792
	ds_read_b128 v[162:165], v244 offset:34816
	ds_read_b128 v[166:169], v244 offset:35840
	ds_read_b128 v[170:173], v244 offset:36864
	ds_read_b128 v[182:185], v244 offset:37888
	ds_read_b128 v[186:189], v244 offset:38912
	ds_read_b128 v[190:193], v244 offset:39936
	global_load_lds_dwordx4 v220, s[28:29]
	s_mov_b32 m0, s43
	s_nop 0
	global_load_lds_dwordx4 v216, s[28:29]
	s_waitcnt vmcnt(8)
	s_waitcnt lgkmcnt(0)
	s_barrier
	s_setprio 1
	v_mfma_f32_16x16x32_bf16 v[178:181], v[78:81], v[154:157], v[178:181]
	v_mfma_f32_16x16x32_bf16 v[174:177], v[94:97], v[154:157], v[174:177]
	v_mfma_f32_16x16x32_bf16 v[138:141], v[78:81], v[162:165], v[138:141]
	v_mfma_f32_16x16x32_bf16 v[130:133], v[94:97], v[162:165], v[130:133]
	v_mfma_f32_16x16x32_bf16 v[110:113], v[78:81], v[170:173], v[110:113]
	v_mfma_f32_16x16x32_bf16 v[106:109], v[94:97], v[170:173], v[106:109]
	v_mfma_f32_16x16x32_bf16 v[82:85], v[78:81], v[186:189], v[82:85]
	v_mfma_f32_16x16x32_bf16 v[74:77], v[94:97], v[186:189], v[74:77]
	v_mfma_f32_16x16x32_bf16 v[178:181], v[86:89], v[158:161], v[178:181]
	v_mfma_f32_16x16x32_bf16 v[174:177], v[102:105], v[158:161], v[174:177]
	v_mfma_f32_16x16x32_bf16 v[138:141], v[86:89], v[166:169], v[138:141]
	v_mfma_f32_16x16x32_bf16 v[130:133], v[102:105], v[166:169], v[130:133]
	v_mfma_f32_16x16x32_bf16 v[110:113], v[86:89], v[182:185], v[110:113]
	v_mfma_f32_16x16x32_bf16 v[106:109], v[102:105], v[182:185], v[106:109]
	v_mfma_f32_16x16x32_bf16 v[82:85], v[86:89], v[190:193], v[82:85]
	v_mfma_f32_16x16x32_bf16 v[74:77], v[102:105], v[190:193], v[74:77]
	s_setprio 0
	s_setprio 1
	v_mfma_f32_16x16x32_bf16 v[150:153], v[118:121], v[154:157], v[150:153]
	v_mfma_f32_16x16x32_bf16 v[146:149], v[134:137], v[154:157], v[146:149]
	v_mfma_f32_16x16x32_bf16 v[122:125], v[118:121], v[162:165], v[122:125]
	v_mfma_f32_16x16x32_bf16 v[114:117], v[134:137], v[162:165], v[114:117]
	v_mfma_f32_16x16x32_bf16 v[98:101], v[118:121], v[170:173], v[98:101]
	v_mfma_f32_16x16x32_bf16 v[90:93], v[134:137], v[170:173], v[90:93]
	v_mfma_f32_16x16x32_bf16 v[70:73], v[118:121], v[186:189], v[70:73]
	v_mfma_f32_16x16x32_bf16 v[66:69], v[134:137], v[186:189], v[66:69]
	v_mfma_f32_16x16x32_bf16 v[150:153], v[126:129], v[158:161], v[150:153]
	v_mfma_f32_16x16x32_bf16 v[146:149], v[142:145], v[158:161], v[146:149]
	v_mfma_f32_16x16x32_bf16 v[122:125], v[126:129], v[166:169], v[122:125]
	v_mfma_f32_16x16x32_bf16 v[114:117], v[142:145], v[166:169], v[114:117]
	v_mfma_f32_16x16x32_bf16 v[98:101], v[126:129], v[182:185], v[98:101]
	v_mfma_f32_16x16x32_bf16 v[90:93], v[142:145], v[182:185], v[90:93]
	v_mfma_f32_16x16x32_bf16 v[70:73], v[126:129], v[190:193], v[70:73]
	v_mfma_f32_16x16x32_bf16 v[66:69], v[142:145], v[190:193], v[66:69]
	s_setprio 0
	s_barrier
; #define PG8_STAGE(bufoff, gbase, voff) do { _Pragma("unroll") for (int _i = 0; _i < 2; ++_i) \
;         __builtin_amdgcn_global_load_lds((const unsigned*)((const char*)(gbase) + (voff)[_i]), (PG8_LAS unsigned*)(lds + (bufoff) + ldsw + _i * 8192), 16, 0, 0); } while (0)
; #define PG8_LDA(dst, b, h) do { _Pragma("unroll") for (int m = 0; m < 4; ++m) _Pragma("unroll") for (int k = 0; k < 2; ++k) dst[m][k] = *(const PG8_LAS bf16x8*)(lds + PG8_SA(b, h) + aoff + m * 2048 + k * 1024); } while (0)
; #define PG8_WAIT_V(n) asm volatile("s_waitcnt vmcnt(" #n ")" ::: "memory")
; template <class Epi, class Sched, bool ALIGN_EPI = false, bool SP2 = false>
; __device__ __forceinline__ void gemm_phase(PG8_LAS unsigned char* lds, const Gemm g, const Sched& S, const Epi& E, const int tid_in) {
;     ...
;         for (int t = 0; t < nt; t += 2) {
;             if constexpr (Epi::KSPLIT > 0) { if (t == Epi::KSPLIT / BK) E.midk(acc, cur, wr, wc, fr, fq); }
;             const bool last = (t == nt - 2);
;             const char* a1 = cA + (size_t)(t + 1) * kstep;
;             const char* a2 = last ? nA : cA + (size_t)(t + 2) * kstep; const char* b2 = last ? nB : cB + (size_t)(t + 2) * kstep;
;             const char* a3 = a2 + kstep; const char* b3 = b2 + kstep;
;             if (last && has_next) S.a_ready(nxt);
;             if constexpr (SP2) {
;             PG8_LDB(B0, 0, 0); PG8_LDB(B1, 0, 1); PG8_SCHED; PG8_LDA(At, 0, 0); PG8_STAGE(PG8_SA(1, 1), a1 + hstep, voffA);
;             PG8_WAIT_V(8); PG8_WAIT_L(0); PG8_BAR; PG8_MMA(0, 0, At, B0); PG8_MMA(0, 1, At, B1); PG8_BAR; PG8_SCHED;
;             PG8_LDA(At, 0, 1); PG8_STAGE(PG8_SB(0, 0), b2, voffB); PG8_STAGE(PG8_SB(0, 1), b2 + hstep, voffB); PG8_STAGE(PG8_SA(0, 0), a2, voffA);
;             PG8_WAIT_V(8); PG8_WAIT_L(0); PG8_BAR; PG8_MMA(1, 0, At, B0); PG8_MMA(1, 1, At, B1); PG8_BAR; PG8_SCHED;
;             PG8_LDB(B0, 1, 0); PG8_LDB(B1, 1, 1); PG8_SCHED; PG8_LDA(At, 1, 0); PG8_STAGE(PG8_SA(0, 1), a2 + hstep, voffA);
;             PG8_WAIT_V(8); PG8_WAIT_L(0); PG8_BAR; PG8_MMA(0, 0, At, B0); PG8_MMA(0, 1, At, B1); PG8_BAR; PG8_SCHED;
;             PG8_LDA(At, 1, 1); PG8_STAGE(PG8_SB(1, 0), b3, voffB); PG8_STAGE(PG8_SB(1, 1), b3 + hstep, voffB); PG8_STAGE(PG8_SA(1, 0), a3, voffA);
;             PG8_WAIT_V(8); PG8_WAIT_L(0); PG8_BAR; PG8_MMA(1, 0, At, B0); PG8_MMA(1, 1, At, B1); PG8_BAR; PG8_SCHED;
	s_add_i32 s28, s57, s19
	s_mov_b32 m0, s28
	ds_read_b128 v[154:157], v244 offset:49152
	ds_read_b128 v[158:161], v244 offset:50176
	ds_read_b128 v[162:165], v244 offset:51200
	ds_read_b128 v[166:169], v244 offset:52224
	ds_read_b128 v[170:173], v244 offset:53248
	ds_read_b128 v[182:185], v244 offset:54272
	ds_read_b128 v[186:189], v244 offset:55296
	ds_read_b128 v[190:193], v244 offset:56320
	global_load_lds_dwordx4 v218, s[98:99]
	s_add_i32 m0, s28, 0x2000
	s_add_u32 s28, s34, 0x160080
	s_addc_u32 s29, s35, 0
	s_add_i32 s34, s58, s19
	global_load_lds_dwordx4 v214, s[98:99]
	s_mov_b32 m0, s34
	s_nop 0
	global_load_lds_dwordx4 v218, s[28:29]
	s_add_i32 m0, s34, 0x2000
	s_nop 0
	global_load_lds_dwordx4 v214, s[28:29]
	s_mov_b32 m0, s46
	s_nop 0
	global_load_lds_dwordx4 v220, s[100:101]
	s_waitcnt vmcnt(7)
	s_waitcnt lgkmcnt(0)
	s_barrier
	s_setprio 1
	v_mfma_f32_16x16x32_bf16 v[62:65], v[78:81], v[154:157], v[62:65]
	v_mfma_f32_16x16x32_bf16 v[58:61], v[94:97], v[154:157], v[58:61]
	v_mfma_f32_16x16x32_bf16 v[46:49], v[78:81], v[162:165], v[46:49]
	v_mfma_f32_16x16x32_bf16 v[42:45], v[94:97], v[162:165], v[42:45]
	v_mfma_f32_16x16x32_bf16 v[30:33], v[78:81], v[170:173], v[30:33]
	v_mfma_f32_16x16x32_bf16 v[26:29], v[94:97], v[170:173], v[26:29]
	v_mfma_f32_16x16x32_bf16 v[12:15], v[78:81], v[186:189], v[12:15]
	v_mfma_f32_16x16x32_bf16 v[8:11], v[94:97], v[186:189], v[8:11]
	v_mfma_f32_16x16x32_bf16 v[62:65], v[86:89], v[158:161], v[62:65]
	v_mfma_f32_16x16x32_bf16 v[58:61], v[102:105], v[158:161], v[58:61]
	v_mfma_f32_16x16x32_bf16 v[46:49], v[86:89], v[166:169], v[46:49]
	v_mfma_f32_16x16x32_bf16 v[42:45], v[102:105], v[166:169], v[42:45]
	v_mfma_f32_16x16x32_bf16 v[30:33], v[86:89], v[182:185], v[30:33]
	v_mfma_f32_16x16x32_bf16 v[26:29], v[102:105], v[182:185], v[26:29]
	v_mfma_f32_16x16x32_bf16 v[12:15], v[86:89], v[190:193], v[12:15]
	v_mfma_f32_16x16x32_bf16 v[8:11], v[102:105], v[190:193], v[8:11]
	s_setprio 0
	s_setprio 1
	v_mfma_f32_16x16x32_bf16 v[54:57], v[118:121], v[154:157], v[54:57]
	v_mfma_f32_16x16x32_bf16 v[50:53], v[134:137], v[154:157], v[50:53]
	v_mfma_f32_16x16x32_bf16 v[38:41], v[118:121], v[162:165], v[38:41]
	v_mfma_f32_16x16x32_bf16 v[34:37], v[134:137], v[162:165], v[34:37]
	v_mfma_f32_16x16x32_bf16 v[22:25], v[118:121], v[170:173], v[22:25]
	v_mfma_f32_16x16x32_bf16 v[16:19], v[134:137], v[170:173], v[16:19]
	v_mfma_f32_16x16x32_bf16 v[4:7], v[118:121], v[186:189], v[4:7]
	v_mfma_f32_16x16x32_bf16 v[0:3], v[134:137], v[186:189], v[0:3]
	v_mfma_f32_16x16x32_bf16 v[54:57], v[126:129], v[158:161], v[54:57]
	v_mfma_f32_16x16x32_bf16 v[50:53], v[142:145], v[158:161], v[50:53]
	v_mfma_f32_16x16x32_bf16 v[38:41], v[126:129], v[166:169], v[38:41]
	v_mfma_f32_16x16x32_bf16 v[34:37], v[142:145], v[166:169], v[34:37]
	v_mfma_f32_16x16x32_bf16 v[22:25], v[126:129], v[182:185], v[22:25]
	v_mfma_f32_16x16x32_bf16 v[16:19], v[142:145], v[182:185], v[16:19]
	v_mfma_f32_16x16x32_bf16 v[4:7], v[126:129], v[190:193], v[4:7]
	v_mfma_f32_16x16x32_bf16 v[0:3], v[142:145], v[190:193], v[0:3]
	s_setprio 0
	s_barrier
	s_add_i32 s56, s56, 2
	s_add_u32 s54, s54, 0x100
	s_addc_u32 s55, s55, 0
	s_cmpk_gt_u32 s56, 0x55
	s_mov_b64 s[28:29], s[30:31]

;     __device__ __forceinline__ void operator()(const f32x4 (&acc)[2][2][4][2], const Unit& u, int wr, int wc, int fr, int fq) const {
;         const int row0 = u.pm * BM + wr * 64 + fr, col0 = u.pn * BM + wc * 32 + 8 * fq;
;         const float* gp = gate + (size_t)(u.pm >> 4) * 12288 + col0;
;         f32x4 gv[2][2];
; #pragma unroll
;         for (int bj = 0; bj < 2; ++bj)
; #pragma unroll
;             for (int n = 0; n < 2; ++n) gv[bj][n] = *(const f32x4*)(gp + bj * HALF + n * 4);
;         if constexpr (F32IN) {
; #pragma unroll
;             for (int ai = 0; ai < 2; ++ai) {
;                 f32x4 xo[4][2][2];
; #pragma unroll
;                 for (int m = 0; m < 4; ++m) { const size_t off = (size_t)(row0 + ai * HALF + m * 16) * 2048 + col0;
; #pragma unroll
;                     for (int bj = 0; bj < 2; ++bj)
; #pragma unroll
;                         for (int n = 0; n < 2; ++n) xo[m][bj][n] = *(const f32x4*)(xin + off + bj * HALF + n * 4); }
; #pragma unroll
;                 for (int m = 0; m < 4; ++m) { const size_t off = (size_t)(row0 + ai * HALF + m * 16) * 2048 + col0;
; #pragma unroll
;                     for (int bj = 0; bj < 2; ++bj) { const f32x4 v0 = xo[m][bj][0] + gv[bj][0] * acc[ai][bj][m][0], v1 = xo[m][bj][1] + gv[bj][1] * acc[ai][bj][m][1];
;                         u32x4 w; w.x = pkh2(v0[0], v0[1]); w.y = pkh2(v0[2], v0[3]); w.z = pkh2(v1[0], v1[1]); w.w = pkh2(v1[2], v1[3]);
;                         *(u32x4*)(xnew + off + bj * HALF) = w; } }
;             }
;         } else {
;             u32x4 xo[2][4][2];
; #pragma unroll
;             for (int ai = 0; ai < 2; ++ai)
; #pragma unroll
;                 for (int m = 0; m < 4; ++m) { const size_t off = (size_t)(row0 + ai * HALF + m * 16) * 2048 + col0;
; #pragma unroll
;                     for (int bj = 0; bj < 2; ++bj) xo[ai][m][bj] = *(const u32x4*)(xold + off + bj * HALF); }
; #pragma unroll
;             for (int ai = 0; ai < 2; ++ai)
; #pragma unroll
;                 for (int m = 0; m < 4; ++m) { const size_t off = (size_t)(row0 + ai * HALF + m * 16) * 2048 + col0;
; #pragma unroll
;                     for (int bj = 0; bj < 2; ++bj) { const u32x4 o = xo[ai][m][bj]; const f32x4 a0 = acc[ai][bj][m][0], a1 = acc[ai][bj][m][1], g0 = gv[bj][0], g1 = gv[bj][1];
;                         u32x4 w;
.LBB0_1308:
	s_ashr_i32 s28, s52, 4
	v_lshl_or_b32 v118, s53, 8, v209
	s_mul_hi_i32 s29, s28, 0xc000
	s_mul_i32 s28, s28, 0xc000
	s_add_u32 s28, s44, s28
	v_ashrrev_i32_e32 v119, 31, v118
	v_lshl_add_u32 v120, s52, 8, v21
	s_addc_u32 s29, s45, s29
	v_lshlrev_b64 v[226:227], 1, v[118:119]
	v_ashrrev_i32_e32 v121, 31, v120
	v_lshl_add_u64 v[86:87], v[118:119], 2, s[28:29]
	v_lshl_add_u64 v[118:119], s[6:7], 0, v[226:227]
	v_lshlrev_b64 v[242:243], 12, v[120:121]
	v_lshl_add_u64 v[126:127], v[118:119], 0, v[242:243]
	global_load_dwordx4 v[94:97], v[86:87], off offset:16
	global_load_dwordx4 v[102:105], v[86:87], off
	global_load_dwordx4 v[78:81], v[86:87], off offset:528
	s_nop 0
	global_load_dwordx4 v[86:89], v[86:87], off offset:512
	s_nop 0
	global_load_dwordx4 v[210:213], v[126:127], off
	global_load_dwordx4 v[202:205], v[126:127], off offset:256
	v_or_b32_e32 v126, 16, v120
	v_ashrrev_i32_e32 v127, 31, v126
	v_lshlrev_b64 v[240:241], 12, v[126:127]
	v_lshl_add_u64 v[126:127], v[118:119], 0, v[240:241]
	global_load_dwordx4 v[198:201], v[126:127], off
	global_load_dwordx4 v[194:197], v[126:127], off offset:256
	v_or_b32_e32 v126, 32, v120
	v_ashrrev_i32_e32 v127, 31, v126
	v_lshlrev_b64 v[238:239], 12, v[126:127]
	v_lshl_add_u64 v[126:127], v[118:119], 0, v[238:239]
	global_load_dwordx4 v[190:193], v[126:127], off
	global_load_dwordx4 v[186:189], v[126:127], off offset:256
	v_or_b32_e32 v120, 48, v120
	v_ashrrev_i32_e32 v121, 31, v120
	v_lshlrev_b64 v[236:237], 12, v[120:121]
	v_lshl_add_u64 v[120:121], v[118:119], 0, v[236:237]
	global_load_dwordx4 v[182:185], v[120:121], off
	global_load_dwordx4 v[170:173], v[120:121], off offset:256
	s_mov_b64 s[28:29], 0x80000
	v_lshl_add_u64 v[234:235], v[242:243], 0, s[28:29]
	v_lshl_add_u64 v[120:121], v[118:119], 0, v[234:235]
	global_load_dwordx4 v[166:169], v[120:121], off
	global_load_dwordx4 v[162:165], v[120:121], off offset:256
	s_mov_b64 s[28:29], 0x90000
	v_lshl_add_u64 v[232:233], v[242:243], 0, s[28:29]
	v_lshl_add_u64 v[120:121], v[118:119], 0, v[232:233]
	global_load_dwordx4 v[158:161], v[120:121], off
	global_load_dwordx4 v[154:157], v[120:121], off offset:256
	s_mov_b64 s[28:29], 0xa0000
	v_lshl_add_u64 v[230:231], v[242:243], 0, s[28:29]
	v_lshl_add_u64 v[120:121], v[118:119], 0, v[230:231]
	global_load_dwordx4 v[142:145], v[120:121], off
	global_load_dwordx4 v[134:137], v[120:121], off offset:256
	s_mov_b64 s[28:29], 0xb0000
	v_lshl_add_u64 v[228:229], v[242:243], 0, s[28:29]
	v_lshl_add_u64 v[118:119], v[118:119], 0, v[228:229]
	global_load_dwordx4 v[126:129], v[118:119], off
	s_nop 0
	global_load_dwordx4 v[118:121], v[118:119], off offset:256
	s_mov_b64 s[28:29], -1
	s_and_b64 vcc, exec, s[36:37]
	v_readlane_b32 s57, v255, 11
	s_movk_i32 s54, 0xffc0
	s_movk_i32 s55, 0xc00
	s_mov_b32 s56, 0xfe03f81
	s_waitcnt vmcnt(0)
	v_cvt_f32_f16_e32 v246, v210
	v_cvt_f32_f16_sdwa v247, v210 dst_sel:DWORD dst_unused:UNUSED_PAD src0_sel:WORD_1
	v_cvt_f32_f16_e32 v210, v211
	v_cvt_f32_f16_sdwa v211, v211 dst_sel:DWORD dst_unused:UNUSED_PAD src0_sel:WORD_1
	v_pk_fma_f32 v[178:179], v[178:179], v[102:103], v[246:247]
	s_nop 0
	v_cvt_pk_f16_f32 v178, v178, v179
	v_pk_fma_f32 v[180:181], v[180:181], v[104:105], v[210:211]
	s_nop 0
	v_cvt_pk_f16_f32 v179, v180, v181
	v_cvt_f32_f16_e32 v180, v212
	v_cvt_f32_f16_sdwa v181, v212 dst_sel:DWORD dst_unused:UNUSED_PAD src0_sel:WORD_1
	v_pk_fma_f32 v[174:175], v[174:175], v[94:95], v[180:181]
	s_nop 0
	v_cvt_pk_f16_f32 v180, v174, v175
	v_cvt_f32_f16_e32 v174, v213
	v_cvt_f32_f16_sdwa v175, v213 dst_sel:DWORD dst_unused:UNUSED_PAD src0_sel:WORD_1
	v_pk_fma_f32 v[174:175], v[176:177], v[96:97], v[174:175]
	v_cvt_f32_f16_e32 v176, v202
	v_cvt_f32_f16_sdwa v177, v202 dst_sel:DWORD dst_unused:UNUSED_PAD src0_sel:WORD_1
	v_cvt_pk_f16_f32 v181, v174, v175
	v_lshl_add_u64 v[174:175], s[6:7], 0, v[242:243]
	v_lshl_add_u64 v[174:175], v[174:175], 0, v[226:227]
	v_pk_fma_f32 v[150:151], v[150:151], v[86:87], v[176:177]
	v_cvt_f32_f16_e32 v176, v203
	v_cvt_f32_f16_sdwa v177, v203 dst_sel:DWORD dst_unused:UNUSED_PAD src0_sel:WORD_1
	v_cvt_pk_f16_f32 v150, v150, v151
	global_store_dwordx4 v[174:175], v[178:181], off
	v_pk_fma_f32 v[152:153], v[152:153], v[88:89], v[176:177]
	s_nop 0
	v_cvt_pk_f16_f32 v151, v152, v153
	v_cvt_f32_f16_e32 v152, v204
	v_cvt_f32_f16_sdwa v153, v204 dst_sel:DWORD dst_unused:UNUSED_PAD src0_sel:WORD_1
	v_pk_fma_f32 v[146:147], v[146:147], v[78:79], v[152:153]
	s_nop 0
	v_cvt_pk_f16_f32 v152, v146, v147
	v_cvt_f32_f16_e32 v146, v205
	v_cvt_f32_f16_sdwa v147, v205 dst_sel:DWORD dst_unused:UNUSED_PAD src0_sel:WORD_1
	v_pk_fma_f32 v[146:147], v[148:149], v[80:81], v[146:147]
	s_nop 0
	v_cvt_pk_f16_f32 v153, v146, v147
	v_cvt_f32_f16_e32 v146, v198
	v_cvt_f32_f16_sdwa v147, v198 dst_sel:DWORD dst_unused:UNUSED_PAD src0_sel:WORD_1
	global_store_dwordx4 v[174:175], v[150:153], off offset:256
	v_pk_fma_f32 v[138:139], v[138:139], v[102:103], v[146:147]
	v_cvt_f32_f16_e32 v146, v199
	v_cvt_f32_f16_sdwa v147, v199 dst_sel:DWORD dst_unused:UNUSED_PAD src0_sel:WORD_1
	v_cvt_pk_f16_f32 v138, v138, v139
	v_pk_fma_f32 v[140:141], v[140:141], v[104:105], v[146:147]
	s_nop 0
	v_cvt_pk_f16_f32 v139, v140, v141
	v_cvt_f32_f16_e32 v140, v200
	v_cvt_f32_f16_sdwa v141, v200 dst_sel:DWORD dst_unused:UNUSED_PAD src0_sel:WORD_1
	v_pk_fma_f32 v[130:131], v[130:131], v[94:95], v[140:141]
	s_nop 0
	v_cvt_pk_f16_f32 v140, v130, v131
	v_cvt_f32_f16_e32 v130, v201
	v_cvt_f32_f16_sdwa v131, v201 dst_sel:DWORD dst_unused:UNUSED_PAD src0_sel:WORD_1
	v_pk_fma_f32 v[130:131], v[132:133], v[96:97], v[130:131]
	v_cvt_f32_f16_e32 v132, v194
; __device__ __forceinline__ float hlo(unsigned w) { return (float)__builtin_bit_cast(h16x2_t, w).x; }
; __device__ __forceinline__ float hhi(unsigned w) { return (float)__builtin_bit_cast(h16x2_t, w).y; }
;     __device__ __forceinline__ void operator()(const f32x4 (&acc)[2][2][4][2], const Unit& u, int wr, int wc, int fr, int fq) const {
;     ...
; #pragma unroll
;             for (int ai = 0; ai < 2; ++ai)
; #pragma unroll
;                 for (int m = 0; m < 4; ++m) { const size_t off = (size_t)(row0 + ai * HALF + m * 16) * 2048 + col0;
; #pragma unroll
;                     for (int bj = 0; bj < 2; ++bj) { const u32x4 o = xo[ai][m][bj]; const f32x4 a0 = acc[ai][bj][m][0], a1 = acc[ai][bj][m][1], g0 = gv[bj][0], g1 = gv[bj][1];
;                         u32x4 w;
;                         w.x = pkh2(hlo(o.x) + g0[0] * a0[0], hhi(o.x) + g0[1] * a0[1]); w.y = pkh2(hlo(o.y) + g0[2] * a0[2], hhi(o.y) + g0[3] * a0[3]);
;                         w.z = pkh2(hlo(o.z) + g1[0] * a1[0], hhi(o.z) + g1[1] * a1[1]); w.w = pkh2(hlo(o.w) + g1[2] * a1[2], hhi(o.w) + g1[3] * a1[3]);
;                         *(u32x4*)(xnew + off + bj * HALF) = w; } }
	v_cvt_f32_f16_sdwa v133, v194 dst_sel:DWORD dst_unused:UNUSED_PAD src0_sel:WORD_1
	v_cvt_pk_f16_f32 v141, v130, v131
	v_lshl_add_u64 v[130:131], s[6:7], 0, v[240:241]
	v_lshl_add_u64 v[130:131], v[130:131], 0, v[226:227]
	v_pk_fma_f32 v[122:123], v[122:123], v[86:87], v[132:133]
	v_cvt_f32_f16_e32 v132, v195
	v_cvt_f32_f16_sdwa v133, v195 dst_sel:DWORD dst_unused:UNUSED_PAD src0_sel:WORD_1
	v_cvt_pk_f16_f32 v122, v122, v123
	global_store_dwordx4 v[130:131], v[138:141], off
	v_pk_fma_f32 v[124:125], v[124:125], v[88:89], v[132:133]
	s_nop 0
	v_cvt_pk_f16_f32 v123, v124, v125
	v_cvt_f32_f16_e32 v124, v196
	v_cvt_f32_f16_sdwa v125, v196 dst_sel:DWORD dst_unused:UNUSED_PAD src0_sel:WORD_1
	v_pk_fma_f32 v[114:115], v[114:115], v[78:79], v[124:125]
	s_nop 0
	v_cvt_pk_f16_f32 v124, v114, v115
	v_cvt_f32_f16_e32 v114, v197
	v_cvt_f32_f16_sdwa v115, v197 dst_sel:DWORD dst_unused:UNUSED_PAD src0_sel:WORD_1
	v_pk_fma_f32 v[114:115], v[116:117], v[80:81], v[114:115]
	s_nop 0
	v_cvt_pk_f16_f32 v125, v114, v115
	v_cvt_f32_f16_e32 v114, v190
	v_cvt_f32_f16_sdwa v115, v190 dst_sel:DWORD dst_unused:UNUSED_PAD src0_sel:WORD_1
	global_store_dwordx4 v[130:131], v[122:125], off offset:256
	v_pk_fma_f32 v[110:111], v[110:111], v[102:103], v[114:115]
	v_cvt_f32_f16_e32 v114, v191
	v_cvt_f32_f16_sdwa v115, v191 dst_sel:DWORD dst_unused:UNUSED_PAD src0_sel:WORD_1
	v_cvt_pk_f16_f32 v110, v110, v111
	v_pk_fma_f32 v[112:113], v[112:113], v[104:105], v[114:115]
	s_nop 0
	v_cvt_pk_f16_f32 v111, v112, v113
	v_cvt_f32_f16_e32 v112, v192
	v_cvt_f32_f16_sdwa v113, v192 dst_sel:DWORD dst_unused:UNUSED_PAD src0_sel:WORD_1
	v_pk_fma_f32 v[106:107], v[106:107], v[94:95], v[112:113]
	s_nop 0
	v_cvt_pk_f16_f32 v112, v106, v107
	v_cvt_f32_f16_e32 v106, v193
	v_cvt_f32_f16_sdwa v107, v193 dst_sel:DWORD dst_unused:UNUSED_PAD src0_sel:WORD_1
	v_pk_fma_f32 v[106:107], v[108:109], v[96:97], v[106:107]
	v_cvt_f32_f16_e32 v108, v186
	v_cvt_f32_f16_sdwa v109, v186 dst_sel:DWORD dst_unused:UNUSED_PAD src0_sel:WORD_1
	v_cvt_pk_f16_f32 v113, v106, v107
	v_lshl_add_u64 v[106:107], s[6:7], 0, v[238:239]
	v_lshl_add_u64 v[106:107], v[106:107], 0, v[226:227]
	v_pk_fma_f32 v[98:99], v[98:99], v[86:87], v[108:109]
	v_cvt_f32_f16_e32 v108, v187
	v_cvt_f32_f16_sdwa v109, v187 dst_sel:DWORD dst_unused:UNUSED_PAD src0_sel:WORD_1
	v_cvt_pk_f16_f32 v98, v98, v99
	global_store_dwordx4 v[106:107], v[110:113], off
	v_pk_fma_f32 v[100:101], v[100:101], v[88:89], v[108:109]
	s_nop 0
	v_cvt_pk_f16_f32 v99, v100, v101
	v_cvt_f32_f16_e32 v100, v188
	v_cvt_f32_f16_sdwa v101, v188 dst_sel:DWORD dst_unused:UNUSED_PAD src0_sel:WORD_1
	v_pk_fma_f32 v[90:91], v[90:91], v[78:79], v[100:101]
	s_nop 0
	v_cvt_pk_f16_f32 v100, v90, v91
	v_cvt_f32_f16_e32 v90, v189
	v_cvt_f32_f16_sdwa v91, v189 dst_sel:DWORD dst_unused:UNUSED_PAD src0_sel:WORD_1
	v_pk_fma_f32 v[90:91], v[92:93], v[80:81], v[90:91]
	s_nop 0
	v_cvt_pk_f16_f32 v101, v90, v91
	v_cvt_f32_f16_e32 v90, v182
	v_cvt_f32_f16_sdwa v91, v182 dst_sel:DWORD dst_unused:UNUSED_PAD src0_sel:WORD_1
	global_store_dwordx4 v[106:107], v[98:101], off offset:256
	v_pk_fma_f32 v[82:83], v[82:83], v[102:103], v[90:91]
	v_cvt_f32_f16_e32 v90, v183
	v_cvt_f32_f16_sdwa v91, v183 dst_sel:DWORD dst_unused:UNUSED_PAD src0_sel:WORD_1
	v_cvt_pk_f16_f32 v82, v82, v83
	v_pk_fma_f32 v[84:85], v[84:85], v[104:105], v[90:91]
	s_nop 0
	v_cvt_pk_f16_f32 v83, v84, v85
	v_cvt_f32_f16_e32 v84, v184
	v_cvt_f32_f16_sdwa v85, v184 dst_sel:DWORD dst_unused:UNUSED_PAD src0_sel:WORD_1
	v_pk_fma_f32 v[74:75], v[74:75], v[94:95], v[84:85]
	s_nop 0
	v_cvt_pk_f16_f32 v84, v74, v75
	v_cvt_f32_f16_e32 v74, v185
	v_cvt_f32_f16_sdwa v75, v185 dst_sel:DWORD dst_unused:UNUSED_PAD src0_sel:WORD_1
	v_pk_fma_f32 v[74:75], v[76:77], v[96:97], v[74:75]
	v_cvt_f32_f16_e32 v76, v170
	v_cvt_f32_f16_sdwa v77, v170 dst_sel:DWORD dst_unused:UNUSED_PAD src0_sel:WORD_1
	v_cvt_pk_f16_f32 v85, v74, v75
	v_lshl_add_u64 v[74:75], s[6:7], 0, v[236:237]
	v_lshl_add_u64 v[74:75], v[74:75], 0, v[226:227]
	v_pk_fma_f32 v[70:71], v[70:71], v[86:87], v[76:77]
	v_cvt_f32_f16_e32 v76, v171
	v_cvt_f32_f16_sdwa v77, v171 dst_sel:DWORD dst_unused:UNUSED_PAD src0_sel:WORD_1
	v_cvt_pk_f16_f32 v70, v70, v71
	global_store_dwordx4 v[74:75], v[82:85], off
	v_pk_fma_f32 v[72:73], v[72:73], v[88:89], v[76:77]
	s_nop 0
	v_cvt_pk_f16_f32 v71, v72, v73
	v_cvt_f32_f16_e32 v72, v172
	v_cvt_f32_f16_sdwa v73, v172 dst_sel:DWORD dst_unused:UNUSED_PAD src0_sel:WORD_1
	v_pk_fma_f32 v[66:67], v[66:67], v[78:79], v[72:73]
	s_nop 0
	v_cvt_pk_f16_f32 v72, v66, v67
	v_cvt_f32_f16_e32 v66, v173
	v_cvt_f32_f16_sdwa v67, v173 dst_sel:DWORD dst_unused:UNUSED_PAD src0_sel:WORD_1
	v_pk_fma_f32 v[66:67], v[68:69], v[80:81], v[66:67]
	s_nop 0
	v_cvt_pk_f16_f32 v73, v66, v67
	v_cvt_f32_f16_e32 v66, v166
	v_cvt_f32_f16_sdwa v67, v166 dst_sel:DWORD dst_unused:UNUSED_PAD src0_sel:WORD_1
	global_store_dwordx4 v[74:75], v[70:73], off offset:256
	v_pk_fma_f32 v[62:63], v[62:63], v[102:103], v[66:67]
	v_cvt_f32_f16_e32 v66, v167
	v_cvt_f32_f16_sdwa v67, v167 dst_sel:DWORD dst_unused:UNUSED_PAD src0_sel:WORD_1
	v_cvt_pk_f16_f32 v62, v62, v63
	v_pk_fma_f32 v[64:65], v[64:65], v[104:105], v[66:67]
	s_nop 0
	v_cvt_pk_f16_f32 v63, v64, v65
	v_cvt_f32_f16_e32 v64, v168
	v_cvt_f32_f16_sdwa v65, v168 dst_sel:DWORD dst_unused:UNUSED_PAD src0_sel:WORD_1
	v_pk_fma_f32 v[58:59], v[58:59], v[94:95], v[64:65]
	s_nop 0
	v_cvt_pk_f16_f32 v64, v58, v59
	v_cvt_f32_f16_e32 v58, v169
	v_cvt_f32_f16_sdwa v59, v169 dst_sel:DWORD dst_unused:UNUSED_PAD src0_sel:WORD_1
	v_pk_fma_f32 v[58:59], v[60:61], v[96:97], v[58:59]
	v_cvt_f32_f16_e32 v60, v162
	v_cvt_f32_f16_sdwa v61, v162 dst_sel:DWORD dst_unused:UNUSED_PAD src0_sel:WORD_1
; __device__ __forceinline__ float hlo(unsigned w) { return (float)__builtin_bit_cast(h16x2_t, w).x; }
; __device__ __forceinline__ float hhi(unsigned w) { return (float)__builtin_bit_cast(h16x2_t, w).y; }
; #define PG8_BAR __builtin_amdgcn_s_barrier()
;     __device__ __forceinline__ void operator()(const f32x4 (&acc)[2][2][4][2], const Unit& u, int wr, int wc, int fr, int fq) const {
;     ...
; #pragma unroll
;             for (int ai = 0; ai < 2; ++ai)
; #pragma unroll
;                 for (int m = 0; m < 4; ++m) { const size_t off = (size_t)(row0 + ai * HALF + m * 16) * 2048 + col0;
; #pragma unroll
;                     for (int bj = 0; bj < 2; ++bj) { const u32x4 o = xo[ai][m][bj]; const f32x4 a0 = acc[ai][bj][m][0], a1 = acc[ai][bj][m][1], g0 = gv[bj][0], g1 = gv[bj][1];
;                         u32x4 w;
;                         w.x = pkh2(hlo(o.x) + g0[0] * a0[0], hhi(o.x) + g0[1] * a0[1]); w.y = pkh2(hlo(o.y) + g0[2] * a0[2], hhi(o.y) + g0[3] * a0[3]);
;                         w.z = pkh2(hlo(o.z) + g1[0] * a1[0], hhi(o.z) + g1[1] * a1[1]); w.w = pkh2(hlo(o.w) + g1[2] * a1[2], hhi(o.w) + g1[3] * a1[3]);
;                         *(u32x4*)(xnew + off + bj * HALF) = w; } }
; template <class Epi, class Sched, bool ALIGN_EPI = false, bool SP2 = false>
; __device__ __forceinline__ void gemm_phase(PG8_LAS unsigned char* lds, const Gemm g, const Sched& S, const Epi& E, const int tid_in) {
;     ...
;         if (!has_next) break;
; #pragma unroll
;         for (int a = 0; a < 2; ++a)
; #pragma unroll
;             for (int b = 0; b < 2; ++b)
; #pragma unroll
;                 for (int m = 0; m < 4; ++m)
; #pragma unroll
;                     for (int n = 0; n < 2; ++n) acc[a][b][m][n] = (f32x4){0.f, 0.f, 0.f, 0.f};
;         cur = nxt; cA = nA; cB = nB; ++ui;
;         if constexpr (ALIGN_EPI) { if (wr == 1) PG8_BAR; }
	v_cvt_pk_f16_f32 v65, v58, v59
	v_lshl_add_u64 v[58:59], s[6:7], 0, v[234:235]
	v_lshl_add_u64 v[58:59], v[58:59], 0, v[226:227]
	v_pk_fma_f32 v[54:55], v[54:55], v[86:87], v[60:61]
	v_cvt_f32_f16_e32 v60, v163
	v_cvt_f32_f16_sdwa v61, v163 dst_sel:DWORD dst_unused:UNUSED_PAD src0_sel:WORD_1
	v_cvt_pk_f16_f32 v54, v54, v55
	global_store_dwordx4 v[58:59], v[62:65], off
	v_pk_fma_f32 v[56:57], v[56:57], v[88:89], v[60:61]
	s_nop 0
	v_cvt_pk_f16_f32 v55, v56, v57
	v_cvt_f32_f16_e32 v56, v164
	v_cvt_f32_f16_sdwa v57, v164 dst_sel:DWORD dst_unused:UNUSED_PAD src0_sel:WORD_1
	v_pk_fma_f32 v[50:51], v[50:51], v[78:79], v[56:57]
	s_nop 0
	v_cvt_pk_f16_f32 v56, v50, v51
	v_cvt_f32_f16_e32 v50, v165
	v_cvt_f32_f16_sdwa v51, v165 dst_sel:DWORD dst_unused:UNUSED_PAD src0_sel:WORD_1
	v_pk_fma_f32 v[50:51], v[52:53], v[80:81], v[50:51]
	s_nop 0
	v_cvt_pk_f16_f32 v57, v50, v51
	v_cvt_f32_f16_e32 v50, v158
	v_cvt_f32_f16_sdwa v51, v158 dst_sel:DWORD dst_unused:UNUSED_PAD src0_sel:WORD_1
	global_store_dwordx4 v[58:59], v[54:57], off offset:256
	v_pk_fma_f32 v[46:47], v[46:47], v[102:103], v[50:51]
	v_cvt_f32_f16_e32 v50, v159
	v_cvt_f32_f16_sdwa v51, v159 dst_sel:DWORD dst_unused:UNUSED_PAD src0_sel:WORD_1
	v_cvt_pk_f16_f32 v46, v46, v47
	v_pk_fma_f32 v[48:49], v[48:49], v[104:105], v[50:51]
	s_nop 0
	v_cvt_pk_f16_f32 v47, v48, v49
	v_cvt_f32_f16_e32 v48, v160
	v_cvt_f32_f16_sdwa v49, v160 dst_sel:DWORD dst_unused:UNUSED_PAD src0_sel:WORD_1
	v_pk_fma_f32 v[42:43], v[42:43], v[94:95], v[48:49]
	s_nop 0
	v_cvt_pk_f16_f32 v48, v42, v43
	v_cvt_f32_f16_e32 v42, v161
	v_cvt_f32_f16_sdwa v43, v161 dst_sel:DWORD dst_unused:UNUSED_PAD src0_sel:WORD_1
	v_pk_fma_f32 v[42:43], v[44:45], v[96:97], v[42:43]
	v_cvt_f32_f16_e32 v44, v154
	v_cvt_f32_f16_sdwa v45, v154 dst_sel:DWORD dst_unused:UNUSED_PAD src0_sel:WORD_1
	v_cvt_pk_f16_f32 v49, v42, v43
	v_lshl_add_u64 v[42:43], s[6:7], 0, v[232:233]
	v_lshl_add_u64 v[42:43], v[42:43], 0, v[226:227]
	v_pk_fma_f32 v[38:39], v[38:39], v[86:87], v[44:45]
	v_cvt_f32_f16_e32 v44, v155
	v_cvt_f32_f16_sdwa v45, v155 dst_sel:DWORD dst_unused:UNUSED_PAD src0_sel:WORD_1
	v_cvt_pk_f16_f32 v38, v38, v39
	global_store_dwordx4 v[42:43], v[46:49], off
	v_pk_fma_f32 v[40:41], v[40:41], v[88:89], v[44:45]
	s_nop 0
	v_cvt_pk_f16_f32 v39, v40, v41
	v_cvt_f32_f16_e32 v40, v156
	v_cvt_f32_f16_sdwa v41, v156 dst_sel:DWORD dst_unused:UNUSED_PAD src0_sel:WORD_1
	v_pk_fma_f32 v[34:35], v[34:35], v[78:79], v[40:41]
	s_nop 0
	v_cvt_pk_f16_f32 v40, v34, v35
	v_cvt_f32_f16_e32 v34, v157
	v_cvt_f32_f16_sdwa v35, v157 dst_sel:DWORD dst_unused:UNUSED_PAD src0_sel:WORD_1
	v_pk_fma_f32 v[34:35], v[36:37], v[80:81], v[34:35]
	s_nop 0
	v_cvt_pk_f16_f32 v41, v34, v35
	v_cvt_f32_f16_e32 v34, v142
	v_cvt_f32_f16_sdwa v35, v142 dst_sel:DWORD dst_unused:UNUSED_PAD src0_sel:WORD_1
	global_store_dwordx4 v[42:43], v[38:41], off offset:256
	v_pk_fma_f32 v[30:31], v[30:31], v[102:103], v[34:35]
	v_cvt_f32_f16_e32 v34, v143
	v_cvt_f32_f16_sdwa v35, v143 dst_sel:DWORD dst_unused:UNUSED_PAD src0_sel:WORD_1
	v_cvt_pk_f16_f32 v30, v30, v31
	v_pk_fma_f32 v[32:33], v[32:33], v[104:105], v[34:35]
	s_nop 0
	v_cvt_pk_f16_f32 v31, v32, v33
	v_cvt_f32_f16_e32 v32, v144
	v_cvt_f32_f16_sdwa v33, v144 dst_sel:DWORD dst_unused:UNUSED_PAD src0_sel:WORD_1
	v_pk_fma_f32 v[26:27], v[26:27], v[94:95], v[32:33]
	s_nop 0
	v_cvt_pk_f16_f32 v32, v26, v27
	v_cvt_f32_f16_e32 v26, v145
	v_cvt_f32_f16_sdwa v27, v145 dst_sel:DWORD dst_unused:UNUSED_PAD src0_sel:WORD_1
	v_pk_fma_f32 v[26:27], v[28:29], v[96:97], v[26:27]
	v_cvt_f32_f16_e32 v28, v134
	v_cvt_f32_f16_sdwa v29, v134 dst_sel:DWORD dst_unused:UNUSED_PAD src0_sel:WORD_1
	v_cvt_pk_f16_f32 v33, v26, v27
	v_lshl_add_u64 v[26:27], s[6:7], 0, v[230:231]
	v_lshl_add_u64 v[26:27], v[26:27], 0, v[226:227]
	v_pk_fma_f32 v[22:23], v[22:23], v[86:87], v[28:29]
	v_cvt_f32_f16_e32 v28, v135
	v_cvt_f32_f16_sdwa v29, v135 dst_sel:DWORD dst_unused:UNUSED_PAD src0_sel:WORD_1
	v_cvt_pk_f16_f32 v22, v22, v23
	global_store_dwordx4 v[26:27], v[30:33], off
	v_pk_fma_f32 v[24:25], v[24:25], v[88:89], v[28:29]
	s_nop 0
	v_cvt_pk_f16_f32 v23, v24, v25
	v_cvt_f32_f16_e32 v24, v136
	v_cvt_f32_f16_sdwa v25, v136 dst_sel:DWORD dst_unused:UNUSED_PAD src0_sel:WORD_1
	v_pk_fma_f32 v[16:17], v[16:17], v[78:79], v[24:25]
	s_nop 0
	v_cvt_pk_f16_f32 v24, v16, v17
	v_cvt_f32_f16_e32 v16, v137
	v_cvt_f32_f16_sdwa v17, v137 dst_sel:DWORD dst_unused:UNUSED_PAD src0_sel:WORD_1
	v_pk_fma_f32 v[16:17], v[18:19], v[80:81], v[16:17]
	s_nop 0
	v_cvt_pk_f16_f32 v25, v16, v17
	v_cvt_f32_f16_e32 v16, v126
	v_cvt_f32_f16_sdwa v17, v126 dst_sel:DWORD dst_unused:UNUSED_PAD src0_sel:WORD_1
	global_store_dwordx4 v[26:27], v[22:25], off offset:256
	v_pk_fma_f32 v[12:13], v[12:13], v[102:103], v[16:17]
	v_cvt_f32_f16_e32 v16, v127
	v_cvt_f32_f16_sdwa v17, v127 dst_sel:DWORD dst_unused:UNUSED_PAD src0_sel:WORD_1
	v_cvt_pk_f16_f32 v12, v12, v13
	v_pk_fma_f32 v[14:15], v[14:15], v[104:105], v[16:17]
	s_nop 0
	v_cvt_pk_f16_f32 v13, v14, v15
	v_cvt_f32_f16_e32 v14, v128
	v_cvt_f32_f16_sdwa v15, v128 dst_sel:DWORD dst_unused:UNUSED_PAD src0_sel:WORD_1
	v_pk_fma_f32 v[8:9], v[8:9], v[94:95], v[14:15]
	s_nop 0
	v_cvt_pk_f16_f32 v14, v8, v9
	v_cvt_f32_f16_e32 v8, v129
	v_cvt_f32_f16_sdwa v9, v129 dst_sel:DWORD dst_unused:UNUSED_PAD src0_sel:WORD_1
	v_pk_fma_f32 v[8:9], v[10:11], v[96:97], v[8:9]
	v_cvt_f32_f16_e32 v10, v118
	v_cvt_f32_f16_sdwa v11, v118 dst_sel:DWORD dst_unused:UNUSED_PAD src0_sel:WORD_1
	v_cvt_pk_f16_f32 v15, v8, v9
	v_lshl_add_u64 v[8:9], s[6:7], 0, v[228:229]
	v_lshl_add_u64 v[8:9], v[8:9], 0, v[226:227]
	v_pk_fma_f32 v[4:5], v[4:5], v[86:87], v[10:11]
	v_cvt_f32_f16_e32 v10, v119
	v_cvt_f32_f16_sdwa v11, v119 dst_sel:DWORD dst_unused:UNUSED_PAD src0_sel:WORD_1
	v_cvt_pk_f16_f32 v4, v4, v5
	global_store_dwordx4 v[8:9], v[12:15], off
	v_pk_fma_f32 v[6:7], v[6:7], v[88:89], v[10:11]
	s_nop 0
	v_cvt_pk_f16_f32 v5, v6, v7
	v_cvt_f32_f16_e32 v6, v120
	v_cvt_f32_f16_sdwa v7, v120 dst_sel:DWORD dst_unused:UNUSED_PAD src0_sel:WORD_1
	v_pk_fma_f32 v[0:1], v[0:1], v[78:79], v[6:7]
	s_nop 0
	v_cvt_pk_f16_f32 v6, v0, v1
	v_cvt_f32_f16_e32 v0, v121
	v_cvt_f32_f16_sdwa v1, v121 dst_sel:DWORD dst_unused:UNUSED_PAD src0_sel:WORD_1
	v_pk_fma_f32 v[0:1], v[2:3], v[80:81], v[0:1]
	s_nop 0
	v_cvt_pk_f16_f32 v7, v0, v1
	global_store_dwordx4 v[8:9], v[4:7], off offset:256
	s_cbranch_vccnz .LBB0_1293
	s_andn2_b64 vcc, exec, s[2:3]
	s_cbranch_vccnz .LBB0_1292
	s_branch .LBB0_1292
